# non-temporal hint on every global store of the layer loop (activations are consumed after a grid barrier by other XCDs)
# baseline (speedup 1.0000x reference)
.Lxn_wd_l0a:
	s_lshl_b32 s4, s16, 11
	s_add_u32 s12, s52, s4
	s_addc_u32 s13, s53, 0
	v_pk_mul_f32 v[24:25], v[56:57], v[24:25]
	v_pk_mul_f32 v[26:27], v[58:59], v[26:27]
	v_pk_add_f32 v[72:73], v[72:73], 1.0 op_sel_hi:[1,0]
	v_pk_add_f32 v[74:75], v[74:75], 1.0 op_sel_hi:[1,0]
	v_pk_fma_f32 v[24:25], v[72:73], v[24:25], v[88:89]
	v_pk_fma_f32 v[26:27], v[74:75], v[26:27], v[90:91]
	v_cvt_pk_bf16_f32 v114, v24, v25
	v_cvt_pk_bf16_f32 v115, v26, v27
	global_store_dwordx2 v21, v[114:115], s[12:13] nt
	v_pk_mul_f32 v[28:29], v[60:61], v[28:29]
	v_pk_mul_f32 v[30:31], v[62:63], v[30:31]
	v_pk_add_f32 v[76:77], v[76:77], 1.0 op_sel_hi:[1,0]
	v_pk_add_f32 v[78:79], v[78:79], 1.0 op_sel_hi:[1,0]
	v_pk_fma_f32 v[28:29], v[76:77], v[28:29], v[92:93]
	v_pk_fma_f32 v[30:31], v[78:79], v[30:31], v[94:95]
	v_cvt_pk_bf16_f32 v114, v28, v29
	v_cvt_pk_bf16_f32 v115, v30, v31
	global_store_dwordx2 v21, v[114:115], s[12:13] offset:512 nt
	v_pk_mul_f32 v[32:33], v[64:65], v[32:33]
	v_pk_mul_f32 v[34:35], v[66:67], v[34:35]
	v_pk_add_f32 v[80:81], v[80:81], 1.0 op_sel_hi:[1,0]
	v_pk_add_f32 v[82:83], v[82:83], 1.0 op_sel_hi:[1,0]
	v_pk_fma_f32 v[32:33], v[80:81], v[32:33], v[96:97]
	v_pk_fma_f32 v[34:35], v[82:83], v[34:35], v[98:99]
	v_cvt_pk_bf16_f32 v114, v32, v33
	v_cvt_pk_bf16_f32 v115, v34, v35
	global_store_dwordx2 v21, v[114:115], s[12:13] offset:1024 nt
	v_pk_mul_f32 v[36:37], v[68:69], v[36:37]
	v_pk_mul_f32 v[38:39], v[70:71], v[38:39]
	v_pk_add_f32 v[84:85], v[84:85], 1.0 op_sel_hi:[1,0]
	v_pk_add_f32 v[86:87], v[86:87], 1.0 op_sel_hi:[1,0]
	v_pk_fma_f32 v[36:37], v[84:85], v[36:37], v[100:101]
	v_pk_fma_f32 v[38:39], v[86:87], v[38:39], v[102:103]
	v_cvt_pk_bf16_f32 v114, v36, v37
	v_cvt_pk_bf16_f32 v115, v38, v39
	global_store_dwordx2 v21, v[114:115], s[12:13] offset:1536 nt
	s_mov_b32 s16, s5
	s_cmp_lt_u32 s16, 0x4000
	s_cbranch_scc0 .Lxn_done
	s_cmp_lt_u32 s16, 0x2000
	s_cbranch_scc1 .Lxn_idx0_l0b
	s_sub_u32 s4, s16, 0x2000
	s_lshr_b32 s4, s4, 12
	s_add_u32 s4, s4, 1
	s_mul_i32 s4, s4, 0x3000
	s_add_u32 s10, s66, s4
	s_addc_u32 s11, s67, 0
	s_branch .Lxn_idxd_l0b

.Lxn_wd_l0b:
	s_lshl_b32 s4, s16, 11
	s_add_u32 s12, s52, s4
	s_addc_u32 s13, s53, 0
	v_pk_mul_f32 v[40:41], v[56:57], v[40:41]
	v_pk_mul_f32 v[42:43], v[58:59], v[42:43]
	v_pk_add_f32 v[72:73], v[72:73], 1.0 op_sel_hi:[1,0]
	v_pk_add_f32 v[74:75], v[74:75], 1.0 op_sel_hi:[1,0]
	v_pk_fma_f32 v[40:41], v[72:73], v[40:41], v[88:89]
	v_pk_fma_f32 v[42:43], v[74:75], v[42:43], v[90:91]
	v_cvt_pk_bf16_f32 v114, v40, v41
	v_cvt_pk_bf16_f32 v115, v42, v43
	global_store_dwordx2 v21, v[114:115], s[12:13] nt
	v_pk_mul_f32 v[44:45], v[60:61], v[44:45]
	v_pk_mul_f32 v[46:47], v[62:63], v[46:47]
	v_pk_add_f32 v[76:77], v[76:77], 1.0 op_sel_hi:[1,0]
	v_pk_add_f32 v[78:79], v[78:79], 1.0 op_sel_hi:[1,0]
	v_pk_fma_f32 v[44:45], v[76:77], v[44:45], v[92:93]
	v_pk_fma_f32 v[46:47], v[78:79], v[46:47], v[94:95]
	v_cvt_pk_bf16_f32 v114, v44, v45
	v_cvt_pk_bf16_f32 v115, v46, v47
	global_store_dwordx2 v21, v[114:115], s[12:13] offset:512 nt
	v_pk_mul_f32 v[48:49], v[64:65], v[48:49]
	v_pk_mul_f32 v[50:51], v[66:67], v[50:51]
	v_pk_add_f32 v[80:81], v[80:81], 1.0 op_sel_hi:[1,0]
	v_pk_add_f32 v[82:83], v[82:83], 1.0 op_sel_hi:[1,0]
	v_pk_fma_f32 v[48:49], v[80:81], v[48:49], v[96:97]
	v_pk_fma_f32 v[50:51], v[82:83], v[50:51], v[98:99]
	v_cvt_pk_bf16_f32 v114, v48, v49
	v_cvt_pk_bf16_f32 v115, v50, v51
	global_store_dwordx2 v21, v[114:115], s[12:13] offset:1024 nt
	v_pk_mul_f32 v[52:53], v[68:69], v[52:53]
	v_pk_mul_f32 v[54:55], v[70:71], v[54:55]
	v_pk_add_f32 v[84:85], v[84:85], 1.0 op_sel_hi:[1,0]
	v_pk_add_f32 v[86:87], v[86:87], 1.0 op_sel_hi:[1,0]
	v_pk_fma_f32 v[52:53], v[84:85], v[52:53], v[100:101]
	v_pk_fma_f32 v[54:55], v[86:87], v[54:55], v[102:103]
	v_cvt_pk_bf16_f32 v114, v52, v53
	v_cvt_pk_bf16_f32 v115, v54, v55
	global_store_dwordx2 v21, v[114:115], s[12:13] offset:1536 nt
	s_mov_b32 s16, s5
	s_cmp_lt_u32 s16, 0x4000
	s_cbranch_scc1 .Lxn_loop_l0
	s_branch .Lxn_done

.Lxn_wd_l1b:
	s_lshl_b32 s4, s16, 11
	s_add_u32 s12, s52, s4
	s_addc_u32 s13, s53, 0
	v_pk_mul_f32 v[40:41], v[56:57], v[40:41]
	v_pk_mul_f32 v[42:43], v[58:59], v[42:43]
	v_pk_add_f32 v[72:73], v[72:73], 1.0 op_sel_hi:[1,0]
	v_pk_add_f32 v[74:75], v[74:75], 1.0 op_sel_hi:[1,0]
	v_pk_fma_f32 v[40:41], v[72:73], v[40:41], v[88:89]
	v_pk_fma_f32 v[42:43], v[74:75], v[42:43], v[90:91]
	v_cvt_pk_bf16_f32 v114, v40, v41
	v_cvt_pk_bf16_f32 v115, v42, v43
	global_store_dwordx2 v21, v[114:115], s[12:13] nt
	v_pk_mul_f32 v[44:45], v[60:61], v[44:45]
	v_pk_mul_f32 v[46:47], v[62:63], v[46:47]
	v_pk_add_f32 v[76:77], v[76:77], 1.0 op_sel_hi:[1,0]
	v_pk_add_f32 v[78:79], v[78:79], 1.0 op_sel_hi:[1,0]
	v_pk_fma_f32 v[44:45], v[76:77], v[44:45], v[92:93]
	v_pk_fma_f32 v[46:47], v[78:79], v[46:47], v[94:95]
	v_cvt_pk_bf16_f32 v114, v44, v45
	v_cvt_pk_bf16_f32 v115, v46, v47
	global_store_dwordx2 v21, v[114:115], s[12:13] offset:512 nt
	v_pk_mul_f32 v[48:49], v[64:65], v[48:49]
	v_pk_mul_f32 v[50:51], v[66:67], v[50:51]
	v_pk_add_f32 v[80:81], v[80:81], 1.0 op_sel_hi:[1,0]
	v_pk_add_f32 v[82:83], v[82:83], 1.0 op_sel_hi:[1,0]
	v_pk_fma_f32 v[48:49], v[80:81], v[48:49], v[96:97]
	v_pk_fma_f32 v[50:51], v[82:83], v[50:51], v[98:99]
	v_cvt_pk_bf16_f32 v114, v48, v49
	v_cvt_pk_bf16_f32 v115, v50, v51
	global_store_dwordx2 v21, v[114:115], s[12:13] offset:1024 nt
	v_pk_mul_f32 v[52:53], v[68:69], v[52:53]
	v_pk_mul_f32 v[54:55], v[70:71], v[54:55]
	v_pk_add_f32 v[84:85], v[84:85], 1.0 op_sel_hi:[1,0]
	v_pk_add_f32 v[86:87], v[86:87], 1.0 op_sel_hi:[1,0]
	v_pk_fma_f32 v[52:53], v[84:85], v[52:53], v[100:101]
	v_pk_fma_f32 v[54:55], v[86:87], v[54:55], v[102:103]
	v_cvt_pk_bf16_f32 v114, v52, v53
	v_cvt_pk_bf16_f32 v115, v54, v55
	global_store_dwordx2 v21, v[114:115], s[12:13] offset:1536 nt
	s_mov_b32 s16, s5
	s_cmp_lt_u32 s16, 0x4000
	s_cbranch_scc1 .Lxn_loop_l1

.LBB0_433:
	s_lshl_b32 s74, s22, 8
	v_mov_b32_e32 v149, v5
	v_mov_b32_e32 v148, v139
	s_or_b32 s76, s74, s94
	s_cmpk_gt_i32 s76, 0x1ff
	v_lshlrev_b32_e32 v148, 3, v148
	s_cselect_b64 s[82:83], -1, 0
	s_add_i32 s6, s76, 0xfffffb00
	v_add_u32_e32 v150, s76, v148
	s_cmpk_gt_u32 s6, 0x19f
	s_movk_i32 s8, 0x500
	s_cselect_b64 s[80:81], -1, 0
	s_cmpk_lt_u32 s76, 0x8a0
	v_cmp_gt_i32_e32 vcc, s8, v150
	v_add_u32_e32 v162, s18, v149
	s_cselect_b64 s[78:79], -1, 0
	s_cmp_eq_u32 s22, 3
	v_cndmask_b32_e32 v149, v249, v250, vcc
	s_cselect_b64 s[6:7], -1, 0
	v_add_u32_e32 v152, v149, v150
	s_lshl_b32 s15, s23, 8
	v_ashrrev_i32_e32 v153, 31, v152
	v_ashrrev_i32_e32 v151, 31, v150
	v_add_u32_e32 v163, s15, v162
	s_mov_b64 s[8:9], -1
	s_and_b64 vcc, exec, s[82:83]
	s_cbranch_vccz .LBB0_441
	s_and_b64 vcc, exec, s[80:81]
	s_cbranch_vccz .LBB0_438
	s_andn2_b64 vcc, exec, s[78:79]
	s_cbranch_vccnz .LBB0_437
	v_mul_f32_e32 v154, 0xbfb8aa3b, v126
	v_exp_f32_e32 v154, v154
	v_mul_f32_e32 v155, 0xbfb8aa3b, v123
	v_mul_f32_e32 v156, 0xbfb8aa3b, v127
	v_exp_f32_e32 v155, v155
	v_add_f32_e32 v154, 1.0, v154
	v_rcp_f32_e32 v154, v154
	v_exp_f32_e32 v156, v156
	v_mul_f32_e32 v158, 0xbfb8aa3b, v128
	v_exp_f32_e32 v158, v158
	v_mul_f32_e32 v154, v126, v154
	v_cndmask_b32_e64 v157, v154, v126, s[6:7]
	v_add_f32_e32 v154, 1.0, v155
	v_add_f32_e32 v155, 1.0, v156
	v_mul_f32_e32 v156, 0xbfb8aa3b, v124
	v_exp_f32_e32 v156, v156
	v_rcp_f32_e32 v155, v155
	v_mul_f32_e32 v164, 0xbfb8aa3b, v129
	v_exp_f32_e32 v164, v164
	v_add_f32_e32 v156, 1.0, v156
	v_rcp_f32_e32 v156, v156
	v_mul_f32_e32 v155, v127, v155
	v_cndmask_b32_e64 v159, v155, v127, s[6:7]
	v_mul_f32_e32 v149, 0xbfb8aa3b, v122
	v_mul_f32_e32 v155, v124, v156
	v_add_f32_e32 v156, 1.0, v158
	v_mul_f32_e32 v158, 0xbfb8aa3b, v125
	v_exp_f32_e32 v158, v158
	v_exp_f32_e32 v149, v149
	v_rcp_f32_e32 v156, v156
	v_add_f32_e32 v164, 1.0, v164
	v_add_f32_e32 v158, 1.0, v158
	v_rcp_f32_e32 v158, v158
	v_rcp_f32_e32 v164, v164
	v_add_f32_e32 v149, 1.0, v149
	v_rcp_f32_e32 v149, v149
	v_rcp_f32_e32 v154, v154
	v_mul_f32_e32 v156, v128, v156
	v_cndmask_b32_e64 v165, v156, v128, s[6:7]
	v_mul_f32_e32 v156, v125, v158
	v_mul_f32_e32 v158, v129, v164
	v_readlane_b32 s8, v254, 8
	v_cndmask_b32_e64 v155, v155, v124, s[6:7]
	v_cndmask_b32_e64 v156, v156, v125, s[6:7]
	v_cndmask_b32_e64 v158, v158, v129, s[6:7]
	v_readlane_b32 s9, v254, 9
	v_mul_f32_e32 v149, v122, v149
	v_mul_f32_e32 v154, v123, v154
	v_cvt_pk_bf16_f32 v155, v155, v156
	v_cvt_pk_bf16_f32 v156, v157, v159
	v_cvt_pk_bf16_f32 v157, v165, v158
	v_mov_b64_e32 v[158:159], s[8:9]
	v_cndmask_b32_e64 v149, v149, v122, s[6:7]
	v_cndmask_b32_e64 v154, v154, v123, s[6:7]
	v_mad_i64_i32 v[158:159], s[8:9], v163, s92, v[158:159]
	v_cvt_pk_bf16_f32 v154, v149, v154
	v_lshl_add_u64 v[158:159], v[152:153], 1, v[158:159]
	global_store_dwordx4 v[158:159], v[154:157], off nt

.LBB0_438:
	s_andn2_b64 vcc, exec, s[8:9]
	s_cbranch_vccnz .LBB0_440
	v_mov_b64_e32 v[158:159], s[46:47]
	v_mad_i64_i32 v[158:159], s[8:9], v163, s65, v[158:159]
	v_cvt_pk_bf16_f32 v154, v122, v123
	v_cvt_pk_bf16_f32 v155, v124, v125
	v_cvt_pk_bf16_f32 v156, v126, v127
	v_cvt_pk_bf16_f32 v157, v128, v129
	v_lshl_add_u64 v[158:159], v[150:151], 1, v[158:159]
	global_store_dwordx4 v[158:159], v[154:157], off offset:-2560 nt

.LBB0_446:
	s_or_b64 exec, exec, s[8:9]
	v_mov_b32_e32 v155, v4
	v_lshl_add_u64 v[154:155], v[154:155], 1, v[156:157]
	v_cvt_pk_bf16_f32 v122, v122, s0
	v_lshlrev_b32_e32 v156, 3, v158
	v_mov_b32_e32 v157, v4
	global_store_short v[154:155], v122, off nt
	v_cvt_pk_bf16_f32 v122, v126, s0
	v_lshl_add_u64 v[154:155], v[154:155], 0, v[156:157]
	global_store_short v[154:155], v122, off nt
	v_cvt_pk_bf16_f32 v126, v123, s0
	v_mul_hi_i32_i24_e32 v123, -6, v158
	v_mul_i32_i24_e32 v122, -6, v158
	v_lshl_add_u64 v[154:155], v[154:155], 0, v[122:123]
	global_store_short v[154:155], v126, off nt
	v_cvt_pk_bf16_f32 v158, v127, s0
	v_lshl_add_u64 v[126:127], v[154:155], 0, v[156:157]
	global_store_short v[126:127], v158, off nt
	v_cvt_pk_bf16_f32 v124, v124, s0
	v_lshl_add_u64 v[126:127], v[126:127], 0, v[122:123]
	global_store_short v[126:127], v124, off nt
	v_cvt_pk_bf16_f32 v124, v128, s0
	v_lshl_add_u64 v[126:127], v[126:127], 0, v[156:157]
	global_store_short v[126:127], v124, off nt
	v_cvt_pk_bf16_f32 v124, v125, s0
	v_lshl_add_u64 v[122:123], v[126:127], 0, v[122:123]
	global_store_short v[122:123], v124, off nt
	v_cvt_pk_bf16_f32 v124, v129, s0
	v_lshl_add_u64 v[122:123], v[122:123], 0, v[156:157]
	global_store_short v[122:123], v124, off nt
.LBB0_447:
	v_add_u32_e32 v129, 16, v162
	v_cndmask_b32_e64 v122, 0, 1, s[82:83]
	v_add_u32_e32 v128, s15, v129
	v_cmp_ne_u32_e64 s[8:9], 1, v122
	s_andn2_b64 vcc, exec, s[82:83]
	s_mov_b64 s[82:83], -1
	s_cbranch_vccnz .LBB0_455
	s_andn2_b64 vcc, exec, s[80:81]
	s_cbranch_vccnz .LBB0_452
	s_andn2_b64 vcc, exec, s[78:79]
	s_cbranch_vccnz .LBB0_451
	v_mul_f32_e32 v123, 0xbfb8aa3b, v114
	v_exp_f32_e32 v123, v123
	v_mul_f32_e32 v124, 0xbfb8aa3b, v119
	v_mul_f32_e32 v125, 0xbfb8aa3b, v115
	v_exp_f32_e32 v124, v124
	v_add_f32_e32 v123, 1.0, v123
	v_rcp_f32_e32 v123, v123
	v_exp_f32_e32 v125, v125
	v_mul_f32_e32 v122, 0xbfb8aa3b, v118
	v_mul_f32_e32 v127, 0xbfb8aa3b, v116
	v_mul_f32_e32 v123, v114, v123
	v_cndmask_b32_e64 v126, v123, v114, s[6:7]
	v_add_f32_e32 v123, 1.0, v124
	v_add_f32_e32 v124, 1.0, v125
	v_mul_f32_e32 v125, 0xbfb8aa3b, v120
	v_mul_f32_e32 v154, 0xbfb8aa3b, v121
	v_mul_f32_e32 v155, 0xbfb8aa3b, v117
	v_exp_f32_e32 v122, v122
	v_exp_f32_e32 v125, v125
	v_exp_f32_e32 v127, v127
	v_exp_f32_e32 v154, v154
	v_exp_f32_e32 v155, v155
	v_add_f32_e32 v122, 1.0, v122
	v_add_f32_e32 v125, 1.0, v125
	v_add_f32_e32 v127, 1.0, v127
	v_add_f32_e32 v154, 1.0, v154
	v_add_f32_e32 v155, 1.0, v155
	v_rcp_f32_e32 v122, v122
	v_rcp_f32_e32 v123, v123
	v_rcp_f32_e32 v124, v124
	v_rcp_f32_e32 v125, v125
	v_rcp_f32_e32 v127, v127
	v_rcp_f32_e32 v154, v154
	v_rcp_f32_e32 v155, v155
	v_mul_f32_e32 v122, v118, v122
	v_mul_f32_e32 v123, v119, v123
	v_mul_f32_e32 v124, v115, v124
	v_mul_f32_e32 v125, v120, v125
	v_mul_f32_e32 v127, v116, v127
	v_mul_f32_e32 v154, v121, v154
	v_mul_f32_e32 v155, v117, v155
	v_readlane_b32 s44, v254, 8
	v_cndmask_b32_e64 v122, v122, v118, s[6:7]
	v_cndmask_b32_e64 v123, v123, v119, s[6:7]
	v_cndmask_b32_e64 v124, v124, v115, s[6:7]
	v_cndmask_b32_e64 v125, v125, v120, s[6:7]
	v_cndmask_b32_e64 v127, v127, v116, s[6:7]
	v_cndmask_b32_e64 v154, v154, v121, s[6:7]
	v_cndmask_b32_e64 v155, v155, v117, s[6:7]
	v_readlane_b32 s45, v254, 9
	v_cvt_pk_bf16_f32 v122, v122, v123
	v_cvt_pk_bf16_f32 v123, v125, v154
	v_cvt_pk_bf16_f32 v124, v126, v124
	v_cvt_pk_bf16_f32 v125, v127, v155
	v_mov_b64_e32 v[126:127], s[44:45]
	v_mad_i64_i32 v[126:127], s[44:45], v128, s92, v[126:127]
	v_lshl_add_u64 v[126:127], v[152:153], 1, v[126:127]
	global_store_dwordx4 v[126:127], v[122:125], off nt

.LBB0_452:
	s_andn2_b64 vcc, exec, s[82:83]
	s_cbranch_vccnz .LBB0_454
	v_mov_b64_e32 v[126:127], s[46:47]
	v_mad_i64_i32 v[126:127], s[44:45], v128, s65, v[126:127]
	v_cvt_pk_bf16_f32 v122, v118, v119
	v_cvt_pk_bf16_f32 v123, v120, v121
	v_cvt_pk_bf16_f32 v124, v114, v115
	v_cvt_pk_bf16_f32 v125, v116, v117
	v_lshl_add_u64 v[126:127], v[150:151], 1, v[126:127]
	global_store_dwordx4 v[126:127], v[122:125], off offset:-2560 nt

.LBB0_460:
	s_or_b64 exec, exec, s[82:83]
	v_mov_b32_e32 v123, v4
	v_lshl_add_u64 v[122:123], v[122:123], 1, v[124:125]
	v_cvt_pk_bf16_f32 v118, v118, s0
	v_lshlrev_b32_e32 v124, 3, v126
	v_mov_b32_e32 v125, v4
	global_store_short v[122:123], v118, off nt
	v_cvt_pk_bf16_f32 v114, v114, s0
	v_lshl_add_u64 v[122:123], v[122:123], 0, v[124:125]
	global_store_short v[122:123], v114, off nt
	v_cvt_pk_bf16_f32 v114, v119, s0
	v_mul_hi_i32_i24_e32 v119, -6, v126
	v_mul_i32_i24_e32 v118, -6, v126
	v_lshl_add_u64 v[122:123], v[122:123], 0, v[118:119]
	global_store_short v[122:123], v114, off nt
	v_cvt_pk_bf16_f32 v126, v115, s0
	v_lshl_add_u64 v[114:115], v[122:123], 0, v[124:125]
	global_store_short v[114:115], v126, off nt
	v_cvt_pk_bf16_f32 v120, v120, s0
	v_lshl_add_u64 v[114:115], v[114:115], 0, v[118:119]
	global_store_short v[114:115], v120, off nt
	v_cvt_pk_bf16_f32 v116, v116, s0
	v_lshl_add_u64 v[114:115], v[114:115], 0, v[124:125]
	global_store_short v[114:115], v116, off nt
	v_cvt_pk_bf16_f32 v116, v121, s0
	v_lshl_add_u64 v[114:115], v[114:115], 0, v[118:119]
	global_store_short v[114:115], v116, off nt
	v_cvt_pk_bf16_f32 v116, v117, s0
	v_lshl_add_u64 v[114:115], v[114:115], 0, v[124:125]
	global_store_short v[114:115], v116, off nt
.LBB0_461:
	v_add_u32_e32 v121, 32, v162
	v_add_u32_e32 v120, s15, v121
	s_and_b64 vcc, exec, s[8:9]
	s_mov_b64 s[82:83], -1
	s_cbranch_vccnz .LBB0_469
	s_andn2_b64 vcc, exec, s[80:81]
	s_cbranch_vccnz .LBB0_466
	s_andn2_b64 vcc, exec, s[78:79]
	s_cbranch_vccnz .LBB0_465
	v_mul_f32_e32 v115, 0xbfb8aa3b, v106
	v_exp_f32_e32 v115, v115
	v_mul_f32_e32 v116, 0xbfb8aa3b, v111
	v_mul_f32_e32 v117, 0xbfb8aa3b, v107
	v_exp_f32_e32 v116, v116
	v_add_f32_e32 v115, 1.0, v115
	v_rcp_f32_e32 v115, v115
	v_exp_f32_e32 v117, v117
	v_mul_f32_e32 v114, 0xbfb8aa3b, v110
	v_mul_f32_e32 v119, 0xbfb8aa3b, v108
	v_mul_f32_e32 v115, v106, v115
	v_cndmask_b32_e64 v118, v115, v106, s[6:7]
	v_add_f32_e32 v115, 1.0, v116
	v_add_f32_e32 v116, 1.0, v117
	v_mul_f32_e32 v117, 0xbfb8aa3b, v112
	v_mul_f32_e32 v122, 0xbfb8aa3b, v113
	v_mul_f32_e32 v123, 0xbfb8aa3b, v109
	v_exp_f32_e32 v114, v114
	v_exp_f32_e32 v117, v117
	v_exp_f32_e32 v119, v119
	v_exp_f32_e32 v122, v122
	v_exp_f32_e32 v123, v123
	v_add_f32_e32 v114, 1.0, v114
	v_add_f32_e32 v117, 1.0, v117
	v_add_f32_e32 v119, 1.0, v119
	v_add_f32_e32 v122, 1.0, v122
	v_add_f32_e32 v123, 1.0, v123
	v_rcp_f32_e32 v114, v114
	v_rcp_f32_e32 v115, v115
	v_rcp_f32_e32 v116, v116
	v_rcp_f32_e32 v117, v117
	v_rcp_f32_e32 v119, v119
	v_rcp_f32_e32 v122, v122
	v_rcp_f32_e32 v123, v123
	v_mul_f32_e32 v114, v110, v114
	v_mul_f32_e32 v115, v111, v115
	v_mul_f32_e32 v116, v107, v116
	v_mul_f32_e32 v117, v112, v117
	v_mul_f32_e32 v119, v108, v119
	v_mul_f32_e32 v122, v113, v122
	v_mul_f32_e32 v123, v109, v123
	v_readlane_b32 s44, v254, 8
	v_cndmask_b32_e64 v114, v114, v110, s[6:7]
	v_cndmask_b32_e64 v115, v115, v111, s[6:7]
	v_cndmask_b32_e64 v116, v116, v107, s[6:7]
	v_cndmask_b32_e64 v117, v117, v112, s[6:7]
	v_cndmask_b32_e64 v119, v119, v108, s[6:7]
	v_cndmask_b32_e64 v122, v122, v113, s[6:7]
	v_cndmask_b32_e64 v123, v123, v109, s[6:7]
	v_readlane_b32 s45, v254, 9
	v_cvt_pk_bf16_f32 v114, v114, v115
	v_cvt_pk_bf16_f32 v115, v117, v122
	v_cvt_pk_bf16_f32 v116, v118, v116
	v_cvt_pk_bf16_f32 v117, v119, v123
	v_mov_b64_e32 v[118:119], s[44:45]
	v_mad_i64_i32 v[118:119], s[44:45], v120, s92, v[118:119]
	v_lshl_add_u64 v[118:119], v[152:153], 1, v[118:119]
	global_store_dwordx4 v[118:119], v[114:117], off nt

.LBB0_466:
	s_andn2_b64 vcc, exec, s[82:83]
	s_cbranch_vccnz .LBB0_468
	v_mov_b64_e32 v[118:119], s[46:47]
	v_mad_i64_i32 v[118:119], s[44:45], v120, s65, v[118:119]
	v_cvt_pk_bf16_f32 v114, v110, v111
	v_cvt_pk_bf16_f32 v115, v112, v113
	v_cvt_pk_bf16_f32 v116, v106, v107
	v_cvt_pk_bf16_f32 v117, v108, v109
	v_lshl_add_u64 v[118:119], v[150:151], 1, v[118:119]
	global_store_dwordx4 v[118:119], v[114:117], off offset:-2560 nt

.LBB0_474:
	s_or_b64 exec, exec, s[82:83]
	v_mov_b32_e32 v115, v4
	v_lshl_add_u64 v[114:115], v[114:115], 1, v[116:117]
	v_cvt_pk_bf16_f32 v110, v110, s0
	v_lshlrev_b32_e32 v116, 3, v118
	v_mov_b32_e32 v117, v4
	global_store_short v[114:115], v110, off nt
	v_cvt_pk_bf16_f32 v106, v106, s0
	v_lshl_add_u64 v[114:115], v[114:115], 0, v[116:117]
	global_store_short v[114:115], v106, off nt
	v_cvt_pk_bf16_f32 v106, v111, s0
	v_mul_hi_i32_i24_e32 v111, -6, v118
	v_mul_i32_i24_e32 v110, -6, v118
	v_lshl_add_u64 v[114:115], v[114:115], 0, v[110:111]
	global_store_short v[114:115], v106, off nt
	v_cvt_pk_bf16_f32 v118, v107, s0
	v_lshl_add_u64 v[106:107], v[114:115], 0, v[116:117]
	global_store_short v[106:107], v118, off nt
	v_cvt_pk_bf16_f32 v112, v112, s0
	v_lshl_add_u64 v[106:107], v[106:107], 0, v[110:111]
	global_store_short v[106:107], v112, off nt
	v_cvt_pk_bf16_f32 v108, v108, s0
	v_lshl_add_u64 v[106:107], v[106:107], 0, v[116:117]
	global_store_short v[106:107], v108, off nt
	v_cvt_pk_bf16_f32 v108, v113, s0
	v_lshl_add_u64 v[106:107], v[106:107], 0, v[110:111]
	global_store_short v[106:107], v108, off nt
	v_cvt_pk_bf16_f32 v108, v109, s0
	v_lshl_add_u64 v[106:107], v[106:107], 0, v[116:117]
	global_store_short v[106:107], v108, off nt
.LBB0_475:
	v_add_u32_e32 v113, 48, v162
	v_add_u32_e32 v112, s15, v113
	s_and_b64 vcc, exec, s[8:9]
	s_mov_b64 s[82:83], -1
	s_cbranch_vccnz .LBB0_483
	s_andn2_b64 vcc, exec, s[80:81]
	s_cbranch_vccnz .LBB0_480
	s_andn2_b64 vcc, exec, s[78:79]
	s_cbranch_vccnz .LBB0_479
	v_mul_f32_e32 v107, 0xbfb8aa3b, v98
	v_exp_f32_e32 v107, v107
	v_mul_f32_e32 v108, 0xbfb8aa3b, v103
	v_mul_f32_e32 v109, 0xbfb8aa3b, v99
	v_exp_f32_e32 v108, v108
	v_add_f32_e32 v107, 1.0, v107
	v_rcp_f32_e32 v107, v107
	v_exp_f32_e32 v109, v109
	v_mul_f32_e32 v106, 0xbfb8aa3b, v102
	v_mul_f32_e32 v111, 0xbfb8aa3b, v100
	v_mul_f32_e32 v107, v98, v107
	v_cndmask_b32_e64 v110, v107, v98, s[6:7]
	v_add_f32_e32 v107, 1.0, v108
	v_add_f32_e32 v108, 1.0, v109
	v_mul_f32_e32 v109, 0xbfb8aa3b, v104
	v_mul_f32_e32 v114, 0xbfb8aa3b, v105
	v_mul_f32_e32 v115, 0xbfb8aa3b, v101
	v_exp_f32_e32 v106, v106
	v_exp_f32_e32 v109, v109
	v_exp_f32_e32 v111, v111
	v_exp_f32_e32 v114, v114
	v_exp_f32_e32 v115, v115
	v_add_f32_e32 v106, 1.0, v106
	v_add_f32_e32 v109, 1.0, v109
	v_add_f32_e32 v111, 1.0, v111
	v_add_f32_e32 v114, 1.0, v114
	v_add_f32_e32 v115, 1.0, v115
	v_rcp_f32_e32 v106, v106
	v_rcp_f32_e32 v107, v107
	v_rcp_f32_e32 v108, v108
	v_rcp_f32_e32 v109, v109
	v_rcp_f32_e32 v111, v111
	v_rcp_f32_e32 v114, v114
	v_rcp_f32_e32 v115, v115
	v_mul_f32_e32 v106, v102, v106
	v_mul_f32_e32 v107, v103, v107
	v_mul_f32_e32 v108, v99, v108
	v_mul_f32_e32 v109, v104, v109
	v_mul_f32_e32 v111, v100, v111
	v_mul_f32_e32 v114, v105, v114
	v_mul_f32_e32 v115, v101, v115
	v_readlane_b32 s44, v254, 8
	v_cndmask_b32_e64 v106, v106, v102, s[6:7]
	v_cndmask_b32_e64 v107, v107, v103, s[6:7]
	v_cndmask_b32_e64 v108, v108, v99, s[6:7]
	v_cndmask_b32_e64 v109, v109, v104, s[6:7]
	v_cndmask_b32_e64 v111, v111, v100, s[6:7]
	v_cndmask_b32_e64 v114, v114, v105, s[6:7]
	v_cndmask_b32_e64 v115, v115, v101, s[6:7]
	v_readlane_b32 s45, v254, 9
	v_cvt_pk_bf16_f32 v106, v106, v107
	v_cvt_pk_bf16_f32 v107, v109, v114
	v_cvt_pk_bf16_f32 v108, v110, v108
	v_cvt_pk_bf16_f32 v109, v111, v115
	v_mov_b64_e32 v[110:111], s[44:45]
	v_mad_i64_i32 v[110:111], s[44:45], v112, s92, v[110:111]
	v_lshl_add_u64 v[110:111], v[152:153], 1, v[110:111]
	global_store_dwordx4 v[110:111], v[106:109], off nt

.LBB0_480:
	s_andn2_b64 vcc, exec, s[82:83]
	s_cbranch_vccnz .LBB0_482
	v_mov_b64_e32 v[110:111], s[46:47]
	v_mad_i64_i32 v[110:111], s[44:45], v112, s65, v[110:111]
	v_cvt_pk_bf16_f32 v106, v102, v103
	v_cvt_pk_bf16_f32 v107, v104, v105
	v_cvt_pk_bf16_f32 v108, v98, v99
	v_cvt_pk_bf16_f32 v109, v100, v101
	v_lshl_add_u64 v[110:111], v[150:151], 1, v[110:111]
	global_store_dwordx4 v[110:111], v[106:109], off offset:-2560 nt

.LBB0_488:
	s_or_b64 exec, exec, s[82:83]
	v_mov_b32_e32 v107, v4
	v_lshl_add_u64 v[106:107], v[106:107], 1, v[108:109]
	v_cvt_pk_bf16_f32 v102, v102, s0
	v_lshlrev_b32_e32 v108, 3, v110
	v_mov_b32_e32 v109, v4
	global_store_short v[106:107], v102, off nt
	v_cvt_pk_bf16_f32 v98, v98, s0
	v_lshl_add_u64 v[106:107], v[106:107], 0, v[108:109]
	global_store_short v[106:107], v98, off nt
	v_cvt_pk_bf16_f32 v98, v103, s0
	v_mul_hi_i32_i24_e32 v103, -6, v110
	v_mul_i32_i24_e32 v102, -6, v110
	v_lshl_add_u64 v[106:107], v[106:107], 0, v[102:103]
	global_store_short v[106:107], v98, off nt
	v_cvt_pk_bf16_f32 v110, v99, s0
	v_lshl_add_u64 v[98:99], v[106:107], 0, v[108:109]
	global_store_short v[98:99], v110, off nt
	v_cvt_pk_bf16_f32 v104, v104, s0
	v_lshl_add_u64 v[98:99], v[98:99], 0, v[102:103]
	global_store_short v[98:99], v104, off nt
	v_cvt_pk_bf16_f32 v100, v100, s0
	v_lshl_add_u64 v[98:99], v[98:99], 0, v[108:109]
	global_store_short v[98:99], v100, off nt
	v_cvt_pk_bf16_f32 v100, v105, s0
	v_lshl_add_u64 v[98:99], v[98:99], 0, v[102:103]
	global_store_short v[98:99], v100, off nt
	v_cvt_pk_bf16_f32 v100, v101, s0
	v_lshl_add_u64 v[98:99], v[98:99], 0, v[108:109]
	global_store_short v[98:99], v100, off nt
.LBB0_489:
	v_add_u32_e32 v105, 0x80, v162
	v_add_u32_e32 v104, s15, v105
	s_and_b64 vcc, exec, s[8:9]
	s_mov_b64 s[82:83], -1
	s_cbranch_vccnz .LBB0_497
	s_andn2_b64 vcc, exec, s[80:81]
	s_cbranch_vccnz .LBB0_494
	s_andn2_b64 vcc, exec, s[78:79]
	s_cbranch_vccnz .LBB0_493
	v_mul_f32_e32 v99, 0xbfb8aa3b, v90
	v_exp_f32_e32 v99, v99
	v_mul_f32_e32 v100, 0xbfb8aa3b, v95
	v_mul_f32_e32 v101, 0xbfb8aa3b, v91
	v_exp_f32_e32 v100, v100
	v_add_f32_e32 v99, 1.0, v99
	v_rcp_f32_e32 v99, v99
	v_exp_f32_e32 v101, v101
	v_mul_f32_e32 v98, 0xbfb8aa3b, v94
	v_mul_f32_e32 v103, 0xbfb8aa3b, v92
	v_mul_f32_e32 v99, v90, v99
	v_cndmask_b32_e64 v102, v99, v90, s[6:7]
	v_add_f32_e32 v99, 1.0, v100
	v_add_f32_e32 v100, 1.0, v101
	v_mul_f32_e32 v101, 0xbfb8aa3b, v96
	v_mul_f32_e32 v106, 0xbfb8aa3b, v97
	v_mul_f32_e32 v107, 0xbfb8aa3b, v93
	v_exp_f32_e32 v98, v98
	v_exp_f32_e32 v101, v101
	v_exp_f32_e32 v103, v103
	v_exp_f32_e32 v106, v106
	v_exp_f32_e32 v107, v107
	v_add_f32_e32 v98, 1.0, v98
	v_add_f32_e32 v101, 1.0, v101
	v_add_f32_e32 v103, 1.0, v103
	v_add_f32_e32 v106, 1.0, v106
	v_add_f32_e32 v107, 1.0, v107
	v_rcp_f32_e32 v98, v98
	v_rcp_f32_e32 v99, v99
	v_rcp_f32_e32 v100, v100
	v_rcp_f32_e32 v101, v101
	v_rcp_f32_e32 v103, v103
	v_rcp_f32_e32 v106, v106
	v_rcp_f32_e32 v107, v107
	v_mul_f32_e32 v98, v94, v98
	v_mul_f32_e32 v99, v95, v99
	v_mul_f32_e32 v100, v91, v100
	v_mul_f32_e32 v101, v96, v101
	v_mul_f32_e32 v103, v92, v103
	v_mul_f32_e32 v106, v97, v106
	v_mul_f32_e32 v107, v93, v107
	v_readlane_b32 s44, v254, 8
	v_cndmask_b32_e64 v98, v98, v94, s[6:7]
	v_cndmask_b32_e64 v99, v99, v95, s[6:7]
	v_cndmask_b32_e64 v100, v100, v91, s[6:7]
	v_cndmask_b32_e64 v101, v101, v96, s[6:7]
	v_cndmask_b32_e64 v103, v103, v92, s[6:7]
	v_cndmask_b32_e64 v106, v106, v97, s[6:7]
	v_cndmask_b32_e64 v107, v107, v93, s[6:7]
	v_readlane_b32 s45, v254, 9
	v_cvt_pk_bf16_f32 v98, v98, v99
	v_cvt_pk_bf16_f32 v99, v101, v106
	v_cvt_pk_bf16_f32 v100, v102, v100
	v_cvt_pk_bf16_f32 v101, v103, v107
	v_mov_b64_e32 v[102:103], s[44:45]
	v_mad_i64_i32 v[102:103], s[44:45], v104, s92, v[102:103]
	v_lshl_add_u64 v[102:103], v[152:153], 1, v[102:103]
	global_store_dwordx4 v[102:103], v[98:101], off nt

.LBB0_494:
	s_andn2_b64 vcc, exec, s[82:83]
	s_cbranch_vccnz .LBB0_496
	v_mov_b64_e32 v[102:103], s[46:47]
	v_mad_i64_i32 v[102:103], s[44:45], v104, s65, v[102:103]
	v_cvt_pk_bf16_f32 v98, v94, v95
	v_cvt_pk_bf16_f32 v99, v96, v97
	v_cvt_pk_bf16_f32 v100, v90, v91
	v_cvt_pk_bf16_f32 v101, v92, v93
	v_lshl_add_u64 v[102:103], v[150:151], 1, v[102:103]
	global_store_dwordx4 v[102:103], v[98:101], off offset:-2560 nt

.LBB0_502:
	s_or_b64 exec, exec, s[82:83]
	v_mov_b32_e32 v99, v4
	v_lshl_add_u64 v[98:99], v[98:99], 1, v[100:101]
	v_cvt_pk_bf16_f32 v94, v94, s0
	v_lshlrev_b32_e32 v100, 3, v102
	v_mov_b32_e32 v101, v4
	global_store_short v[98:99], v94, off nt
	v_cvt_pk_bf16_f32 v90, v90, s0
	v_lshl_add_u64 v[98:99], v[98:99], 0, v[100:101]
	global_store_short v[98:99], v90, off nt
	v_cvt_pk_bf16_f32 v90, v95, s0
	v_mul_hi_i32_i24_e32 v95, -6, v102
	v_mul_i32_i24_e32 v94, -6, v102
	v_lshl_add_u64 v[98:99], v[98:99], 0, v[94:95]
	global_store_short v[98:99], v90, off nt
	v_cvt_pk_bf16_f32 v102, v91, s0
	v_lshl_add_u64 v[90:91], v[98:99], 0, v[100:101]
	global_store_short v[90:91], v102, off nt
	v_cvt_pk_bf16_f32 v96, v96, s0
	v_lshl_add_u64 v[90:91], v[90:91], 0, v[94:95]
	global_store_short v[90:91], v96, off nt
	v_cvt_pk_bf16_f32 v92, v92, s0
	v_lshl_add_u64 v[90:91], v[90:91], 0, v[100:101]
	global_store_short v[90:91], v92, off nt
	v_cvt_pk_bf16_f32 v92, v97, s0
	v_lshl_add_u64 v[90:91], v[90:91], 0, v[94:95]
	global_store_short v[90:91], v92, off nt
	v_cvt_pk_bf16_f32 v92, v93, s0
	v_lshl_add_u64 v[90:91], v[90:91], 0, v[100:101]
	global_store_short v[90:91], v92, off nt
.LBB0_503:
	v_add_u32_e32 v97, 0x90, v162
	v_add_u32_e32 v96, s15, v97
	s_and_b64 vcc, exec, s[8:9]
	s_mov_b64 s[82:83], -1
	s_cbranch_vccnz .LBB0_511
	s_andn2_b64 vcc, exec, s[80:81]
	s_cbranch_vccnz .LBB0_508
	s_andn2_b64 vcc, exec, s[78:79]
	s_cbranch_vccnz .LBB0_507
	v_mul_f32_e32 v91, 0xbfb8aa3b, v82
	v_exp_f32_e32 v91, v91
	v_mul_f32_e32 v92, 0xbfb8aa3b, v87
	v_mul_f32_e32 v93, 0xbfb8aa3b, v83
	v_exp_f32_e32 v92, v92
	v_add_f32_e32 v91, 1.0, v91
	v_rcp_f32_e32 v91, v91
	v_exp_f32_e32 v93, v93
	v_mul_f32_e32 v90, 0xbfb8aa3b, v86
	v_mul_f32_e32 v95, 0xbfb8aa3b, v84
	v_mul_f32_e32 v91, v82, v91
	v_cndmask_b32_e64 v94, v91, v82, s[6:7]
	v_add_f32_e32 v91, 1.0, v92
	v_add_f32_e32 v92, 1.0, v93
	v_mul_f32_e32 v93, 0xbfb8aa3b, v88
	v_mul_f32_e32 v98, 0xbfb8aa3b, v89
	v_mul_f32_e32 v99, 0xbfb8aa3b, v85
	v_exp_f32_e32 v90, v90
	v_exp_f32_e32 v93, v93
	v_exp_f32_e32 v95, v95
	v_exp_f32_e32 v98, v98
	v_exp_f32_e32 v99, v99
	v_add_f32_e32 v90, 1.0, v90
	v_add_f32_e32 v93, 1.0, v93
	v_add_f32_e32 v95, 1.0, v95
	v_add_f32_e32 v98, 1.0, v98
	v_add_f32_e32 v99, 1.0, v99
	v_rcp_f32_e32 v90, v90
	v_rcp_f32_e32 v91, v91
	v_rcp_f32_e32 v92, v92
	v_rcp_f32_e32 v93, v93
	v_rcp_f32_e32 v95, v95
	v_rcp_f32_e32 v98, v98
	v_rcp_f32_e32 v99, v99
	v_mul_f32_e32 v90, v86, v90
	v_mul_f32_e32 v91, v87, v91
	v_mul_f32_e32 v92, v83, v92
	v_mul_f32_e32 v93, v88, v93
	v_mul_f32_e32 v95, v84, v95
	v_mul_f32_e32 v98, v89, v98
	v_mul_f32_e32 v99, v85, v99
	v_readlane_b32 s44, v254, 8
	v_cndmask_b32_e64 v90, v90, v86, s[6:7]
	v_cndmask_b32_e64 v91, v91, v87, s[6:7]
	v_cndmask_b32_e64 v92, v92, v83, s[6:7]
	v_cndmask_b32_e64 v93, v93, v88, s[6:7]
	v_cndmask_b32_e64 v95, v95, v84, s[6:7]
	v_cndmask_b32_e64 v98, v98, v89, s[6:7]
	v_cndmask_b32_e64 v99, v99, v85, s[6:7]
	v_readlane_b32 s45, v254, 9
	v_cvt_pk_bf16_f32 v90, v90, v91
	v_cvt_pk_bf16_f32 v91, v93, v98
	v_cvt_pk_bf16_f32 v92, v94, v92
	v_cvt_pk_bf16_f32 v93, v95, v99
	v_mov_b64_e32 v[94:95], s[44:45]
	v_mad_i64_i32 v[94:95], s[44:45], v96, s92, v[94:95]
	v_lshl_add_u64 v[94:95], v[152:153], 1, v[94:95]
	global_store_dwordx4 v[94:95], v[90:93], off nt

.LBB0_508:
	s_andn2_b64 vcc, exec, s[82:83]
	s_cbranch_vccnz .LBB0_510
	v_mov_b64_e32 v[94:95], s[46:47]
	v_mad_i64_i32 v[94:95], s[44:45], v96, s65, v[94:95]
	v_cvt_pk_bf16_f32 v90, v86, v87
	v_cvt_pk_bf16_f32 v91, v88, v89
	v_cvt_pk_bf16_f32 v92, v82, v83
	v_cvt_pk_bf16_f32 v93, v84, v85
	v_lshl_add_u64 v[94:95], v[150:151], 1, v[94:95]
	global_store_dwordx4 v[94:95], v[90:93], off offset:-2560 nt

.LBB0_516:
	s_or_b64 exec, exec, s[82:83]
	v_mov_b32_e32 v91, v4
	v_lshl_add_u64 v[90:91], v[90:91], 1, v[92:93]
	v_cvt_pk_bf16_f32 v86, v86, s0
	v_lshlrev_b32_e32 v92, 3, v94
	v_mov_b32_e32 v93, v4
	global_store_short v[90:91], v86, off nt
	v_cvt_pk_bf16_f32 v82, v82, s0
	v_lshl_add_u64 v[90:91], v[90:91], 0, v[92:93]
	global_store_short v[90:91], v82, off nt
	v_cvt_pk_bf16_f32 v82, v87, s0
	v_mul_hi_i32_i24_e32 v87, -6, v94
	v_mul_i32_i24_e32 v86, -6, v94
	v_lshl_add_u64 v[90:91], v[90:91], 0, v[86:87]
	global_store_short v[90:91], v82, off nt
	v_cvt_pk_bf16_f32 v94, v83, s0
	v_lshl_add_u64 v[82:83], v[90:91], 0, v[92:93]
	global_store_short v[82:83], v94, off nt
	v_cvt_pk_bf16_f32 v88, v88, s0
	v_lshl_add_u64 v[82:83], v[82:83], 0, v[86:87]
	global_store_short v[82:83], v88, off nt
	v_cvt_pk_bf16_f32 v84, v84, s0
	v_lshl_add_u64 v[82:83], v[82:83], 0, v[92:93]
	global_store_short v[82:83], v84, off nt
	v_cvt_pk_bf16_f32 v84, v89, s0
	v_lshl_add_u64 v[82:83], v[82:83], 0, v[86:87]
	global_store_short v[82:83], v84, off nt
	v_cvt_pk_bf16_f32 v84, v85, s0
	v_lshl_add_u64 v[82:83], v[82:83], 0, v[92:93]
	global_store_short v[82:83], v84, off nt
.LBB0_517:
	v_add_u32_e32 v89, 0xa0, v162
	v_add_u32_e32 v88, s15, v89
	s_and_b64 vcc, exec, s[8:9]
	s_mov_b64 s[82:83], -1
	s_cbranch_vccnz .LBB0_525
	s_andn2_b64 vcc, exec, s[80:81]
	s_cbranch_vccnz .LBB0_522
	s_andn2_b64 vcc, exec, s[78:79]
	s_cbranch_vccnz .LBB0_521
	v_mul_f32_e32 v83, 0xbfb8aa3b, v74
	v_exp_f32_e32 v83, v83
	v_mul_f32_e32 v84, 0xbfb8aa3b, v79
	v_mul_f32_e32 v85, 0xbfb8aa3b, v75
	v_exp_f32_e32 v84, v84
	v_add_f32_e32 v83, 1.0, v83
	v_rcp_f32_e32 v83, v83
	v_exp_f32_e32 v85, v85
	v_mul_f32_e32 v82, 0xbfb8aa3b, v78
	v_mul_f32_e32 v87, 0xbfb8aa3b, v76
	v_mul_f32_e32 v83, v74, v83
	v_cndmask_b32_e64 v86, v83, v74, s[6:7]
	v_add_f32_e32 v83, 1.0, v84
	v_add_f32_e32 v84, 1.0, v85
	v_mul_f32_e32 v85, 0xbfb8aa3b, v80
	v_mul_f32_e32 v90, 0xbfb8aa3b, v81
	v_mul_f32_e32 v91, 0xbfb8aa3b, v77
	v_exp_f32_e32 v82, v82
	v_exp_f32_e32 v85, v85
	v_exp_f32_e32 v87, v87
	v_exp_f32_e32 v90, v90
	v_exp_f32_e32 v91, v91
	v_add_f32_e32 v82, 1.0, v82
	v_add_f32_e32 v85, 1.0, v85
	v_add_f32_e32 v87, 1.0, v87
	v_add_f32_e32 v90, 1.0, v90
	v_add_f32_e32 v91, 1.0, v91
	v_rcp_f32_e32 v82, v82
	v_rcp_f32_e32 v83, v83
	v_rcp_f32_e32 v84, v84
	v_rcp_f32_e32 v85, v85
	v_rcp_f32_e32 v87, v87
	v_rcp_f32_e32 v90, v90
	v_rcp_f32_e32 v91, v91
	v_mul_f32_e32 v82, v78, v82
	v_mul_f32_e32 v83, v79, v83
	v_mul_f32_e32 v84, v75, v84
	v_mul_f32_e32 v85, v80, v85
	v_mul_f32_e32 v87, v76, v87
	v_mul_f32_e32 v90, v81, v90
	v_mul_f32_e32 v91, v77, v91
	v_readlane_b32 s44, v254, 8
	v_cndmask_b32_e64 v82, v82, v78, s[6:7]
	v_cndmask_b32_e64 v83, v83, v79, s[6:7]
	v_cndmask_b32_e64 v84, v84, v75, s[6:7]
	v_cndmask_b32_e64 v85, v85, v80, s[6:7]
	v_cndmask_b32_e64 v87, v87, v76, s[6:7]
	v_cndmask_b32_e64 v90, v90, v81, s[6:7]
	v_cndmask_b32_e64 v91, v91, v77, s[6:7]
	v_readlane_b32 s45, v254, 9
	v_cvt_pk_bf16_f32 v82, v82, v83
	v_cvt_pk_bf16_f32 v83, v85, v90
	v_cvt_pk_bf16_f32 v84, v86, v84
	v_cvt_pk_bf16_f32 v85, v87, v91
	v_mov_b64_e32 v[86:87], s[44:45]
	v_mad_i64_i32 v[86:87], s[44:45], v88, s92, v[86:87]
	v_lshl_add_u64 v[86:87], v[152:153], 1, v[86:87]
	global_store_dwordx4 v[86:87], v[82:85], off nt

.LBB0_522:
	s_andn2_b64 vcc, exec, s[82:83]
	s_cbranch_vccnz .LBB0_524
	v_mov_b64_e32 v[86:87], s[46:47]
	v_mad_i64_i32 v[86:87], s[44:45], v88, s65, v[86:87]
	v_cvt_pk_bf16_f32 v82, v78, v79
	v_cvt_pk_bf16_f32 v83, v80, v81
	v_cvt_pk_bf16_f32 v84, v74, v75
	v_cvt_pk_bf16_f32 v85, v76, v77
	v_lshl_add_u64 v[86:87], v[150:151], 1, v[86:87]
	global_store_dwordx4 v[86:87], v[82:85], off offset:-2560 nt

.LBB0_530:
	s_or_b64 exec, exec, s[82:83]
	v_mov_b32_e32 v83, v4
	v_lshl_add_u64 v[82:83], v[82:83], 1, v[84:85]
	v_cvt_pk_bf16_f32 v78, v78, s0
	v_lshlrev_b32_e32 v84, 3, v86
	v_mov_b32_e32 v85, v4
	global_store_short v[82:83], v78, off nt
	v_cvt_pk_bf16_f32 v74, v74, s0
	v_lshl_add_u64 v[82:83], v[82:83], 0, v[84:85]
	global_store_short v[82:83], v74, off nt
	v_cvt_pk_bf16_f32 v74, v79, s0
	v_mul_hi_i32_i24_e32 v79, -6, v86
	v_mul_i32_i24_e32 v78, -6, v86
	v_lshl_add_u64 v[82:83], v[82:83], 0, v[78:79]
	global_store_short v[82:83], v74, off nt
	v_cvt_pk_bf16_f32 v86, v75, s0
	v_lshl_add_u64 v[74:75], v[82:83], 0, v[84:85]
	global_store_short v[74:75], v86, off nt
	v_cvt_pk_bf16_f32 v80, v80, s0
	v_lshl_add_u64 v[74:75], v[74:75], 0, v[78:79]
	global_store_short v[74:75], v80, off nt
	v_cvt_pk_bf16_f32 v76, v76, s0
	v_lshl_add_u64 v[74:75], v[74:75], 0, v[84:85]
	global_store_short v[74:75], v76, off nt
	v_cvt_pk_bf16_f32 v76, v81, s0
	v_lshl_add_u64 v[74:75], v[74:75], 0, v[78:79]
	global_store_short v[74:75], v76, off nt
	v_cvt_pk_bf16_f32 v76, v77, s0
	v_lshl_add_u64 v[74:75], v[74:75], 0, v[84:85]
	global_store_short v[74:75], v76, off nt
.LBB0_531:
	v_add_u32_e32 v81, 0xb0, v162
	v_add_u32_e32 v80, s15, v81
	s_and_b64 vcc, exec, s[8:9]
	s_mov_b64 s[8:9], -1
	s_cbranch_vccnz .LBB0_539
	s_andn2_b64 vcc, exec, s[80:81]
	s_cbranch_vccnz .LBB0_536
	s_andn2_b64 vcc, exec, s[78:79]
	s_cbranch_vccnz .LBB0_535
	v_mul_f32_e32 v75, 0xbfb8aa3b, v66
	v_exp_f32_e32 v75, v75
	v_mul_f32_e32 v76, 0xbfb8aa3b, v71
	v_mul_f32_e32 v77, 0xbfb8aa3b, v67
	v_exp_f32_e32 v76, v76
	v_add_f32_e32 v75, 1.0, v75
	v_rcp_f32_e32 v75, v75
	v_exp_f32_e32 v77, v77
	v_mul_f32_e32 v74, 0xbfb8aa3b, v70
	v_mul_f32_e32 v79, 0xbfb8aa3b, v68
	v_mul_f32_e32 v75, v66, v75
	v_cndmask_b32_e64 v78, v75, v66, s[6:7]
	v_add_f32_e32 v75, 1.0, v76
	v_add_f32_e32 v76, 1.0, v77
	v_mul_f32_e32 v77, 0xbfb8aa3b, v72
	v_mul_f32_e32 v82, 0xbfb8aa3b, v73
	v_mul_f32_e32 v83, 0xbfb8aa3b, v69
	v_exp_f32_e32 v74, v74
	v_exp_f32_e32 v77, v77
	v_exp_f32_e32 v79, v79
	v_exp_f32_e32 v82, v82
	v_exp_f32_e32 v83, v83
	v_add_f32_e32 v74, 1.0, v74
	v_add_f32_e32 v77, 1.0, v77
	v_add_f32_e32 v79, 1.0, v79
	v_add_f32_e32 v82, 1.0, v82
	v_add_f32_e32 v83, 1.0, v83
	v_rcp_f32_e32 v74, v74
	v_rcp_f32_e32 v75, v75
	v_rcp_f32_e32 v76, v76
	v_rcp_f32_e32 v77, v77
	v_rcp_f32_e32 v79, v79
	v_rcp_f32_e32 v82, v82
	v_rcp_f32_e32 v83, v83
	v_mul_f32_e32 v74, v70, v74
	v_mul_f32_e32 v75, v71, v75
	v_mul_f32_e32 v76, v67, v76
	v_mul_f32_e32 v77, v72, v77
	v_mul_f32_e32 v79, v68, v79
	v_mul_f32_e32 v82, v73, v82
	v_mul_f32_e32 v83, v69, v83
	v_readlane_b32 s8, v254, 8
	v_cndmask_b32_e64 v74, v74, v70, s[6:7]
	v_cndmask_b32_e64 v75, v75, v71, s[6:7]
	v_cndmask_b32_e64 v76, v76, v67, s[6:7]
	v_cndmask_b32_e64 v77, v77, v72, s[6:7]
	v_cndmask_b32_e64 v79, v79, v68, s[6:7]
	v_cndmask_b32_e64 v82, v82, v73, s[6:7]
	v_cndmask_b32_e64 v83, v83, v69, s[6:7]
	v_readlane_b32 s9, v254, 9
	v_cvt_pk_bf16_f32 v74, v74, v75
	v_cvt_pk_bf16_f32 v75, v77, v82
	v_cvt_pk_bf16_f32 v76, v78, v76
	v_cvt_pk_bf16_f32 v77, v79, v83
	v_mov_b64_e32 v[78:79], s[8:9]
	v_mad_i64_i32 v[78:79], s[8:9], v80, s92, v[78:79]
	v_lshl_add_u64 v[78:79], v[152:153], 1, v[78:79]
	global_store_dwordx4 v[78:79], v[74:77], off nt

.LBB0_536:
	s_andn2_b64 vcc, exec, s[8:9]
	s_cbranch_vccnz .LBB0_538
	v_mov_b64_e32 v[78:79], s[46:47]
	v_mad_i64_i32 v[78:79], s[8:9], v80, s65, v[78:79]
	v_cvt_pk_bf16_f32 v74, v70, v71
	v_cvt_pk_bf16_f32 v75, v72, v73
	v_cvt_pk_bf16_f32 v76, v66, v67
	v_cvt_pk_bf16_f32 v77, v68, v69
	v_lshl_add_u64 v[78:79], v[150:151], 1, v[78:79]
	global_store_dwordx4 v[78:79], v[74:77], off offset:-2560 nt

.LBB0_544:
	s_or_b64 exec, exec, s[8:9]
	v_mov_b32_e32 v75, v4
	v_lshl_add_u64 v[74:75], v[74:75], 1, v[76:77]
	v_cvt_pk_bf16_f32 v70, v70, s0
	v_lshlrev_b32_e32 v76, 3, v78
	v_mov_b32_e32 v77, v4
	global_store_short v[74:75], v70, off nt
	v_cvt_pk_bf16_f32 v66, v66, s0
	v_lshl_add_u64 v[74:75], v[74:75], 0, v[76:77]
	global_store_short v[74:75], v66, off nt
	v_cvt_pk_bf16_f32 v66, v71, s0
	v_mul_hi_i32_i24_e32 v71, -6, v78
	v_mul_i32_i24_e32 v70, -6, v78
	v_lshl_add_u64 v[74:75], v[74:75], 0, v[70:71]
	global_store_short v[74:75], v66, off nt
	v_cvt_pk_bf16_f32 v78, v67, s0
	v_lshl_add_u64 v[66:67], v[74:75], 0, v[76:77]
	global_store_short v[66:67], v78, off nt
	v_cvt_pk_bf16_f32 v72, v72, s0
	v_lshl_add_u64 v[66:67], v[66:67], 0, v[70:71]
	global_store_short v[66:67], v72, off nt
	v_cvt_pk_bf16_f32 v68, v68, s0
	v_lshl_add_u64 v[66:67], v[66:67], 0, v[76:77]
	global_store_short v[66:67], v68, off nt
	v_cvt_pk_bf16_f32 v68, v73, s0
	v_lshl_add_u64 v[66:67], v[66:67], 0, v[70:71]
	global_store_short v[66:67], v68, off nt
	v_cvt_pk_bf16_f32 v68, v69, s0
	v_lshl_add_u64 v[66:67], v[66:67], 0, v[76:77]
	global_store_short v[66:67], v68, off nt
.LBB0_545:
	s_or_b32 s8, s76, 0x80
	s_cmpk_gt_i32 s8, 0x1ff
	s_cselect_b64 s[82:83], -1, 0
	s_add_i32 s9, s76, 0xfffffb80
	s_cmpk_gt_u32 s9, 0x19f
	s_cselect_b64 s[80:81], -1, 0
	s_cmpk_lt_u32 s8, 0x8a0
	v_add_u32_e32 v68, s8, v148
	s_cselect_b64 s[78:79], -1, 0
	s_cmpk_lt_i32 s8, 0x200
	s_movk_i32 s8, 0x500
	v_cmp_gt_i32_e32 vcc, s8, v68
	s_mov_b64 s[8:9], -1
	s_nop 0
	v_cndmask_b32_e32 v66, v249, v250, vcc
	s_cbranch_scc1 .LBB0_553
	s_andn2_b64 vcc, exec, s[80:81]
	s_cbranch_vccnz .LBB0_550
	s_andn2_b64 vcc, exec, s[78:79]
	s_cbranch_vccnz .LBB0_549
	v_mul_f32_e32 v71, 0xbfb8aa3b, v59
	v_exp_f32_e32 v71, v71
	v_mul_f32_e32 v72, 0xbfb8aa3b, v64
	v_exp_f32_e32 v72, v72
	v_mul_f32_e32 v73, 0xbfb8aa3b, v60
	v_add_f32_e32 v71, 1.0, v71
	v_rcp_f32_e32 v71, v71
	v_add_f32_e32 v72, 1.0, v72
	v_rcp_f32_e32 v72, v72
	v_exp_f32_e32 v73, v73
	v_mul_f32_e32 v71, v59, v71
	v_mul_f32_e32 v67, 0xbfb8aa3b, v62
	v_mul_f32_e32 v69, 0xbfb8aa3b, v58
	v_mul_f32_e32 v70, 0xbfb8aa3b, v63
	v_cndmask_b32_e64 v74, v71, v59, s[6:7]
	v_mul_f32_e32 v71, v64, v72
	v_add_f32_e32 v72, 1.0, v73
	v_mul_f32_e32 v73, 0xbfb8aa3b, v65
	v_mul_f32_e32 v75, 0xbfb8aa3b, v61
	v_exp_f32_e32 v67, v67
	v_exp_f32_e32 v69, v69
	v_exp_f32_e32 v70, v70
	v_exp_f32_e32 v73, v73
	v_exp_f32_e32 v75, v75
	v_add_f32_e32 v67, 1.0, v67
	v_add_f32_e32 v69, 1.0, v69
	v_add_f32_e32 v70, 1.0, v70
	v_rcp_f32_e32 v72, v72
	v_add_f32_e32 v73, 1.0, v73
	v_add_f32_e32 v75, 1.0, v75
	v_rcp_f32_e32 v67, v67
	v_rcp_f32_e32 v69, v69
	v_rcp_f32_e32 v70, v70
	v_rcp_f32_e32 v73, v73
	v_rcp_f32_e32 v75, v75
	v_mul_f32_e32 v72, v60, v72
	v_mul_f32_e32 v67, v62, v67
	v_mul_f32_e32 v69, v58, v69
	v_mul_f32_e32 v70, v63, v70
	v_cndmask_b32_e64 v76, v72, v60, s[6:7]
	v_mul_f32_e32 v72, v65, v73
	v_mul_f32_e32 v73, v61, v75
	v_readlane_b32 s8, v254, 8
	v_cndmask_b32_e64 v67, v67, v62, s[6:7]
	v_cndmask_b32_e64 v69, v69, v58, s[6:7]
	v_cndmask_b32_e64 v70, v70, v63, s[6:7]
	v_cndmask_b32_e64 v71, v71, v64, s[6:7]
	v_cndmask_b32_e64 v72, v72, v65, s[6:7]
	v_cndmask_b32_e64 v73, v73, v61, s[6:7]
	v_readlane_b32 s9, v254, 9
	v_ashrrev_i32_e32 v149, 31, v148
	s_ashr_i32 s77, s76, 31
	v_cvt_pk_bf16_f32 v70, v67, v70
	v_cvt_pk_bf16_f32 v71, v71, v72
	v_cvt_pk_bf16_f32 v72, v69, v74
	v_cvt_pk_bf16_f32 v73, v76, v73
	v_mov_b64_e32 v[74:75], s[8:9]
	v_ashrrev_i32_e32 v67, 31, v66
	v_lshl_add_u64 v[76:77], v[148:149], 0, s[76:77]
	v_mad_i64_i32 v[74:75], s[8:9], v163, s92, v[74:75]
	v_lshl_add_u64 v[76:77], v[66:67], 0, v[76:77]
	v_lshl_add_u64 v[74:75], v[76:77], 1, v[74:75]
	global_store_dwordx4 v[74:75], v[70:73], off offset:256 nt

.LBB0_550:
	s_andn2_b64 vcc, exec, s[8:9]
	s_cbranch_vccnz .LBB0_552
	v_mov_b64_e32 v[74:75], s[46:47]
	v_ashrrev_i32_e32 v149, 31, v148
	s_ashr_i32 s77, s76, 31
	v_mad_i64_i32 v[74:75], s[8:9], v163, s65, v[74:75]
	v_lshl_add_u64 v[76:77], v[148:149], 0, s[76:77]
	v_cvt_pk_bf16_f32 v70, v62, v63
	v_cvt_pk_bf16_f32 v71, v64, v65
	v_cvt_pk_bf16_f32 v72, v58, v59
	v_cvt_pk_bf16_f32 v73, v60, v61
	v_lshl_add_u64 v[74:75], v[76:77], 1, v[74:75]
	global_store_dwordx4 v[74:75], v[70:73], off offset:-2304 nt

.LBB0_558:
	s_or_b64 exec, exec, s[8:9]
	v_mov_b32_e32 v69, v4
	v_lshl_add_u64 v[68:69], v[68:69], 1, v[70:71]
	v_cvt_pk_bf16_f32 v62, v62, s0
	v_lshlrev_b32_e32 v70, 3, v72
	v_mov_b32_e32 v71, v4
	global_store_short v[68:69], v62, off nt
	v_cvt_pk_bf16_f32 v58, v58, s0
	v_lshl_add_u64 v[68:69], v[68:69], 0, v[70:71]
	global_store_short v[68:69], v58, off nt
	v_cvt_pk_bf16_f32 v58, v63, s0
	v_mul_hi_i32_i24_e32 v63, -6, v72
	v_mul_i32_i24_e32 v62, -6, v72
	v_lshl_add_u64 v[68:69], v[68:69], 0, v[62:63]
	global_store_short v[68:69], v58, off nt
	v_cvt_pk_bf16_f32 v67, v59, s0
	v_lshl_add_u64 v[58:59], v[68:69], 0, v[70:71]
	global_store_short v[58:59], v67, off nt
	v_cvt_pk_bf16_f32 v64, v64, s0
	v_lshl_add_u64 v[58:59], v[58:59], 0, v[62:63]
	global_store_short v[58:59], v64, off nt
	v_cvt_pk_bf16_f32 v60, v60, s0
	v_lshl_add_u64 v[58:59], v[58:59], 0, v[70:71]
	global_store_short v[58:59], v60, off nt
	v_cvt_pk_bf16_f32 v60, v65, s0
	v_lshl_add_u64 v[58:59], v[58:59], 0, v[62:63]
	global_store_short v[58:59], v60, off nt
	v_cvt_pk_bf16_f32 v60, v61, s0
	v_lshl_add_u64 v[58:59], v[58:59], 0, v[70:71]
	global_store_short v[58:59], v60, off nt
.LBB0_559:
	v_cndmask_b32_e64 v58, 0, 1, s[82:83]
	v_cmp_ne_u32_e64 s[8:9], 1, v58
	s_andn2_b64 vcc, exec, s[82:83]
	s_mov_b64 s[82:83], -1
	s_cbranch_vccnz .LBB0_616
	s_andn2_b64 vcc, exec, s[80:81]
	s_cbranch_vccnz .LBB0_564
	s_andn2_b64 vcc, exec, s[78:79]
	s_cbranch_vccnz .LBB0_563
	v_mul_f32_e32 v59, 0xbfb8aa3b, v50
	v_exp_f32_e32 v59, v59
	v_mul_f32_e32 v60, 0xbfb8aa3b, v55
	v_mul_f32_e32 v61, 0xbfb8aa3b, v51
	v_exp_f32_e32 v60, v60
	v_add_f32_e32 v59, 1.0, v59
	v_rcp_f32_e32 v59, v59
	v_exp_f32_e32 v61, v61
	v_mul_f32_e32 v58, 0xbfb8aa3b, v54
	v_mul_f32_e32 v63, 0xbfb8aa3b, v52
	v_mul_f32_e32 v59, v50, v59
	v_cndmask_b32_e64 v62, v59, v50, s[6:7]
	v_add_f32_e32 v59, 1.0, v60
	v_add_f32_e32 v60, 1.0, v61
	v_mul_f32_e32 v61, 0xbfb8aa3b, v56
	v_mul_f32_e32 v64, 0xbfb8aa3b, v57
	v_mul_f32_e32 v65, 0xbfb8aa3b, v53
	v_exp_f32_e32 v58, v58
	v_exp_f32_e32 v61, v61
	v_exp_f32_e32 v63, v63
	v_exp_f32_e32 v64, v64
	v_exp_f32_e32 v65, v65
	v_add_f32_e32 v58, 1.0, v58
	v_add_f32_e32 v61, 1.0, v61
	v_add_f32_e32 v63, 1.0, v63
	v_add_f32_e32 v64, 1.0, v64
	v_add_f32_e32 v65, 1.0, v65
	v_rcp_f32_e32 v58, v58
	v_rcp_f32_e32 v59, v59
	v_rcp_f32_e32 v60, v60
	v_rcp_f32_e32 v61, v61
	v_rcp_f32_e32 v63, v63
	v_rcp_f32_e32 v64, v64
	v_rcp_f32_e32 v65, v65
	v_mul_f32_e32 v58, v54, v58
	v_mul_f32_e32 v59, v55, v59
	v_mul_f32_e32 v60, v51, v60
	v_mul_f32_e32 v61, v56, v61
	v_mul_f32_e32 v63, v52, v63
	v_mul_f32_e32 v64, v57, v64
	v_mul_f32_e32 v65, v53, v65
	v_readlane_b32 s44, v254, 8
	v_cndmask_b32_e64 v58, v58, v54, s[6:7]
	v_cndmask_b32_e64 v59, v59, v55, s[6:7]
	v_cndmask_b32_e64 v60, v60, v51, s[6:7]
	v_cndmask_b32_e64 v61, v61, v56, s[6:7]
	v_cndmask_b32_e64 v63, v63, v52, s[6:7]
	v_cndmask_b32_e64 v64, v64, v57, s[6:7]
	v_cndmask_b32_e64 v65, v65, v53, s[6:7]
	v_readlane_b32 s45, v254, 9
	v_ashrrev_i32_e32 v149, 31, v148
	s_ashr_i32 s77, s76, 31
	v_cvt_pk_bf16_f32 v58, v58, v59
	v_cvt_pk_bf16_f32 v59, v61, v64
	v_cvt_pk_bf16_f32 v60, v62, v60
	v_cvt_pk_bf16_f32 v61, v63, v65
	v_mov_b64_e32 v[62:63], s[44:45]
	v_ashrrev_i32_e32 v67, 31, v66
	v_lshl_add_u64 v[64:65], v[148:149], 0, s[76:77]
	v_mad_i64_i32 v[62:63], s[44:45], v128, s92, v[62:63]
	v_lshl_add_u64 v[64:65], v[66:67], 0, v[64:65]
	v_lshl_add_u64 v[62:63], v[64:65], 1, v[62:63]
	global_store_dwordx4 v[62:63], v[58:61], off offset:256 nt

.LBB0_564:
	s_andn2_b64 vcc, exec, s[82:83]
	s_cbranch_vccnz .LBB0_566
	v_mov_b64_e32 v[62:63], s[46:47]
	v_ashrrev_i32_e32 v149, 31, v148
	s_ashr_i32 s77, s76, 31
	v_mad_i64_i32 v[62:63], s[44:45], v128, s65, v[62:63]
	v_lshl_add_u64 v[64:65], v[148:149], 0, s[76:77]
	v_cvt_pk_bf16_f32 v58, v54, v55
	v_cvt_pk_bf16_f32 v59, v56, v57
	v_cvt_pk_bf16_f32 v60, v50, v51
	v_cvt_pk_bf16_f32 v61, v52, v53
	v_lshl_add_u64 v[62:63], v[64:65], 1, v[62:63]
	global_store_dwordx4 v[62:63], v[58:61], off offset:-2304 nt

.LBB0_568:
	s_andn2_b64 vcc, exec, s[80:81]
	s_cbranch_vccnz .LBB0_572
	s_andn2_b64 vcc, exec, s[78:79]
	s_cbranch_vccnz .LBB0_571
	v_mul_f32_e32 v51, 0xbfb8aa3b, v42
	v_exp_f32_e32 v51, v51
	v_mul_f32_e32 v52, 0xbfb8aa3b, v47
	v_mul_f32_e32 v53, 0xbfb8aa3b, v43
	v_exp_f32_e32 v52, v52
	v_add_f32_e32 v51, 1.0, v51
	v_rcp_f32_e32 v51, v51
	v_exp_f32_e32 v53, v53
	v_mul_f32_e32 v50, 0xbfb8aa3b, v46
	v_mul_f32_e32 v55, 0xbfb8aa3b, v44
	v_mul_f32_e32 v51, v42, v51
	v_cndmask_b32_e64 v54, v51, v42, s[6:7]
	v_add_f32_e32 v51, 1.0, v52
	v_add_f32_e32 v52, 1.0, v53
	v_mul_f32_e32 v53, 0xbfb8aa3b, v48
	v_mul_f32_e32 v56, 0xbfb8aa3b, v49
	v_mul_f32_e32 v57, 0xbfb8aa3b, v45
	v_exp_f32_e32 v50, v50
	v_exp_f32_e32 v53, v53
	v_exp_f32_e32 v55, v55
	v_exp_f32_e32 v56, v56
	v_exp_f32_e32 v57, v57
	v_add_f32_e32 v50, 1.0, v50
	v_add_f32_e32 v53, 1.0, v53
	v_add_f32_e32 v55, 1.0, v55
	v_add_f32_e32 v56, 1.0, v56
	v_add_f32_e32 v57, 1.0, v57
	v_rcp_f32_e32 v50, v50
	v_rcp_f32_e32 v51, v51
	v_rcp_f32_e32 v52, v52
	v_rcp_f32_e32 v53, v53
	v_rcp_f32_e32 v55, v55
	v_rcp_f32_e32 v56, v56
	v_rcp_f32_e32 v57, v57
	v_mul_f32_e32 v50, v46, v50
	v_mul_f32_e32 v51, v47, v51
	v_mul_f32_e32 v52, v43, v52
	v_mul_f32_e32 v53, v48, v53
	v_mul_f32_e32 v55, v44, v55
	v_mul_f32_e32 v56, v49, v56
	v_mul_f32_e32 v57, v45, v57
	v_readlane_b32 s44, v254, 8
	v_cndmask_b32_e64 v50, v50, v46, s[6:7]
	v_cndmask_b32_e64 v51, v51, v47, s[6:7]
	v_cndmask_b32_e64 v52, v52, v43, s[6:7]
	v_cndmask_b32_e64 v53, v53, v48, s[6:7]
	v_cndmask_b32_e64 v55, v55, v44, s[6:7]
	v_cndmask_b32_e64 v56, v56, v49, s[6:7]
	v_cndmask_b32_e64 v57, v57, v45, s[6:7]
	v_readlane_b32 s45, v254, 9
	v_ashrrev_i32_e32 v149, 31, v148
	s_ashr_i32 s77, s76, 31
	v_cvt_pk_bf16_f32 v50, v50, v51
	v_cvt_pk_bf16_f32 v51, v53, v56
	v_cvt_pk_bf16_f32 v52, v54, v52
	v_cvt_pk_bf16_f32 v53, v55, v57
	v_mov_b64_e32 v[54:55], s[44:45]
	v_ashrrev_i32_e32 v67, 31, v66
	v_lshl_add_u64 v[56:57], v[148:149], 0, s[76:77]
	v_mad_i64_i32 v[54:55], s[44:45], v120, s92, v[54:55]
	v_lshl_add_u64 v[56:57], v[66:67], 0, v[56:57]
	v_lshl_add_u64 v[54:55], v[56:57], 1, v[54:55]
	global_store_dwordx4 v[54:55], v[50:53], off offset:256 nt

.LBB0_572:
	s_andn2_b64 vcc, exec, s[82:83]
	s_cbranch_vccnz .LBB0_574
	v_mov_b64_e32 v[54:55], s[46:47]
	v_ashrrev_i32_e32 v149, 31, v148
	s_ashr_i32 s77, s76, 31
	v_mad_i64_i32 v[54:55], s[44:45], v120, s65, v[54:55]
	v_lshl_add_u64 v[56:57], v[148:149], 0, s[76:77]
	v_cvt_pk_bf16_f32 v50, v46, v47
	v_cvt_pk_bf16_f32 v51, v48, v49
	v_cvt_pk_bf16_f32 v52, v42, v43
	v_cvt_pk_bf16_f32 v53, v44, v45
	v_lshl_add_u64 v[54:55], v[56:57], 1, v[54:55]
	global_store_dwordx4 v[54:55], v[50:53], off offset:-2304 nt

.LBB0_576:
	s_andn2_b64 vcc, exec, s[80:81]
	s_cbranch_vccnz .LBB0_580
	s_andn2_b64 vcc, exec, s[78:79]
	s_cbranch_vccnz .LBB0_579
	v_mul_f32_e32 v43, 0xbfb8aa3b, v34
	v_exp_f32_e32 v43, v43
	v_mul_f32_e32 v44, 0xbfb8aa3b, v39
	v_mul_f32_e32 v45, 0xbfb8aa3b, v35
	v_exp_f32_e32 v44, v44
	v_add_f32_e32 v43, 1.0, v43
	v_rcp_f32_e32 v43, v43
	v_exp_f32_e32 v45, v45
	v_mul_f32_e32 v42, 0xbfb8aa3b, v38
	v_mul_f32_e32 v47, 0xbfb8aa3b, v36
	v_mul_f32_e32 v43, v34, v43
	v_cndmask_b32_e64 v46, v43, v34, s[6:7]
	v_add_f32_e32 v43, 1.0, v44
	v_add_f32_e32 v44, 1.0, v45
	v_mul_f32_e32 v45, 0xbfb8aa3b, v40
	v_mul_f32_e32 v48, 0xbfb8aa3b, v41
	v_mul_f32_e32 v49, 0xbfb8aa3b, v37
	v_exp_f32_e32 v42, v42
	v_exp_f32_e32 v45, v45
	v_exp_f32_e32 v47, v47
	v_exp_f32_e32 v48, v48
	v_exp_f32_e32 v49, v49
	v_add_f32_e32 v42, 1.0, v42
	v_add_f32_e32 v45, 1.0, v45
	v_add_f32_e32 v47, 1.0, v47
	v_add_f32_e32 v48, 1.0, v48
	v_add_f32_e32 v49, 1.0, v49
	v_rcp_f32_e32 v42, v42
	v_rcp_f32_e32 v43, v43
	v_rcp_f32_e32 v44, v44
	v_rcp_f32_e32 v45, v45
	v_rcp_f32_e32 v47, v47
	v_rcp_f32_e32 v48, v48
	v_rcp_f32_e32 v49, v49
	v_mul_f32_e32 v42, v38, v42
	v_mul_f32_e32 v43, v39, v43
	v_mul_f32_e32 v44, v35, v44
	v_mul_f32_e32 v45, v40, v45
	v_mul_f32_e32 v47, v36, v47
	v_mul_f32_e32 v48, v41, v48
	v_mul_f32_e32 v49, v37, v49
	v_readlane_b32 s44, v254, 8
	v_cndmask_b32_e64 v42, v42, v38, s[6:7]
	v_cndmask_b32_e64 v43, v43, v39, s[6:7]
	v_cndmask_b32_e64 v44, v44, v35, s[6:7]
	v_cndmask_b32_e64 v45, v45, v40, s[6:7]
	v_cndmask_b32_e64 v47, v47, v36, s[6:7]
	v_cndmask_b32_e64 v48, v48, v41, s[6:7]
	v_cndmask_b32_e64 v49, v49, v37, s[6:7]
	v_readlane_b32 s45, v254, 9
	v_ashrrev_i32_e32 v149, 31, v148
	s_ashr_i32 s77, s76, 31
	v_cvt_pk_bf16_f32 v42, v42, v43
	v_cvt_pk_bf16_f32 v43, v45, v48
	v_cvt_pk_bf16_f32 v44, v46, v44
	v_cvt_pk_bf16_f32 v45, v47, v49
	v_mov_b64_e32 v[46:47], s[44:45]
	v_ashrrev_i32_e32 v67, 31, v66
	v_lshl_add_u64 v[48:49], v[148:149], 0, s[76:77]
	v_mad_i64_i32 v[46:47], s[44:45], v112, s92, v[46:47]
	v_lshl_add_u64 v[48:49], v[66:67], 0, v[48:49]
	v_lshl_add_u64 v[46:47], v[48:49], 1, v[46:47]
	global_store_dwordx4 v[46:47], v[42:45], off offset:256 nt

.LBB0_580:
	s_andn2_b64 vcc, exec, s[82:83]
	s_cbranch_vccnz .LBB0_582
	v_mov_b64_e32 v[46:47], s[46:47]
	v_ashrrev_i32_e32 v149, 31, v148
	s_ashr_i32 s77, s76, 31
	v_mad_i64_i32 v[46:47], s[44:45], v112, s65, v[46:47]
	v_lshl_add_u64 v[48:49], v[148:149], 0, s[76:77]
	v_cvt_pk_bf16_f32 v42, v38, v39
	v_cvt_pk_bf16_f32 v43, v40, v41
	v_cvt_pk_bf16_f32 v44, v34, v35
	v_cvt_pk_bf16_f32 v45, v36, v37
	v_lshl_add_u64 v[46:47], v[48:49], 1, v[46:47]
	global_store_dwordx4 v[46:47], v[42:45], off offset:-2304 nt

.LBB0_584:
	s_andn2_b64 vcc, exec, s[80:81]
	s_cbranch_vccnz .LBB0_588
	s_andn2_b64 vcc, exec, s[78:79]
	s_cbranch_vccnz .LBB0_587
	v_mul_f32_e32 v35, 0xbfb8aa3b, v26
	v_exp_f32_e32 v35, v35
	v_mul_f32_e32 v36, 0xbfb8aa3b, v31
	v_mul_f32_e32 v37, 0xbfb8aa3b, v27
	v_exp_f32_e32 v36, v36
	v_add_f32_e32 v35, 1.0, v35
	v_rcp_f32_e32 v35, v35
	v_exp_f32_e32 v37, v37
	v_mul_f32_e32 v34, 0xbfb8aa3b, v30
	v_mul_f32_e32 v39, 0xbfb8aa3b, v28
	v_mul_f32_e32 v35, v26, v35
	v_cndmask_b32_e64 v38, v35, v26, s[6:7]
	v_add_f32_e32 v35, 1.0, v36
	v_add_f32_e32 v36, 1.0, v37
	v_mul_f32_e32 v37, 0xbfb8aa3b, v32
	v_mul_f32_e32 v40, 0xbfb8aa3b, v33
	v_mul_f32_e32 v41, 0xbfb8aa3b, v29
	v_exp_f32_e32 v34, v34
	v_exp_f32_e32 v37, v37
	v_exp_f32_e32 v39, v39
	v_exp_f32_e32 v40, v40
	v_exp_f32_e32 v41, v41
	v_add_f32_e32 v34, 1.0, v34
	v_add_f32_e32 v37, 1.0, v37
	v_add_f32_e32 v39, 1.0, v39
	v_add_f32_e32 v40, 1.0, v40
	v_add_f32_e32 v41, 1.0, v41
	v_rcp_f32_e32 v34, v34
	v_rcp_f32_e32 v35, v35
	v_rcp_f32_e32 v36, v36
	v_rcp_f32_e32 v37, v37
	v_rcp_f32_e32 v39, v39
	v_rcp_f32_e32 v40, v40
	v_rcp_f32_e32 v41, v41
	v_mul_f32_e32 v34, v30, v34
	v_mul_f32_e32 v35, v31, v35
	v_mul_f32_e32 v36, v27, v36
	v_mul_f32_e32 v37, v32, v37
	v_mul_f32_e32 v39, v28, v39
	v_mul_f32_e32 v40, v33, v40
	v_mul_f32_e32 v41, v29, v41
	v_readlane_b32 s44, v254, 8
	v_cndmask_b32_e64 v34, v34, v30, s[6:7]
	v_cndmask_b32_e64 v35, v35, v31, s[6:7]
	v_cndmask_b32_e64 v36, v36, v27, s[6:7]
	v_cndmask_b32_e64 v37, v37, v32, s[6:7]
	v_cndmask_b32_e64 v39, v39, v28, s[6:7]
	v_cndmask_b32_e64 v40, v40, v33, s[6:7]
	v_cndmask_b32_e64 v41, v41, v29, s[6:7]
	v_readlane_b32 s45, v254, 9
	v_ashrrev_i32_e32 v149, 31, v148
	s_ashr_i32 s77, s76, 31
	v_cvt_pk_bf16_f32 v34, v34, v35
	v_cvt_pk_bf16_f32 v35, v37, v40
	v_cvt_pk_bf16_f32 v36, v38, v36
	v_cvt_pk_bf16_f32 v37, v39, v41
	v_mov_b64_e32 v[38:39], s[44:45]
	v_ashrrev_i32_e32 v67, 31, v66
	v_lshl_add_u64 v[40:41], v[148:149], 0, s[76:77]
	v_mad_i64_i32 v[38:39], s[44:45], v104, s92, v[38:39]
	v_lshl_add_u64 v[40:41], v[66:67], 0, v[40:41]
	v_lshl_add_u64 v[38:39], v[40:41], 1, v[38:39]
	global_store_dwordx4 v[38:39], v[34:37], off offset:256 nt

.LBB0_588:
	s_andn2_b64 vcc, exec, s[82:83]
	s_cbranch_vccnz .LBB0_590
	v_mov_b64_e32 v[38:39], s[46:47]
	v_ashrrev_i32_e32 v149, 31, v148
	s_ashr_i32 s77, s76, 31
	v_mad_i64_i32 v[38:39], s[44:45], v104, s65, v[38:39]
	v_lshl_add_u64 v[40:41], v[148:149], 0, s[76:77]
	v_cvt_pk_bf16_f32 v34, v30, v31
	v_cvt_pk_bf16_f32 v35, v32, v33
	v_cvt_pk_bf16_f32 v36, v26, v27
	v_cvt_pk_bf16_f32 v37, v28, v29
	v_lshl_add_u64 v[38:39], v[40:41], 1, v[38:39]
	global_store_dwordx4 v[38:39], v[34:37], off offset:-2304 nt

.LBB0_592:
	s_andn2_b64 vcc, exec, s[80:81]
	s_cbranch_vccnz .LBB0_596
	s_andn2_b64 vcc, exec, s[78:79]
	s_cbranch_vccnz .LBB0_595
	v_mul_f32_e32 v27, 0xbfb8aa3b, v18
	v_exp_f32_e32 v27, v27
	v_mul_f32_e32 v28, 0xbfb8aa3b, v23
	v_mul_f32_e32 v29, 0xbfb8aa3b, v19
	v_exp_f32_e32 v28, v28
	v_add_f32_e32 v27, 1.0, v27
	v_rcp_f32_e32 v27, v27
	v_exp_f32_e32 v29, v29
	v_mul_f32_e32 v26, 0xbfb8aa3b, v22
	v_mul_f32_e32 v31, 0xbfb8aa3b, v20
	v_mul_f32_e32 v27, v18, v27
	v_cndmask_b32_e64 v30, v27, v18, s[6:7]
	v_add_f32_e32 v27, 1.0, v28
	v_add_f32_e32 v28, 1.0, v29
	v_mul_f32_e32 v29, 0xbfb8aa3b, v24
	v_mul_f32_e32 v32, 0xbfb8aa3b, v25
	v_mul_f32_e32 v33, 0xbfb8aa3b, v21
	v_exp_f32_e32 v26, v26
	v_exp_f32_e32 v29, v29
	v_exp_f32_e32 v31, v31
	v_exp_f32_e32 v32, v32
	v_exp_f32_e32 v33, v33
	v_add_f32_e32 v26, 1.0, v26
	v_add_f32_e32 v29, 1.0, v29
	v_add_f32_e32 v31, 1.0, v31
	v_add_f32_e32 v32, 1.0, v32
	v_add_f32_e32 v33, 1.0, v33
	v_rcp_f32_e32 v26, v26
	v_rcp_f32_e32 v27, v27
	v_rcp_f32_e32 v28, v28
	v_rcp_f32_e32 v29, v29
	v_rcp_f32_e32 v31, v31
	v_rcp_f32_e32 v32, v32
	v_rcp_f32_e32 v33, v33
	v_mul_f32_e32 v26, v22, v26
	v_mul_f32_e32 v27, v23, v27
	v_mul_f32_e32 v28, v19, v28
	v_mul_f32_e32 v29, v24, v29
	v_mul_f32_e32 v31, v20, v31
	v_mul_f32_e32 v32, v25, v32
	v_mul_f32_e32 v33, v21, v33
	v_readlane_b32 s44, v254, 8
	v_cndmask_b32_e64 v26, v26, v22, s[6:7]
	v_cndmask_b32_e64 v27, v27, v23, s[6:7]
	v_cndmask_b32_e64 v28, v28, v19, s[6:7]
	v_cndmask_b32_e64 v29, v29, v24, s[6:7]
	v_cndmask_b32_e64 v31, v31, v20, s[6:7]
	v_cndmask_b32_e64 v32, v32, v25, s[6:7]
	v_cndmask_b32_e64 v33, v33, v21, s[6:7]
	v_readlane_b32 s45, v254, 9
	v_ashrrev_i32_e32 v149, 31, v148
	s_ashr_i32 s77, s76, 31
	v_cvt_pk_bf16_f32 v26, v26, v27
	v_cvt_pk_bf16_f32 v27, v29, v32
	v_cvt_pk_bf16_f32 v28, v30, v28
	v_cvt_pk_bf16_f32 v29, v31, v33
	v_mov_b64_e32 v[30:31], s[44:45]
	v_ashrrev_i32_e32 v67, 31, v66
	v_lshl_add_u64 v[32:33], v[148:149], 0, s[76:77]
	v_mad_i64_i32 v[30:31], s[44:45], v96, s92, v[30:31]
	v_lshl_add_u64 v[32:33], v[66:67], 0, v[32:33]
	v_lshl_add_u64 v[30:31], v[32:33], 1, v[30:31]
	global_store_dwordx4 v[30:31], v[26:29], off offset:256 nt

.LBB0_596:
	s_andn2_b64 vcc, exec, s[82:83]
	s_cbranch_vccnz .LBB0_598
	v_mov_b64_e32 v[30:31], s[46:47]
	v_ashrrev_i32_e32 v149, 31, v148
	s_ashr_i32 s77, s76, 31
	v_mad_i64_i32 v[30:31], s[44:45], v96, s65, v[30:31]
	v_lshl_add_u64 v[32:33], v[148:149], 0, s[76:77]
	v_cvt_pk_bf16_f32 v26, v22, v23
	v_cvt_pk_bf16_f32 v27, v24, v25
	v_cvt_pk_bf16_f32 v28, v18, v19
	v_cvt_pk_bf16_f32 v29, v20, v21
	v_lshl_add_u64 v[30:31], v[32:33], 1, v[30:31]
	global_store_dwordx4 v[30:31], v[26:29], off offset:-2304 nt

.LBB0_600:
	s_andn2_b64 vcc, exec, s[80:81]
	s_cbranch_vccnz .LBB0_604
	s_andn2_b64 vcc, exec, s[78:79]
	s_cbranch_vccnz .LBB0_603
	v_mul_f32_e32 v19, 0xbfb8aa3b, v10
	v_exp_f32_e32 v19, v19
	v_mul_f32_e32 v20, 0xbfb8aa3b, v15
	v_mul_f32_e32 v21, 0xbfb8aa3b, v11
	v_exp_f32_e32 v20, v20
	v_add_f32_e32 v19, 1.0, v19
	v_rcp_f32_e32 v19, v19
	v_exp_f32_e32 v21, v21
	v_mul_f32_e32 v18, 0xbfb8aa3b, v14
	v_mul_f32_e32 v23, 0xbfb8aa3b, v12
	v_mul_f32_e32 v19, v10, v19
	v_cndmask_b32_e64 v22, v19, v10, s[6:7]
	v_add_f32_e32 v19, 1.0, v20
	v_add_f32_e32 v20, 1.0, v21
	v_mul_f32_e32 v21, 0xbfb8aa3b, v16
	v_mul_f32_e32 v24, 0xbfb8aa3b, v17
	v_mul_f32_e32 v25, 0xbfb8aa3b, v13
	v_exp_f32_e32 v18, v18
	v_exp_f32_e32 v21, v21
	v_exp_f32_e32 v23, v23
	v_exp_f32_e32 v24, v24
	v_exp_f32_e32 v25, v25
	v_add_f32_e32 v18, 1.0, v18
	v_add_f32_e32 v21, 1.0, v21
	v_add_f32_e32 v23, 1.0, v23
	v_add_f32_e32 v24, 1.0, v24
	v_add_f32_e32 v25, 1.0, v25
	v_rcp_f32_e32 v18, v18
	v_rcp_f32_e32 v19, v19
	v_rcp_f32_e32 v20, v20
	v_rcp_f32_e32 v21, v21
	v_rcp_f32_e32 v23, v23
	v_rcp_f32_e32 v24, v24
	v_rcp_f32_e32 v25, v25
	v_mul_f32_e32 v18, v14, v18
	v_mul_f32_e32 v19, v15, v19
	v_mul_f32_e32 v20, v11, v20
	v_mul_f32_e32 v21, v16, v21
	v_mul_f32_e32 v23, v12, v23
	v_mul_f32_e32 v24, v17, v24
	v_mul_f32_e32 v25, v13, v25
	v_readlane_b32 s44, v254, 8
	v_cndmask_b32_e64 v18, v18, v14, s[6:7]
	v_cndmask_b32_e64 v19, v19, v15, s[6:7]
	v_cndmask_b32_e64 v20, v20, v11, s[6:7]
	v_cndmask_b32_e64 v21, v21, v16, s[6:7]
	v_cndmask_b32_e64 v23, v23, v12, s[6:7]
	v_cndmask_b32_e64 v24, v24, v17, s[6:7]
	v_cndmask_b32_e64 v25, v25, v13, s[6:7]
	v_readlane_b32 s45, v254, 9
	v_ashrrev_i32_e32 v149, 31, v148
	s_ashr_i32 s77, s76, 31
	v_cvt_pk_bf16_f32 v18, v18, v19
	v_cvt_pk_bf16_f32 v19, v21, v24
	v_cvt_pk_bf16_f32 v20, v22, v20
	v_cvt_pk_bf16_f32 v21, v23, v25
	v_mov_b64_e32 v[22:23], s[44:45]
	v_ashrrev_i32_e32 v67, 31, v66
	v_lshl_add_u64 v[24:25], v[148:149], 0, s[76:77]
	v_mad_i64_i32 v[22:23], s[44:45], v88, s92, v[22:23]
	v_lshl_add_u64 v[24:25], v[66:67], 0, v[24:25]
	v_lshl_add_u64 v[22:23], v[24:25], 1, v[22:23]
	global_store_dwordx4 v[22:23], v[18:21], off offset:256 nt

.LBB0_604:
	s_andn2_b64 vcc, exec, s[82:83]
	s_cbranch_vccnz .LBB0_606
	v_mov_b64_e32 v[22:23], s[46:47]
	v_ashrrev_i32_e32 v149, 31, v148
	s_ashr_i32 s77, s76, 31
	v_mad_i64_i32 v[22:23], s[44:45], v88, s65, v[22:23]
	v_lshl_add_u64 v[24:25], v[148:149], 0, s[76:77]
	v_cvt_pk_bf16_f32 v18, v14, v15
	v_cvt_pk_bf16_f32 v19, v16, v17
	v_cvt_pk_bf16_f32 v20, v10, v11
	v_cvt_pk_bf16_f32 v21, v12, v13
	v_lshl_add_u64 v[22:23], v[24:25], 1, v[22:23]
	global_store_dwordx4 v[22:23], v[18:21], off offset:-2304 nt

.LBB0_608:
	s_andn2_b64 vcc, exec, s[80:81]
	s_cbranch_vccnz .LBB0_612
	s_andn2_b64 vcc, exec, s[78:79]
	s_cbranch_vccnz .LBB0_611
	v_mul_f32_e32 v11, 0xbfb8aa3b, v0
	v_exp_f32_e32 v11, v11
	v_mul_f32_e32 v12, 0xbfb8aa3b, v7
	v_mul_f32_e32 v13, 0xbfb8aa3b, v1
	v_exp_f32_e32 v12, v12
	v_add_f32_e32 v11, 1.0, v11
	v_rcp_f32_e32 v11, v11
	v_exp_f32_e32 v13, v13
	v_mul_f32_e32 v10, 0xbfb8aa3b, v6
	v_mul_f32_e32 v15, 0xbfb8aa3b, v2
	v_mul_f32_e32 v11, v0, v11
	v_cndmask_b32_e64 v14, v11, v0, s[6:7]
	v_add_f32_e32 v11, 1.0, v12
	v_add_f32_e32 v12, 1.0, v13
	v_mul_f32_e32 v13, 0xbfb8aa3b, v8
	v_mul_f32_e32 v16, 0xbfb8aa3b, v9
	v_mul_f32_e32 v17, 0xbfb8aa3b, v3
	v_exp_f32_e32 v10, v10
	v_exp_f32_e32 v13, v13
	v_exp_f32_e32 v15, v15
	v_exp_f32_e32 v16, v16
	v_exp_f32_e32 v17, v17
	v_add_f32_e32 v10, 1.0, v10
	v_add_f32_e32 v13, 1.0, v13
	v_add_f32_e32 v15, 1.0, v15
	v_add_f32_e32 v16, 1.0, v16
	v_add_f32_e32 v17, 1.0, v17
	v_rcp_f32_e32 v10, v10
	v_rcp_f32_e32 v11, v11
	v_rcp_f32_e32 v12, v12
	v_rcp_f32_e32 v13, v13
	v_rcp_f32_e32 v15, v15
	v_rcp_f32_e32 v16, v16
	v_rcp_f32_e32 v17, v17
	v_mul_f32_e32 v10, v6, v10
	v_mul_f32_e32 v11, v7, v11
	v_mul_f32_e32 v12, v1, v12
	v_mul_f32_e32 v13, v8, v13
	v_mul_f32_e32 v15, v2, v15
	v_mul_f32_e32 v16, v9, v16
	v_mul_f32_e32 v17, v3, v17
	v_cndmask_b32_e64 v10, v10, v6, s[6:7]
	v_cndmask_b32_e64 v11, v11, v7, s[6:7]
	v_cndmask_b32_e64 v12, v12, v1, s[6:7]
	v_cndmask_b32_e64 v13, v13, v8, s[6:7]
	v_cndmask_b32_e64 v15, v15, v2, s[6:7]
	v_cndmask_b32_e64 v16, v16, v9, s[6:7]
	v_cndmask_b32_e64 v17, v17, v3, s[6:7]
	v_readlane_b32 s6, v254, 8
	v_readlane_b32 s7, v254, 9
	v_ashrrev_i32_e32 v149, 31, v148
	s_ashr_i32 s77, s76, 31
	v_cvt_pk_bf16_f32 v10, v10, v11
	v_cvt_pk_bf16_f32 v11, v13, v16
	v_cvt_pk_bf16_f32 v12, v14, v12
	v_cvt_pk_bf16_f32 v13, v15, v17
	v_mov_b64_e32 v[14:15], s[6:7]
	v_ashrrev_i32_e32 v67, 31, v66
	v_lshl_add_u64 v[16:17], v[148:149], 0, s[76:77]
	v_mad_i64_i32 v[14:15], s[6:7], v80, s92, v[14:15]
	v_lshl_add_u64 v[16:17], v[66:67], 0, v[16:17]
	v_lshl_add_u64 v[14:15], v[16:17], 1, v[14:15]
	global_store_dwordx4 v[14:15], v[10:13], off offset:256 nt

.LBB0_612:
	s_andn2_b64 vcc, exec, s[8:9]
	s_cbranch_vccnz .LBB0_614
	v_mov_b64_e32 v[14:15], s[46:47]
	v_ashrrev_i32_e32 v149, 31, v148
	s_ashr_i32 s77, s76, 31
	v_mad_i64_i32 v[14:15], s[6:7], v80, s65, v[14:15]
	v_lshl_add_u64 v[16:17], v[148:149], 0, s[76:77]
	v_cvt_pk_bf16_f32 v10, v6, v7
	v_cvt_pk_bf16_f32 v11, v8, v9
	v_cvt_pk_bf16_f32 v12, v0, v1
	v_cvt_pk_bf16_f32 v13, v2, v3
	v_lshl_add_u64 v[14:15], v[16:17], 1, v[14:15]
	global_store_dwordx4 v[14:15], v[10:13], off offset:-2304 nt

.LBB0_621:
	s_or_b64 exec, exec, s[82:83]
	v_mov_b32_e32 v59, v4
	v_lshl_add_u64 v[58:59], v[58:59], 1, v[60:61]
	v_cvt_pk_bf16_f32 v54, v54, s0
	v_lshlrev_b32_e32 v60, 3, v62
	v_mov_b32_e32 v61, v4
	global_store_short v[58:59], v54, off nt
	v_cvt_pk_bf16_f32 v50, v50, s0
	v_lshl_add_u64 v[58:59], v[58:59], 0, v[60:61]
	global_store_short v[58:59], v50, off nt
	v_cvt_pk_bf16_f32 v50, v55, s0
	v_mul_hi_i32_i24_e32 v55, -6, v62
	v_mul_i32_i24_e32 v54, -6, v62
	v_lshl_add_u64 v[58:59], v[58:59], 0, v[54:55]
	global_store_short v[58:59], v50, off nt
	v_cvt_pk_bf16_f32 v62, v51, s0
	v_lshl_add_u64 v[50:51], v[58:59], 0, v[60:61]
	global_store_short v[50:51], v62, off nt
	v_cvt_pk_bf16_f32 v56, v56, s0
	v_lshl_add_u64 v[50:51], v[50:51], 0, v[54:55]
	global_store_short v[50:51], v56, off nt
	v_cvt_pk_bf16_f32 v52, v52, s0
	v_lshl_add_u64 v[50:51], v[50:51], 0, v[60:61]
	global_store_short v[50:51], v52, off nt
	v_cvt_pk_bf16_f32 v52, v57, s0
	v_lshl_add_u64 v[50:51], v[50:51], 0, v[54:55]
	global_store_short v[50:51], v52, off nt
	v_cvt_pk_bf16_f32 v52, v53, s0
	v_lshl_add_u64 v[50:51], v[50:51], 0, v[60:61]
	global_store_short v[50:51], v52, off nt
	s_and_b64 vcc, exec, s[8:9]
	s_mov_b64 s[82:83], -1
	s_cbranch_vccz .LBB0_568

.LBB0_627:
	s_or_b64 exec, exec, s[82:83]
	v_mov_b32_e32 v51, v4
	v_lshl_add_u64 v[50:51], v[50:51], 1, v[52:53]
	v_cvt_pk_bf16_f32 v46, v46, s0
	v_lshlrev_b32_e32 v52, 3, v54
	v_mov_b32_e32 v53, v4
	global_store_short v[50:51], v46, off nt
	v_cvt_pk_bf16_f32 v42, v42, s0
	v_lshl_add_u64 v[50:51], v[50:51], 0, v[52:53]
	global_store_short v[50:51], v42, off nt
	v_cvt_pk_bf16_f32 v42, v47, s0
	v_mul_hi_i32_i24_e32 v47, -6, v54
	v_mul_i32_i24_e32 v46, -6, v54
	v_lshl_add_u64 v[50:51], v[50:51], 0, v[46:47]
	global_store_short v[50:51], v42, off nt
	v_cvt_pk_bf16_f32 v54, v43, s0
	v_lshl_add_u64 v[42:43], v[50:51], 0, v[52:53]
	global_store_short v[42:43], v54, off nt
	v_cvt_pk_bf16_f32 v48, v48, s0
	v_lshl_add_u64 v[42:43], v[42:43], 0, v[46:47]
	global_store_short v[42:43], v48, off nt
	v_cvt_pk_bf16_f32 v44, v44, s0
	v_lshl_add_u64 v[42:43], v[42:43], 0, v[52:53]
	global_store_short v[42:43], v44, off nt
	v_cvt_pk_bf16_f32 v44, v49, s0
	v_lshl_add_u64 v[42:43], v[42:43], 0, v[46:47]
	global_store_short v[42:43], v44, off nt
	v_cvt_pk_bf16_f32 v44, v45, s0
	v_lshl_add_u64 v[42:43], v[42:43], 0, v[52:53]
	global_store_short v[42:43], v44, off nt
	s_and_b64 vcc, exec, s[8:9]
	s_mov_b64 s[82:83], -1
	s_cbranch_vccz .LBB0_576

.LBB0_633:
	s_or_b64 exec, exec, s[82:83]
	v_mov_b32_e32 v43, v4
	v_lshl_add_u64 v[42:43], v[42:43], 1, v[44:45]
	v_cvt_pk_bf16_f32 v38, v38, s0
	v_lshlrev_b32_e32 v44, 3, v46
	v_mov_b32_e32 v45, v4
	global_store_short v[42:43], v38, off nt
	v_cvt_pk_bf16_f32 v34, v34, s0
	v_lshl_add_u64 v[42:43], v[42:43], 0, v[44:45]
	global_store_short v[42:43], v34, off nt
	v_cvt_pk_bf16_f32 v34, v39, s0
	v_mul_hi_i32_i24_e32 v39, -6, v46
	v_mul_i32_i24_e32 v38, -6, v46
	v_lshl_add_u64 v[42:43], v[42:43], 0, v[38:39]
	global_store_short v[42:43], v34, off nt
	v_cvt_pk_bf16_f32 v46, v35, s0
	v_lshl_add_u64 v[34:35], v[42:43], 0, v[44:45]
	global_store_short v[34:35], v46, off nt
	v_cvt_pk_bf16_f32 v40, v40, s0
	v_lshl_add_u64 v[34:35], v[34:35], 0, v[38:39]
	global_store_short v[34:35], v40, off nt
	v_cvt_pk_bf16_f32 v36, v36, s0
	v_lshl_add_u64 v[34:35], v[34:35], 0, v[44:45]
	global_store_short v[34:35], v36, off nt
	v_cvt_pk_bf16_f32 v36, v41, s0
	v_lshl_add_u64 v[34:35], v[34:35], 0, v[38:39]
	global_store_short v[34:35], v36, off nt
	v_cvt_pk_bf16_f32 v36, v37, s0
	v_lshl_add_u64 v[34:35], v[34:35], 0, v[44:45]
	global_store_short v[34:35], v36, off nt
	s_and_b64 vcc, exec, s[8:9]
	s_mov_b64 s[82:83], -1
	s_cbranch_vccz .LBB0_584

.LBB0_639:
	s_or_b64 exec, exec, s[82:83]
	v_mov_b32_e32 v35, v4
	v_lshl_add_u64 v[34:35], v[34:35], 1, v[36:37]
	v_cvt_pk_bf16_f32 v30, v30, s0
	v_lshlrev_b32_e32 v36, 3, v38
	v_mov_b32_e32 v37, v4
	global_store_short v[34:35], v30, off nt
	v_cvt_pk_bf16_f32 v26, v26, s0
	v_lshl_add_u64 v[34:35], v[34:35], 0, v[36:37]
	global_store_short v[34:35], v26, off nt
	v_cvt_pk_bf16_f32 v26, v31, s0
	v_mul_hi_i32_i24_e32 v31, -6, v38
	v_mul_i32_i24_e32 v30, -6, v38
	v_lshl_add_u64 v[34:35], v[34:35], 0, v[30:31]
	global_store_short v[34:35], v26, off nt
	v_cvt_pk_bf16_f32 v38, v27, s0
	v_lshl_add_u64 v[26:27], v[34:35], 0, v[36:37]
	global_store_short v[26:27], v38, off nt
	v_cvt_pk_bf16_f32 v32, v32, s0
	v_lshl_add_u64 v[26:27], v[26:27], 0, v[30:31]
	global_store_short v[26:27], v32, off nt
	v_cvt_pk_bf16_f32 v28, v28, s0
	v_lshl_add_u64 v[26:27], v[26:27], 0, v[36:37]
	global_store_short v[26:27], v28, off nt
	v_cvt_pk_bf16_f32 v28, v33, s0
	v_lshl_add_u64 v[26:27], v[26:27], 0, v[30:31]
	global_store_short v[26:27], v28, off nt
	v_cvt_pk_bf16_f32 v28, v29, s0
	v_lshl_add_u64 v[26:27], v[26:27], 0, v[36:37]
	global_store_short v[26:27], v28, off nt
	s_and_b64 vcc, exec, s[8:9]
	s_mov_b64 s[82:83], -1
	s_cbranch_vccz .LBB0_592

.LBB0_645:
	s_or_b64 exec, exec, s[82:83]
	v_mov_b32_e32 v27, v4
	v_lshl_add_u64 v[26:27], v[26:27], 1, v[28:29]
	v_cvt_pk_bf16_f32 v22, v22, s0
	v_lshlrev_b32_e32 v28, 3, v30
	v_mov_b32_e32 v29, v4
	global_store_short v[26:27], v22, off nt
	v_cvt_pk_bf16_f32 v18, v18, s0
	v_lshl_add_u64 v[26:27], v[26:27], 0, v[28:29]
	global_store_short v[26:27], v18, off nt
	v_cvt_pk_bf16_f32 v18, v23, s0
	v_mul_hi_i32_i24_e32 v23, -6, v30
	v_mul_i32_i24_e32 v22, -6, v30
	v_lshl_add_u64 v[26:27], v[26:27], 0, v[22:23]
	global_store_short v[26:27], v18, off nt
	v_cvt_pk_bf16_f32 v30, v19, s0
	v_lshl_add_u64 v[18:19], v[26:27], 0, v[28:29]
	global_store_short v[18:19], v30, off nt
	v_cvt_pk_bf16_f32 v24, v24, s0
	v_lshl_add_u64 v[18:19], v[18:19], 0, v[22:23]
	global_store_short v[18:19], v24, off nt
	v_cvt_pk_bf16_f32 v20, v20, s0
	v_lshl_add_u64 v[18:19], v[18:19], 0, v[28:29]
	global_store_short v[18:19], v20, off nt
	v_cvt_pk_bf16_f32 v20, v25, s0
	v_lshl_add_u64 v[18:19], v[18:19], 0, v[22:23]
	global_store_short v[18:19], v20, off nt
	v_cvt_pk_bf16_f32 v20, v21, s0
	v_lshl_add_u64 v[18:19], v[18:19], 0, v[28:29]
	global_store_short v[18:19], v20, off nt
	s_and_b64 vcc, exec, s[8:9]
	s_mov_b64 s[82:83], -1
	s_cbranch_vccz .LBB0_600

.LBB0_651:
	s_or_b64 exec, exec, s[82:83]
	v_mov_b32_e32 v19, v4
	v_lshl_add_u64 v[18:19], v[18:19], 1, v[20:21]
	v_cvt_pk_bf16_f32 v14, v14, s0
	v_lshlrev_b32_e32 v20, 3, v22
	v_mov_b32_e32 v21, v4
	global_store_short v[18:19], v14, off nt
	v_cvt_pk_bf16_f32 v10, v10, s0
	v_lshl_add_u64 v[18:19], v[18:19], 0, v[20:21]
	global_store_short v[18:19], v10, off nt
	v_cvt_pk_bf16_f32 v10, v15, s0
	v_mul_hi_i32_i24_e32 v15, -6, v22
	v_mul_i32_i24_e32 v14, -6, v22
	v_lshl_add_u64 v[18:19], v[18:19], 0, v[14:15]
	global_store_short v[18:19], v10, off nt
	v_cvt_pk_bf16_f32 v22, v11, s0
	v_lshl_add_u64 v[10:11], v[18:19], 0, v[20:21]
	global_store_short v[10:11], v22, off nt
	v_cvt_pk_bf16_f32 v16, v16, s0
	v_lshl_add_u64 v[10:11], v[10:11], 0, v[14:15]
	global_store_short v[10:11], v16, off nt
	v_cvt_pk_bf16_f32 v12, v12, s0
	v_lshl_add_u64 v[10:11], v[10:11], 0, v[20:21]
	global_store_short v[10:11], v12, off nt
	v_cvt_pk_bf16_f32 v12, v17, s0
	v_lshl_add_u64 v[10:11], v[10:11], 0, v[14:15]
	global_store_short v[10:11], v12, off nt
	v_cvt_pk_bf16_f32 v12, v13, s0
	v_lshl_add_u64 v[10:11], v[10:11], 0, v[20:21]
	global_store_short v[10:11], v12, off nt
	s_and_b64 vcc, exec, s[8:9]
	s_mov_b64 s[8:9], -1
	s_cbranch_vccz .LBB0_608

.LBB0_657:
	s_or_b64 exec, exec, s[6:7]
	v_mov_b32_e32 v11, v4
	v_lshl_add_u64 v[10:11], v[10:11], 1, v[12:13]
	v_cvt_pk_bf16_f32 v6, v6, s0
	v_lshlrev_b32_e32 v12, 3, v14
	v_mov_b32_e32 v13, v4
	global_store_short v[10:11], v6, off nt
	v_cvt_pk_bf16_f32 v0, v0, s0
	v_lshl_add_u64 v[10:11], v[10:11], 0, v[12:13]
	global_store_short v[10:11], v0, off nt
	v_cvt_pk_bf16_f32 v0, v7, s0
	v_mul_hi_i32_i24_e32 v7, -6, v14
	v_mul_i32_i24_e32 v6, -6, v14
	v_lshl_add_u64 v[10:11], v[10:11], 0, v[6:7]
	global_store_short v[10:11], v0, off nt
	v_cvt_pk_bf16_f32 v14, v1, s0
	v_lshl_add_u64 v[0:1], v[10:11], 0, v[12:13]
	global_store_short v[0:1], v14, off nt
	v_cvt_pk_bf16_f32 v8, v8, s0
	v_lshl_add_u64 v[0:1], v[0:1], 0, v[6:7]
	global_store_short v[0:1], v8, off nt
	v_cvt_pk_bf16_f32 v2, v2, s0
	v_lshl_add_u64 v[0:1], v[0:1], 0, v[12:13]
	global_store_short v[0:1], v2, off nt
	v_cvt_pk_bf16_f32 v2, v9, s0
	v_lshl_add_u64 v[0:1], v[0:1], 0, v[6:7]
	global_store_short v[0:1], v2, off nt
	v_cvt_pk_bf16_f32 v2, v3, s0
	v_lshl_add_u64 v[0:1], v[0:1], 0, v[12:13]
	global_store_short v[0:1], v2, off nt
	s_andn2_b64 vcc, exec, s[4:5]
	s_mov_b64 s[4:5], -1
	s_cbranch_vccnz .LBB0_420

.LBB0_724:
	v_mul_f32_e32 v155, 0xbfb8aa3b, v122
	v_exp_f32_e32 v155, v155
	v_mul_f32_e32 v154, 0xbfb8aa3b, v126
	v_exp_f32_e32 v154, v154
	v_mov_b32_e32 v149, v5
	v_add_f32_e32 v155, 1.0, v155
	v_rcp_f32_e32 v156, v155
	v_mul_f32_e32 v155, 0xbfb8aa3b, v127
	v_exp_f32_e32 v155, v155
	v_add_f32_e32 v154, 1.0, v154
	v_rcp_f32_e32 v154, v154
	v_mov_b32_e32 v148, v139
	v_add_f32_e32 v155, 1.0, v155
	v_rcp_f32_e32 v155, v155
	s_movk_i32 s20, 0x500
	v_lshlrev_b32_e32 v148, 3, v148
	v_pk_mul_f32 v[126:127], v[126:127], v[154:155]
	v_mul_f32_e32 v154, 0xbfb8aa3b, v123
	v_exp_f32_e32 v154, v154
	v_mul_f32_e32 v155, 0xbfb8aa3b, v124
	v_exp_f32_e32 v155, v155
	v_add_u32_e32 v150, s57, v148
	v_add_f32_e32 v154, 1.0, v154
	v_rcp_f32_e32 v157, v154
	v_add_f32_e32 v155, 1.0, v155
	v_mul_f32_e32 v154, 0xbfb8aa3b, v128
	v_exp_f32_e32 v154, v154
	v_pk_mul_f32 v[122:123], v[122:123], v[156:157]
	v_rcp_f32_e32 v156, v155
	v_mul_f32_e32 v155, 0xbfb8aa3b, v129
	v_exp_f32_e32 v155, v155
	v_add_f32_e32 v154, 1.0, v154
	v_rcp_f32_e32 v154, v154
	v_cmp_gt_i32_e32 vcc, s20, v150
	v_add_f32_e32 v155, 1.0, v155
	v_rcp_f32_e32 v155, v155
	s_lshl_b32 s20, s68, 8
	s_add_i32 s20, s20, s45
	v_cndmask_b32_e32 v151, v249, v250, vcc
	v_pk_mul_f32 v[128:129], v[128:129], v[154:155]
	v_mul_f32_e32 v154, 0xbfb8aa3b, v125
	v_exp_f32_e32 v154, v154
	v_add_u32_e32 v149, s20, v149
	v_readlane_b32 s20, v254, 8
	v_add_u32_e32 v150, v151, v150
	v_add_f32_e32 v154, 1.0, v154
	v_rcp_f32_e32 v157, v154
	v_readlane_b32 s21, v254, 9
	v_ashrrev_i32_e32 v151, 31, v150
	v_cvt_pk_bf16_f32 v154, v126, v127
	v_pk_mul_f32 v[124:125], v[124:125], v[156:157]
	v_cvt_pk_bf16_f32 v156, v122, v123
	v_cvt_pk_bf16_f32 v157, v124, v125
	v_mov_b64_e32 v[124:125], s[20:21]
	v_mad_i64_i32 v[122:123], s[20:21], v149, s92, v[124:125]
	v_lshlrev_b64 v[126:127], 1, v[150:151]
	v_cvt_pk_bf16_f32 v155, v128, v129
	v_lshl_add_u64 v[128:129], v[122:123], 0, v[126:127]
	global_store_dwordx4 v[128:129], v[154:157], off nt
	v_mul_f32_e32 v129, 0xbfb8aa3b, v114
	v_exp_f32_e32 v129, v129
	v_mul_f32_e32 v128, 0xbfb8aa3b, v118
	v_exp_f32_e32 v128, v128
	v_add_u32_e32 v154, 16, v149
	v_add_f32_e32 v129, 1.0, v129
	v_rcp_f32_e32 v150, v129
	v_mul_f32_e32 v129, 0xbfb8aa3b, v119
	v_exp_f32_e32 v129, v129
	v_add_f32_e32 v128, 1.0, v128
	v_rcp_f32_e32 v128, v128
	s_andn2_b64 vcc, exec, s[10:11]
	v_add_f32_e32 v129, 1.0, v129
	v_rcp_f32_e32 v129, v129
	s_nop 0
	v_pk_mul_f32 v[118:119], v[118:119], v[128:129]
	v_mul_f32_e32 v128, 0xbfb8aa3b, v115
	v_exp_f32_e32 v128, v128
	v_mul_f32_e32 v129, 0xbfb8aa3b, v116
	v_exp_f32_e32 v129, v129
	v_add_f32_e32 v128, 1.0, v128
	v_rcp_f32_e32 v151, v128
	v_add_f32_e32 v129, 1.0, v129
	v_mul_f32_e32 v128, 0xbfb8aa3b, v120
	v_exp_f32_e32 v128, v128
	v_pk_mul_f32 v[114:115], v[114:115], v[150:151]
	v_rcp_f32_e32 v150, v129
	v_mul_f32_e32 v129, 0xbfb8aa3b, v121
	v_exp_f32_e32 v129, v129
	v_add_f32_e32 v128, 1.0, v128
	v_rcp_f32_e32 v128, v128
	v_add_f32_e32 v129, 1.0, v129
	v_rcp_f32_e32 v129, v129
	s_nop 0
	v_pk_mul_f32 v[120:121], v[120:121], v[128:129]
	v_mul_f32_e32 v128, 0xbfb8aa3b, v117
	v_exp_f32_e32 v128, v128
	s_nop 0
	v_add_f32_e32 v128, 1.0, v128
	v_rcp_f32_e32 v151, v128
	s_nop 0
	v_pk_mul_f32 v[128:129], v[116:117], v[150:151]
	v_cvt_pk_bf16_f32 v116, v118, v119
	v_cvt_pk_bf16_f32 v118, v114, v115
	v_mad_i64_i32 v[114:115], s[20:21], v154, s92, v[124:125]
	v_cvt_pk_bf16_f32 v117, v120, v121
	v_cvt_pk_bf16_f32 v119, v128, v129
	v_lshl_add_u64 v[120:121], v[114:115], 0, v[126:127]
	global_store_dwordx4 v[120:121], v[116:119], off nt
	v_add_u32_e32 v120, 32, v149
	s_nop 0
	v_mul_f32_e32 v117, 0xbfb8aa3b, v106
	v_exp_f32_e32 v117, v117
	v_mul_f32_e32 v116, 0xbfb8aa3b, v110
	v_exp_f32_e32 v116, v116
	v_add_f32_e32 v117, 1.0, v117
	v_rcp_f32_e32 v118, v117
	v_mul_f32_e32 v117, 0xbfb8aa3b, v111
	v_exp_f32_e32 v117, v117
	v_add_f32_e32 v116, 1.0, v116
	v_rcp_f32_e32 v116, v116
	v_add_f32_e32 v117, 1.0, v117
	v_rcp_f32_e32 v117, v117
	s_nop 0
	v_pk_mul_f32 v[110:111], v[110:111], v[116:117]
	v_mul_f32_e32 v116, 0xbfb8aa3b, v107
	v_exp_f32_e32 v116, v116
	v_mul_f32_e32 v117, 0xbfb8aa3b, v108
	v_exp_f32_e32 v117, v117
	v_add_f32_e32 v116, 1.0, v116
	v_rcp_f32_e32 v119, v116
	v_add_f32_e32 v117, 1.0, v117
	v_mul_f32_e32 v116, 0xbfb8aa3b, v112
	v_exp_f32_e32 v116, v116
	v_pk_mul_f32 v[106:107], v[106:107], v[118:119]
	v_rcp_f32_e32 v118, v117
	v_mul_f32_e32 v117, 0xbfb8aa3b, v113
	v_exp_f32_e32 v117, v117
	v_add_f32_e32 v116, 1.0, v116
	v_rcp_f32_e32 v116, v116
	v_add_f32_e32 v117, 1.0, v117
	v_rcp_f32_e32 v117, v117
	s_nop 0
	v_pk_mul_f32 v[112:113], v[112:113], v[116:117]
	v_mul_f32_e32 v116, 0xbfb8aa3b, v109
	v_exp_f32_e32 v116, v116
	s_nop 0
	v_add_f32_e32 v116, 1.0, v116
	v_rcp_f32_e32 v119, v116
	s_nop 0
	v_pk_mul_f32 v[116:117], v[108:109], v[118:119]
	v_cvt_pk_bf16_f32 v108, v110, v111
	v_cvt_pk_bf16_f32 v110, v106, v107
	v_mad_i64_i32 v[106:107], s[20:21], v120, s92, v[124:125]
	v_cvt_pk_bf16_f32 v109, v112, v113
	v_cvt_pk_bf16_f32 v111, v116, v117
	v_lshl_add_u64 v[112:113], v[106:107], 0, v[126:127]
	global_store_dwordx4 v[112:113], v[108:111], off nt
	v_add_u32_e32 v112, 48, v149
	s_nop 0
	v_mul_f32_e32 v109, 0xbfb8aa3b, v98
	v_exp_f32_e32 v109, v109
	v_mul_f32_e32 v108, 0xbfb8aa3b, v102
	v_exp_f32_e32 v108, v108
	v_add_f32_e32 v109, 1.0, v109
	v_rcp_f32_e32 v110, v109
	v_mul_f32_e32 v109, 0xbfb8aa3b, v103
	v_exp_f32_e32 v109, v109
	v_add_f32_e32 v108, 1.0, v108
	v_rcp_f32_e32 v108, v108
	v_add_f32_e32 v109, 1.0, v109
	v_rcp_f32_e32 v109, v109
	s_nop 0
	v_pk_mul_f32 v[102:103], v[102:103], v[108:109]
	v_mul_f32_e32 v108, 0xbfb8aa3b, v99
	v_exp_f32_e32 v108, v108
	v_mul_f32_e32 v109, 0xbfb8aa3b, v100
	v_exp_f32_e32 v109, v109
	v_add_f32_e32 v108, 1.0, v108
	v_rcp_f32_e32 v111, v108
	v_add_f32_e32 v109, 1.0, v109
	v_mul_f32_e32 v108, 0xbfb8aa3b, v104
	v_exp_f32_e32 v108, v108
	v_pk_mul_f32 v[98:99], v[98:99], v[110:111]
	v_rcp_f32_e32 v110, v109
	v_mul_f32_e32 v109, 0xbfb8aa3b, v105
	v_exp_f32_e32 v109, v109
	v_add_f32_e32 v108, 1.0, v108
	v_rcp_f32_e32 v108, v108
	v_add_f32_e32 v109, 1.0, v109
	v_rcp_f32_e32 v109, v109
	s_nop 0
	v_pk_mul_f32 v[104:105], v[104:105], v[108:109]
	v_mul_f32_e32 v108, 0xbfb8aa3b, v101
	v_exp_f32_e32 v108, v108
	s_nop 0
	v_add_f32_e32 v108, 1.0, v108
	v_rcp_f32_e32 v111, v108
	s_nop 0
	v_pk_mul_f32 v[108:109], v[100:101], v[110:111]
	v_cvt_pk_bf16_f32 v100, v102, v103
	v_cvt_pk_bf16_f32 v102, v98, v99
	v_mad_i64_i32 v[98:99], s[20:21], v112, s92, v[124:125]
	v_cvt_pk_bf16_f32 v101, v104, v105
	v_cvt_pk_bf16_f32 v103, v108, v109
	v_lshl_add_u64 v[104:105], v[98:99], 0, v[126:127]
	global_store_dwordx4 v[104:105], v[100:103], off nt
	v_add_u32_e32 v104, 0x80, v149
	s_nop 0
	v_mul_f32_e32 v101, 0xbfb8aa3b, v90
	v_exp_f32_e32 v101, v101
	v_mul_f32_e32 v100, 0xbfb8aa3b, v94
	v_exp_f32_e32 v100, v100
	v_add_f32_e32 v101, 1.0, v101
	v_rcp_f32_e32 v102, v101
	v_mul_f32_e32 v101, 0xbfb8aa3b, v95
	v_exp_f32_e32 v101, v101
	v_add_f32_e32 v100, 1.0, v100
	v_rcp_f32_e32 v100, v100
	v_add_f32_e32 v101, 1.0, v101
	v_rcp_f32_e32 v101, v101
	s_nop 0
	v_pk_mul_f32 v[94:95], v[94:95], v[100:101]
	v_mul_f32_e32 v100, 0xbfb8aa3b, v91
	v_exp_f32_e32 v100, v100
	v_mul_f32_e32 v101, 0xbfb8aa3b, v92
	v_exp_f32_e32 v101, v101
	v_add_f32_e32 v100, 1.0, v100
	v_rcp_f32_e32 v103, v100
	v_add_f32_e32 v101, 1.0, v101
	v_mul_f32_e32 v100, 0xbfb8aa3b, v96
	v_exp_f32_e32 v100, v100
	v_pk_mul_f32 v[90:91], v[90:91], v[102:103]
	v_rcp_f32_e32 v102, v101
	v_mul_f32_e32 v101, 0xbfb8aa3b, v97
	v_exp_f32_e32 v101, v101
	v_add_f32_e32 v100, 1.0, v100
	v_rcp_f32_e32 v100, v100
	v_add_f32_e32 v101, 1.0, v101
	v_rcp_f32_e32 v101, v101
	s_nop 0
	v_pk_mul_f32 v[96:97], v[96:97], v[100:101]
	v_mul_f32_e32 v100, 0xbfb8aa3b, v93
	v_exp_f32_e32 v100, v100
	s_nop 0
	v_add_f32_e32 v100, 1.0, v100
	v_rcp_f32_e32 v103, v100
	s_nop 0
	v_pk_mul_f32 v[100:101], v[92:93], v[102:103]
	v_cvt_pk_bf16_f32 v92, v94, v95
	v_cvt_pk_bf16_f32 v94, v90, v91
	v_mad_i64_i32 v[90:91], s[20:21], v104, s92, v[124:125]
	v_cvt_pk_bf16_f32 v93, v96, v97
	v_cvt_pk_bf16_f32 v95, v100, v101
	v_lshl_add_u64 v[96:97], v[90:91], 0, v[126:127]
	global_store_dwordx4 v[96:97], v[92:95], off nt
	v_add_u32_e32 v96, 0x90, v149
	s_nop 0
	v_mul_f32_e32 v93, 0xbfb8aa3b, v82
	v_exp_f32_e32 v93, v93
	v_mul_f32_e32 v92, 0xbfb8aa3b, v86
	v_exp_f32_e32 v92, v92
	v_add_f32_e32 v93, 1.0, v93
	v_rcp_f32_e32 v94, v93
	v_mul_f32_e32 v93, 0xbfb8aa3b, v87
	v_exp_f32_e32 v93, v93
	v_add_f32_e32 v92, 1.0, v92
	v_rcp_f32_e32 v92, v92
	v_add_f32_e32 v93, 1.0, v93
	v_rcp_f32_e32 v93, v93
	s_nop 0
	v_pk_mul_f32 v[86:87], v[86:87], v[92:93]
	v_mul_f32_e32 v92, 0xbfb8aa3b, v83
	v_exp_f32_e32 v92, v92
	v_mul_f32_e32 v93, 0xbfb8aa3b, v84
	v_exp_f32_e32 v93, v93
	v_add_f32_e32 v92, 1.0, v92
	v_rcp_f32_e32 v95, v92
	v_add_f32_e32 v93, 1.0, v93
	v_mul_f32_e32 v92, 0xbfb8aa3b, v88
	v_exp_f32_e32 v92, v92
	v_pk_mul_f32 v[82:83], v[82:83], v[94:95]
	v_rcp_f32_e32 v94, v93
	v_mul_f32_e32 v93, 0xbfb8aa3b, v89
	v_exp_f32_e32 v93, v93
	v_add_f32_e32 v92, 1.0, v92
	v_rcp_f32_e32 v92, v92
	v_add_f32_e32 v93, 1.0, v93
	v_rcp_f32_e32 v93, v93
	s_nop 0
	v_pk_mul_f32 v[88:89], v[88:89], v[92:93]
	v_mul_f32_e32 v92, 0xbfb8aa3b, v85
	v_exp_f32_e32 v92, v92
	s_nop 0
	v_add_f32_e32 v92, 1.0, v92
	v_rcp_f32_e32 v95, v92
	s_nop 0
	v_pk_mul_f32 v[92:93], v[84:85], v[94:95]
	v_cvt_pk_bf16_f32 v84, v86, v87
	v_cvt_pk_bf16_f32 v86, v82, v83
	v_mad_i64_i32 v[82:83], s[20:21], v96, s92, v[124:125]
	v_cvt_pk_bf16_f32 v85, v88, v89
	v_cvt_pk_bf16_f32 v87, v92, v93
	v_lshl_add_u64 v[88:89], v[82:83], 0, v[126:127]
	global_store_dwordx4 v[88:89], v[84:87], off nt
	v_add_u32_e32 v88, 0xa0, v149
	s_nop 0
	v_mul_f32_e32 v85, 0xbfb8aa3b, v74
	v_exp_f32_e32 v85, v85
	v_mul_f32_e32 v84, 0xbfb8aa3b, v78
	v_exp_f32_e32 v84, v84
	v_add_f32_e32 v85, 1.0, v85
	v_rcp_f32_e32 v86, v85
	v_mul_f32_e32 v85, 0xbfb8aa3b, v79
	v_exp_f32_e32 v85, v85
	v_add_f32_e32 v84, 1.0, v84
	v_rcp_f32_e32 v84, v84
	v_add_f32_e32 v85, 1.0, v85
	v_rcp_f32_e32 v85, v85
	s_nop 0
	v_pk_mul_f32 v[78:79], v[78:79], v[84:85]
	v_mul_f32_e32 v84, 0xbfb8aa3b, v75
	v_exp_f32_e32 v84, v84
	v_mul_f32_e32 v85, 0xbfb8aa3b, v76
	v_exp_f32_e32 v85, v85
	v_add_f32_e32 v84, 1.0, v84
	v_rcp_f32_e32 v87, v84
	v_add_f32_e32 v85, 1.0, v85
	v_mul_f32_e32 v84, 0xbfb8aa3b, v80
	v_exp_f32_e32 v84, v84
	v_pk_mul_f32 v[74:75], v[74:75], v[86:87]
	v_rcp_f32_e32 v86, v85
	v_mul_f32_e32 v85, 0xbfb8aa3b, v81
	v_exp_f32_e32 v85, v85
	v_add_f32_e32 v84, 1.0, v84
	v_rcp_f32_e32 v84, v84
	v_add_f32_e32 v85, 1.0, v85
	v_rcp_f32_e32 v85, v85
	s_nop 0
	v_pk_mul_f32 v[80:81], v[80:81], v[84:85]
	v_mul_f32_e32 v84, 0xbfb8aa3b, v77
	v_exp_f32_e32 v84, v84
	s_nop 0
	v_add_f32_e32 v84, 1.0, v84
	v_rcp_f32_e32 v87, v84
	s_nop 0
	v_pk_mul_f32 v[84:85], v[76:77], v[86:87]
	v_cvt_pk_bf16_f32 v76, v78, v79
	v_cvt_pk_bf16_f32 v78, v74, v75
	v_mad_i64_i32 v[74:75], s[20:21], v88, s92, v[124:125]
	v_cvt_pk_bf16_f32 v77, v80, v81
	v_cvt_pk_bf16_f32 v79, v84, v85
	v_lshl_add_u64 v[80:81], v[74:75], 0, v[126:127]
	global_store_dwordx4 v[80:81], v[76:79], off nt
	v_add_u32_e32 v80, 0xb0, v149
	s_nop 0
	v_mul_f32_e32 v77, 0xbfb8aa3b, v66
	v_exp_f32_e32 v77, v77
	v_mul_f32_e32 v76, 0xbfb8aa3b, v70
	v_exp_f32_e32 v76, v76
	v_add_f32_e32 v77, 1.0, v77
	v_rcp_f32_e32 v78, v77
	v_mul_f32_e32 v77, 0xbfb8aa3b, v71
	v_exp_f32_e32 v77, v77
	v_add_f32_e32 v76, 1.0, v76
	v_rcp_f32_e32 v76, v76
	v_add_f32_e32 v77, 1.0, v77
	v_rcp_f32_e32 v77, v77
	s_nop 0
	v_pk_mul_f32 v[70:71], v[70:71], v[76:77]
	v_mul_f32_e32 v76, 0xbfb8aa3b, v67
	v_exp_f32_e32 v76, v76
	v_mul_f32_e32 v77, 0xbfb8aa3b, v68
	v_exp_f32_e32 v77, v77
	v_add_f32_e32 v76, 1.0, v76
	v_rcp_f32_e32 v79, v76
	v_add_f32_e32 v77, 1.0, v77
	v_mul_f32_e32 v76, 0xbfb8aa3b, v72
	v_exp_f32_e32 v76, v76
	v_pk_mul_f32 v[66:67], v[66:67], v[78:79]
	v_rcp_f32_e32 v78, v77
	v_mul_f32_e32 v77, 0xbfb8aa3b, v73
	v_exp_f32_e32 v77, v77
	v_add_f32_e32 v76, 1.0, v76
	v_rcp_f32_e32 v76, v76
	v_add_f32_e32 v77, 1.0, v77
	v_rcp_f32_e32 v77, v77
	s_nop 0
	v_pk_mul_f32 v[72:73], v[72:73], v[76:77]
	v_mul_f32_e32 v76, 0xbfb8aa3b, v69
	v_exp_f32_e32 v76, v76
	s_nop 0
	v_add_f32_e32 v76, 1.0, v76
	v_rcp_f32_e32 v79, v76
	s_nop 0
	v_pk_mul_f32 v[76:77], v[68:69], v[78:79]
	v_cvt_pk_bf16_f32 v68, v70, v71
	v_cvt_pk_bf16_f32 v70, v66, v67
	v_mad_i64_i32 v[66:67], s[20:21], v80, s92, v[124:125]
	v_cvt_pk_bf16_f32 v69, v72, v73
	v_cvt_pk_bf16_f32 v71, v76, v77
	v_lshl_add_u64 v[72:73], v[66:67], 0, v[126:127]
	global_store_dwordx4 v[72:73], v[68:71], off nt
	s_cbranch_vccnz .LBB0_726
	s_nop 0
	v_mul_f32_e32 v71, 0xbfb8aa3b, v58
	v_exp_f32_e32 v71, v71
	v_mul_f32_e32 v70, 0xbfb8aa3b, v62
	v_exp_f32_e32 v70, v70
	v_add_u32_e32 v68, s60, v148
	v_add_f32_e32 v71, 1.0, v71
	v_rcp_f32_e32 v72, v71
	v_mul_f32_e32 v71, 0xbfb8aa3b, v63
	v_exp_f32_e32 v71, v71
	v_add_f32_e32 v70, 1.0, v70
	v_rcp_f32_e32 v70, v70
	s_movk_i32 s20, 0x500
	v_add_f32_e32 v71, 1.0, v71
	v_rcp_f32_e32 v71, v71
	v_cmp_gt_i32_e32 vcc, s20, v68
	v_pk_mul_f32 v[62:63], v[62:63], v[70:71]
	v_mul_f32_e32 v70, 0xbfb8aa3b, v59
	v_exp_f32_e32 v70, v70
	v_mul_f32_e32 v71, 0xbfb8aa3b, v60
	v_exp_f32_e32 v71, v71
	v_cndmask_b32_e32 v69, v249, v250, vcc
	v_add_f32_e32 v70, 1.0, v70
	v_rcp_f32_e32 v73, v70
	v_add_f32_e32 v71, 1.0, v71
	v_mul_f32_e32 v70, 0xbfb8aa3b, v64
	v_exp_f32_e32 v70, v70
	v_pk_mul_f32 v[58:59], v[58:59], v[72:73]
	v_rcp_f32_e32 v72, v71
	v_mul_f32_e32 v71, 0xbfb8aa3b, v65
	v_exp_f32_e32 v71, v71
	v_add_f32_e32 v70, 1.0, v70
	v_rcp_f32_e32 v70, v70
	v_add_u32_e32 v68, v69, v68
	v_add_f32_e32 v71, 1.0, v71
	v_rcp_f32_e32 v71, v71
	v_ashrrev_i32_e32 v69, 31, v68
	v_pk_mul_f32 v[64:65], v[64:65], v[70:71]
	v_mul_f32_e32 v70, 0xbfb8aa3b, v61
	v_exp_f32_e32 v70, v70
	s_nop 0
	v_add_f32_e32 v70, 1.0, v70
	v_rcp_f32_e32 v73, v70
	s_nop 0
	v_pk_mul_f32 v[70:71], v[60:61], v[72:73]
	v_cvt_pk_bf16_f32 v60, v62, v63
	v_cvt_pk_bf16_f32 v62, v58, v59
	v_lshlrev_b64 v[58:59], 1, v[68:69]
	v_cvt_pk_bf16_f32 v61, v64, v65
	v_cvt_pk_bf16_f32 v63, v70, v71
	v_lshl_add_u64 v[64:65], v[122:123], 0, v[58:59]
	global_store_dwordx4 v[64:65], v[60:63], off nt
	s_nop 1
	v_mul_f32_e32 v61, 0xbfb8aa3b, v50
	v_exp_f32_e32 v61, v61
	v_mul_f32_e32 v60, 0xbfb8aa3b, v54
	v_exp_f32_e32 v60, v60
	v_add_f32_e32 v61, 1.0, v61
	v_rcp_f32_e32 v62, v61
	v_mul_f32_e32 v61, 0xbfb8aa3b, v55
	v_exp_f32_e32 v61, v61
	v_add_f32_e32 v60, 1.0, v60
	v_rcp_f32_e32 v60, v60
	v_add_f32_e32 v61, 1.0, v61
	v_rcp_f32_e32 v61, v61
	s_nop 0
	v_pk_mul_f32 v[54:55], v[54:55], v[60:61]
	v_mul_f32_e32 v60, 0xbfb8aa3b, v51
	v_exp_f32_e32 v60, v60
	s_nop 0
	v_add_f32_e32 v60, 1.0, v60
	v_rcp_f32_e32 v63, v60
	s_nop 0
	v_pk_mul_f32 v[60:61], v[50:51], v[62:63]
	v_mul_f32_e32 v51, 0xbfb8aa3b, v52
	v_exp_f32_e32 v51, v51
	v_mul_f32_e32 v50, 0xbfb8aa3b, v56
	v_exp_f32_e32 v50, v50
	v_add_f32_e32 v51, 1.0, v51
	v_rcp_f32_e32 v62, v51
	v_mul_f32_e32 v51, 0xbfb8aa3b, v57
	v_exp_f32_e32 v51, v51
	v_add_f32_e32 v50, 1.0, v50
	v_rcp_f32_e32 v50, v50
	v_add_f32_e32 v51, 1.0, v51
	v_rcp_f32_e32 v51, v51
	s_nop 0
	v_pk_mul_f32 v[56:57], v[56:57], v[50:51]
	v_mul_f32_e32 v50, 0xbfb8aa3b, v53
	v_exp_f32_e32 v50, v50
	v_cvt_pk_bf16_f32 v51, v56, v57
	v_add_f32_e32 v50, 1.0, v50
	v_rcp_f32_e32 v63, v50
	v_cvt_pk_bf16_f32 v50, v54, v55
	v_lshl_add_u64 v[54:55], v[114:115], 0, v[58:59]
	v_pk_mul_f32 v[62:63], v[52:53], v[62:63]
	v_cvt_pk_bf16_f32 v52, v60, v61
	v_cvt_pk_bf16_f32 v53, v62, v63
	global_store_dwordx4 v[54:55], v[50:53], off nt
	s_nop 1
	v_mul_f32_e32 v51, 0xbfb8aa3b, v42
	v_exp_f32_e32 v51, v51
	v_mul_f32_e32 v50, 0xbfb8aa3b, v46
	v_exp_f32_e32 v50, v50
	v_add_f32_e32 v51, 1.0, v51
	v_rcp_f32_e32 v52, v51
	v_mul_f32_e32 v51, 0xbfb8aa3b, v47
	v_exp_f32_e32 v51, v51
	v_add_f32_e32 v50, 1.0, v50
	v_rcp_f32_e32 v50, v50
	v_add_f32_e32 v51, 1.0, v51
	v_rcp_f32_e32 v51, v51
	s_nop 0
	v_pk_mul_f32 v[46:47], v[46:47], v[50:51]
	v_mul_f32_e32 v50, 0xbfb8aa3b, v43
	v_exp_f32_e32 v50, v50
	s_nop 0
	v_add_f32_e32 v50, 1.0, v50
	v_rcp_f32_e32 v53, v50
	s_nop 0
	v_pk_mul_f32 v[50:51], v[42:43], v[52:53]
	v_mul_f32_e32 v43, 0xbfb8aa3b, v44
	v_exp_f32_e32 v43, v43
	v_mul_f32_e32 v42, 0xbfb8aa3b, v48
	v_exp_f32_e32 v42, v42
	v_add_f32_e32 v43, 1.0, v43
	v_rcp_f32_e32 v52, v43
	v_mul_f32_e32 v43, 0xbfb8aa3b, v49
	v_exp_f32_e32 v43, v43
	v_add_f32_e32 v42, 1.0, v42
	v_rcp_f32_e32 v42, v42
	v_add_f32_e32 v43, 1.0, v43
	v_rcp_f32_e32 v43, v43
	s_nop 0
	v_pk_mul_f32 v[48:49], v[48:49], v[42:43]
	v_mul_f32_e32 v42, 0xbfb8aa3b, v45
	v_exp_f32_e32 v42, v42
	v_cvt_pk_bf16_f32 v43, v48, v49
	v_add_f32_e32 v42, 1.0, v42
	v_rcp_f32_e32 v53, v42
	v_cvt_pk_bf16_f32 v42, v46, v47
	v_lshl_add_u64 v[46:47], v[106:107], 0, v[58:59]
	v_pk_mul_f32 v[52:53], v[44:45], v[52:53]
	v_cvt_pk_bf16_f32 v44, v50, v51
	v_cvt_pk_bf16_f32 v45, v52, v53
	global_store_dwordx4 v[46:47], v[42:45], off nt
	s_nop 1
	v_mul_f32_e32 v43, 0xbfb8aa3b, v34
	v_exp_f32_e32 v43, v43
	v_mul_f32_e32 v42, 0xbfb8aa3b, v38
	v_exp_f32_e32 v42, v42
	v_add_f32_e32 v43, 1.0, v43
	v_rcp_f32_e32 v44, v43
	v_mul_f32_e32 v43, 0xbfb8aa3b, v39
	v_exp_f32_e32 v43, v43
	v_add_f32_e32 v42, 1.0, v42
	v_rcp_f32_e32 v42, v42
	v_add_f32_e32 v43, 1.0, v43
	v_rcp_f32_e32 v43, v43
	s_nop 0
	v_pk_mul_f32 v[38:39], v[38:39], v[42:43]
	v_mul_f32_e32 v42, 0xbfb8aa3b, v35
	v_exp_f32_e32 v42, v42
	s_nop 0
	v_add_f32_e32 v42, 1.0, v42
	v_rcp_f32_e32 v45, v42
	s_nop 0
	v_pk_mul_f32 v[42:43], v[34:35], v[44:45]
	v_mul_f32_e32 v35, 0xbfb8aa3b, v36
	v_exp_f32_e32 v35, v35
	v_mul_f32_e32 v34, 0xbfb8aa3b, v40
	v_exp_f32_e32 v34, v34
	v_add_f32_e32 v35, 1.0, v35
	v_rcp_f32_e32 v44, v35
	v_mul_f32_e32 v35, 0xbfb8aa3b, v41
	v_exp_f32_e32 v35, v35
	v_add_f32_e32 v34, 1.0, v34
	v_rcp_f32_e32 v34, v34
	v_add_f32_e32 v35, 1.0, v35
	v_rcp_f32_e32 v35, v35
	s_nop 0
	v_pk_mul_f32 v[40:41], v[40:41], v[34:35]
	v_mul_f32_e32 v34, 0xbfb8aa3b, v37
	v_exp_f32_e32 v34, v34
	v_cvt_pk_bf16_f32 v35, v40, v41
	v_add_f32_e32 v34, 1.0, v34
	v_rcp_f32_e32 v45, v34
	v_cvt_pk_bf16_f32 v34, v38, v39
	v_lshl_add_u64 v[38:39], v[98:99], 0, v[58:59]
	v_pk_mul_f32 v[44:45], v[36:37], v[44:45]
	v_cvt_pk_bf16_f32 v36, v42, v43
	v_cvt_pk_bf16_f32 v37, v44, v45
	global_store_dwordx4 v[38:39], v[34:37], off nt
	s_nop 1
	v_mul_f32_e32 v35, 0xbfb8aa3b, v26
	v_exp_f32_e32 v35, v35
	v_mul_f32_e32 v34, 0xbfb8aa3b, v30
	v_exp_f32_e32 v34, v34
	v_add_f32_e32 v35, 1.0, v35
	v_rcp_f32_e32 v36, v35
	v_mul_f32_e32 v35, 0xbfb8aa3b, v31
	v_exp_f32_e32 v35, v35
	v_add_f32_e32 v34, 1.0, v34
	v_rcp_f32_e32 v34, v34
	v_add_f32_e32 v35, 1.0, v35
	v_rcp_f32_e32 v35, v35
	s_nop 0
	v_pk_mul_f32 v[30:31], v[30:31], v[34:35]
	v_mul_f32_e32 v34, 0xbfb8aa3b, v27
	v_exp_f32_e32 v34, v34
	s_nop 0
	v_add_f32_e32 v34, 1.0, v34
	v_rcp_f32_e32 v37, v34
	s_nop 0
	v_pk_mul_f32 v[34:35], v[26:27], v[36:37]
	v_mul_f32_e32 v27, 0xbfb8aa3b, v28
	v_exp_f32_e32 v27, v27
	v_mul_f32_e32 v26, 0xbfb8aa3b, v32
	v_exp_f32_e32 v26, v26
	v_add_f32_e32 v27, 1.0, v27
	v_rcp_f32_e32 v36, v27
	v_mul_f32_e32 v27, 0xbfb8aa3b, v33
	v_exp_f32_e32 v27, v27
	v_add_f32_e32 v26, 1.0, v26
	v_rcp_f32_e32 v26, v26
	v_add_f32_e32 v27, 1.0, v27
	v_rcp_f32_e32 v27, v27
	s_nop 0
	v_pk_mul_f32 v[32:33], v[32:33], v[26:27]
	v_mul_f32_e32 v26, 0xbfb8aa3b, v29
	v_exp_f32_e32 v26, v26
	v_cvt_pk_bf16_f32 v27, v32, v33
	v_add_f32_e32 v26, 1.0, v26
	v_rcp_f32_e32 v37, v26
	v_cvt_pk_bf16_f32 v26, v30, v31
	v_lshl_add_u64 v[30:31], v[90:91], 0, v[58:59]
	v_pk_mul_f32 v[36:37], v[28:29], v[36:37]
	v_cvt_pk_bf16_f32 v28, v34, v35
	v_cvt_pk_bf16_f32 v29, v36, v37
	global_store_dwordx4 v[30:31], v[26:29], off nt
	s_nop 1
	v_mul_f32_e32 v27, 0xbfb8aa3b, v18
	v_exp_f32_e32 v27, v27
	v_mul_f32_e32 v26, 0xbfb8aa3b, v22
	v_exp_f32_e32 v26, v26
	v_add_f32_e32 v27, 1.0, v27
	v_rcp_f32_e32 v28, v27
	v_mul_f32_e32 v27, 0xbfb8aa3b, v23
	v_exp_f32_e32 v27, v27
	v_add_f32_e32 v26, 1.0, v26
	v_rcp_f32_e32 v26, v26
	v_add_f32_e32 v27, 1.0, v27
	v_rcp_f32_e32 v27, v27
	s_nop 0
	v_pk_mul_f32 v[22:23], v[22:23], v[26:27]
	v_mul_f32_e32 v26, 0xbfb8aa3b, v19
	v_exp_f32_e32 v26, v26
	s_nop 0
	v_add_f32_e32 v26, 1.0, v26
	v_rcp_f32_e32 v29, v26
	s_nop 0
	v_pk_mul_f32 v[26:27], v[18:19], v[28:29]
	v_mul_f32_e32 v19, 0xbfb8aa3b, v20
	v_exp_f32_e32 v19, v19
	v_mul_f32_e32 v18, 0xbfb8aa3b, v24
	v_exp_f32_e32 v18, v18
	v_add_f32_e32 v19, 1.0, v19
	v_rcp_f32_e32 v28, v19
	v_mul_f32_e32 v19, 0xbfb8aa3b, v25
	v_exp_f32_e32 v19, v19
	v_add_f32_e32 v18, 1.0, v18
	v_rcp_f32_e32 v18, v18
	v_add_f32_e32 v19, 1.0, v19
	v_rcp_f32_e32 v19, v19
	s_nop 0
	v_pk_mul_f32 v[24:25], v[24:25], v[18:19]
	v_mul_f32_e32 v18, 0xbfb8aa3b, v21
	v_exp_f32_e32 v18, v18
	v_cvt_pk_bf16_f32 v19, v24, v25
	v_add_f32_e32 v18, 1.0, v18
	v_rcp_f32_e32 v29, v18
	v_cvt_pk_bf16_f32 v18, v22, v23
	v_lshl_add_u64 v[22:23], v[82:83], 0, v[58:59]
	v_pk_mul_f32 v[28:29], v[20:21], v[28:29]
	v_cvt_pk_bf16_f32 v20, v26, v27
	v_cvt_pk_bf16_f32 v21, v28, v29
	global_store_dwordx4 v[22:23], v[18:21], off nt
	s_nop 1
	v_mul_f32_e32 v19, 0xbfb8aa3b, v10
	v_exp_f32_e32 v19, v19
	v_mul_f32_e32 v18, 0xbfb8aa3b, v14
	v_exp_f32_e32 v18, v18
	v_add_f32_e32 v19, 1.0, v19
	v_rcp_f32_e32 v20, v19
	v_mul_f32_e32 v19, 0xbfb8aa3b, v15
	v_exp_f32_e32 v19, v19
	v_add_f32_e32 v18, 1.0, v18
	v_rcp_f32_e32 v18, v18
	v_add_f32_e32 v19, 1.0, v19
	v_rcp_f32_e32 v19, v19
	s_nop 0
	v_pk_mul_f32 v[14:15], v[14:15], v[18:19]
	v_mul_f32_e32 v18, 0xbfb8aa3b, v11
	v_exp_f32_e32 v18, v18
	s_nop 0
	v_add_f32_e32 v18, 1.0, v18
	v_rcp_f32_e32 v21, v18
	s_nop 0
	v_pk_mul_f32 v[18:19], v[10:11], v[20:21]
	v_mul_f32_e32 v11, 0xbfb8aa3b, v12
	v_exp_f32_e32 v11, v11
	v_mul_f32_e32 v10, 0xbfb8aa3b, v16
	v_exp_f32_e32 v10, v10
	v_add_f32_e32 v11, 1.0, v11
	v_rcp_f32_e32 v20, v11
	v_mul_f32_e32 v11, 0xbfb8aa3b, v17
	v_exp_f32_e32 v11, v11
	v_add_f32_e32 v10, 1.0, v10
	v_rcp_f32_e32 v10, v10
	v_add_f32_e32 v11, 1.0, v11
	v_rcp_f32_e32 v11, v11
	s_nop 0
	v_pk_mul_f32 v[16:17], v[16:17], v[10:11]
	v_mul_f32_e32 v10, 0xbfb8aa3b, v13
	v_exp_f32_e32 v10, v10
	v_cvt_pk_bf16_f32 v11, v16, v17
	v_add_f32_e32 v10, 1.0, v10
	v_rcp_f32_e32 v21, v10
	v_cvt_pk_bf16_f32 v10, v14, v15
	v_lshl_add_u64 v[14:15], v[74:75], 0, v[58:59]
	v_pk_mul_f32 v[20:21], v[12:13], v[20:21]
	v_cvt_pk_bf16_f32 v12, v18, v19
	v_cvt_pk_bf16_f32 v13, v20, v21
	global_store_dwordx4 v[14:15], v[10:13], off nt
	s_nop 1
	v_mul_f32_e32 v11, 0xbfb8aa3b, v0
	v_exp_f32_e32 v11, v11
	v_mul_f32_e32 v10, 0xbfb8aa3b, v6
	v_exp_f32_e32 v10, v10
	v_add_f32_e32 v11, 1.0, v11
	v_rcp_f32_e32 v12, v11
	v_mul_f32_e32 v11, 0xbfb8aa3b, v7
	v_exp_f32_e32 v11, v11
	v_add_f32_e32 v10, 1.0, v10
	v_rcp_f32_e32 v10, v10
	v_add_f32_e32 v11, 1.0, v11
	v_rcp_f32_e32 v11, v11
	s_nop 0
	v_pk_mul_f32 v[6:7], v[6:7], v[10:11]
	v_mul_f32_e32 v10, 0xbfb8aa3b, v1
	v_exp_f32_e32 v10, v10
	s_nop 0
	v_add_f32_e32 v10, 1.0, v10
	v_rcp_f32_e32 v13, v10
	s_nop 0
	v_pk_mul_f32 v[10:11], v[0:1], v[12:13]
	v_mul_f32_e32 v1, 0xbfb8aa3b, v2
	v_exp_f32_e32 v1, v1
	v_mul_f32_e32 v0, 0xbfb8aa3b, v8
	v_exp_f32_e32 v0, v0
	v_add_f32_e32 v1, 1.0, v1
	v_rcp_f32_e32 v12, v1
	v_mul_f32_e32 v1, 0xbfb8aa3b, v9
	v_exp_f32_e32 v1, v1
	v_add_f32_e32 v0, 1.0, v0
	v_rcp_f32_e32 v0, v0
	v_add_f32_e32 v1, 1.0, v1
	v_rcp_f32_e32 v1, v1
	s_nop 0
	v_pk_mul_f32 v[8:9], v[8:9], v[0:1]
	v_mul_f32_e32 v0, 0xbfb8aa3b, v3
	v_exp_f32_e32 v0, v0
	v_cvt_pk_bf16_f32 v1, v8, v9
	v_add_f32_e32 v0, 1.0, v0
	v_rcp_f32_e32 v13, v0
	v_cvt_pk_bf16_f32 v0, v6, v7
	v_lshl_add_u64 v[6:7], v[66:67], 0, v[58:59]
	v_pk_mul_f32 v[12:13], v[2:3], v[12:13]
	v_cvt_pk_bf16_f32 v2, v10, v11
	v_cvt_pk_bf16_f32 v3, v12, v13
	global_store_dwordx4 v[6:7], v[0:3], off nt
	s_andn2_b64 vcc, exec, s[14:15]
	s_mov_b64 s[14:15], -1
	s_cbranch_vccnz .LBB0_718
	s_branch .LBB0_727

.LBB0_774:
	s_or_b64 exec, exec, s[0:1]
	global_load_dwordx4 v[16:19], v[30:31], off
	global_load_dwordx2 v[66:67], v[32:33], off
	s_mov_b64 s[70:71], 0
	s_and_saveexec_b64 s[0:1], s[14:15]
	s_xor_b64 s[0:1], exec, s[0:1]
	s_cbranch_execz .LBB0_800
	v_mov_b32_e32 v79, v4
	v_lshlrev_b64 v[8:9], 8, v[78:79]
	s_waitcnt vmcnt(0)
	v_cvt_pk_bf16_f32 v6, v84, v85
	v_lshl_add_u64 v[8:9], v[34:35], 0, v[8:9]
	s_mov_b64 s[14:15], 0
	global_store_dword v[8:9], v6, off nt
	s_and_saveexec_b64 s[16:17], s[4:5]
	s_xor_b64 s[70:71], exec, s[16:17]
	s_cbranch_execz .LBB0_777
	v_add_u32_e32 v6, 0xffffc000, v78
	v_lshrrev_b32_e32 v6, 9, v6
	v_mul_hi_u32_u24_e32 v9, 0x1200, v6
	v_mul_u32_u24_e32 v6, 0x1200, v6
	s_movk_i32 s16, 0x1ff
	v_and_or_b32 v8, v78, s16, v6
	s_mov_b64 s[16:17], 0x3000
	s_mov_b64 s[14:15], exec
	v_lshl_add_u64 v[8:9], v[8:9], 0, s[16:17]
	v_mov_b32_e32 v6, v0

.LBB0_779:
	v_lshlrev_b64 v[8:9], 6, v[8:9]
	s_waitcnt vmcnt(0)
	v_cvt_pk_bf16_f32 v0, v6, s0
	v_lshl_add_u64 v[8:9], v[38:39], 0, v[8:9]
	global_store_short v[8:9], v0, off nt
.LBB0_780:
	s_or_b64 exec, exec, s[0:1]
	s_movk_i32 s0, 0x4400
	v_cmp_gt_i32_e32 vcc, s0, v68
	s_and_saveexec_b64 s[14:15], vcc
	s_cbranch_execz .LBB0_733
	s_mov_b64 s[70:71], 0
	s_and_saveexec_b64 s[0:1], s[12:13]
	s_xor_b64 s[0:1], exec, s[0:1]
	s_cbranch_execz .LBB0_810
	v_mov_b32_e32 v69, v4
	v_lshlrev_b64 v[8:9], 8, v[68:69]
	s_waitcnt vmcnt(0)
	v_cvt_pk_bf16_f32 v0, v74, v75
	v_lshl_add_u64 v[8:9], v[34:35], 0, v[8:9]
	s_mov_b64 s[12:13], 0
	global_store_dword v[8:9], v0, off nt
	s_and_saveexec_b64 s[70:71], s[4:5]
	s_cbranch_execz .LBB0_784
	v_add_u32_e32 v0, 0xffffc000, v68
	v_lshrrev_b32_e32 v0, 9, v0
	v_mul_hi_u32_u24_e32 v9, 0x1200, v0
	v_mul_u32_u24_e32 v0, 0x1200, v0
	s_movk_i32 s16, 0x1ff
	v_and_or_b32 v8, v68, s16, v0
	s_mov_b64 s[16:17], 0x3000
	s_mov_b64 s[12:13], exec
	v_lshl_add_u64 v[68:69], v[8:9], 0, s[16:17]
	v_mov_b32_e32 v0, v1

.LBB0_786:
	s_waitcnt vmcnt(0)
	v_cvt_pk_bf16_f32 v5, v0, s0
	v_lshlrev_b64 v[0:1], 6, v[68:69]
	v_lshl_add_u64 v[0:1], v[38:39], 0, v[0:1]
	global_store_short v[0:1], v5, off nt
.LBB0_787:
	s_or_b64 exec, exec, s[0:1]
	s_movk_i32 s0, 0x4400
	v_cmp_gt_i32_e32 vcc, s0, v58
	s_and_b64 exec, exec, vcc
	s_cbranch_execz .LBB0_733
	s_mov_b64 s[12:13], 0
	s_and_saveexec_b64 s[0:1], s[10:11]
	s_xor_b64 s[0:1], exec, s[0:1]
	s_cbranch_execz .LBB0_820
	v_mov_b32_e32 v59, v4
	s_waitcnt vmcnt(0)
	v_lshlrev_b64 v[0:1], 8, v[58:59]
	v_cvt_pk_bf16_f32 v5, v10, v11
	v_lshl_add_u64 v[0:1], v[34:35], 0, v[0:1]
	s_mov_b64 s[10:11], 0
	global_store_dword v[0:1], v5, off nt
	s_and_saveexec_b64 s[12:13], s[4:5]
	s_cbranch_execz .LBB0_791
	v_add_u32_e32 v0, 0xffffc000, v58
	v_lshrrev_b32_e32 v0, 9, v0
	v_mul_hi_u32_u24_e32 v1, 0x1200, v0
	v_mul_u32_u24_e32 v0, 0x1200, v0
	s_movk_i32 s16, 0x1ff
	v_and_or_b32 v0, v58, s16, v0
	s_mov_b64 s[16:17], 0x3000
	s_mov_b64 s[10:11], exec
	v_lshl_add_u64 v[58:59], v[0:1], 0, s[16:17]
	v_mov_b32_e32 v5, v2

.LBB0_793:
	s_waitcnt vmcnt(0) lgkmcnt(0)
	v_lshlrev_b64 v[0:1], 6, v[58:59]
	v_cvt_pk_bf16_f32 v2, v5, s0
	v_lshl_add_u64 v[0:1], v[38:39], 0, v[0:1]
	global_store_short v[0:1], v2, off nt
.LBB0_794:
	s_or_b64 exec, exec, s[0:1]
	s_movk_i32 s0, 0x4400
	v_cmp_gt_i32_e32 vcc, s0, v56
	s_and_b64 exec, exec, vcc
	s_cbranch_execz .LBB0_733
	s_mov_b64 s[10:11], 0
	s_and_saveexec_b64 s[0:1], s[8:9]
	s_xor_b64 s[0:1], exec, s[0:1]
	s_cbranch_execz .LBB0_830
	v_mov_b32_e32 v57, v4
	s_waitcnt vmcnt(0) lgkmcnt(0)
	v_lshlrev_b64 v[0:1], 8, v[56:57]
	v_cvt_pk_bf16_f32 v2, v60, v61
	v_lshl_add_u64 v[0:1], v[34:35], 0, v[0:1]
	s_mov_b64 s[8:9], 0
	global_store_dword v[0:1], v2, off nt
	s_and_saveexec_b64 s[10:11], s[4:5]
	v_add_u32_e32 v0, 0xffffc000, v56
	v_lshrrev_b32_e32 v0, 9, v0
	v_mul_hi_u32_u24_e32 v1, 0x1200, v0
	v_mul_u32_u24_e32 v0, 0x1200, v0
	s_movk_i32 s12, 0x1ff
	v_and_or_b32 v0, v56, s12, v0
	s_mov_b64 s[12:13], 0x3000
	s_mov_b64 s[8:9], exec
	v_lshl_add_u64 v[56:57], v[0:1], 0, s[12:13]
	s_or_b64 exec, exec, s[10:11]
	s_and_b64 s[10:11], s[8:9], exec
	s_andn2_saveexec_b64 s[8:9], s[0:1]
	s_cbranch_execnz .LBB0_831

.LBB0_801:
	v_mul_f32_e32 v6, v87, v87
	v_pk_fma_f32 v[12:13], v[86:87], v[86:87], v[6:7] op_sel_hi:[1,1,0]
	v_pk_mul_f32 v[8:9], v[88:89], v[88:89]
	v_pk_fma_f32 v[12:13], v[88:89], v[88:89], v[12:13]
	v_cmp_lt_i32_e32 vcc, v248, v242
	s_waitcnt vmcnt(0)
	v_pk_mul_f32 v[92:93], v[84:85], v[84:85]
	s_brev_b32 s0, 60
	v_cndmask_b32_e32 v6, v241, v248, vcc
	v_mov_b32_e32 v8, v92
	v_pk_mov_b32 v[12:13], v[92:93], v[12:13] op_sel:[1,0]
	v_lshlrev_b32_e32 v6, 2, v6
	v_pk_add_f32 v[8:9], v[8:9], v[12:13]
	ds_bpermute_b32 v13, v6, v9
	ds_bpermute_b32 v12, v6, v8
	v_cmp_lt_i32_e32 vcc, v247, v242
	s_mov_b32 s1, 0x3b800000
	s_waitcnt lgkmcnt(0)
	v_pk_add_f32 v[8:9], v[8:9], v[12:13]
	v_cndmask_b32_e32 v6, v241, v247, vcc
	v_lshlrev_b32_e32 v6, 2, v6
	ds_bpermute_b32 v13, v6, v9
	ds_bpermute_b32 v12, v6, v8
	v_cmp_lt_i32_e32 vcc, v246, v242
	s_waitcnt lgkmcnt(0)
	v_pk_add_f32 v[8:9], v[8:9], v[12:13]
	v_cndmask_b32_e32 v6, v241, v246, vcc
	v_lshlrev_b32_e32 v57, 2, v6
	ds_bpermute_b32 v13, v57, v9
	ds_bpermute_b32 v12, v57, v8
	v_cmp_lt_i32_e32 vcc, v245, v242
	s_waitcnt lgkmcnt(0)
	v_pk_add_f32 v[8:9], v[8:9], v[12:13]
	v_cndmask_b32_e32 v6, v241, v245, vcc
	v_lshlrev_b32_e32 v6, 2, v6
	ds_bpermute_b32 v13, v6, v9
	ds_bpermute_b32 v12, v6, v8
	v_cmp_lt_i32_e32 vcc, v244, v242
	s_waitcnt lgkmcnt(0)
	v_pk_add_f32 v[8:9], v[8:9], v[12:13]
	v_cndmask_b32_e32 v6, v241, v244, vcc
	v_lshlrev_b32_e32 v6, 2, v6
	ds_bpermute_b32 v13, v6, v9
	ds_bpermute_b32 v12, v6, v8
	v_cmp_lt_i32_e32 vcc, v243, v242
	s_waitcnt lgkmcnt(0)
	v_pk_add_f32 v[8:9], v[8:9], v[12:13]
	v_cndmask_b32_e32 v6, v241, v243, vcc
	v_lshlrev_b32_e32 v6, 2, v6
	ds_bpermute_b32 v13, v6, v9
	ds_bpermute_b32 v12, v6, v8
	s_waitcnt lgkmcnt(0)
	v_pk_add_f32 v[8:9], v[8:9], v[12:13]
	s_nop 0
	v_pk_fma_f32 v[8:9], v[8:9], s[0:1], v[138:139] op_sel_hi:[1,1,0]
	s_mov_b32 s0, 0x800000
	v_mul_f32_e32 v6, 0x4b800000, v9
	v_cmp_gt_f32_e32 vcc, s0, v9
	v_cmp_gt_f32_e64 s[0:1], s0, v8
	s_nop 0
	v_cndmask_b32_e32 v6, v9, v6, vcc
	v_rsq_f32_e32 v6, v6
	v_mul_f32_e32 v9, 0x4b800000, v8
	v_cndmask_b32_e64 v8, v8, v9, s[0:1]
	v_rsq_f32_e32 v8, v8
	v_mul_f32_e32 v9, 0x45800000, v6
	v_cndmask_b32_e32 v6, v6, v9, vcc
	v_pk_mul_f32 v[12:13], v[86:87], v[6:7] op_sel_hi:[1,0]
	v_mul_f32_e32 v9, 0x45800000, v8
	v_pk_mul_f32 v[86:87], v[88:89], v[6:7] op_sel_hi:[1,0]
	v_cndmask_b32_e64 v8, v8, v9, s[0:1]
	v_pk_mul_f32 v[12:13], v[16:17], v[12:13]
	v_pk_mul_f32 v[86:87], v[18:19], v[86:87]
	v_cvt_pk_bf16_f32 v12, v12, v13
	v_cvt_pk_bf16_f32 v13, v86, v87
	v_lshl_add_u64 v[86:87], s[26:27], 0, v[48:49]
	v_pk_mul_f32 v[8:9], v[84:85], v[8:9] op_sel_hi:[1,0]
	global_store_dwordx2 v[86:87], v[12:13], off nt
	v_pk_mul_f32 v[12:13], v[66:67], v[8:9]
	v_lshl_add_u64 v[8:9], s[26:27], 0, v[46:47]
	v_cvt_pk_bf16_f32 v6, v12, v13
	v_cmp_lt_i32_e32 vcc, s89, v78
	s_mov_b64 s[0:1], s[70:71]
	global_store_dword v[8:9], v6, off nt
	s_and_saveexec_b64 s[16:17], vcc
	s_xor_b64 s[72:73], exec, s[16:17]
	s_cbranch_execz .LBB0_805
	ds_bpermute_b32 v12, v57, v0
	s_mov_b64 s[74:75], s[70:71]
	s_and_saveexec_b64 s[0:1], s[4:5]
	s_xor_b64 s[0:1], exec, s[0:1]
	s_cbranch_execz .LBB0_804
	v_add_u32_e32 v6, 0xffffe000, v78
	v_and_b32_e32 v13, 0xfff, v78
	s_waitcnt lgkmcnt(0)
	v_cndmask_b32_e64 v9, v12, -v12, s[6:7]
	v_mov_b32_e32 v78, v20
	v_mov_b32_e32 v8, v0
	v_pk_mul_f32 v[8:9], v[78:79], v[8:9]
	v_lshrrev_b32_e32 v57, 12, v6
	v_add_f32_e32 v6, v8, v9
	v_or_b32_e32 v8, 0x2000, v13
	v_mov_b32_e32 v9, v4
	s_movk_i32 s16, 0x1200
	v_mad_u64_u32 v[8:9], s[16:17], v57, s16, v[8:9]
	s_or_b64 s[74:75], s[70:71], exec

.LBB0_805:
	s_andn2_saveexec_b64 s[72:73], s[72:73]
	s_cbranch_execz .LBB0_809
	v_ashrrev_i32_e32 v6, 7, v78
	v_readlane_b32 s16, v255, 47
	s_mov_b64 s[76:77], s[0:1]
	v_readlane_b32 s17, v255, 48
	v_and_or_b32 v8, v6, -2, s16
	v_ashrrev_i32_e32 v9, 31, v8
	v_lshlrev_b64 v[8:9], 8, v[8:9]
	s_movk_i32 s16, 0xff
	v_and_or_b32 v8, v78, s16, v8
	v_lshlrev_b64 v[78:79], 9, v[8:9]
	v_lshl_add_u64 v[78:79], v[44:45], 0, v[78:79]
	s_waitcnt lgkmcnt(0)
	global_store_dwordx2 v[78:79], v[12:13], off nt
	s_and_saveexec_b64 s[74:75], s[4:5]
	s_cbranch_execz .LBB0_808
	v_lshlrev_b64 v[8:9], 7, v[8:9]
	v_lshl_add_u64 v[8:9], s[30:31], 0, v[8:9]
	v_lshlrev_b32_e32 v12, 2, v24
	v_mov_b32_e32 v13, v4
	v_lshl_add_u64 v[8:9], v[8:9], 0, v[12:13]
	v_add_co_u32_e32 v8, vcc, 0x4800000, v8
	s_or_b64 s[76:77], s[0:1], exec
	s_nop 0
	v_addc_co_u32_e32 v9, vcc, 0, v9, vcc
	v_mov_b32_e32 v6, v0
	global_store_dword v[8:9], v0, off nt

.LBB0_811:
	s_waitcnt vmcnt(0)
	v_mul_f32_e32 v0, v83, v83
	s_waitcnt lgkmcnt(0)
	v_pk_fma_f32 v[12:13], v[82:83], v[82:83], v[0:1] op_sel_hi:[1,1,0]
	v_pk_mul_f32 v[8:9], v[80:81], v[80:81]
	v_pk_fma_f32 v[12:13], v[80:81], v[80:81], v[12:13]
	v_cmp_lt_i32_e32 vcc, v248, v242
	v_pk_mul_f32 v[78:79], v[74:75], v[74:75]
	s_brev_b32 s0, 60
	v_cndmask_b32_e32 v0, v241, v248, vcc
	v_mov_b32_e32 v8, v78
	v_pk_mov_b32 v[12:13], v[78:79], v[12:13] op_sel:[1,0]
	v_lshlrev_b32_e32 v0, 2, v0
	v_pk_add_f32 v[8:9], v[8:9], v[12:13]
	ds_bpermute_b32 v13, v0, v9
	ds_bpermute_b32 v12, v0, v8
	v_cmp_lt_i32_e32 vcc, v247, v242
	s_mov_b32 s1, 0x3b800000
	v_ashrrev_i32_e32 v69, 31, v68
	v_cndmask_b32_e32 v0, v241, v247, vcc
	v_lshlrev_b32_e32 v0, 2, v0
	s_waitcnt lgkmcnt(0)
	v_pk_add_f32 v[8:9], v[8:9], v[12:13]
	ds_bpermute_b32 v13, v0, v9
	ds_bpermute_b32 v12, v0, v8
	v_cmp_lt_i32_e32 vcc, v246, v242
	s_waitcnt lgkmcnt(0)
	v_pk_add_f32 v[8:9], v[8:9], v[12:13]
	v_cndmask_b32_e32 v0, v241, v246, vcc
	v_lshlrev_b32_e32 v6, 2, v0
	ds_bpermute_b32 v13, v6, v9
	ds_bpermute_b32 v12, v6, v8
	v_cmp_lt_i32_e32 vcc, v245, v242
	s_waitcnt lgkmcnt(0)
	v_pk_add_f32 v[8:9], v[8:9], v[12:13]
	v_cndmask_b32_e32 v0, v241, v245, vcc
	v_lshlrev_b32_e32 v0, 2, v0
	ds_bpermute_b32 v13, v0, v9
	ds_bpermute_b32 v12, v0, v8
	v_cmp_lt_i32_e32 vcc, v244, v242
	s_waitcnt lgkmcnt(0)
	v_pk_add_f32 v[8:9], v[8:9], v[12:13]
	v_cndmask_b32_e32 v0, v241, v244, vcc
	v_lshlrev_b32_e32 v0, 2, v0
	ds_bpermute_b32 v13, v0, v9
	ds_bpermute_b32 v12, v0, v8
	v_cmp_lt_i32_e32 vcc, v243, v242
	s_waitcnt lgkmcnt(0)
	v_pk_add_f32 v[8:9], v[8:9], v[12:13]
	v_cndmask_b32_e32 v0, v241, v243, vcc
	v_lshlrev_b32_e32 v0, 2, v0
	ds_bpermute_b32 v13, v0, v9
	ds_bpermute_b32 v12, v0, v8
	s_waitcnt lgkmcnt(0)
	v_pk_add_f32 v[8:9], v[8:9], v[12:13]
	s_nop 0
	v_pk_fma_f32 v[8:9], v[8:9], s[0:1], v[138:139] op_sel_hi:[1,1,0]
	s_mov_b32 s0, 0x800000
	v_mul_f32_e32 v0, 0x4b800000, v9
	v_cmp_gt_f32_e32 vcc, s0, v9
	v_cmp_gt_f32_e64 s[0:1], s0, v8
	s_nop 0
	v_cndmask_b32_e32 v0, v9, v0, vcc
	v_rsq_f32_e32 v0, v0
	v_mul_f32_e32 v9, 0x4b800000, v8
	v_cndmask_b32_e64 v8, v8, v9, s[0:1]
	v_rsq_f32_e32 v8, v8
	v_mul_f32_e32 v9, 0x45800000, v0
	v_cndmask_b32_e32 v0, v0, v9, vcc
	v_pk_mul_f32 v[12:13], v[82:83], v[0:1] op_sel_hi:[1,0]
	v_pk_mul_f32 v[78:79], v[80:81], v[0:1] op_sel_hi:[1,0]
	v_mul_f32_e32 v9, 0x45800000, v8
	v_pk_mul_f32 v[12:13], v[16:17], v[12:13]
	v_pk_mul_f32 v[78:79], v[18:19], v[78:79]
	v_cndmask_b32_e64 v8, v8, v9, s[0:1]
	v_cvt_pk_bf16_f32 v12, v12, v13
	v_cvt_pk_bf16_f32 v13, v78, v79
	v_lshlrev_b64 v[78:79], 9, v[68:69]
	v_lshl_add_u64 v[78:79], v[36:37], 0, v[78:79]
	v_pk_mul_f32 v[8:9], v[74:75], v[8:9] op_sel_hi:[1,0]
	global_store_dwordx2 v[78:79], v[12:13], off nt
	v_pk_mul_f32 v[8:9], v[66:67], v[8:9]
	v_lshlrev_b64 v[12:13], 8, v[68:69]
	v_cvt_pk_bf16_f32 v0, v8, v9
	v_lshl_add_u64 v[12:13], v[34:35], 0, v[12:13]
	v_cmp_lt_i32_e32 vcc, s89, v68
	s_mov_b64 s[0:1], s[70:71]
	global_store_dword v[12:13], v0, off nt
	s_and_saveexec_b64 s[16:17], vcc
	s_xor_b64 s[72:73], exec, s[16:17]
	s_cbranch_execz .LBB0_815
	ds_bpermute_b32 v6, v6, v1
	s_mov_b64 s[74:75], s[70:71]
	s_and_saveexec_b64 s[0:1], s[4:5]
	s_cbranch_execz .LBB0_814
	s_waitcnt lgkmcnt(0)
	v_cndmask_b32_e64 v9, v6, -v6, s[6:7]
	v_mov_b32_e32 v76, v5
	v_mov_b32_e32 v8, v1
	v_add_u32_e32 v0, 0xffffe000, v68
	v_and_b32_e32 v12, 0xfff, v68
	v_pk_mul_f32 v[8:9], v[76:77], v[8:9]
	v_lshrrev_b32_e32 v13, 12, v0
	v_add_f32_e32 v0, v8, v9
	v_or_b32_e32 v8, 0x2000, v12
	v_mov_b32_e32 v9, v4
	s_movk_i32 s16, 0x1200
	v_mad_u64_u32 v[68:69], s[16:17], v13, s16, v[8:9]
	s_or_b64 s[74:75], s[70:71], exec

.LBB0_815:
	s_andn2_saveexec_b64 s[72:73], s[72:73]
	s_cbranch_execz .LBB0_819
	v_ashrrev_i32_e32 v0, 7, v68
	v_readlane_b32 s16, v255, 47
	s_mov_b64 s[76:77], s[0:1]
	v_readlane_b32 s17, v255, 48
	v_and_or_b32 v12, v0, -2, s16
	v_ashrrev_i32_e32 v13, 31, v12
	v_lshlrev_b64 v[12:13], 8, v[12:13]
	s_movk_i32 s16, 0xff
	v_and_or_b32 v12, v68, s16, v12
	v_lshlrev_b64 v[74:75], 9, v[12:13]
	v_lshl_add_u64 v[74:75], v[44:45], 0, v[74:75]
	global_store_dwordx2 v[74:75], v[8:9], off nt
	s_and_saveexec_b64 s[74:75], s[4:5]
	s_cbranch_execz .LBB0_818
	v_lshlrev_b64 v[8:9], 7, v[12:13]
	v_lshl_add_u64 v[8:9], s[30:31], 0, v[8:9]
	v_lshlrev_b32_e32 v12, 2, v24
	v_mov_b32_e32 v13, v4
	v_lshl_add_u64 v[8:9], v[8:9], 0, v[12:13]
	v_add_co_u32_e32 v8, vcc, 0x4800000, v8
	s_or_b64 s[76:77], s[0:1], exec
	s_nop 0
	v_addc_co_u32_e32 v9, vcc, 0, v9, vcc
	v_mov_b32_e32 v0, v1
	global_store_dword v[8:9], v1, off nt

.LBB0_821:
	s_waitcnt vmcnt(0)
	v_pk_mul_f32 v[0:1], v[70:71], v[70:71]
	v_cmp_lt_i32_e32 vcc, v248, v242
	v_mul_f32_e32 v0, v73, v73
	v_pk_fma_f32 v[8:9], v[72:73], v[72:73], v[0:1] op_sel_hi:[1,1,0]
	v_cndmask_b32_e32 v0, v241, v248, vcc
	v_pk_fma_f32 v[8:9], v[70:71], v[70:71], v[8:9]
	s_waitcnt lgkmcnt(0)
	v_pk_mul_f32 v[12:13], v[10:11], v[10:11]
	v_lshlrev_b32_e32 v5, 2, v0
	v_mov_b32_e32 v0, v12
	v_pk_mov_b32 v[8:9], v[12:13], v[8:9] op_sel:[1,0]
	v_cmp_lt_i32_e32 vcc, v247, v242
	v_pk_add_f32 v[0:1], v[0:1], v[8:9]
	ds_bpermute_b32 v9, v5, v1
	ds_bpermute_b32 v8, v5, v0
	v_cndmask_b32_e32 v5, v241, v247, vcc
	v_lshlrev_b32_e32 v5, 2, v5
	v_cmp_lt_i32_e32 vcc, v246, v242
	s_brev_b32 s0, 60
	s_waitcnt lgkmcnt(0)
	v_pk_add_f32 v[0:1], v[0:1], v[8:9]
	ds_bpermute_b32 v9, v5, v1
	ds_bpermute_b32 v8, v5, v0
	v_cndmask_b32_e32 v5, v241, v246, vcc
	v_lshlrev_b32_e32 v6, 2, v5
	v_cmp_lt_i32_e32 vcc, v245, v242
	s_mov_b32 s1, 0x3b800000
	s_waitcnt lgkmcnt(0)
	v_pk_add_f32 v[0:1], v[0:1], v[8:9]
	ds_bpermute_b32 v9, v6, v1
	ds_bpermute_b32 v8, v6, v0
	v_cndmask_b32_e32 v5, v241, v245, vcc
	v_lshlrev_b32_e32 v5, 2, v5
	v_cmp_lt_i32_e32 vcc, v244, v242
	v_ashrrev_i32_e32 v59, 31, v58
	s_waitcnt lgkmcnt(0)
	v_pk_add_f32 v[0:1], v[0:1], v[8:9]
	ds_bpermute_b32 v9, v5, v1
	ds_bpermute_b32 v8, v5, v0
	v_cndmask_b32_e32 v5, v241, v244, vcc
	v_lshlrev_b32_e32 v5, 2, v5
	v_cmp_lt_i32_e32 vcc, v243, v242
	s_waitcnt lgkmcnt(0)
	v_pk_add_f32 v[0:1], v[0:1], v[8:9]
	ds_bpermute_b32 v9, v5, v1
	ds_bpermute_b32 v8, v5, v0
	v_cndmask_b32_e32 v5, v241, v243, vcc
	v_lshlrev_b32_e32 v5, 2, v5
	s_waitcnt lgkmcnt(0)
	v_pk_add_f32 v[0:1], v[0:1], v[8:9]
	ds_bpermute_b32 v9, v5, v1
	ds_bpermute_b32 v8, v5, v0
	s_waitcnt lgkmcnt(0)
	v_pk_add_f32 v[0:1], v[0:1], v[8:9]
	s_nop 0
	v_pk_fma_f32 v[0:1], v[0:1], s[0:1], v[138:139] op_sel_hi:[1,1,0]
	s_mov_b32 s0, 0x800000
	v_mul_f32_e32 v5, 0x4b800000, v1
	v_cmp_gt_f32_e32 vcc, s0, v1
	v_cmp_gt_f32_e64 s[0:1], s0, v0
	s_nop 0
	v_cndmask_b32_e32 v1, v1, v5, vcc
	v_mul_f32_e32 v5, 0x4b800000, v0
	v_rsq_f32_e32 v1, v1
	v_cndmask_b32_e64 v0, v0, v5, s[0:1]
	v_rsq_f32_e32 v5, v0
	v_mul_f32_e32 v0, 0x45800000, v1
	v_cndmask_b32_e32 v0, v1, v0, vcc
	v_mul_f32_e32 v1, 0x45800000, v5
	v_cndmask_b32_e64 v8, v5, v1, s[0:1]
	v_pk_mul_f32 v[12:13], v[72:73], v[0:1] op_sel_hi:[1,0]
	v_pk_mul_f32 v[0:1], v[70:71], v[0:1] op_sel_hi:[1,0]
	v_pk_mul_f32 v[12:13], v[16:17], v[12:13]
	v_pk_mul_f32 v[0:1], v[18:19], v[0:1]
	v_cvt_pk_bf16_f32 v12, v12, v13
	v_cvt_pk_bf16_f32 v13, v0, v1
	v_lshlrev_b64 v[0:1], 9, v[58:59]
	v_lshl_add_u64 v[0:1], v[36:37], 0, v[0:1]
	global_store_dwordx2 v[0:1], v[12:13], off nt
	v_pk_mul_f32 v[0:1], v[10:11], v[8:9] op_sel_hi:[1,0]
	v_lshlrev_b64 v[8:9], 8, v[58:59]
	v_pk_mul_f32 v[0:1], v[66:67], v[0:1]
	v_lshl_add_u64 v[8:9], v[34:35], 0, v[8:9]
	v_cvt_pk_bf16_f32 v5, v0, v1
	v_cmp_lt_i32_e32 vcc, s89, v58
	s_mov_b64 s[0:1], s[12:13]
	global_store_dword v[8:9], v5, off nt
	s_and_saveexec_b64 s[16:17], vcc
	s_xor_b64 s[70:71], exec, s[16:17]
	s_cbranch_execz .LBB0_825
	ds_bpermute_b32 v0, v6, v2
	s_mov_b64 s[72:73], s[12:13]
	s_and_saveexec_b64 s[0:1], s[4:5]
	s_cbranch_execz .LBB0_824
	v_add_u32_e32 v1, 0xffffe000, v58
	v_lshrrev_b32_e32 v9, 12, v1
	s_waitcnt lgkmcnt(0)
	v_cndmask_b32_e64 v1, v0, -v0, s[6:7]
	v_mov_b32_e32 v6, v14
	v_mov_b32_e32 v0, v2
	v_and_b32_e32 v8, 0xfff, v58
	v_pk_mul_f32 v[0:1], v[6:7], v[0:1]
	s_movk_i32 s16, 0x1200
	v_add_f32_e32 v5, v0, v1
	v_or_b32_e32 v0, 0x2000, v8
	v_mov_b32_e32 v1, v4
	v_mad_u64_u32 v[58:59], s[16:17], v9, s16, v[0:1]
	s_or_b64 s[72:73], s[12:13], exec

.LBB0_825:
	s_andn2_saveexec_b64 s[70:71], s[70:71]
	s_cbranch_execz .LBB0_829
	v_ashrrev_i32_e32 v5, 7, v58
	v_readlane_b32 s16, v255, 47
	s_mov_b64 s[74:75], s[0:1]
	v_readlane_b32 s17, v255, 48
	v_and_or_b32 v6, v5, -2, s16
	v_ashrrev_i32_e32 v7, 31, v6
	v_lshlrev_b64 v[6:7], 8, v[6:7]
	s_movk_i32 s16, 0xff
	v_and_or_b32 v6, v58, s16, v6
	v_lshlrev_b64 v[8:9], 9, v[6:7]
	v_lshl_add_u64 v[8:9], v[44:45], 0, v[8:9]
	s_waitcnt lgkmcnt(0)
	global_store_dwordx2 v[8:9], v[0:1], off nt
	s_and_saveexec_b64 s[72:73], s[4:5]
	s_cbranch_execz .LBB0_828
	v_lshlrev_b64 v[0:1], 7, v[6:7]
	v_lshl_add_u64 v[0:1], s[30:31], 0, v[0:1]
	v_lshlrev_b32_e32 v6, 2, v24
	v_mov_b32_e32 v7, v4
	v_lshl_add_u64 v[0:1], v[0:1], 0, v[6:7]
	v_add_co_u32_e32 v0, vcc, 0x4800000, v0
	s_or_b64 s[74:75], s[0:1], exec
	s_nop 0
	v_addc_co_u32_e32 v1, vcc, 0, v1, vcc
	v_mov_b32_e32 v5, v2
	global_store_dword v[0:1], v2, off nt

.LBB0_831:
	s_waitcnt vmcnt(0) lgkmcnt(0)
	v_pk_mul_f32 v[0:1], v[62:63], v[62:63]
	v_cmp_lt_i32_e32 vcc, v248, v242
	v_mul_f32_e32 v0, v65, v65
	v_pk_fma_f32 v[6:7], v[64:65], v[64:65], v[0:1] op_sel_hi:[1,1,0]
	v_cndmask_b32_e32 v0, v241, v248, vcc
	v_pk_fma_f32 v[6:7], v[62:63], v[62:63], v[6:7]
	v_pk_mul_f32 v[8:9], v[60:61], v[60:61]
	v_lshlrev_b32_e32 v2, 2, v0
	v_mov_b32_e32 v0, v8
	v_pk_mov_b32 v[6:7], v[8:9], v[6:7] op_sel:[1,0]
	v_cmp_lt_i32_e32 vcc, v247, v242
	v_pk_add_f32 v[0:1], v[0:1], v[6:7]
	ds_bpermute_b32 v7, v2, v1
	ds_bpermute_b32 v6, v2, v0
	v_cndmask_b32_e32 v2, v241, v247, vcc
	v_lshlrev_b32_e32 v2, 2, v2
	v_cmp_lt_i32_e32 vcc, v246, v242
	s_brev_b32 s0, 60
	s_waitcnt lgkmcnt(0)
	v_pk_add_f32 v[0:1], v[0:1], v[6:7]
	ds_bpermute_b32 v7, v2, v1
	ds_bpermute_b32 v6, v2, v0
	v_cndmask_b32_e32 v2, v241, v246, vcc
	v_lshlrev_b32_e32 v2, 2, v2
	v_cmp_lt_i32_e32 vcc, v245, v242
	s_mov_b32 s1, 0x3b800000
	s_waitcnt lgkmcnt(0)
	v_pk_add_f32 v[0:1], v[0:1], v[6:7]
	ds_bpermute_b32 v7, v2, v1
	ds_bpermute_b32 v6, v2, v0
	v_cndmask_b32_e32 v5, v241, v245, vcc
	v_lshlrev_b32_e32 v5, 2, v5
	v_cmp_lt_i32_e32 vcc, v244, v242
	v_ashrrev_i32_e32 v57, 31, v56
	s_waitcnt lgkmcnt(0)
	v_pk_add_f32 v[0:1], v[0:1], v[6:7]
	ds_bpermute_b32 v7, v5, v1
	ds_bpermute_b32 v6, v5, v0
	v_cndmask_b32_e32 v5, v241, v244, vcc
	v_lshlrev_b32_e32 v5, 2, v5
	v_cmp_lt_i32_e32 vcc, v243, v242
	s_waitcnt lgkmcnt(0)
	v_pk_add_f32 v[0:1], v[0:1], v[6:7]
	ds_bpermute_b32 v7, v5, v1
	ds_bpermute_b32 v6, v5, v0
	v_cndmask_b32_e32 v5, v241, v243, vcc
	v_lshlrev_b32_e32 v5, 2, v5
	s_waitcnt lgkmcnt(0)
	v_pk_add_f32 v[0:1], v[0:1], v[6:7]
	ds_bpermute_b32 v7, v5, v1
	ds_bpermute_b32 v6, v5, v0
	s_waitcnt lgkmcnt(0)
	v_pk_add_f32 v[0:1], v[0:1], v[6:7]
	s_nop 0
	v_pk_fma_f32 v[0:1], v[0:1], s[0:1], v[138:139] op_sel_hi:[1,1,0]
	s_mov_b32 s0, 0x800000
	v_mul_f32_e32 v5, 0x4b800000, v1
	v_cmp_gt_f32_e32 vcc, s0, v1
	v_cmp_gt_f32_e64 s[0:1], s0, v0
	s_nop 0
	v_cndmask_b32_e32 v1, v1, v5, vcc
	v_mul_f32_e32 v5, 0x4b800000, v0
	v_rsq_f32_e32 v1, v1
	v_cndmask_b32_e64 v0, v0, v5, s[0:1]
	v_rsq_f32_e32 v5, v0
	v_mul_f32_e32 v0, 0x45800000, v1
	v_cndmask_b32_e32 v0, v1, v0, vcc
	v_mul_f32_e32 v1, 0x45800000, v5
	v_cndmask_b32_e64 v6, v5, v1, s[0:1]
	v_pk_mul_f32 v[8:9], v[64:65], v[0:1] op_sel_hi:[1,0]
	v_pk_mul_f32 v[0:1], v[62:63], v[0:1] op_sel_hi:[1,0]
	v_pk_mul_f32 v[8:9], v[16:17], v[8:9]
	v_pk_mul_f32 v[0:1], v[18:19], v[0:1]
	v_cvt_pk_bf16_f32 v8, v8, v9
	v_cvt_pk_bf16_f32 v9, v0, v1
	v_lshlrev_b64 v[0:1], 9, v[56:57]
	v_lshl_add_u64 v[0:1], v[36:37], 0, v[0:1]
	global_store_dwordx2 v[0:1], v[8:9], off nt
	v_pk_mul_f32 v[0:1], v[60:61], v[6:7] op_sel_hi:[1,0]
	v_lshlrev_b64 v[6:7], 8, v[56:57]
	v_pk_mul_f32 v[0:1], v[66:67], v[0:1]
	v_lshl_add_u64 v[6:7], v[34:35], 0, v[6:7]
	v_cvt_pk_bf16_f32 v5, v0, v1
	v_cmp_lt_i32_e32 vcc, s89, v56
	s_mov_b64 s[0:1], s[10:11]
	global_store_dword v[6:7], v5, off nt
	s_and_saveexec_b64 s[12:13], vcc
	s_xor_b64 s[12:13], exec, s[12:13]
	s_cbranch_execz .LBB0_835
	ds_bpermute_b32 v0, v2, v3
	s_mov_b64 s[70:71], s[10:11]
	s_and_saveexec_b64 s[0:1], s[4:5]
	s_cbranch_execz .LBB0_834
	v_add_u32_e32 v1, 0xffffe000, v56
	v_lshrrev_b32_e32 v5, 12, v1
	s_waitcnt lgkmcnt(0)
	v_cndmask_b32_e64 v1, v0, -v0, s[6:7]
	v_mov_b32_e32 v20, v15
	v_mov_b32_e32 v0, v3
	v_and_b32_e32 v2, 0xfff, v56
	v_pk_mul_f32 v[0:1], v[20:21], v[0:1]
	s_movk_i32 s16, 0x1200
	v_add_f32_e32 v3, v0, v1
	v_or_b32_e32 v0, 0x2000, v2
	v_mov_b32_e32 v1, v4
	v_mad_u64_u32 v[56:57], s[16:17], v5, s16, v[0:1]
	s_or_b64 s[70:71], s[10:11], exec

.LBB0_835:
	s_andn2_saveexec_b64 s[12:13], s[12:13]
	s_cbranch_execz .LBB0_839
	v_ashrrev_i32_e32 v2, 7, v56
	v_readlane_b32 s16, v255, 47
	s_mov_b64 s[72:73], s[0:1]
	v_readlane_b32 s17, v255, 48
	v_and_or_b32 v6, v2, -2, s16
	v_ashrrev_i32_e32 v7, 31, v6
	v_lshlrev_b64 v[6:7], 8, v[6:7]
	s_movk_i32 s16, 0xff
	v_and_or_b32 v6, v56, s16, v6
	v_lshlrev_b64 v[8:9], 9, v[6:7]
	v_lshl_add_u64 v[8:9], v[44:45], 0, v[8:9]
	s_waitcnt lgkmcnt(0)
	global_store_dwordx2 v[8:9], v[0:1], off nt
	s_and_saveexec_b64 s[70:71], s[4:5]
	s_cbranch_execz .LBB0_838
	v_lshlrev_b64 v[0:1], 7, v[6:7]
	v_lshl_add_u64 v[0:1], s[30:31], 0, v[0:1]
	v_lshlrev_b32_e32 v6, 2, v24
	v_mov_b32_e32 v7, v4
	v_lshl_add_u64 v[0:1], v[0:1], 0, v[6:7]
	v_add_co_u32_e32 v0, vcc, 0x4800000, v0
	s_or_b64 s[72:73], s[0:1], exec
	s_nop 0
	v_addc_co_u32_e32 v1, vcc, 0, v1, vcc
	global_store_dword v[0:1], v3, off nt

.LBB0_840:
	s_waitcnt vmcnt(0) lgkmcnt(0)
	v_lshlrev_b64 v[0:1], 6, v[56:57]
	v_cvt_pk_bf16_f32 v2, v3, s0
	v_lshl_add_u64 v[0:1], v[38:39], 0, v[0:1]
	global_store_short v[0:1], v2, off nt
	s_branch .LBB0_733

.LBB0_855:
	v_mov_b32_e32 v135, v5
	s_mov_b64 s[4:5], -1
	v_lshlrev_b32_e32 v0, 3, v135
	s_cmpk_gt_i32 s9, 0x7f
	v_lshrrev_b32_e32 v134, 3, v135
	v_and_b32_e32 v34, 56, v0
	s_cbranch_scc0 .LBB0_869
	v_add_u32_e32 v0, s8, v135
	v_ashrrev_i32_e32 v0, 5, v0
	v_bfi_b32 v30, -8, v0, v134
	v_cmp_gt_i32_e32 vcc, s88, v30
	v_mov_b32_e32 v2, 0x100
	v_bfe_u32 v1, v135, 6, 2
	v_cndmask_b32_e32 v35, v238, v2, vcc
	v_mov_b32_e32 v2, 0x7ffff000
	v_cndmask_b32_e32 v2, v2, v239, vcc
	v_and_b32_e32 v20, v2, v0
	v_sub_u32_e32 v31, v30, v20
	v_add_u32_e32 v21, -1, v35
	v_lshl_or_b32 v0, v1, 6, v34
	v_cmp_lt_i32_e32 vcc, 1, v1
	s_and_saveexec_b64 s[4:5], vcc
	s_xor_b64 s[4:5], exec, s[4:5]
	s_cbranch_execz .LBB0_862
	v_cmp_lt_i32_e32 vcc, 2, v1
	s_and_saveexec_b64 s[6:7], vcc
	s_xor_b64 s[6:7], exec, s[6:7]
	s_cbranch_execz .LBB0_859
	v_add_u32_e32 v72, -8, v31
	v_min_u32_e32 v1, v72, v21
	v_cmp_lt_i32_e32 vcc, 7, v31
	v_readlane_b32 s10, v254, 8
	v_readlane_b32 s11, v254, 9
	v_cndmask_b32_e32 v1, 0, v1, vcc
	v_add_u32_e32 v1, v1, v20
	v_mov_b64_e32 v[18:19], s[10:11]
	v_mad_i64_i32 v[2:3], s[10:11], v1, s92, v[18:19]
	v_lshlrev_b32_e32 v32, 1, v0
	v_mov_b32_e32 v33, v4
	v_add_u32_e32 v73, -7, v31
	v_lshl_add_u64 v[0:1], v[2:3], 0, v[32:33]
	v_min_u32_e32 v2, v73, v21
	v_cmp_lt_i32_e32 vcc, 6, v31
	v_add_u32_e32 v75, -6, v31
	v_add_u32_e32 v77, -5, v31
	v_cndmask_b32_e32 v2, 0, v2, vcc
	v_add_u32_e32 v2, v2, v20
	v_mad_i64_i32 v[2:3], s[10:11], v2, s92, v[18:19]
	v_lshl_add_u64 v[2:3], v[2:3], 0, v[32:33]
	global_load_dwordx4 v[36:39], v[0:1], off offset:512
	global_load_dwordx4 v[26:29], v[2:3], off offset:512
	v_min_u32_e32 v0, v75, v21
	v_cmp_lt_i32_e32 vcc, 5, v31
	v_min_u32_e32 v2, v77, v21
	v_add_u32_e32 v79, -4, v31
	v_cndmask_b32_e32 v0, 0, v0, vcc
	v_cmp_lt_i32_e32 vcc, 4, v31
	v_add_u32_e32 v0, v0, v20
	v_mad_i64_i32 v[0:1], s[10:11], v0, s92, v[18:19]
	v_cndmask_b32_e32 v2, 0, v2, vcc
	v_add_u32_e32 v2, v2, v20
	v_lshl_add_u64 v[0:1], v[0:1], 0, v[32:33]
	v_mad_i64_i32 v[2:3], s[10:11], v2, s92, v[18:19]
	v_lshl_add_u64 v[2:3], v[2:3], 0, v[32:33]
	global_load_dwordx4 v[40:43], v[0:1], off offset:512
	global_load_dwordx4 v[44:47], v[2:3], off offset:512
	v_min_u32_e32 v0, v79, v21
	v_cmp_lt_i32_e32 vcc, 3, v31
	v_add_u32_e32 v81, -3, v31
	v_min_u32_e32 v2, v81, v21
	v_cndmask_b32_e32 v0, 0, v0, vcc
	v_cmp_lt_i32_e32 vcc, 2, v31
	v_add_u32_e32 v0, v0, v20
	v_mad_i64_i32 v[0:1], s[10:11], v0, s92, v[18:19]
	v_cndmask_b32_e32 v2, 0, v2, vcc
	v_add_u32_e32 v2, v2, v20
	v_lshl_add_u64 v[0:1], v[0:1], 0, v[32:33]
	v_mad_i64_i32 v[2:3], s[10:11], v2, s92, v[18:19]
	v_add_u32_e32 v83, -2, v31
	v_lshl_add_u64 v[2:3], v[2:3], 0, v[32:33]
	global_load_dwordx4 v[48:51], v[0:1], off offset:512
	global_load_dwordx4 v[52:55], v[2:3], off offset:512
	v_min_u32_e32 v0, v83, v21
	v_cmp_lt_i32_e32 vcc, 1, v31
	v_add_u32_e32 v85, -1, v31
	v_min_u32_e32 v2, v85, v21
	v_cndmask_b32_e32 v0, 0, v0, vcc
	v_cmp_lt_i32_e32 vcc, 0, v31
	v_add_u32_e32 v0, v0, v20
	v_mad_i64_i32 v[0:1], s[10:11], v0, s92, v[18:19]
	v_cndmask_b32_e32 v2, 0, v2, vcc
	v_add_u32_e32 v2, v2, v20
	v_lshl_add_u64 v[0:1], v[0:1], 0, v[32:33]
	v_mad_i64_i32 v[2:3], s[10:11], v2, s92, v[18:19]
	v_lshl_add_u64 v[2:3], v[2:3], 0, v[32:33]
	global_load_dwordx4 v[56:59], v[0:1], off offset:512
	global_load_dwordx4 v[60:63], v[2:3], off offset:512
	v_min_u32_e32 v0, v31, v21
	v_cmp_lt_i32_e32 vcc, -1, v31
	v_add_u32_e32 v90, 1, v31
	v_min_u32_e32 v2, v90, v21
	v_cndmask_b32_e32 v0, 0, v0, vcc
	v_cmp_lt_i32_e32 vcc, -2, v31
	v_add_u32_e32 v0, v0, v20
	v_mad_i64_i32 v[0:1], s[10:11], v0, s92, v[18:19]
	v_cndmask_b32_e32 v2, 0, v2, vcc
	v_add_u32_e32 v2, v2, v20
	v_mad_i64_i32 v[2:3], s[10:11], v2, s92, v[18:19]
	v_lshl_add_u64 v[0:1], v[0:1], 0, v[32:33]
	v_lshl_add_u64 v[6:7], v[2:3], 0, v[32:33]
	v_add_u32_e32 v91, 2, v31
	global_load_dwordx4 v[0:3], v[0:1], off offset:512
	s_nop 0
	global_load_dwordx4 v[64:67], v[6:7], off offset:512
	v_min_u32_e32 v6, v91, v21
	v_cmp_lt_i32_e32 vcc, -3, v31
	v_add_u32_e32 v92, 3, v31
	v_min_u32_e32 v8, v92, v21
	v_cndmask_b32_e32 v6, 0, v6, vcc
	v_cmp_lt_i32_e32 vcc, -4, v31
	v_add_u32_e32 v6, v6, v20
	v_mad_i64_i32 v[6:7], s[10:11], v6, s92, v[18:19]
	v_cndmask_b32_e32 v8, 0, v8, vcc
	v_add_u32_e32 v8, v8, v20
	v_mad_i64_i32 v[8:9], s[10:11], v8, s92, v[18:19]
	v_lshl_add_u64 v[6:7], v[6:7], 0, v[32:33]
	v_lshl_add_u64 v[8:9], v[8:9], 0, v[32:33]
	global_load_dwordx4 v[68:71], v[6:7], off offset:512
	s_nop 0
	global_load_dwordx4 v[6:9], v[8:9], off offset:512
	v_add_u32_e32 v93, 4, v31
	v_min_u32_e32 v10, v93, v21
	v_cmp_lt_i32_e32 vcc, -5, v31
	v_add_u32_e32 v94, 5, v31
	v_min_u32_e32 v12, v94, v21
	v_cndmask_b32_e32 v10, 0, v10, vcc
	v_cmp_lt_i32_e32 vcc, -6, v31
	v_add_u32_e32 v95, 6, v31
	v_min_u32_e32 v22, v95, v21
	v_cndmask_b32_e32 v12, 0, v12, vcc
	v_cmp_lt_i32_e32 vcc, -7, v31
	v_add_u32_e32 v96, 7, v31
	v_add_u32_e32 v10, v10, v20
	v_add_u32_e32 v12, v12, v20
	v_cndmask_b32_e32 v22, 0, v22, vcc
	v_min_i32_e32 v97, v96, v21
	v_cmp_lt_i32_e32 vcc, -8, v31
	v_mad_i64_i32 v[10:11], s[10:11], v10, s92, v[18:19]
	v_mad_i64_i32 v[12:13], s[10:11], v12, s92, v[18:19]
	v_cndmask_b32_e32 v21, 0, v97, vcc
	v_lshl_add_u64 v[10:11], v[10:11], 0, v[32:33]
	v_lshl_add_u64 v[12:13], v[12:13], 0, v[32:33]
	v_add_u32_e32 v22, v22, v20
	v_add_u32_e32 v20, v21, v20
	global_load_dwordx4 v[14:17], v[10:11], off offset:512
	s_nop 0
	global_load_dwordx4 v[10:13], v[12:13], off offset:512
	v_mad_i64_i32 v[22:23], s[10:11], v22, s92, v[18:19]
	v_mad_i64_i32 v[18:19], s[10:11], v20, s92, v[18:19]
	v_lshl_add_u64 v[22:23], v[22:23], 0, v[32:33]
	v_lshl_add_u64 v[18:19], v[18:19], 0, v[32:33]
	global_load_dwordx4 v[22:25], v[22:23], off offset:512
	s_nop 0
	global_load_dwordx4 v[18:21], v[18:19], off offset:512
	v_cmp_lt_u32_e32 vcc, v72, v35
	s_waitcnt vmcnt(0)
	v_lshlrev_b32_e32 v86, 16, v36
	v_and_b32_e32 v87, 0xffff0000, v36
	v_cndmask_b32_e64 v72, 0, 1.0, vcc
	v_cmp_lt_u32_e32 vcc, v73, v35
	v_lshlrev_b32_e32 v36, 16, v37
	v_and_b32_e32 v37, 0xffff0000, v37
	v_cndmask_b32_e64 v74, 0, 1.0, vcc
	v_cmp_lt_u32_e32 vcc, v75, v35
	v_lshlrev_b32_e32 v88, 16, v26
	v_and_b32_e32 v89, 0xffff0000, v26
	v_pk_fma_f32 v[36:37], v[72:73], v[36:37], 0 op_sel_hi:[0,1,0]
	v_lshlrev_b32_e32 v26, 16, v27
	v_and_b32_e32 v27, 0xffff0000, v27
	v_cndmask_b32_e64 v76, 0, 1.0, vcc
	v_cmp_lt_u32_e32 vcc, v77, v35
	v_pk_fma_f32 v[26:27], v[74:75], v[26:27], v[36:37] op_sel_hi:[0,1,1]
	v_lshlrev_b32_e32 v36, 16, v41
	v_and_b32_e32 v37, 0xffff0000, v41
	v_cndmask_b32_e64 v78, 0, 1.0, vcc
	v_cmp_lt_u32_e32 vcc, v79, v35
	v_pk_fma_f32 v[26:27], v[76:77], v[36:37], v[26:27] op_sel_hi:[0,1,1]
	v_lshlrev_b32_e32 v36, 16, v45
	v_and_b32_e32 v37, 0xffff0000, v45
	v_cndmask_b32_e64 v80, 0, 1.0, vcc
	v_cmp_lt_u32_e32 vcc, v81, v35
	v_pk_fma_f32 v[26:27], v[78:79], v[36:37], v[26:27] op_sel_hi:[0,1,1]
	v_lshlrev_b32_e32 v36, 16, v49
	v_and_b32_e32 v37, 0xffff0000, v49
	v_cndmask_b32_e64 v82, 0, 1.0, vcc
	v_cmp_lt_u32_e32 vcc, v83, v35
	v_pk_fma_f32 v[26:27], v[80:81], v[36:37], v[26:27] op_sel_hi:[0,1,1]
	v_lshlrev_b32_e32 v36, 16, v53
	v_and_b32_e32 v37, 0xffff0000, v53
	v_cndmask_b32_e64 v84, 0, 1.0, vcc
	v_pk_fma_f32 v[26:27], v[82:83], v[36:37], v[26:27] op_sel_hi:[0,1,1]
	v_lshlrev_b32_e32 v36, 16, v57
	v_and_b32_e32 v37, 0xffff0000, v57
	v_pk_fma_f32 v[86:87], v[72:73], v[86:87], 0 op_sel_hi:[0,1,0]
	v_pk_fma_f32 v[26:27], v[84:85], v[36:37], v[26:27] op_sel_hi:[0,1,1]
	v_lshlrev_b32_e32 v36, 16, v38
	v_and_b32_e32 v37, 0xffff0000, v38
	v_lshlrev_b32_e32 v38, 16, v39
	v_and_b32_e32 v39, 0xffff0000, v39
	v_pk_fma_f32 v[86:87], v[74:75], v[88:89], v[86:87] op_sel_hi:[0,1,1]
	v_lshlrev_b32_e32 v88, 16, v40
	v_and_b32_e32 v89, 0xffff0000, v40
	v_lshlrev_b32_e32 v40, 16, v28
	v_and_b32_e32 v41, 0xffff0000, v28
	v_pk_fma_f32 v[38:39], v[72:73], v[38:39], 0 op_sel_hi:[0,1,0]
	v_lshlrev_b32_e32 v28, 16, v29
	v_and_b32_e32 v29, 0xffff0000, v29
	v_pk_fma_f32 v[28:29], v[74:75], v[28:29], v[38:39] op_sel_hi:[0,1,1]
	v_lshlrev_b32_e32 v38, 16, v43
	v_and_b32_e32 v39, 0xffff0000, v43
	v_pk_fma_f32 v[28:29], v[76:77], v[38:39], v[28:29] op_sel_hi:[0,1,1]
	v_lshlrev_b32_e32 v38, 16, v47
	v_and_b32_e32 v39, 0xffff0000, v47
	v_pk_fma_f32 v[28:29], v[78:79], v[38:39], v[28:29] op_sel_hi:[0,1,1]
	v_lshlrev_b32_e32 v38, 16, v51
	v_and_b32_e32 v39, 0xffff0000, v51
	v_pk_fma_f32 v[28:29], v[80:81], v[38:39], v[28:29] op_sel_hi:[0,1,1]
	v_lshlrev_b32_e32 v38, 16, v55
	v_and_b32_e32 v39, 0xffff0000, v55
	v_pk_fma_f32 v[28:29], v[82:83], v[38:39], v[28:29] op_sel_hi:[0,1,1]
	v_lshlrev_b32_e32 v38, 16, v59
	v_and_b32_e32 v39, 0xffff0000, v59
	v_cmp_lt_u32_e32 vcc, v85, v35
	v_pk_fma_f32 v[28:29], v[84:85], v[38:39], v[28:29] op_sel_hi:[0,1,1]
	v_pk_fma_f32 v[36:37], v[72:73], v[36:37], 0 op_sel_hi:[0,1,0]
	v_cndmask_b32_e64 v38, 0, 1.0, vcc
	v_cmp_lt_u32_e32 vcc, v31, v35
	v_max_i32_e32 v31, 8, v31
	v_sub_u32_e32 v31, v97, v31
	v_add_u32_e32 v31, 9, v31
	v_pk_fma_f32 v[36:37], v[74:75], v[40:41], v[36:37] op_sel_hi:[0,1,1]
	v_lshlrev_b32_e32 v40, 16, v42
	v_and_b32_e32 v41, 0xffff0000, v42
	v_cvt_f32_i32_e32 v31, v31
	v_pk_fma_f32 v[36:37], v[76:77], v[40:41], v[36:37] op_sel_hi:[0,1,1]
	v_lshlrev_b32_e32 v40, 16, v46
	v_and_b32_e32 v41, 0xffff0000, v46
	v_pk_fma_f32 v[86:87], v[76:77], v[88:89], v[86:87] op_sel_hi:[0,1,1]
	v_lshlrev_b32_e32 v88, 16, v44
	v_and_b32_e32 v89, 0xffff0000, v44
	v_pk_fma_f32 v[36:37], v[78:79], v[40:41], v[36:37] op_sel_hi:[0,1,1]
	v_lshlrev_b32_e32 v40, 16, v50
	v_and_b32_e32 v41, 0xffff0000, v50
	v_pk_fma_f32 v[86:87], v[78:79], v[88:89], v[86:87] op_sel_hi:[0,1,1]
	v_lshlrev_b32_e32 v88, 16, v48
	v_and_b32_e32 v89, 0xffff0000, v48
	v_pk_fma_f32 v[36:37], v[80:81], v[40:41], v[36:37] op_sel_hi:[0,1,1]
	v_lshlrev_b32_e32 v40, 16, v54
	v_and_b32_e32 v41, 0xffff0000, v54
	v_cndmask_b32_e64 v48, 0, 1.0, vcc
	v_cmp_lt_u32_e32 vcc, v90, v35
	v_pk_fma_f32 v[36:37], v[82:83], v[40:41], v[36:37] op_sel_hi:[0,1,1]
	v_lshlrev_b32_e32 v40, 16, v58
	v_and_b32_e32 v41, 0xffff0000, v58
	v_cndmask_b32_e64 v50, 0, 1.0, vcc
	v_cmp_lt_u32_e32 vcc, v91, v35
	v_div_scale_f32 v39, s[10:11], v31, v31, 1.0
	v_pk_fma_f32 v[86:87], v[80:81], v[88:89], v[86:87] op_sel_hi:[0,1,1]
	v_lshlrev_b32_e32 v88, 16, v52
	v_and_b32_e32 v89, 0xffff0000, v52
	v_pk_fma_f32 v[36:37], v[84:85], v[40:41], v[36:37] op_sel_hi:[0,1,1]
	v_lshlrev_b32_e32 v40, 16, v60
	v_and_b32_e32 v41, 0xffff0000, v60
	v_cndmask_b32_e64 v60, 0, 1.0, vcc
	v_cmp_lt_u32_e32 vcc, v92, v35
	v_rcp_f32_e32 v49, v39
	v_pk_fma_f32 v[86:87], v[82:83], v[88:89], v[86:87] op_sel_hi:[0,1,1]
	v_lshlrev_b32_e32 v88, 16, v56
	v_and_b32_e32 v89, 0xffff0000, v56
	v_lshlrev_b32_e32 v56, 16, v66
	v_and_b32_e32 v57, 0xffff0000, v66
	v_lshlrev_b32_e32 v58, 16, v67
	v_and_b32_e32 v59, 0xffff0000, v67
	v_lshlrev_b32_e32 v66, 16, v70
	v_and_b32_e32 v67, 0xffff0000, v70
	v_cndmask_b32_e64 v70, 0, 1.0, vcc
	v_cmp_lt_u32_e32 vcc, v93, v35
	v_pk_fma_f32 v[86:87], v[84:85], v[88:89], v[86:87] op_sel_hi:[0,1,1]
	v_lshlrev_b32_e32 v42, 16, v61
	v_cndmask_b32_e64 v72, 0, 1.0, vcc
	v_cmp_lt_u32_e32 vcc, v94, v35
	v_and_b32_e32 v43, 0xffff0000, v61
	v_pk_fma_f32 v[40:41], v[38:39], v[40:41], v[86:87] op_sel_hi:[0,1,1]
	v_cndmask_b32_e64 v74, 0, 1.0, vcc
	v_cmp_lt_u32_e32 vcc, v95, v35
	v_lshlrev_b32_e32 v82, 16, v0
	v_and_b32_e32 v83, 0xffff0000, v0
	v_cndmask_b32_e64 v76, 0, 1.0, vcc
	v_cmp_lt_u32_e32 vcc, v96, v35
	v_fma_f32 v35, -v39, v49, 1.0
	v_fmac_f32_e32 v49, v35, v49
	v_cndmask_b32_e64 v78, 0, 1.0, vcc
	v_div_scale_f32 v35, vcc, 1.0, v31, 1.0
	v_mul_f32_e32 v51, v35, v49
	v_fma_f32 v61, -v39, v51, v35
	v_lshlrev_b32_e32 v52, 16, v64
	v_and_b32_e32 v53, 0xffff0000, v64
	v_fmac_f32_e32 v51, v61, v49
	v_pk_fma_f32 v[40:41], v[48:49], v[82:83], v[40:41] op_sel_hi:[0,1,1]
	v_lshlrev_b32_e32 v44, 16, v62
	v_and_b32_e32 v45, 0xffff0000, v62
	v_lshlrev_b32_e32 v46, 16, v63
	v_and_b32_e32 v47, 0xffff0000, v63
	v_lshlrev_b32_e32 v62, 16, v68
	v_and_b32_e32 v63, 0xffff0000, v68
	v_pk_fma_f32 v[40:41], v[50:51], v[52:53], v[40:41] op_sel_hi:[0,1,1]
	v_pk_fma_f32 v[40:41], v[60:61], v[62:63], v[40:41] op_sel_hi:[0,1,1]
	v_lshlrev_b32_e32 v52, 16, v6
	v_and_b32_e32 v53, 0xffff0000, v6
	v_pk_fma_f32 v[40:41], v[70:71], v[52:53], v[40:41] op_sel_hi:[0,1,1]
	v_lshlrev_b32_e32 v52, 16, v14
	v_and_b32_e32 v53, 0xffff0000, v14
	v_pk_fma_f32 v[40:41], v[72:73], v[52:53], v[40:41] op_sel_hi:[0,1,1]
	v_lshlrev_b32_e32 v52, 16, v10
	v_and_b32_e32 v53, 0xffff0000, v10
	v_fma_f32 v35, -v39, v51, v35
	v_pk_fma_f32 v[40:41], v[74:75], v[52:53], v[40:41] op_sel_hi:[0,1,1]
	v_lshlrev_b32_e32 v52, 16, v22
	v_and_b32_e32 v53, 0xffff0000, v22
	v_div_fmas_f32 v35, v35, v49, v51
	v_pk_fma_f32 v[40:41], v[76:77], v[52:53], v[40:41] op_sel_hi:[0,1,1]
	v_lshlrev_b32_e32 v52, 16, v18
	v_and_b32_e32 v53, 0xffff0000, v18
	v_div_fixup_f32 v80, v35, v31, 1.0
	v_pk_fma_f32 v[40:41], v[78:79], v[52:53], v[40:41] op_sel_hi:[0,1,1]
	v_pk_fma_f32 v[40:41], v[80:81], v[40:41], v[82:83] op_sel_hi:[0,1,1] neg_lo:[0,0,1] neg_hi:[0,0,1]
	v_cvt_pk_bf16_f32 v0, v40, v41
	v_pk_fma_f32 v[26:27], v[38:39], v[42:43], v[26:27] op_sel_hi:[0,1,1]
	v_lshlrev_b32_e32 v40, 16, v1
	v_and_b32_e32 v41, 0xffff0000, v1
	v_lshlrev_b32_e32 v54, 16, v65
	v_and_b32_e32 v55, 0xffff0000, v65
	v_pk_fma_f32 v[26:27], v[48:49], v[40:41], v[26:27] op_sel_hi:[0,1,1]
	v_lshlrev_b32_e32 v64, 16, v69
	v_and_b32_e32 v65, 0xffff0000, v69
	v_pk_fma_f32 v[26:27], v[50:51], v[54:55], v[26:27] op_sel_hi:[0,1,1]
	v_pk_fma_f32 v[26:27], v[60:61], v[64:65], v[26:27] op_sel_hi:[0,1,1]
	v_lshlrev_b32_e32 v6, 16, v7
	v_and_b32_e32 v7, 0xffff0000, v7
	v_pk_fma_f32 v[6:7], v[70:71], v[6:7], v[26:27] op_sel_hi:[0,1,1]
	v_lshlrev_b32_e32 v14, 16, v15
	v_and_b32_e32 v15, 0xffff0000, v15
	v_pk_fma_f32 v[6:7], v[72:73], v[14:15], v[6:7] op_sel_hi:[0,1,1]
	v_lshlrev_b32_e32 v10, 16, v11
	v_and_b32_e32 v11, 0xffff0000, v11
	v_pk_fma_f32 v[6:7], v[74:75], v[10:11], v[6:7] op_sel_hi:[0,1,1]
	v_lshlrev_b32_e32 v10, 16, v23
	v_and_b32_e32 v11, 0xffff0000, v23
	v_pk_fma_f32 v[6:7], v[76:77], v[10:11], v[6:7] op_sel_hi:[0,1,1]
	v_lshlrev_b32_e32 v10, 16, v19
	v_and_b32_e32 v11, 0xffff0000, v19
	v_pk_fma_f32 v[6:7], v[78:79], v[10:11], v[6:7] op_sel_hi:[0,1,1]
	v_pk_fma_f32 v[6:7], v[80:81], v[6:7], v[40:41] op_sel_hi:[0,1,1] neg_lo:[0,0,1] neg_hi:[0,0,1]
	v_cvt_pk_bf16_f32 v1, v6, v7
	v_pk_fma_f32 v[6:7], v[38:39], v[44:45], v[36:37] op_sel_hi:[0,1,1]
	v_lshlrev_b32_e32 v10, 16, v2
	v_and_b32_e32 v11, 0xffff0000, v2
	v_pk_fma_f32 v[6:7], v[48:49], v[10:11], v[6:7] op_sel_hi:[0,1,1]
	v_pk_fma_f32 v[6:7], v[50:51], v[56:57], v[6:7] op_sel_hi:[0,1,1]
	v_pk_fma_f32 v[6:7], v[60:61], v[66:67], v[6:7] op_sel_hi:[0,1,1]
	v_lshlrev_b32_e32 v14, 16, v8
	v_and_b32_e32 v15, 0xffff0000, v8
	v_pk_fma_f32 v[6:7], v[70:71], v[14:15], v[6:7] op_sel_hi:[0,1,1]
	v_lshlrev_b32_e32 v14, 16, v16
	v_and_b32_e32 v15, 0xffff0000, v16
	v_pk_fma_f32 v[6:7], v[72:73], v[14:15], v[6:7] op_sel_hi:[0,1,1]
	v_lshlrev_b32_e32 v14, 16, v12
	v_and_b32_e32 v15, 0xffff0000, v12
	v_pk_fma_f32 v[6:7], v[74:75], v[14:15], v[6:7] op_sel_hi:[0,1,1]
	v_lshlrev_b32_e32 v14, 16, v24
	v_and_b32_e32 v15, 0xffff0000, v24
	v_pk_fma_f32 v[6:7], v[76:77], v[14:15], v[6:7] op_sel_hi:[0,1,1]
	v_lshlrev_b32_e32 v14, 16, v20
	v_and_b32_e32 v15, 0xffff0000, v20
	v_pk_fma_f32 v[6:7], v[78:79], v[14:15], v[6:7] op_sel_hi:[0,1,1]
	v_pk_fma_f32 v[6:7], v[80:81], v[6:7], v[10:11] op_sel_hi:[0,1,1] neg_lo:[0,0,1] neg_hi:[0,0,1]
	v_cvt_pk_bf16_f32 v2, v6, v7
	v_pk_fma_f32 v[6:7], v[38:39], v[46:47], v[28:29] op_sel_hi:[0,1,1]
	v_lshlrev_b32_e32 v10, 16, v3
	v_and_b32_e32 v11, 0xffff0000, v3
	v_pk_fma_f32 v[6:7], v[48:49], v[10:11], v[6:7] op_sel_hi:[0,1,1]
	v_lshlrev_b32_e32 v68, 16, v71
	v_and_b32_e32 v69, 0xffff0000, v71
	v_pk_fma_f32 v[6:7], v[50:51], v[58:59], v[6:7] op_sel_hi:[0,1,1]
	v_pk_fma_f32 v[6:7], v[60:61], v[68:69], v[6:7] op_sel_hi:[0,1,1]
	v_lshlrev_b32_e32 v8, 16, v9
	v_and_b32_e32 v9, 0xffff0000, v9
	v_pk_fma_f32 v[6:7], v[70:71], v[8:9], v[6:7] op_sel_hi:[0,1,1]
	v_lshlrev_b32_e32 v8, 16, v17
	v_and_b32_e32 v9, 0xffff0000, v17
	v_pk_fma_f32 v[6:7], v[72:73], v[8:9], v[6:7] op_sel_hi:[0,1,1]
	v_lshlrev_b32_e32 v8, 16, v13
	v_and_b32_e32 v9, 0xffff0000, v13
	v_pk_fma_f32 v[6:7], v[74:75], v[8:9], v[6:7] op_sel_hi:[0,1,1]
	v_lshlrev_b32_e32 v8, 16, v25
	v_and_b32_e32 v9, 0xffff0000, v25
	v_pk_fma_f32 v[6:7], v[76:77], v[8:9], v[6:7] op_sel_hi:[0,1,1]
	v_lshlrev_b32_e32 v8, 16, v21
	v_and_b32_e32 v9, 0xffff0000, v21
	v_pk_fma_f32 v[6:7], v[78:79], v[8:9], v[6:7] op_sel_hi:[0,1,1]
	v_pk_fma_f32 v[6:7], v[80:81], v[6:7], v[10:11] op_sel_hi:[0,1,1] neg_lo:[0,0,1] neg_hi:[0,0,1]
	v_ashrrev_i32_e32 v31, 31, v30
	v_readlane_b32 s10, v254, 33
	v_cvt_pk_bf16_f32 v3, v6, v7
	v_lshlrev_b64 v[6:7], 9, v[30:31]
	v_readlane_b32 s11, v254, 34
	s_nop 1
	v_lshl_add_u64 v[6:7], s[10:11], 0, v[6:7]
	v_lshl_add_u64 v[6:7], v[6:7], 0, v[32:33]
	global_store_dwordx4 v[6:7], v[0:3], off nt
.LBB0_859:
	s_andn2_saveexec_b64 s[6:7], s[6:7]
	s_cbranch_execz .LBB0_861
	v_add_u32_e32 v44, -4, v31
	v_min_u32_e32 v1, v44, v21
	v_cmp_lt_i32_e32 vcc, 3, v31
	v_add_u32_e32 v45, -3, v31
	v_min_u32_e32 v10, v45, v21
	v_cndmask_b32_e32 v1, 0, v1, vcc
	v_cmp_lt_i32_e32 vcc, 2, v31
	v_add_u32_e32 v52, -2, v31
	v_min_u32_e32 v14, v52, v21
	v_cndmask_b32_e32 v10, 0, v10, vcc
	v_cmp_lt_i32_e32 vcc, 1, v31
	v_readlane_b32 s10, v254, 8
	v_add_u32_e32 v53, -1, v31
	v_cndmask_b32_e32 v14, 0, v14, vcc
	v_min_u32_e32 v18, v31, v21
	v_cmp_lt_i32_e32 vcc, -1, v31
	v_readlane_b32 s11, v254, 9
	v_add_u32_e32 v59, 1, v31
	v_min_u32_e32 v19, v53, v21
	v_cndmask_b32_e32 v18, 0, v18, vcc
	v_cmp_lt_i32_e32 vcc, 0, v31
	v_add_u32_e32 v1, v1, v20
	v_mov_b64_e32 v[2:3], s[10:11]
	v_add_u32_e32 v61, 2, v31
	v_add_u32_e32 v63, 3, v31
	v_min_u32_e32 v22, v59, v21
	v_cndmask_b32_e32 v19, 0, v19, vcc
	v_cmp_lt_i32_e32 vcc, -2, v31
	v_mad_i64_i32 v[6:7], s[10:11], v1, s92, v[2:3]
	v_lshlrev_b32_e32 v0, 1, v0
	v_mov_b32_e32 v1, v4
	v_add_u32_e32 v10, v10, v20
	v_min_u32_e32 v23, v61, v21
	v_min_i32_e32 v62, v63, v21
	v_cndmask_b32_e32 v21, 0, v22, vcc
	v_cmp_lt_i32_e32 vcc, -3, v31
	v_lshl_add_u64 v[6:7], v[6:7], 0, v[0:1]
	v_mad_i64_i32 v[10:11], s[10:11], v10, s92, v[2:3]
	v_add_u32_e32 v14, v14, v20
	v_cndmask_b32_e32 v22, 0, v23, vcc
	v_cmp_lt_i32_e32 vcc, -4, v31
	global_load_dwordx4 v[6:9], v[6:7], off offset:512
	v_lshl_add_u64 v[10:11], v[10:11], 0, v[0:1]
	v_mad_i64_i32 v[14:15], s[10:11], v14, s92, v[2:3]
	v_add_u32_e32 v18, v18, v20
	v_cndmask_b32_e32 v23, 0, v62, vcc
	v_add_u32_e32 v24, v19, v20
	global_load_dwordx4 v[10:13], v[10:11], off offset:512
	v_lshl_add_u64 v[14:15], v[14:15], 0, v[0:1]
	v_mad_i64_i32 v[18:19], s[10:11], v18, s92, v[2:3]
	v_add_u32_e32 v25, v21, v20
	v_add_u32_e32 v28, v22, v20
	v_add_u32_e32 v40, v23, v20
	v_mad_i64_i32 v[20:21], s[10:11], v24, s92, v[2:3]
	global_load_dwordx4 v[14:17], v[14:15], off offset:512
	v_lshl_add_u64 v[22:23], v[18:19], 0, v[0:1]
	v_lshl_add_u64 v[18:19], v[20:21], 0, v[0:1]
	global_load_dwordx4 v[18:21], v[18:19], off offset:512
	v_mad_i64_i32 v[26:27], s[10:11], v25, s92, v[2:3]
	global_load_dwordx4 v[22:25], v[22:23], off offset:512
	v_mad_i64_i32 v[32:33], s[10:11], v28, s92, v[2:3]
	v_lshl_add_u64 v[26:27], v[26:27], 0, v[0:1]
	global_load_dwordx4 v[26:29], v[26:27], off offset:512
	v_lshl_add_u64 v[32:33], v[32:33], 0, v[0:1]
	v_mad_i64_i32 v[2:3], s[10:11], v40, s92, v[2:3]
	global_load_dwordx4 v[36:39], v[32:33], off offset:512
	v_lshl_add_u64 v[2:3], v[2:3], 0, v[0:1]
	global_load_dwordx4 v[40:43], v[2:3], off offset:512
	v_max_i32_e32 v3, 4, v31
	v_sub_u32_e32 v3, v62, v3
	v_add_u32_e32 v3, 5, v3
	v_cmp_lt_u32_e32 vcc, v44, v35
	v_cvt_f32_i32_e32 v3, v3
	s_waitcnt vmcnt(0)
	v_lshlrev_b32_e32 v44, 16, v6
	v_cndmask_b32_e64 v2, 0, 1.0, vcc
	v_cmp_lt_u32_e32 vcc, v45, v35
	v_and_b32_e32 v45, 0xffff0000, v6
	v_lshlrev_b32_e32 v46, 16, v7
	v_cndmask_b32_e64 v32, 0, 1.0, vcc
	v_cmp_lt_u32_e32 vcc, v52, v35
	v_and_b32_e32 v47, 0xffff0000, v7
	v_lshlrev_b32_e32 v6, 16, v10
	v_cndmask_b32_e64 v52, 0, 1.0, vcc
	v_cmp_lt_u32_e32 vcc, v53, v35
	v_and_b32_e32 v7, 0xffff0000, v10
	v_pk_fma_f32 v[44:45], v[2:3], v[44:45], 0 op_sel_hi:[0,1,0]
	v_cndmask_b32_e64 v58, 0, 1.0, vcc
	v_cmp_lt_u32_e32 vcc, v31, v35
	v_div_scale_f32 v31, s[10:11], v3, v3, 1.0
	v_rcp_f32_e32 v33, v31
	v_cndmask_b32_e64 v60, 0, 1.0, vcc
	v_cmp_lt_u32_e32 vcc, v59, v35
	v_lshlrev_b32_e32 v54, 16, v14
	v_and_b32_e32 v55, 0xffff0000, v14
	v_cndmask_b32_e64 v62, 0, 1.0, vcc
	v_cmp_lt_u32_e32 vcc, v61, v35
	v_lshlrev_b32_e32 v48, 16, v8
	v_and_b32_e32 v49, 0xffff0000, v8
	v_cndmask_b32_e64 v64, 0, 1.0, vcc
	v_cmp_lt_u32_e32 vcc, v63, v35
	v_fma_f32 v35, -v31, v33, 1.0
	v_fmac_f32_e32 v33, v35, v33
	v_cndmask_b32_e64 v66, 0, 1.0, vcc
	v_div_scale_f32 v35, vcc, 1.0, v3, 1.0
	v_mul_f32_e32 v53, v35, v33
	v_fma_f32 v59, -v31, v53, v35
	v_fmac_f32_e32 v53, v59, v33
	v_pk_fma_f32 v[6:7], v[32:33], v[6:7], v[44:45] op_sel_hi:[0,1,1]
	v_pk_fma_f32 v[6:7], v[52:53], v[54:55], v[6:7] op_sel_hi:[0,1,1]
	v_lshlrev_b32_e32 v44, 16, v18
	v_and_b32_e32 v45, 0xffff0000, v18
	v_pk_fma_f32 v[6:7], v[58:59], v[44:45], v[6:7] op_sel_hi:[0,1,1]
	v_lshlrev_b32_e32 v44, 16, v22
	v_and_b32_e32 v45, 0xffff0000, v22
	v_pk_fma_f32 v[6:7], v[60:61], v[44:45], v[6:7] op_sel_hi:[0,1,1]
	v_lshlrev_b32_e32 v54, 16, v26
	v_and_b32_e32 v55, 0xffff0000, v26
	v_fma_f32 v31, -v31, v53, v35
	v_pk_fma_f32 v[6:7], v[62:63], v[54:55], v[6:7] op_sel_hi:[0,1,1]
	v_lshlrev_b32_e32 v54, 16, v36
	v_and_b32_e32 v55, 0xffff0000, v36
	v_div_fmas_f32 v31, v31, v33, v53
	v_pk_fma_f32 v[6:7], v[64:65], v[54:55], v[6:7] op_sel_hi:[0,1,1]
	v_lshlrev_b32_e32 v54, 16, v40
	v_and_b32_e32 v55, 0xffff0000, v40
	v_div_fixup_f32 v68, v31, v3, 1.0
	v_pk_fma_f32 v[6:7], v[66:67], v[54:55], v[6:7] op_sel_hi:[0,1,1]
	v_lshlrev_b32_e32 v50, 16, v9
	v_and_b32_e32 v51, 0xffff0000, v9
	v_lshlrev_b32_e32 v8, 16, v11
	v_and_b32_e32 v9, 0xffff0000, v11
	v_pk_fma_f32 v[6:7], v[68:69], v[6:7], v[44:45] op_sel_hi:[0,1,1] neg_lo:[0,0,1] neg_hi:[0,0,1]
	v_pk_fma_f32 v[44:45], v[2:3], v[46:47], 0 op_sel_hi:[0,1,0]
	v_lshlrev_b32_e32 v14, 16, v15
	v_and_b32_e32 v15, 0xffff0000, v15
	v_pk_fma_f32 v[8:9], v[32:33], v[8:9], v[44:45] op_sel_hi:[0,1,1]
	v_pk_fma_f32 v[8:9], v[52:53], v[14:15], v[8:9] op_sel_hi:[0,1,1]
	v_lshlrev_b32_e32 v14, 16, v19
	v_and_b32_e32 v15, 0xffff0000, v19
	v_pk_fma_f32 v[8:9], v[58:59], v[14:15], v[8:9] op_sel_hi:[0,1,1]
	v_lshlrev_b32_e32 v14, 16, v23
	v_and_b32_e32 v15, 0xffff0000, v23
	v_pk_fma_f32 v[8:9], v[60:61], v[14:15], v[8:9] op_sel_hi:[0,1,1]
	v_lshlrev_b32_e32 v18, 16, v27
	v_and_b32_e32 v19, 0xffff0000, v27
	v_pk_fma_f32 v[8:9], v[62:63], v[18:19], v[8:9] op_sel_hi:[0,1,1]
	v_lshlrev_b32_e32 v18, 16, v37
	v_and_b32_e32 v19, 0xffff0000, v37
	v_pk_fma_f32 v[8:9], v[64:65], v[18:19], v[8:9] op_sel_hi:[0,1,1]
	v_lshlrev_b32_e32 v18, 16, v41
	v_and_b32_e32 v19, 0xffff0000, v41
	v_pk_fma_f32 v[8:9], v[66:67], v[18:19], v[8:9] op_sel_hi:[0,1,1]
	v_pk_fma_f32 v[8:9], v[68:69], v[8:9], v[14:15] op_sel_hi:[0,1,1] neg_lo:[0,0,1] neg_hi:[0,0,1]
	v_lshlrev_b32_e32 v10, 16, v12
	v_and_b32_e32 v11, 0xffff0000, v12
	v_cvt_pk_bf16_f32 v6, v6, v7
	v_cvt_pk_bf16_f32 v7, v8, v9
	v_pk_fma_f32 v[8:9], v[2:3], v[48:49], 0 op_sel_hi:[0,1,0]
	v_lshlrev_b32_e32 v56, 16, v16
	v_and_b32_e32 v57, 0xffff0000, v16
	v_pk_fma_f32 v[8:9], v[32:33], v[10:11], v[8:9] op_sel_hi:[0,1,1]
	v_pk_fma_f32 v[8:9], v[52:53], v[56:57], v[8:9] op_sel_hi:[0,1,1]
	v_lshlrev_b32_e32 v10, 16, v20
	v_and_b32_e32 v11, 0xffff0000, v20
	v_pk_fma_f32 v[8:9], v[58:59], v[10:11], v[8:9] op_sel_hi:[0,1,1]
	v_lshlrev_b32_e32 v10, 16, v24
	v_and_b32_e32 v11, 0xffff0000, v24
	v_pk_fma_f32 v[8:9], v[60:61], v[10:11], v[8:9] op_sel_hi:[0,1,1]
	v_lshlrev_b32_e32 v14, 16, v28
	v_and_b32_e32 v15, 0xffff0000, v28
	v_pk_fma_f32 v[8:9], v[62:63], v[14:15], v[8:9] op_sel_hi:[0,1,1]
	v_lshlrev_b32_e32 v14, 16, v38
	v_and_b32_e32 v15, 0xffff0000, v38
	v_lshlrev_b32_e32 v12, 16, v13
	v_and_b32_e32 v13, 0xffff0000, v13
	v_pk_fma_f32 v[8:9], v[64:65], v[14:15], v[8:9] op_sel_hi:[0,1,1]
	v_lshlrev_b32_e32 v14, 16, v42
	v_and_b32_e32 v15, 0xffff0000, v42
	v_pk_fma_f32 v[2:3], v[2:3], v[50:51], 0 op_sel_hi:[0,1,0]
	v_lshlrev_b32_e32 v16, 16, v17
	v_and_b32_e32 v17, 0xffff0000, v17
	v_pk_fma_f32 v[8:9], v[66:67], v[14:15], v[8:9] op_sel_hi:[0,1,1]
	v_pk_fma_f32 v[2:3], v[32:33], v[12:13], v[2:3] op_sel_hi:[0,1,1]
	v_pk_fma_f32 v[8:9], v[68:69], v[8:9], v[10:11] op_sel_hi:[0,1,1] neg_lo:[0,0,1] neg_hi:[0,0,1]
	v_pk_fma_f32 v[2:3], v[52:53], v[16:17], v[2:3] op_sel_hi:[0,1,1]
	v_lshlrev_b32_e32 v10, 16, v21
	v_and_b32_e32 v11, 0xffff0000, v21
	v_pk_fma_f32 v[2:3], v[58:59], v[10:11], v[2:3] op_sel_hi:[0,1,1]
	v_lshlrev_b32_e32 v10, 16, v25
	v_and_b32_e32 v11, 0xffff0000, v25
	v_pk_fma_f32 v[2:3], v[60:61], v[10:11], v[2:3] op_sel_hi:[0,1,1]
	v_lshlrev_b32_e32 v12, 16, v29
	v_and_b32_e32 v13, 0xffff0000, v29
	v_pk_fma_f32 v[2:3], v[62:63], v[12:13], v[2:3] op_sel_hi:[0,1,1]
	v_lshlrev_b32_e32 v12, 16, v39
	v_and_b32_e32 v13, 0xffff0000, v39
	v_pk_fma_f32 v[2:3], v[64:65], v[12:13], v[2:3] op_sel_hi:[0,1,1]
	v_lshlrev_b32_e32 v12, 16, v43
	v_and_b32_e32 v13, 0xffff0000, v43
	v_pk_fma_f32 v[2:3], v[66:67], v[12:13], v[2:3] op_sel_hi:[0,1,1]
	v_pk_fma_f32 v[2:3], v[68:69], v[2:3], v[10:11] op_sel_hi:[0,1,1] neg_lo:[0,0,1] neg_hi:[0,0,1]
	v_ashrrev_i32_e32 v31, 31, v30
	v_readlane_b32 s10, v254, 33
	v_cvt_pk_bf16_f32 v8, v8, v9
	v_cvt_pk_bf16_f32 v9, v2, v3
	v_lshlrev_b64 v[2:3], 9, v[30:31]
	v_readlane_b32 s11, v254, 34
	s_nop 1
	v_lshl_add_u64 v[2:3], s[10:11], 0, v[2:3]
	v_lshl_add_u64 v[0:1], v[2:3], 0, v[0:1]
	global_store_dwordx4 v[0:1], v[6:9], off nt

.LBB0_862:
	s_andn2_saveexec_b64 s[4:5], s[4:5]
	s_cbranch_execz .LBB0_868
	v_cmp_ne_u32_e32 vcc, 1, v1
	s_and_saveexec_b64 s[6:7], vcc
	s_xor_b64 s[6:7], exec, s[6:7]
	s_cbranch_execz .LBB0_865
	v_add_u32_e32 v12, -1, v31
	v_min_u32_e32 v1, v12, v21
	v_cmp_lt_i32_e32 vcc, 0, v31
	v_readlane_b32 s10, v254, 8
	v_readlane_b32 s11, v254, 9
	v_cndmask_b32_e32 v1, 0, v1, vcc
	v_min_i32_e32 v13, v31, v21
	v_cmp_lt_i32_e32 vcc, -1, v31
	v_add_u32_e32 v1, v1, v20
	v_mov_b64_e32 v[8:9], s[10:11]
	v_cndmask_b32_e32 v10, 0, v13, vcc
	v_mad_i64_i32 v[2:3], s[10:11], v1, s92, v[8:9]
	v_lshlrev_b32_e32 v6, 1, v0
	v_mov_b32_e32 v7, v4
	v_add_u32_e32 v10, v10, v20
	v_lshl_add_u64 v[0:1], v[2:3], 0, v[6:7]
	v_mad_i64_i32 v[8:9], s[10:11], v10, s92, v[8:9]
	global_load_dwordx4 v[0:3], v[0:1], off offset:512
	v_lshl_add_u64 v[8:9], v[8:9], 0, v[6:7]
	global_load_dwordx4 v[8:11], v[8:9], off offset:512
	v_max_i32_e32 v15, 1, v31
	v_sub_u32_e32 v13, v13, v15
	v_add_u32_e32 v13, 2, v13
	v_cvt_f32_i32_e32 v13, v13
	v_cmp_lt_u32_e32 vcc, v12, v35
	v_div_scale_f32 v15, s[10:11], v13, v13, 1.0
	v_rcp_f32_e32 v16, v15
	v_cndmask_b32_e64 v12, 0, 1.0, vcc
	v_cmp_lt_u32_e32 vcc, v31, v35
	v_ashrrev_i32_e32 v31, 31, v30
	v_fma_f32 v17, -v15, v16, 1.0
	v_cndmask_b32_e64 v14, 0, 1.0, vcc
	v_fmac_f32_e32 v16, v17, v16
	v_div_scale_f32 v17, vcc, 1.0, v13, 1.0
	v_mul_f32_e32 v18, v17, v16
	v_fma_f32 v19, -v15, v18, v17
	v_fmac_f32_e32 v18, v19, v16
	v_fma_f32 v15, -v15, v18, v17
	v_div_fmas_f32 v15, v15, v16, v18
	v_div_fixup_f32 v16, v15, v13, 1.0
	v_readlane_b32 s10, v254, 33
	v_readlane_b32 s11, v254, 34
	s_waitcnt vmcnt(0)
	v_lshlrev_b32_e32 v18, 16, v0
	v_and_b32_e32 v19, 0xffff0000, v0
	v_pk_fma_f32 v[18:19], v[12:13], v[18:19], 0 op_sel_hi:[0,1,0]
	v_lshlrev_b32_e32 v20, 16, v8
	v_and_b32_e32 v21, 0xffff0000, v8
	v_pk_fma_f32 v[18:19], v[14:15], v[20:21], v[18:19] op_sel_hi:[0,1,1]
	v_pk_fma_f32 v[18:19], v[16:17], v[18:19], v[20:21] op_sel_hi:[0,1,1] neg_lo:[0,0,1] neg_hi:[0,0,1]
	v_cvt_pk_bf16_f32 v0, v18, v19
	v_lshlrev_b32_e32 v18, 16, v1
	v_and_b32_e32 v19, 0xffff0000, v1
	v_pk_fma_f32 v[18:19], v[12:13], v[18:19], 0 op_sel_hi:[0,1,0]
	v_lshlrev_b32_e32 v8, 16, v9
	v_and_b32_e32 v9, 0xffff0000, v9
	v_pk_fma_f32 v[18:19], v[14:15], v[8:9], v[18:19] op_sel_hi:[0,1,1]
	v_pk_fma_f32 v[8:9], v[16:17], v[18:19], v[8:9] op_sel_hi:[0,1,1] neg_lo:[0,0,1] neg_hi:[0,0,1]
	v_cvt_pk_bf16_f32 v1, v8, v9
	v_lshlrev_b32_e32 v8, 16, v2
	v_and_b32_e32 v9, 0xffff0000, v2
	v_pk_fma_f32 v[8:9], v[12:13], v[8:9], 0 op_sel_hi:[0,1,0]
	v_lshlrev_b32_e32 v18, 16, v10
	v_and_b32_e32 v19, 0xffff0000, v10
	v_pk_fma_f32 v[8:9], v[14:15], v[18:19], v[8:9] op_sel_hi:[0,1,1]
	v_pk_fma_f32 v[8:9], v[16:17], v[8:9], v[18:19] op_sel_hi:[0,1,1] neg_lo:[0,0,1] neg_hi:[0,0,1]
	v_cvt_pk_bf16_f32 v2, v8, v9
	v_lshlrev_b32_e32 v8, 16, v3
	v_and_b32_e32 v9, 0xffff0000, v3
	v_pk_fma_f32 v[8:9], v[12:13], v[8:9], 0 op_sel_hi:[0,1,0]
	v_lshlrev_b32_e32 v10, 16, v11
	v_and_b32_e32 v11, 0xffff0000, v11
	v_pk_fma_f32 v[8:9], v[14:15], v[10:11], v[8:9] op_sel_hi:[0,1,1]
	v_pk_fma_f32 v[8:9], v[16:17], v[8:9], v[10:11] op_sel_hi:[0,1,1] neg_lo:[0,0,1] neg_hi:[0,0,1]
	v_cvt_pk_bf16_f32 v3, v8, v9
	v_lshlrev_b64 v[8:9], 9, v[30:31]
	v_lshl_add_u64 v[8:9], s[10:11], 0, v[8:9]
	v_lshl_add_u64 v[6:7], v[8:9], 0, v[6:7]
	global_store_dwordx4 v[6:7], v[0:3], off nt
.LBB0_865:
	s_andn2_saveexec_b64 s[6:7], s[6:7]
	s_cbranch_execz .LBB0_867
	v_add_u32_e32 v22, -2, v31
	v_min_u32_e32 v1, v22, v21
	v_cmp_lt_i32_e32 vcc, 1, v31
	v_readlane_b32 s10, v254, 8
	v_add_u32_e32 v23, -1, v31
	v_cndmask_b32_e32 v1, 0, v1, vcc
	v_readlane_b32 s11, v254, 9
	v_min_u32_e32 v6, v23, v21
	v_cmp_lt_i32_e32 vcc, 0, v31
	v_add_u32_e32 v1, v1, v20
	v_mov_b64_e32 v[14:15], s[10:11]
	v_cndmask_b32_e32 v6, 0, v6, vcc
	v_min_u32_e32 v10, v31, v21
	v_cmp_lt_i32_e32 vcc, -1, v31
	v_add_u32_e32 v24, 1, v31
	v_mad_i64_i32 v[2:3], s[10:11], v1, s92, v[14:15]
	v_lshlrev_b32_e32 v18, 1, v0
	v_mov_b32_e32 v19, v4
	v_add_u32_e32 v6, v6, v20
	v_cndmask_b32_e32 v10, 0, v10, vcc
	v_min_i32_e32 v21, v24, v21
	v_cmp_lt_i32_e32 vcc, -2, v31
	v_lshl_add_u64 v[0:1], v[2:3], 0, v[18:19]
	v_mad_i64_i32 v[6:7], s[10:11], v6, s92, v[14:15]
	v_add_u32_e32 v10, v10, v20
	v_cndmask_b32_e32 v16, 0, v21, vcc
	global_load_dwordx4 v[0:3], v[0:1], off offset:512
	v_lshl_add_u64 v[6:7], v[6:7], 0, v[18:19]
	v_mad_i64_i32 v[10:11], s[10:11], v10, s92, v[14:15]
	v_add_u32_e32 v16, v16, v20
	global_load_dwordx4 v[6:9], v[6:7], off offset:512
	v_lshl_add_u64 v[10:11], v[10:11], 0, v[18:19]
	v_mad_i64_i32 v[14:15], s[10:11], v16, s92, v[14:15]
	global_load_dwordx4 v[10:13], v[10:11], off offset:512
	v_lshl_add_u64 v[14:15], v[14:15], 0, v[18:19]
	global_load_dwordx4 v[14:17], v[14:15], off offset:512
	v_cmp_lt_u32_e32 vcc, v22, v35
	s_waitcnt vmcnt(0)
	v_lshlrev_b32_e32 v32, 16, v0
	v_cndmask_b32_e64 v22, 0, 1.0, vcc
	v_cmp_lt_u32_e32 vcc, v23, v35
	v_max_i32_e32 v23, 2, v31
	v_sub_u32_e32 v21, v21, v23
	v_add_u32_e32 v21, 3, v21
	v_cvt_f32_i32_e32 v21, v21
	v_cndmask_b32_e64 v20, 0, 1.0, vcc
	v_cmp_lt_u32_e32 vcc, v31, v35
	v_and_b32_e32 v33, 0xffff0000, v0
	v_div_scale_f32 v23, s[10:11], v21, v21, 1.0
	v_rcp_f32_e32 v25, v23
	v_cndmask_b32_e64 v26, 0, 1.0, vcc
	v_cmp_lt_u32_e32 vcc, v24, v35
	v_lshlrev_b32_e32 v36, 16, v6
	v_fma_f32 v27, -v23, v25, 1.0
	v_cndmask_b32_e64 v24, 0, 1.0, vcc
	v_fmac_f32_e32 v25, v27, v25
	v_div_scale_f32 v27, vcc, 1.0, v21, 1.0
	v_mul_f32_e32 v28, v27, v25
	v_fma_f32 v29, -v23, v28, v27
	v_fmac_f32_e32 v28, v29, v25
	v_fma_f32 v23, -v23, v28, v27
	v_div_fmas_f32 v23, v23, v25, v28
	v_pk_fma_f32 v[32:33], v[22:23], v[32:33], 0 op_sel_hi:[0,1,0]
	v_and_b32_e32 v37, 0xffff0000, v6
	v_pk_fma_f32 v[32:33], v[20:21], v[36:37], v[32:33] op_sel_hi:[0,1,1]
	v_lshlrev_b32_e32 v36, 16, v10
	v_and_b32_e32 v37, 0xffff0000, v10
	v_pk_fma_f32 v[32:33], v[26:27], v[36:37], v[32:33] op_sel_hi:[0,1,1]
	v_lshlrev_b32_e32 v38, 16, v14
	v_and_b32_e32 v39, 0xffff0000, v14
	v_div_fixup_f32 v28, v23, v21, 1.0
	v_pk_fma_f32 v[32:33], v[24:25], v[38:39], v[32:33] op_sel_hi:[0,1,1]
	v_pk_fma_f32 v[32:33], v[28:29], v[32:33], v[36:37] op_sel_hi:[0,1,1] neg_lo:[0,0,1] neg_hi:[0,0,1]
	v_cvt_pk_bf16_f32 v0, v32, v33
	v_lshlrev_b32_e32 v32, 16, v1
	v_and_b32_e32 v33, 0xffff0000, v1
	v_pk_fma_f32 v[32:33], v[22:23], v[32:33], 0 op_sel_hi:[0,1,0]
	v_lshlrev_b32_e32 v6, 16, v7
	v_and_b32_e32 v7, 0xffff0000, v7
	v_pk_fma_f32 v[6:7], v[20:21], v[6:7], v[32:33] op_sel_hi:[0,1,1]
	v_lshlrev_b32_e32 v10, 16, v11
	v_and_b32_e32 v11, 0xffff0000, v11
	v_pk_fma_f32 v[6:7], v[26:27], v[10:11], v[6:7] op_sel_hi:[0,1,1]
	v_lshlrev_b32_e32 v14, 16, v15
	v_and_b32_e32 v15, 0xffff0000, v15
	v_pk_fma_f32 v[6:7], v[24:25], v[14:15], v[6:7] op_sel_hi:[0,1,1]
	v_pk_fma_f32 v[6:7], v[28:29], v[6:7], v[10:11] op_sel_hi:[0,1,1] neg_lo:[0,0,1] neg_hi:[0,0,1]
	v_cvt_pk_bf16_f32 v1, v6, v7
	v_lshlrev_b32_e32 v6, 16, v2
	v_and_b32_e32 v7, 0xffff0000, v2
	v_pk_fma_f32 v[6:7], v[22:23], v[6:7], 0 op_sel_hi:[0,1,0]
	v_lshlrev_b32_e32 v10, 16, v8
	v_and_b32_e32 v11, 0xffff0000, v8
	v_pk_fma_f32 v[6:7], v[20:21], v[10:11], v[6:7] op_sel_hi:[0,1,1]
	v_lshlrev_b32_e32 v10, 16, v12
	v_and_b32_e32 v11, 0xffff0000, v12
	v_pk_fma_f32 v[6:7], v[26:27], v[10:11], v[6:7] op_sel_hi:[0,1,1]
	v_lshlrev_b32_e32 v14, 16, v16
	v_and_b32_e32 v15, 0xffff0000, v16
	v_pk_fma_f32 v[6:7], v[24:25], v[14:15], v[6:7] op_sel_hi:[0,1,1]
	v_pk_fma_f32 v[6:7], v[28:29], v[6:7], v[10:11] op_sel_hi:[0,1,1] neg_lo:[0,0,1] neg_hi:[0,0,1]
	v_cvt_pk_bf16_f32 v2, v6, v7
	v_lshlrev_b32_e32 v6, 16, v3
	v_and_b32_e32 v7, 0xffff0000, v3
	v_pk_fma_f32 v[6:7], v[22:23], v[6:7], 0 op_sel_hi:[0,1,0]
	v_lshlrev_b32_e32 v8, 16, v9
	v_and_b32_e32 v9, 0xffff0000, v9
	v_pk_fma_f32 v[6:7], v[20:21], v[8:9], v[6:7] op_sel_hi:[0,1,1]
	v_lshlrev_b32_e32 v8, 16, v13
	v_and_b32_e32 v9, 0xffff0000, v13
	v_pk_fma_f32 v[6:7], v[26:27], v[8:9], v[6:7] op_sel_hi:[0,1,1]
	v_lshlrev_b32_e32 v10, 16, v17
	v_and_b32_e32 v11, 0xffff0000, v17
	v_pk_fma_f32 v[6:7], v[24:25], v[10:11], v[6:7] op_sel_hi:[0,1,1]
	v_pk_fma_f32 v[6:7], v[28:29], v[6:7], v[8:9] op_sel_hi:[0,1,1] neg_lo:[0,0,1] neg_hi:[0,0,1]
	v_ashrrev_i32_e32 v31, 31, v30
	v_readlane_b32 s10, v254, 33
	v_cvt_pk_bf16_f32 v3, v6, v7
	v_lshlrev_b64 v[6:7], 9, v[30:31]
	v_readlane_b32 s11, v254, 34
	s_nop 1
	v_lshl_add_u64 v[6:7], s[10:11], 0, v[6:7]
	v_lshl_add_u64 v[6:7], v[6:7], 0, v[18:19]
	global_store_dwordx4 v[6:7], v[0:3], off nt

.LBB0_869:
	s_and_b64 vcc, exec, s[4:5]
	s_cbranch_vccz .LBB0_854
	v_ashrrev_i32_e32 v1, 6, v135
	v_bfe_u32 v0, v135, 3, 3
	v_lshl_or_b32 v0, v1, 3, v0
	v_lshlrev_b32_e32 v22, 10, v1
	v_lshrrev_b32_e32 v1, 1, v0
	s_ashr_i32 s1, s0, 31
	v_xor_b32_e32 v2, v1, v135
	v_ashrrev_i32_e32 v1, 31, v0
	s_lshl_b64 s[4:5], s[0:1], 14
	v_readlane_b32 s6, v254, 10
	v_lshlrev_b64 v[10:11], 9, v[0:1]
	v_lshlrev_b32_e32 v0, 4, v2
	v_readlane_b32 s7, v254, 11
	s_add_u32 s6, s6, s4
	v_and_b32_e32 v18, 0x70, v0
	v_bfe_u32 v0, v135, 3, 6
	v_ashrrev_i32_e32 v23, 9, v135
	s_addc_u32 s7, s7, s5
	v_lshlrev_b32_e32 v0, 7, v0
	v_mov_b32_e32 v1, v4
	v_lshlrev_b32_e32 v8, 1, v23
	v_lshl_add_u64 v[0:1], s[6:7], 0, v[0:1]
	v_lshlrev_b32_e32 v2, 1, v34
	v_mov_b32_e32 v3, v4
	v_ashrrev_i32_e32 v9, 31, v8
	v_lshl_add_u64 v[6:7], v[0:1], 0, v[2:3]
	v_lshlrev_b64 v[0:1], 13, v[8:9]
	v_lshl_add_u64 v[0:1], v[6:7], 0, v[0:1]
	s_waitcnt vmcnt(0) lgkmcnt(0)
	s_barrier
	global_load_dwordx4 v[0:3], v[0:1], off
	v_readlane_b32 s10, v254, 38
	v_add_u32_e32 v9, 32, v22
	v_readlane_b32 s11, v254, 39
	v_add_u32_e32 v14, 0x8000, v9
	v_mov_b32_e32 v19, v4
	v_lshl_add_u64 v[12:13], s[10:11], 0, v[10:11]
	v_readfirstlane_b32 s1, v14
	v_lshl_add_u64 v[12:13], v[12:13], 0, v[18:19]
	s_mov_b32 m0, s1
	s_mov_b64 s[6:7], 0x8000
	global_load_lds_dwordx4 v[12:13], off
	v_lshl_add_u64 v[12:13], v[10:11], 0, s[6:7]
	v_add_u32_e32 v16, 0xa000, v9
	v_lshl_add_u64 v[14:15], s[10:11], 0, v[12:13]
	v_readfirstlane_b32 s1, v16
	v_lshl_add_u64 v[14:15], v[14:15], 0, v[18:19]
	s_mov_b32 m0, s1
	s_mov_b64 s[6:7], 0x10000
	global_load_lds_dwordx4 v[14:15], off
	v_lshl_add_u64 v[14:15], v[10:11], 0, s[6:7]
	v_add_u32_e32 v20, 0xc000, v9
	v_lshl_add_u64 v[16:17], s[10:11], 0, v[14:15]
	v_readfirstlane_b32 s1, v20
	s_mov_b64 s[6:7], 0x18000
	v_add_u32_e32 v9, 0xe000, v9
	v_lshl_add_u64 v[16:17], v[16:17], 0, v[18:19]
	s_mov_b32 m0, s1
	v_lshl_add_u64 v[20:21], v[10:11], 0, s[6:7]
	v_readfirstlane_b32 s1, v9
	global_load_lds_dwordx4 v[16:17], off
	v_lshl_add_u64 v[16:17], s[10:11], 0, v[20:21]
	s_mov_b32 m0, s1
	s_add_i32 s1, 32, 0x10000
	v_lshl_add_u64 v[16:17], v[16:17], 0, v[18:19]
	v_readlane_b32 s10, v254, 40
	v_add_u32_e32 v9, s1, v22
	global_load_lds_dwordx4 v[16:17], off
	v_readlane_b32 s11, v254, 41
	v_add_u32_e32 v16, 0x8000, v9
	v_bfe_u32 v28, v134, 3, 3
	v_lshl_add_u64 v[10:11], s[10:11], 0, v[10:11]
	v_readfirstlane_b32 s6, v16
	v_lshl_add_u64 v[10:11], v[10:11], 0, v[18:19]
	s_mov_b32 m0, s6
	v_bfe_u32 v137, v135, 5, 1
	global_load_lds_dwordx4 v[10:11], off
	v_lshl_add_u64 v[10:11], s[10:11], 0, v[12:13]
	v_add_u32_e32 v12, 0xa000, v9
	v_lshl_add_u64 v[10:11], v[10:11], 0, v[18:19]
	v_readfirstlane_b32 s6, v12
	s_mov_b32 m0, s6
	s_nop 0
	global_load_lds_dwordx4 v[10:11], off
	v_lshl_add_u64 v[10:11], s[10:11], 0, v[14:15]
	v_lshl_add_u64 v[12:13], v[10:11], 0, v[18:19]
	v_add_u32_e32 v10, 0xc000, v9
	v_add_u32_e32 v9, 0xe000, v9
	v_readfirstlane_b32 s6, v10
	v_add_u32_e32 v10, 0x200, v135
	v_ashrrev_i32_e32 v22, 9, v10
	v_lshlrev_b32_e32 v10, 1, v22
	v_ashrrev_i32_e32 v11, 31, v10
	v_lshlrev_b64 v[14:15], 13, v[10:11]
	v_lshl_add_u64 v[14:15], v[6:7], 0, v[14:15]
	global_load_dwordx4 v[14:17], v[14:15], off
	s_mov_b32 m0, s6
	v_readfirstlane_b32 s6, v9
	global_load_lds_dwordx4 v[12:13], off
	v_lshl_add_u64 v[12:13], s[10:11], 0, v[20:21]
	v_lshl_add_u64 v[12:13], v[12:13], 0, v[18:19]
	s_mov_b32 m0, s6
	v_lshl_or_b32 v11, v23, 6, v34
	global_load_lds_dwordx4 v[12:13], off
	v_lshlrev_b32_e32 v13, 2, v135
	v_lshrrev_b32_e32 v9, 2, v135
	v_lshlrev_b32_e32 v29, 7, v11
	v_bitop3_b32 v13, v13, v28, 4 bitop3:0x6c
	v_and_b32_e32 v9, 14, v9
	v_add_u32_e32 v12, 32, v29
	v_lshlrev_b32_e32 v30, 4, v13
	v_add3_u32 v12, v12, v30, v9
	s_waitcnt vmcnt(0)
	ds_write_b16 v12, v0
	ds_write_b16_d16_hi v12, v0 offset:128
	v_or_b32_e32 v0, 2, v11
	v_lshlrev_b32_e32 v31, 7, v0
	v_lshrrev_b32_e32 v0, 1, v0
	v_bitop3_b32 v0, v0, v28, 5 bitop3:0x6c
	v_add_u32_e32 v12, 32, v31
	v_lshlrev_b32_e32 v32, 4, v0
	v_add3_u32 v0, v12, v32, v9
	ds_write_b16 v0, v1
	v_or_b32_e32 v0, 3, v11
	v_lshlrev_b32_e32 v33, 7, v0
	v_lshrrev_b32_e32 v0, 1, v0
	v_bitop3_b32 v0, v0, v28, 5 bitop3:0x6c
	v_add_u32_e32 v12, 32, v33
	v_lshlrev_b32_e32 v35, 4, v0
	v_add3_u32 v0, v12, v35, v9
	ds_write_b16_d16_hi v0, v1
	v_or_b32_e32 v0, 4, v11
	v_lshlrev_b32_e32 v36, 7, v0
	v_lshrrev_b32_e32 v0, 1, v0
	v_bitop3_b32 v0, v0, v28, 6 bitop3:0x6c
	v_add_u32_e32 v1, 32, v36
	v_lshlrev_b32_e32 v37, 4, v0
	v_add3_u32 v0, v1, v37, v9
	ds_write_b16 v0, v2
	v_or_b32_e32 v0, 5, v11
	v_lshlrev_b32_e32 v38, 7, v0
	v_lshrrev_b32_e32 v0, 1, v0
	v_bitop3_b32 v0, v0, v28, 6 bitop3:0x6c
	v_add_u32_e32 v1, 32, v38
	v_lshlrev_b32_e32 v39, 4, v0
	v_add3_u32 v0, v1, v39, v9
	ds_write_b16_d16_hi v0, v2
	v_add_u32_e32 v0, 0x400, v135
	v_ashrrev_i32_e32 v23, 9, v0
	v_lshlrev_b32_e32 v12, 1, v23
	v_ashrrev_i32_e32 v13, 31, v12
	v_lshlrev_b64 v[0:1], 13, v[12:13]
	v_lshl_add_u64 v[0:1], v[6:7], 0, v[0:1]
	global_load_dwordx4 v[18:21], v[0:1], off
	v_or_b32_e32 v2, 6, v11
	v_lshrrev_b32_e32 v1, 1, v2
	v_lshlrev_b32_e32 v40, 7, v2
	v_bitop3_b32 v1, v1, v28, 7 bitop3:0x6c
	v_add_u32_e32 v0, 32, v40
	v_lshlrev_b32_e32 v41, 4, v1
	v_add3_u32 v0, v0, v41, v9
	ds_write_b16 v0, v3
	v_or_b32_e32 v0, 7, v11
	v_lshlrev_b32_e32 v42, 7, v0
	v_lshrrev_b32_e32 v0, 1, v0
	v_bitop3_b32 v0, v0, v28, 7 bitop3:0x6c
	v_add_u32_e32 v1, 32, v42
	v_lshlrev_b32_e32 v43, 4, v0
	v_lshl_or_b32 v11, v22, 6, v34
	v_add3_u32 v0, v1, v43, v9
	v_lshlrev_b32_e32 v44, 7, v11
	ds_write_b16_d16_hi v0, v3
	v_add_u32_e32 v0, 32, v44
	v_add3_u32 v0, v0, v30, v9
	ds_write_b16 v0, v14
	ds_write_b16_d16_hi v0, v14 offset:128
	v_or_b32_e32 v0, 2, v11
	v_lshlrev_b32_e32 v45, 7, v0
	v_lshrrev_b32_e32 v0, 1, v0
	v_bitop3_b32 v0, v0, v28, 5 bitop3:0x6c
	v_add_u32_e32 v1, 32, v45
	v_lshlrev_b32_e32 v46, 4, v0
	v_add3_u32 v0, v1, v46, v9
	ds_write_b16 v0, v15
	v_or_b32_e32 v0, 3, v11
	v_lshlrev_b32_e32 v47, 7, v0
	v_lshrrev_b32_e32 v0, 1, v0
	v_bitop3_b32 v0, v0, v28, 5 bitop3:0x6c
	v_add_u32_e32 v1, 32, v47
	v_lshlrev_b32_e32 v48, 4, v0
	v_add3_u32 v0, v1, v48, v9
	ds_write_b16_d16_hi v0, v15
	v_or_b32_e32 v0, 4, v11
	v_lshlrev_b32_e32 v49, 7, v0
	v_lshrrev_b32_e32 v0, 1, v0
	v_bitop3_b32 v0, v0, v28, 6 bitop3:0x6c
	v_add_u32_e32 v1, 32, v49
	v_lshlrev_b32_e32 v50, 4, v0
	v_add3_u32 v0, v1, v50, v9
	ds_write_b16 v0, v16
	v_or_b32_e32 v0, 5, v11
	v_lshlrev_b32_e32 v51, 7, v0
	v_lshrrev_b32_e32 v0, 1, v0
	v_bitop3_b32 v0, v0, v28, 6 bitop3:0x6c
	v_add_u32_e32 v1, 32, v51
	v_lshlrev_b32_e32 v52, 4, v0
	v_add3_u32 v0, v1, v52, v9
	ds_write_b16_d16_hi v0, v16
	v_add_u32_e32 v0, 0x600, v135
	v_ashrrev_i32_e32 v13, 9, v0
	v_lshlrev_b32_e32 v14, 1, v13
	v_ashrrev_i32_e32 v15, 31, v14
	v_lshlrev_b64 v[0:1], 13, v[14:15]
	v_lshl_add_u64 v[0:1], v[6:7], 0, v[0:1]
	global_load_dwordx4 v[0:3], v[0:1], off
	v_or_b32_e32 v15, 6, v11
	v_lshlrev_b32_e32 v53, 7, v15
	v_lshrrev_b32_e32 v15, 1, v15
	v_bitop3_b32 v15, v15, v28, 7 bitop3:0x6c
	v_or_b32_e32 v11, 7, v11
	v_add_u32_e32 v16, 32, v53
	v_lshlrev_b32_e32 v15, 4, v15
	v_lshlrev_b32_e32 v54, 7, v11
	v_lshrrev_b32_e32 v11, 1, v11
	v_add3_u32 v16, v16, v15, v9
	v_bitop3_b32 v11, v11, v28, 7 bitop3:0x6c
	ds_write_b16 v16, v17
	v_add_u32_e32 v16, 32, v54
	v_lshlrev_b32_e32 v55, 4, v11
	v_add3_u32 v11, v16, v55, v9
	ds_write_b16_d16_hi v11, v17
	v_lshl_or_b32 v11, v23, 6, v34
	v_lshlrev_b32_e32 v56, 7, v11
	v_add_u32_e32 v16, 32, v56
	v_add3_u32 v16, v16, v30, v9
	s_waitcnt vmcnt(0)
	ds_write_b16 v16, v18
	ds_write_b16_d16_hi v16, v18 offset:128
	v_or_b32_e32 v16, 2, v11
	v_lshlrev_b32_e32 v57, 7, v16
	v_lshrrev_b32_e32 v16, 1, v16
	v_bitop3_b32 v16, v16, v28, 5 bitop3:0x6c
	v_add_u32_e32 v17, 32, v57
	v_lshlrev_b32_e32 v58, 4, v16
	v_add3_u32 v16, v17, v58, v9
	ds_write_b16 v16, v19
	v_or_b32_e32 v16, 3, v11
	v_lshlrev_b32_e32 v59, 7, v16
	v_lshrrev_b32_e32 v16, 1, v16
	v_bitop3_b32 v16, v16, v28, 5 bitop3:0x6c
	v_add_u32_e32 v17, 32, v59
	v_lshlrev_b32_e32 v60, 4, v16
	v_add3_u32 v16, v17, v60, v9
	ds_write_b16_d16_hi v16, v19
	v_or_b32_e32 v16, 4, v11
	v_lshlrev_b32_e32 v61, 7, v16
	v_lshrrev_b32_e32 v16, 1, v16
	v_bitop3_b32 v16, v16, v28, 6 bitop3:0x6c
	v_add_u32_e32 v17, 32, v61
	v_lshlrev_b32_e32 v62, 4, v16
	v_add3_u32 v16, v17, v62, v9
	ds_write_b16 v16, v20
	v_or_b32_e32 v16, 5, v11
	v_lshlrev_b32_e32 v63, 7, v16
	v_lshrrev_b32_e32 v16, 1, v16
	v_bitop3_b32 v16, v16, v28, 6 bitop3:0x6c
	v_add_u32_e32 v17, 32, v63
	v_lshlrev_b32_e32 v64, 4, v16
	v_add3_u32 v16, v17, v64, v9
	ds_write_b16_d16_hi v16, v20
	v_or_b32_e32 v16, 6, v11
	v_lshlrev_b32_e32 v65, 7, v16
	v_lshrrev_b32_e32 v16, 1, v16
	v_bitop3_b32 v16, v16, v28, 7 bitop3:0x6c
	v_add_u32_e32 v17, 32, v65
	v_lshlrev_b32_e32 v66, 4, v16
	v_add3_u32 v16, v17, v66, v9
	ds_write_b16 v16, v21
	v_or_b32_e32 v16, 1, v8
	v_ashrrev_i32_e32 v17, 31, v16
	v_lshlrev_b64 v[16:17], 13, v[16:17]
	v_lshl_add_u64 v[16:17], v[6:7], 0, v[16:17]
	global_load_dwordx4 v[16:19], v[16:17], off
	v_or_b32_e32 v8, 7, v11
	v_lshlrev_b32_e32 v67, 7, v8
	v_lshrrev_b32_e32 v8, 1, v8
	v_bitop3_b32 v8, v8, v28, 7 bitop3:0x6c
	v_add_u32_e32 v11, 32, v67
	v_lshlrev_b32_e32 v8, 4, v8
	v_lshl_or_b32 v34, v13, 6, v34
	v_add3_u32 v11, v11, v8, v9
	v_lshlrev_b32_e32 v68, 7, v34
	ds_write_b16_d16_hi v11, v21
	v_add_u32_e32 v11, 32, v68
	v_add3_u32 v11, v11, v30, v9
	v_or_b32_e32 v10, 1, v10
	ds_write_b16 v11, v0
	ds_write_b16_d16_hi v11, v0 offset:128
	v_ashrrev_i32_e32 v11, 31, v10
	v_or_b32_e32 v0, 2, v34
	v_lshlrev_b64 v[10:11], 13, v[10:11]
	v_lshlrev_b32_e32 v69, 7, v0
	v_lshrrev_b32_e32 v0, 1, v0
	v_lshl_add_u64 v[10:11], v[6:7], 0, v[10:11]
	global_load_dwordx4 v[20:23], v[10:11], off
	v_bitop3_b32 v0, v0, v28, 5 bitop3:0x6c
	v_add_u32_e32 v13, 32, v69
	v_lshlrev_b32_e32 v70, 4, v0
	v_add3_u32 v0, v13, v70, v9
	ds_write_b16 v0, v1
	v_or_b32_e32 v0, 3, v34
	v_lshlrev_b32_e32 v71, 7, v0
	v_lshrrev_b32_e32 v0, 1, v0
	v_bitop3_b32 v0, v0, v28, 5 bitop3:0x6c
	v_add_u32_e32 v10, 32, v71
	v_lshlrev_b32_e32 v72, 4, v0
	v_add3_u32 v0, v10, v72, v9
	ds_write_b16_d16_hi v0, v1
	v_or_b32_e32 v0, 4, v34
	v_lshlrev_b32_e32 v73, 7, v0
	v_lshrrev_b32_e32 v0, 1, v0
	v_bitop3_b32 v25, v0, v28, 6 bitop3:0x6c
	v_or_b32_e32 v0, 1, v12
	v_ashrrev_i32_e32 v1, 31, v0
	v_lshlrev_b64 v[0:1], 13, v[0:1]
	v_add_u32_e32 v24, 32, v73
	v_lshl_add_u64 v[0:1], v[6:7], 0, v[0:1]
	v_lshlrev_b32_e32 v74, 4, v25
	global_load_dwordx4 v[10:13], v[0:1], off
	v_add3_u32 v0, v24, v74, v9
	ds_write_b16 v0, v2
	v_or_b32_e32 v0, 5, v34
	v_lshlrev_b32_e32 v75, 7, v0
	v_lshrrev_b32_e32 v0, 1, v0
	v_bitop3_b32 v0, v0, v28, 6 bitop3:0x6c
	v_add_u32_e32 v1, 32, v75
	v_lshlrev_b32_e32 v76, 4, v0
	v_add3_u32 v0, v1, v76, v9
	ds_write_b16_d16_hi v0, v2
	v_or_b32_e32 v0, 6, v34
	v_lshlrev_b32_e32 v2, 7, v0
	v_lshrrev_b32_e32 v0, 1, v0
	v_bitop3_b32 v0, v0, v28, 7 bitop3:0x6c
	v_lshlrev_b32_e32 v78, 4, v0
	v_or_b32_e32 v0, 1, v14
	v_ashrrev_i32_e32 v1, 31, v0
	v_lshlrev_b64 v[0:1], 13, v[0:1]
	v_lshl_add_u64 v[0:1], v[6:7], 0, v[0:1]
	global_load_dwordx4 v[24:27], v[0:1], off
	v_add_u32_e32 v77, 32, v2
	v_add3_u32 v0, v77, v78, v9
	ds_write_b16 v0, v3
	v_or_b32_e32 v0, 7, v34
	v_lshlrev_b32_e32 v1, 7, v0
	v_lshrrev_b32_e32 v0, 1, v0
	v_bitop3_b32 v0, v0, v28, 7 bitop3:0x6c
	v_add_u32_e32 v6, 32, v1
	v_lshlrev_b32_e32 v0, 4, v0
	v_add3_u32 v6, v6, v0, v9
	ds_write_b16_d16_hi v6, v3
	v_add_u32_e32 v3, s1, v30
	v_add3_u32 v6, v3, v29, v9
	v_add_u32_e32 v2, s1, v2
	s_waitcnt vmcnt(0)
	ds_write_b16 v6, v16
	v_add_u32_e32 v6, v3, v9
	v_add_u32_e32 v7, v6, v29
	ds_write_b16_d16_hi v7, v16 offset:128
	v_add_u32_e32 v7, s1, v31
	v_add3_u32 v7, v7, v32, v9
	ds_write_b16 v7, v17
	v_add_u32_e32 v7, s1, v33
	v_add3_u32 v7, v7, v35, v9
	ds_write_b16_d16_hi v7, v17
	v_add_u32_e32 v7, s1, v36
	v_add3_u32 v7, v7, v37, v9
	ds_write_b16 v7, v18
	v_add_u32_e32 v7, s1, v38
	v_add3_u32 v7, v7, v39, v9
	ds_write_b16_d16_hi v7, v18
	v_add_u32_e32 v7, s1, v40
	v_add3_u32 v7, v7, v41, v9
	ds_write_b16 v7, v19
	v_add_u32_e32 v7, s1, v42
	v_add3_u32 v7, v7, v43, v9
	ds_write_b16_d16_hi v7, v19
	v_add3_u32 v7, v3, v44, v9
	ds_write_b16 v7, v20
	v_add_u32_e32 v7, v6, v44
	ds_write_b16_d16_hi v7, v20 offset:128
	v_add_u32_e32 v7, s1, v45
	v_add3_u32 v7, v7, v46, v9
	ds_write_b16 v7, v21
	v_add_u32_e32 v7, s1, v47
	v_add3_u32 v7, v7, v48, v9
	ds_write_b16_d16_hi v7, v21
	v_add_u32_e32 v7, s1, v49
	v_add3_u32 v7, v7, v50, v9
	ds_write_b16 v7, v22
	v_add_u32_e32 v7, s1, v51
	v_add3_u32 v7, v7, v52, v9
	ds_write_b16_d16_hi v7, v22
	v_add_u32_e32 v7, s1, v53
	v_add3_u32 v7, v7, v15, v9
	ds_write_b16 v7, v23
	v_add_u32_e32 v7, s1, v54
	v_add3_u32 v7, v7, v55, v9
	ds_write_b16_d16_hi v7, v23
	v_add3_u32 v7, v3, v56, v9
	ds_write_b16 v7, v10
	v_add_u32_e32 v7, v6, v56
	ds_write_b16_d16_hi v7, v10 offset:128
	v_add_u32_e32 v7, s1, v57
	v_add3_u32 v7, v7, v58, v9
	ds_write_b16 v7, v11
	v_add_u32_e32 v7, s1, v59
	v_add3_u32 v7, v7, v60, v9
	ds_write_b16_d16_hi v7, v11
	v_add_u32_e32 v7, s1, v61
	v_add3_u32 v7, v7, v62, v9
	ds_write_b16 v7, v12
	v_add_u32_e32 v7, s1, v63
	v_add3_u32 v7, v7, v64, v9
	ds_write_b16_d16_hi v7, v12
	v_add_u32_e32 v7, s1, v65
	v_add3_u32 v7, v7, v66, v9
	ds_write_b16 v7, v13
	v_add_u32_e32 v7, s1, v67
	v_add3_u32 v7, v7, v8, v9
	v_add3_u32 v3, v3, v68, v9
	ds_write_b16_d16_hi v7, v13
	ds_write_b16 v3, v24
	v_add_u32_e32 v3, v6, v68
	ds_write_b16_d16_hi v3, v24 offset:128
	v_add_u32_e32 v3, s1, v69
	v_add3_u32 v3, v3, v70, v9
	ds_write_b16 v3, v25
	v_add_u32_e32 v3, s1, v71
	v_add3_u32 v3, v3, v72, v9
	ds_write_b16_d16_hi v3, v25
	v_add_u32_e32 v3, s1, v73
	v_add3_u32 v3, v3, v74, v9
	ds_write_b16 v3, v26
	v_add_u32_e32 v3, s1, v75
	v_add3_u32 v3, v3, v76, v9
	v_add_u32_e32 v1, s1, v1
	ds_write_b16_d16_hi v3, v26
	v_add3_u32 v2, v2, v78, v9
	v_add3_u32 v0, v1, v0, v9
	v_lshrrev_b32_e32 v1, 5, v135
	v_bfe_u32 v3, v135, 1, 3
	ds_write_b16 v2, v27
	ds_write_b16_d16_hi v0, v27
	v_and_b32_e32 v0, 31, v135
	v_lshrrev_b32_e32 v2, 1, v135
	v_bitop3_b32 v1, v1, v3, 1 bitop3:0x6c
	s_mov_b32 s6, 0x1ffff80
	v_lshlrev_b32_e32 v1, 4, v1
	v_lshlrev_b32_e32 v6, 7, v135
	v_and_or_b32 v2, v2, s6, v0
	v_add_u32_e32 v10, 32, v1
	v_and_b32_e32 v136, 0x6f80, v6
	v_lshlrev_b32_e32 v2, 7, v2
	v_add_u32_e32 v14, v10, v136
	v_add_u32_e32 v18, v10, v2
	s_waitcnt vmcnt(0)
	s_waitcnt lgkmcnt(0)
	s_barrier
	ds_read_b128 v[6:9], v14 offset:32768
	ds_read_b128 v[10:13], v18
	ds_read_b128 v[14:17], v14 offset:36864
	v_bitop3_b32 v139, v137, v3, 2 bitop3:0x36
	v_lshlrev_b32_e32 v139, 4, v139
	v_add_u32_e32 v148, 32, v139
	v_add_u32_e32 v152, v148, v136
	s_waitcnt lgkmcnt(1)
	v_mfma_f32_32x32x16_bf16 v[118:133], v[6:9], v[10:13], 0
	ds_read_b128 v[144:147], v152 offset:32768
	ds_read_b128 v[152:155], v152 offset:36864
	v_add_u32_e32 v156, v148, v2
	ds_read_b128 v[148:151], v156
	s_add_i32 s6, 32, 0x18000
	s_waitcnt lgkmcnt(3)
	v_mfma_f32_32x32x16_bf16 v[102:117], v[14:17], v[10:13], 0
	ds_read_b128 v[10:13], v18 offset:4096
	s_waitcnt lgkmcnt(0)
	v_mfma_f32_32x32x16_bf16 v[86:101], v[6:9], v[10:13], 0
	v_mfma_f32_32x32x16_bf16 v[70:85], v[14:17], v[10:13], 0
	ds_read_b128 v[10:13], v18 offset:8192
	s_waitcnt lgkmcnt(0)
	v_mfma_f32_32x32x16_bf16 v[54:69], v[6:9], v[10:13], 0
	v_mfma_f32_32x32x16_bf16 v[38:53], v[14:17], v[10:13], 0
	ds_read_b128 v[10:13], v18 offset:12288
	v_mfma_f32_32x32x16_bf16 v[118:133], v[144:147], v[148:151], v[118:133]
	v_mfma_f32_32x32x16_bf16 v[102:117], v[152:155], v[148:151], v[102:117]
	ds_read_b128 v[148:151], v156 offset:4096
	s_waitcnt lgkmcnt(0)
	v_mfma_f32_32x32x16_bf16 v[86:101], v[144:147], v[148:151], v[86:101]
	v_mfma_f32_32x32x16_bf16 v[70:85], v[152:155], v[148:151], v[70:85]
	ds_read_b128 v[148:151], v156 offset:8192
	v_mfma_f32_32x32x16_bf16 v[22:37], v[6:9], v[10:13], 0
	v_mfma_f32_32x32x16_bf16 v[6:21], v[14:17], v[10:13], 0
	s_waitcnt lgkmcnt(0)
	v_mfma_f32_32x32x16_bf16 v[54:69], v[144:147], v[148:151], v[54:69]
	v_mfma_f32_32x32x16_bf16 v[38:53], v[152:155], v[148:151], v[38:53]
	ds_read_b128 v[148:151], v156 offset:12288
	s_waitcnt lgkmcnt(0)
	v_mfma_f32_32x32x16_bf16 v[22:37], v[144:147], v[148:151], v[22:37]
	v_bitop3_b32 v144, v137, v3, 4 bitop3:0x36
	v_lshlrev_b32_e32 v156, 4, v144
	v_bitop3_b32 v3, v137, v3, 6 bitop3:0x36
	v_lshlrev_b32_e32 v3, 4, v3
	v_add_u32_e32 v137, 32, v3
	v_mfma_f32_32x32x16_bf16 v[6:21], v[152:155], v[148:151], v[6:21]
	v_add_u32_e32 v148, 32, v156
	v_add_u32_e32 v152, v148, v136
	v_add_u32_e32 v157, v148, v2
	ds_read_b128 v[144:147], v152 offset:32768
	ds_read_b128 v[148:151], v157
	ds_read_b128 v[152:155], v152 offset:36864
	s_waitcnt lgkmcnt(1)
	v_mfma_f32_32x32x16_bf16 v[118:133], v[144:147], v[148:151], v[118:133]
	s_waitcnt lgkmcnt(0)
	v_mfma_f32_32x32x16_bf16 v[102:117], v[152:155], v[148:151], v[102:117]
	ds_read_b128 v[148:151], v157 offset:4096
	s_waitcnt lgkmcnt(0)
	v_mfma_f32_32x32x16_bf16 v[86:101], v[144:147], v[148:151], v[86:101]
	v_mfma_f32_32x32x16_bf16 v[70:85], v[152:155], v[148:151], v[70:85]
	ds_read_b128 v[148:151], v157 offset:8192
	s_waitcnt lgkmcnt(0)
	v_mfma_f32_32x32x16_bf16 v[54:69], v[144:147], v[148:151], v[54:69]
	v_mfma_f32_32x32x16_bf16 v[38:53], v[152:155], v[148:151], v[38:53]
	ds_read_b128 v[148:151], v157 offset:12288
	s_waitcnt lgkmcnt(0)
	v_mfma_f32_32x32x16_bf16 v[6:21], v[152:155], v[148:151], v[6:21]
	v_add_u32_e32 v152, v137, v136
	v_add_u32_e32 v137, v137, v2
	v_mfma_f32_32x32x16_bf16 v[22:37], v[144:147], v[148:151], v[22:37]
	ds_read_b128 v[144:147], v152 offset:32768
	ds_read_b128 v[148:151], v137
	ds_read_b128 v[152:155], v152 offset:36864
	s_waitcnt lgkmcnt(1)
	v_mfma_f32_32x32x16_bf16 v[118:133], v[144:147], v[148:151], v[118:133]
	s_waitcnt lgkmcnt(0)
	v_mfma_f32_32x32x16_bf16 v[102:117], v[152:155], v[148:151], v[102:117]
	ds_read_b128 v[148:151], v137 offset:4096
	s_waitcnt lgkmcnt(0)
	v_mfma_f32_32x32x16_bf16 v[86:101], v[144:147], v[148:151], v[86:101]
	v_mfma_f32_32x32x16_bf16 v[70:85], v[152:155], v[148:151], v[70:85]
	ds_read_b128 v[148:151], v137 offset:8192
	s_waitcnt lgkmcnt(0)
	v_mfma_f32_32x32x16_bf16 v[54:69], v[144:147], v[148:151], v[54:69]
	v_mfma_f32_32x32x16_bf16 v[38:53], v[152:155], v[148:151], v[38:53]
	ds_read_b128 v[148:151], v137 offset:12288
	v_add3_u32 v137, s6, v1, v136
	v_add3_u32 v1, s1, v1, v2
	s_waitcnt lgkmcnt(0)
	v_mfma_f32_32x32x16_bf16 v[22:37], v[144:147], v[148:151], v[22:37]
	ds_read_b128 v[144:147], v137
	v_mfma_f32_32x32x16_bf16 v[6:21], v[152:155], v[148:151], v[6:21]
	ds_read_b128 v[152:155], v137 offset:4096
	ds_read_b128 v[148:151], v1
	v_add3_u32 v137, s1, v139, v2
	s_waitcnt lgkmcnt(0)
	v_mfma_f32_32x32x16_bf16 v[118:133], v[144:147], v[148:151], v[118:133]
	v_mfma_f32_32x32x16_bf16 v[102:117], v[152:155], v[148:151], v[102:117]
	ds_read_b128 v[148:151], v1 offset:4096
	s_waitcnt lgkmcnt(0)
	v_mfma_f32_32x32x16_bf16 v[86:101], v[144:147], v[148:151], v[86:101]
	v_mfma_f32_32x32x16_bf16 v[70:85], v[152:155], v[148:151], v[70:85]
	ds_read_b128 v[148:151], v1 offset:8192
	s_waitcnt lgkmcnt(0)
	v_mfma_f32_32x32x16_bf16 v[54:69], v[144:147], v[148:151], v[54:69]
	v_mfma_f32_32x32x16_bf16 v[38:53], v[152:155], v[148:151], v[38:53]
	ds_read_b128 v[148:151], v1 offset:12288
	v_add3_u32 v1, s6, v139, v136
	s_waitcnt lgkmcnt(0)
	v_mfma_f32_32x32x16_bf16 v[22:37], v[144:147], v[148:151], v[22:37]
	ds_read_b128 v[144:147], v1
	v_mfma_f32_32x32x16_bf16 v[6:21], v[152:155], v[148:151], v[6:21]
	ds_read_b128 v[152:155], v1 offset:4096
	ds_read_b128 v[148:151], v137
	v_add3_u32 v1, s6, v156, v136
	s_waitcnt lgkmcnt(0)
	v_mfma_f32_32x32x16_bf16 v[118:133], v[144:147], v[148:151], v[118:133]
	v_mfma_f32_32x32x16_bf16 v[102:117], v[152:155], v[148:151], v[102:117]
	ds_read_b128 v[148:151], v137 offset:4096
	s_waitcnt lgkmcnt(0)
	v_mfma_f32_32x32x16_bf16 v[86:101], v[144:147], v[148:151], v[86:101]
	v_mfma_f32_32x32x16_bf16 v[70:85], v[152:155], v[148:151], v[70:85]
	ds_read_b128 v[148:151], v137 offset:8192
	s_waitcnt lgkmcnt(0)
	v_mfma_f32_32x32x16_bf16 v[54:69], v[144:147], v[148:151], v[54:69]
	v_mfma_f32_32x32x16_bf16 v[38:53], v[152:155], v[148:151], v[38:53]
	ds_read_b128 v[148:151], v137 offset:12288
	v_add3_u32 v137, s1, v156, v2
	v_add3_u32 v2, s1, v3, v2
	s_movk_i32 s1, 0x80
	s_waitcnt lgkmcnt(0)
	v_mfma_f32_32x32x16_bf16 v[22:37], v[144:147], v[148:151], v[22:37]
	ds_read_b128 v[144:147], v1
	v_mfma_f32_32x32x16_bf16 v[6:21], v[152:155], v[148:151], v[6:21]
	ds_read_b128 v[152:155], v1 offset:4096
	ds_read_b128 v[148:151], v137
	v_add3_u32 v1, s6, v3, v136
	s_waitcnt lgkmcnt(0)
	v_mfma_f32_32x32x16_bf16 v[118:133], v[144:147], v[148:151], v[118:133]
	v_mfma_f32_32x32x16_bf16 v[102:117], v[152:155], v[148:151], v[102:117]
	ds_read_b128 v[148:151], v137 offset:4096
	s_waitcnt lgkmcnt(0)
	v_mfma_f32_32x32x16_bf16 v[86:101], v[144:147], v[148:151], v[86:101]
	v_mfma_f32_32x32x16_bf16 v[70:85], v[152:155], v[148:151], v[70:85]
	ds_read_b128 v[148:151], v137 offset:8192
	s_waitcnt lgkmcnt(0)
	v_mfma_f32_32x32x16_bf16 v[54:69], v[144:147], v[148:151], v[54:69]
	v_mfma_f32_32x32x16_bf16 v[38:53], v[152:155], v[148:151], v[38:53]
	ds_read_b128 v[148:151], v137 offset:12288
	s_waitcnt lgkmcnt(0)
	v_mfma_f32_32x32x16_bf16 v[22:37], v[144:147], v[148:151], v[22:37]
	ds_read_b128 v[144:147], v1
	v_mfma_f32_32x32x16_bf16 v[6:21], v[152:155], v[148:151], v[6:21]
	ds_read_b128 v[152:155], v1 offset:4096
	ds_read_b128 v[148:151], v2
	v_and_b32_e32 v1, 0xc0, v135
	v_cmp_gt_u32_e32 vcc, s1, v1
	s_waitcnt lgkmcnt(0)
	v_mfma_f32_32x32x16_bf16 v[118:133], v[144:147], v[148:151], v[118:133]
	v_mfma_f32_32x32x16_bf16 v[102:117], v[152:155], v[148:151], v[102:117]
	ds_read_b128 v[148:151], v2 offset:4096
	s_waitcnt lgkmcnt(0)
	v_mfma_f32_32x32x16_bf16 v[86:101], v[144:147], v[148:151], v[86:101]
	v_mfma_f32_32x32x16_bf16 v[70:85], v[152:155], v[148:151], v[70:85]
	ds_read_b128 v[148:151], v2 offset:8192
	s_waitcnt lgkmcnt(0)
	v_mfma_f32_32x32x16_bf16 v[54:69], v[144:147], v[148:151], v[54:69]
	v_mfma_f32_32x32x16_bf16 v[38:53], v[152:155], v[148:151], v[38:53]
	ds_read_b128 v[148:151], v2 offset:12288
	s_waitcnt lgkmcnt(0)
	s_barrier
	v_mfma_f32_32x32x16_bf16 v[22:37], v[144:147], v[148:151], v[22:37]
	v_mfma_f32_32x32x16_bf16 v[6:21], v[152:155], v[148:151], v[6:21]
	s_and_saveexec_b64 s[6:7], vcc
	s_cbranch_execz .LBB0_853
	v_ashrrev_i32_e32 v135, 7, v135
	v_readlane_b32 s1, v254, 42
	v_and_b32_e32 v2, -2, v135
	s_add_u32 s4, s1, s4
	v_readlane_b32 s1, v254, 43
	v_ashrrev_i32_e32 v3, 31, v2
	s_addc_u32 s5, s1, s5
	v_lshlrev_b64 v[2:3], 14, v[2:3]
	v_lshlrev_b32_e32 v136, 1, v0
	v_lshlrev_b32_e32 v0, 7, v134
	s_movk_i32 s1, 0x200
	v_lshl_add_u64 v[2:3], s[4:5], 0, v[2:3]
	v_mov_b32_e32 v137, v4
	v_and_or_b32 v0, v0, s1, v1
	v_lshl_add_u64 v[2:3], v[2:3], 0, v[136:137]
	v_lshlrev_b32_e32 v0, 1, v0
	v_mov_b32_e32 v1, v4
	v_cvt_pk_bf16_f32 v118, v118, s0
	v_lshl_add_u64 v[2:3], v[2:3], 0, v[0:1]
	global_store_short v[2:3], v118, off nt
	v_cvt_pk_bf16_f32 v118, v119, s0
	global_store_short v[2:3], v118, off offset:256 nt
	v_cvt_pk_bf16_f32 v118, v120, s0
	global_store_short v[2:3], v118, off offset:512 nt
	v_cvt_pk_bf16_f32 v118, v121, s0
	global_store_short v[2:3], v118, off offset:768 nt
	v_cvt_pk_bf16_f32 v118, v122, s0
	global_store_short v[2:3], v118, off offset:2048 nt
	v_cvt_pk_bf16_f32 v118, v123, s0
	global_store_short v[2:3], v118, off offset:2304 nt
	v_cvt_pk_bf16_f32 v118, v124, s0
	global_store_short v[2:3], v118, off offset:2560 nt
	v_cvt_pk_bf16_f32 v118, v125, s0
	s_movk_i32 s1, 0x1000
	global_store_short v[2:3], v118, off offset:2816 nt
	v_add_co_u32_e32 v118, vcc, s1, v2
	v_cvt_pk_bf16_f32 v102, v102, s0
	s_nop 0
	v_addc_co_u32_e32 v119, vcc, 0, v3, vcc
	v_add_co_u32_e32 v120, vcc, s88, v2
	v_cvt_pk_bf16_f32 v86, v86, s0
	s_nop 0
	v_addc_co_u32_e32 v121, vcc, 0, v3, vcc
	global_store_short v[120:121], v102, off nt
	v_cvt_pk_bf16_f32 v102, v103, s0
	global_store_short v[2:3], v86, off offset:64 nt
	v_cvt_pk_bf16_f32 v86, v87, s0
	global_store_short v[120:121], v102, off offset:256 nt
	v_cvt_pk_bf16_f32 v102, v104, s0
	global_store_short v[2:3], v86, off offset:320 nt
	v_cvt_pk_bf16_f32 v86, v88, s0
	global_store_short v[120:121], v102, off offset:512 nt
	v_cvt_pk_bf16_f32 v102, v105, s0
	global_store_short v[2:3], v86, off offset:576 nt
	v_cvt_pk_bf16_f32 v86, v89, s0
	global_store_short v[120:121], v102, off offset:768 nt
	v_cvt_pk_bf16_f32 v102, v106, s0
	global_store_short v[2:3], v86, off offset:832 nt
	v_cvt_pk_bf16_f32 v86, v90, s0
	global_store_short v[120:121], v102, off offset:2048 nt
	v_cvt_pk_bf16_f32 v102, v107, s0
	global_store_short v[2:3], v86, off offset:2112 nt
	v_cvt_pk_bf16_f32 v86, v91, s0
	global_store_short v[120:121], v102, off offset:2304 nt
	v_cvt_pk_bf16_f32 v102, v108, s0
	global_store_short v[2:3], v86, off offset:2368 nt
	v_cvt_pk_bf16_f32 v86, v92, s0
	global_store_short v[120:121], v102, off offset:2560 nt
	v_cvt_pk_bf16_f32 v102, v109, s0
	s_movk_i32 s10, 0x3000
	global_store_short v[2:3], v86, off offset:2624 nt
	v_cvt_pk_bf16_f32 v86, v93, s0
	global_store_short v[120:121], v102, off offset:2816 nt
	v_add_co_u32_e32 v102, vcc, s10, v2
	global_store_short v[2:3], v86, off offset:2880 nt
	v_cvt_pk_bf16_f32 v2, v94, s0
	global_store_short v[118:119], v2, off offset:64 nt
	v_cvt_pk_bf16_f32 v2, v95, s0
	global_store_short v[118:119], v2, off offset:320 nt
	v_cvt_pk_bf16_f32 v2, v96, s0
	global_store_short v[118:119], v2, off offset:576 nt
	v_cvt_pk_bf16_f32 v2, v97, s0
	global_store_short v[118:119], v2, off offset:832 nt
	v_cvt_pk_bf16_f32 v2, v98, s0
	global_store_short v[118:119], v2, off offset:2112 nt
	v_cvt_pk_bf16_f32 v2, v99, s0
	global_store_short v[118:119], v2, off offset:2368 nt
	v_cvt_pk_bf16_f32 v2, v100, s0
	global_store_short v[118:119], v2, off offset:2624 nt
	v_cvt_pk_bf16_f32 v2, v101, s0
	global_store_short v[118:119], v2, off offset:2880 nt
	v_cvt_pk_bf16_f32 v2, v70, s0
	global_store_short v[120:121], v2, off offset:64 nt
	v_cvt_pk_bf16_f32 v2, v71, s0
	global_store_short v[120:121], v2, off offset:320 nt
	v_cvt_pk_bf16_f32 v2, v72, s0
	global_store_short v[120:121], v2, off offset:576 nt
	v_cvt_pk_bf16_f32 v2, v73, s0
	global_store_short v[120:121], v2, off offset:832 nt
	v_cvt_pk_bf16_f32 v2, v74, s0
	global_store_short v[120:121], v2, off offset:2112 nt
	v_cvt_pk_bf16_f32 v2, v75, s0
	global_store_short v[120:121], v2, off offset:2368 nt
	v_cvt_pk_bf16_f32 v2, v76, s0
	global_store_short v[120:121], v2, off offset:2624 nt
	v_cvt_pk_bf16_f32 v2, v77, s0
	v_addc_co_u32_e32 v103, vcc, 0, v3, vcc
	global_store_short v[120:121], v2, off offset:2880 nt
	v_cvt_pk_bf16_f32 v2, v78, s0
	global_store_short v[102:103], v2, off offset:64 nt
	v_cvt_pk_bf16_f32 v2, v79, s0
	global_store_short v[102:103], v2, off offset:320 nt
	v_cvt_pk_bf16_f32 v2, v80, s0
	global_store_short v[102:103], v2, off offset:576 nt
	v_cvt_pk_bf16_f32 v2, v81, s0
	global_store_short v[102:103], v2, off offset:832 nt
	v_cvt_pk_bf16_f32 v2, v82, s0
	global_store_short v[102:103], v2, off offset:2112 nt
	v_cvt_pk_bf16_f32 v2, v83, s0
	global_store_short v[102:103], v2, off offset:2368 nt
	v_cvt_pk_bf16_f32 v2, v84, s0
	global_store_short v[102:103], v2, off offset:2624 nt
	v_cvt_pk_bf16_f32 v2, v85, s0
	global_store_short v[102:103], v2, off offset:2880 nt
	v_or_b32_e32 v2, 1, v135
	v_ashrrev_i32_e32 v3, 31, v2
	v_lshlrev_b64 v[2:3], 14, v[2:3]
	v_lshl_add_u64 v[2:3], s[4:5], 0, v[2:3]
	v_lshl_add_u64 v[2:3], v[2:3], 0, v[136:137]
	v_lshl_add_u64 v[0:1], v[2:3], 0, v[0:1]
	v_cvt_pk_bf16_f32 v2, v55, s0
	global_store_short v[0:1], v2, off offset:256 nt
	v_cvt_pk_bf16_f32 v2, v56, s0
	global_store_short v[0:1], v2, off offset:512 nt
	v_cvt_pk_bf16_f32 v2, v57, s0
	global_store_short v[0:1], v2, off offset:768 nt
	v_cvt_pk_bf16_f32 v2, v58, s0
	global_store_short v[0:1], v2, off offset:2048 nt
	v_cvt_pk_bf16_f32 v2, v59, s0
	global_store_short v[0:1], v2, off offset:2304 nt
	v_cvt_pk_bf16_f32 v2, v60, s0
	global_store_short v[0:1], v2, off offset:2560 nt
	v_cvt_pk_bf16_f32 v2, v61, s0
	global_store_short v[0:1], v2, off offset:2816 nt
	v_add_co_u32_e32 v2, vcc, s1, v0
	v_cvt_pk_bf16_f32 v54, v54, s0
	s_nop 0
	v_addc_co_u32_e32 v3, vcc, 0, v1, vcc
	global_store_short v[0:1], v54, off nt
	v_add_co_u32_e32 v54, vcc, s88, v0
	v_cvt_pk_bf16_f32 v38, v38, s0
	s_nop 0
	v_addc_co_u32_e32 v55, vcc, 0, v1, vcc
	v_cvt_pk_bf16_f32 v22, v22, s0
	global_store_short v[54:55], v38, off nt
	v_cvt_pk_bf16_f32 v38, v39, s0
	global_store_short v[0:1], v22, off offset:64 nt
	v_cvt_pk_bf16_f32 v22, v23, s0
	global_store_short v[54:55], v38, off offset:256 nt
	v_cvt_pk_bf16_f32 v38, v40, s0
	global_store_short v[0:1], v22, off offset:320 nt
	v_cvt_pk_bf16_f32 v22, v24, s0
	global_store_short v[54:55], v38, off offset:512 nt
	v_cvt_pk_bf16_f32 v38, v41, s0
	global_store_short v[0:1], v22, off offset:576 nt
	v_cvt_pk_bf16_f32 v22, v25, s0
	global_store_short v[54:55], v38, off offset:768 nt
	v_cvt_pk_bf16_f32 v38, v42, s0
	global_store_short v[0:1], v22, off offset:832 nt
	v_cvt_pk_bf16_f32 v22, v26, s0
	global_store_short v[54:55], v38, off offset:2048 nt
	v_cvt_pk_bf16_f32 v38, v43, s0
	global_store_short v[0:1], v22, off offset:2112 nt
	v_cvt_pk_bf16_f32 v22, v27, s0
	global_store_short v[54:55], v38, off offset:2304 nt
	v_cvt_pk_bf16_f32 v38, v44, s0
	global_store_short v[0:1], v22, off offset:2368 nt
	v_cvt_pk_bf16_f32 v22, v28, s0
	global_store_short v[54:55], v38, off offset:2560 nt
	v_cvt_pk_bf16_f32 v38, v45, s0
	global_store_short v[0:1], v22, off offset:2624 nt
	v_cvt_pk_bf16_f32 v22, v29, s0
	global_store_short v[54:55], v38, off offset:2816 nt
	v_add_co_u32_e32 v38, vcc, s10, v0
	global_store_short v[0:1], v22, off offset:2880 nt
	v_cvt_pk_bf16_f32 v0, v30, s0
	global_store_short v[2:3], v0, off offset:64 nt
	v_cvt_pk_bf16_f32 v0, v31, s0
	global_store_short v[2:3], v0, off offset:320 nt
	v_cvt_pk_bf16_f32 v0, v32, s0
	global_store_short v[2:3], v0, off offset:576 nt
	v_cvt_pk_bf16_f32 v0, v33, s0
	global_store_short v[2:3], v0, off offset:832 nt
	v_cvt_pk_bf16_f32 v0, v34, s0
	global_store_short v[2:3], v0, off offset:2112 nt
	v_cvt_pk_bf16_f32 v0, v35, s0
	global_store_short v[2:3], v0, off offset:2368 nt
	v_cvt_pk_bf16_f32 v0, v36, s0
	global_store_short v[2:3], v0, off offset:2624 nt
	v_cvt_pk_bf16_f32 v0, v37, s0
	global_store_short v[2:3], v0, off offset:2880 nt
	v_cvt_pk_bf16_f32 v0, v6, s0
	global_store_short v[54:55], v0, off offset:64 nt
	v_cvt_pk_bf16_f32 v0, v7, s0
	global_store_short v[54:55], v0, off offset:320 nt
	v_cvt_pk_bf16_f32 v0, v8, s0
	global_store_short v[54:55], v0, off offset:576 nt
	v_cvt_pk_bf16_f32 v0, v9, s0
	global_store_short v[54:55], v0, off offset:832 nt
	v_cvt_pk_bf16_f32 v0, v10, s0
	global_store_short v[54:55], v0, off offset:2112 nt
	v_cvt_pk_bf16_f32 v0, v11, s0
	global_store_short v[54:55], v0, off offset:2368 nt
	v_cvt_pk_bf16_f32 v0, v12, s0
	global_store_short v[54:55], v0, off offset:2624 nt
	v_cvt_pk_bf16_f32 v0, v13, s0
	v_cvt_pk_bf16_f32 v122, v126, s0
	v_cvt_pk_bf16_f32 v104, v110, s0
	v_cvt_pk_bf16_f32 v56, v62, s0
	v_cvt_pk_bf16_f32 v40, v46, s0
	v_addc_co_u32_e32 v39, vcc, 0, v1, vcc
	global_store_short v[54:55], v0, off offset:2880 nt
	v_cvt_pk_bf16_f32 v0, v14, s0
	global_store_short v[120:121], v122, off offset:-4096 nt
	v_cvt_pk_bf16_f32 v122, v127, s0
	global_store_short v[102:103], v104, off nt
	v_cvt_pk_bf16_f32 v104, v111, s0
	global_store_short v[54:55], v56, off offset:-4096 nt
	v_cvt_pk_bf16_f32 v56, v63, s0
	global_store_short v[38:39], v40, off nt
	v_cvt_pk_bf16_f32 v40, v47, s0
	global_store_short v[38:39], v0, off offset:64 nt
	v_cvt_pk_bf16_f32 v0, v15, s0
	global_store_short v[118:119], v122, off offset:256 nt
	v_cvt_pk_bf16_f32 v122, v128, s0
	global_store_short v[102:103], v104, off offset:256 nt
	v_cvt_pk_bf16_f32 v104, v112, s0
	global_store_short v[2:3], v56, off offset:256 nt
	v_cvt_pk_bf16_f32 v56, v64, s0
	global_store_short v[38:39], v40, off offset:256 nt
	v_cvt_pk_bf16_f32 v40, v48, s0
	global_store_short v[38:39], v0, off offset:320 nt
	v_cvt_pk_bf16_f32 v0, v16, s0
	global_store_short v[118:119], v122, off offset:512 nt
	v_cvt_pk_bf16_f32 v122, v129, s0
	global_store_short v[102:103], v104, off offset:512 nt
	v_cvt_pk_bf16_f32 v104, v113, s0
	global_store_short v[2:3], v56, off offset:512 nt
	v_cvt_pk_bf16_f32 v56, v65, s0
	global_store_short v[38:39], v40, off offset:512 nt
	v_cvt_pk_bf16_f32 v40, v49, s0
	global_store_short v[38:39], v0, off offset:576 nt
	v_cvt_pk_bf16_f32 v0, v17, s0
	global_store_short v[118:119], v122, off offset:768 nt
	v_cvt_pk_bf16_f32 v122, v130, s0
	global_store_short v[102:103], v104, off offset:768 nt
	v_cvt_pk_bf16_f32 v104, v114, s0
	global_store_short v[2:3], v56, off offset:768 nt
	v_cvt_pk_bf16_f32 v56, v66, s0
	global_store_short v[38:39], v40, off offset:768 nt
	v_cvt_pk_bf16_f32 v40, v50, s0
	global_store_short v[38:39], v0, off offset:832 nt
	v_cvt_pk_bf16_f32 v0, v18, s0
	global_store_short v[118:119], v122, off offset:2048 nt
	v_cvt_pk_bf16_f32 v122, v131, s0
	global_store_short v[102:103], v104, off offset:2048 nt
	v_cvt_pk_bf16_f32 v104, v115, s0
	global_store_short v[2:3], v56, off offset:2048 nt
	v_cvt_pk_bf16_f32 v56, v67, s0
	global_store_short v[38:39], v40, off offset:2048 nt
	v_cvt_pk_bf16_f32 v40, v51, s0
	global_store_short v[38:39], v0, off offset:2112 nt
	v_cvt_pk_bf16_f32 v0, v19, s0
	global_store_short v[118:119], v122, off offset:2304 nt
	v_cvt_pk_bf16_f32 v122, v132, s0
	global_store_short v[102:103], v104, off offset:2304 nt
	v_cvt_pk_bf16_f32 v104, v116, s0
	global_store_short v[2:3], v56, off offset:2304 nt
	v_cvt_pk_bf16_f32 v56, v68, s0
	global_store_short v[38:39], v40, off offset:2304 nt
	v_cvt_pk_bf16_f32 v40, v52, s0
	global_store_short v[38:39], v0, off offset:2368 nt
	v_cvt_pk_bf16_f32 v0, v20, s0
	global_store_short v[118:119], v122, off offset:2560 nt
	v_cvt_pk_bf16_f32 v122, v133, s0
	global_store_short v[102:103], v104, off offset:2560 nt
	v_cvt_pk_bf16_f32 v104, v117, s0
	global_store_short v[2:3], v56, off offset:2560 nt
	v_cvt_pk_bf16_f32 v56, v69, s0
	global_store_short v[38:39], v40, off offset:2560 nt
	v_cvt_pk_bf16_f32 v40, v53, s0
	global_store_short v[38:39], v0, off offset:2624 nt
	v_cvt_pk_bf16_f32 v0, v21, s0
	global_store_short v[118:119], v122, off offset:2816 nt
	global_store_short v[102:103], v104, off offset:2816 nt
	global_store_short v[2:3], v56, off offset:2816 nt
	global_store_short v[38:39], v40, off offset:2816 nt
	global_store_short v[38:39], v0, off offset:2880 nt
	s_branch .LBB0_853

.LBB0_915:
	s_or_b64 exec, exec, s[0:1]
	v_lshl_add_u64 v[0:1], s[26:27], 0, v[24:25]
	v_add_u32_e32 v24, v148, v121
	v_ashrrev_i32_e32 v25, 31, v24
	v_lshlrev_b64 v[22:23], v22, v[24:25]
	v_mov_b32_e32 v39, v4
	v_lshl_add_u64 v[22:23], v[22:23], 0, v[38:39]
	v_mad_u64_u32 v[0:1], s[0:1], v22, s50, v[0:1]
	v_mad_i32_i24 v1, v23, s50, v1
	v_lshl_add_u64 v[0:1], v[118:119], 1, v[0:1]
	v_mov_b32_e32 v3, v4
	v_lshl_add_u64 v[0:1], v[0:1], 0, v[2:3]
	v_pk_mul_f32 v[2:3], v[6:7], s[64:65] op_sel_hi:[1,0]
	v_pk_mul_f32 v[6:7], v[8:9], s[64:65] op_sel_hi:[1,0]
	v_cvt_pk_bf16_f32 v2, v2, v3
	v_cvt_pk_bf16_f32 v3, v6, v7
	global_store_dwordx2 v[0:1], v[2:3], off nt
	v_pk_mul_f32 v[2:3], v[10:11], s[64:65] op_sel_hi:[1,0]
	v_pk_mul_f32 v[6:7], v[12:13], s[64:65] op_sel_hi:[1,0]
	v_cvt_pk_bf16_f32 v2, v2, v3
	v_cvt_pk_bf16_f32 v3, v6, v7
	global_store_dwordx2 v[0:1], v[2:3], off offset:16 nt
	v_pk_mul_f32 v[2:3], v[14:15], s[64:65] op_sel_hi:[1,0]
	v_pk_mul_f32 v[6:7], v[16:17], s[64:65] op_sel_hi:[1,0]
	v_cvt_pk_bf16_f32 v2, v2, v3
	v_cvt_pk_bf16_f32 v3, v6, v7
	global_store_dwordx2 v[0:1], v[2:3], off offset:32 nt
	v_pk_mul_f32 v[2:3], v[18:19], s[64:65] op_sel_hi:[1,0]
	v_pk_mul_f32 v[6:7], v[20:21], s[64:65] op_sel_hi:[1,0]
	v_cvt_pk_bf16_f32 v2, v2, v3
	v_cvt_pk_bf16_f32 v3, v6, v7
	global_store_dwordx2 v[0:1], v[2:3], off offset:48 nt

.LBB0_917:
	v_mov_b32_e32 v139, v5
	s_cmpk_gt_i32 s12, 0xbf
	s_mov_b64 s[0:1], -1
	s_cbranch_scc0 .LBB0_967
	s_add_i32 s0, s12, 0xffffff40
	v_ashrrev_i32_e32 v1, 6, v139
	v_bfe_u32 v0, v139, 3, 3
	s_lshr_b32 s68, s0, 2
	v_lshl_or_b32 v0, v1, 3, v0
	s_and_b32 s13, s12, 3
	s_lshl_b64 s[0:1], s[68:69], 16
	v_readlane_b32 s4, v254, 27
	v_lshlrev_b32_e32 v20, 10, v1
	v_lshrrev_b32_e32 v1, 1, v0
	v_readlane_b32 s5, v254, 28
	s_add_u32 s0, s4, s0
	v_xor_b32_e32 v6, v1, v139
	v_ashrrev_i32_e32 v1, 31, v0
	s_addc_u32 s1, s5, s1
	v_add_u32_e32 v21, 32, v20
	v_lshlrev_b64 v[0:1], 8, v[0:1]
	v_lshlrev_b32_e32 v6, 4, v6
	s_lshl_b32 s4, s13, 16
	v_lshl_add_u64 v[2:3], s[0:1], 0, v[0:1]
	v_and_b32_e32 v6, 0x70, v6
	v_mov_b32_e32 v7, v4
	v_readfirstlane_b32 s6, v21
	v_add_u32_e32 v10, 0x8000, v21
	s_add_u32 s4, s10, s4
	v_lshl_add_u64 v[2:3], v[2:3], 0, v[6:7]
	s_mov_b32 m0, s6
	v_readfirstlane_b32 s6, v10
	s_addc_u32 s5, s11, 0
	global_load_lds_dwordx4 v[2:3], off
	s_mov_b32 m0, s6
	s_mov_b64 s[6:7], 0x4000
	v_lshl_add_u64 v[8:9], s[4:5], 0, v[0:1]
	v_add_u32_e32 v14, 0x2000, v21
	v_lshl_add_u64 v[10:11], v[0:1], 0, s[6:7]
	v_lshl_add_u64 v[8:9], v[8:9], 0, v[6:7]
	v_lshl_add_u64 v[12:13], s[0:1], 0, v[10:11]
	v_readfirstlane_b32 s6, v14
	v_add_u32_e32 v14, 0xa000, v21
	global_load_lds_dwordx4 v[8:9], off
	v_lshl_add_u64 v[12:13], v[12:13], 0, v[6:7]
	s_mov_b32 m0, s6
	v_readfirstlane_b32 s6, v14
	global_load_lds_dwordx4 v[12:13], off
	s_mov_b32 m0, s6
	s_mov_b64 s[6:7], 0x8000
	v_lshl_add_u64 v[10:11], s[4:5], 0, v[10:11]
	v_add_u32_e32 v18, 0x4000, v21
	v_lshl_add_u64 v[14:15], v[0:1], 0, s[6:7]
	v_lshl_add_u64 v[10:11], v[10:11], 0, v[6:7]
	v_lshl_add_u64 v[16:17], s[0:1], 0, v[14:15]
	v_readfirstlane_b32 s6, v18
	v_add_u32_e32 v18, 0xc000, v21
	global_load_lds_dwordx4 v[10:11], off
	v_lshl_add_u64 v[16:17], v[16:17], 0, v[6:7]
	s_mov_b32 m0, s6
	v_readfirstlane_b32 s6, v18
	global_load_lds_dwordx4 v[16:17], off
	s_mov_b32 m0, s6
	s_mov_b64 s[6:7], 0xc000
	v_lshl_add_u64 v[0:1], v[0:1], 0, s[6:7]
	v_lshl_add_u64 v[14:15], s[4:5], 0, v[14:15]
	v_add_u32_e32 v22, 0x6000, v21
	v_lshl_add_u64 v[18:19], s[0:1], 0, v[0:1]
	v_lshl_add_u64 v[0:1], s[4:5], 0, v[0:1]
	v_lshl_add_u64 v[14:15], v[14:15], 0, v[6:7]
	v_lshl_add_u64 v[18:19], v[18:19], 0, v[6:7]
	v_readfirstlane_b32 s0, v22
	v_lshl_add_u64 v[0:1], v[0:1], 0, v[6:7]
	v_add_u32_e32 v6, 0xe000, v21
	global_load_lds_dwordx4 v[14:15], off
	s_mov_b32 m0, s0
	v_readfirstlane_b32 s0, v6
	v_lshrrev_b32_e32 v6, 5, v139
	v_bfe_u32 v148, v139, 1, 3
	v_bitop3_b32 v6, v6, v148, 1 bitop3:0x6c
	global_load_lds_dwordx4 v[18:19], off
	s_mov_b32 m0, s0
	v_lshlrev_b32_e32 v149, 4, v6
	v_lshlrev_b32_e32 v6, 7, v139
	s_add_i32 s0, 32, 0x10000
	v_and_b32_e32 v150, 0x6f80, v6
	v_add_u32_e32 v6, s0, v20
	global_load_lds_dwordx4 v[0:1], off
	v_readfirstlane_b32 s1, v6
	v_lshl_add_u64 v[2:3], v[2:3], 0, s[54:55]
	s_mov_b32 m0, s1
	s_waitcnt vmcnt(0)
	s_waitcnt vmcnt(0) lgkmcnt(0)
	s_barrier
	global_load_lds_dwordx4 v[2:3], off
	v_lshl_add_u64 v[2:3], v[8:9], 0, s[54:55]
	v_add_u32_e32 v8, 0x8000, v6
	v_and_b32_e32 v152, 31, v139
	v_readfirstlane_b32 s1, v8
	v_add_u32_e32 v8, 0x2000, v6
	s_mov_b32 m0, s1
	v_readfirstlane_b32 s1, v8
	v_add_u32_e32 v8, 0xa000, v6
	global_load_lds_dwordx4 v[2:3], off
	v_lshl_add_u64 v[2:3], v[12:13], 0, s[54:55]
	s_mov_b32 m0, s1
	v_readfirstlane_b32 s1, v8
	v_add_u32_e32 v8, 0x4000, v6
	global_load_lds_dwordx4 v[2:3], off
	v_lshl_add_u64 v[2:3], v[10:11], 0, s[54:55]
	s_mov_b32 m0, s1
	v_readfirstlane_b32 s1, v8
	v_add_u32_e32 v8, 0xc000, v6
	global_load_lds_dwordx4 v[2:3], off
	v_lshl_add_u64 v[2:3], v[16:17], 0, s[54:55]
	s_mov_b32 m0, s1
	v_readfirstlane_b32 s1, v8
	v_add_u32_e32 v8, 0x6000, v6
	global_load_lds_dwordx4 v[2:3], off
	v_lshl_add_u64 v[2:3], v[14:15], 0, s[54:55]
	s_mov_b32 m0, s1
	v_readfirstlane_b32 s1, v8
	global_load_lds_dwordx4 v[2:3], off
	v_lshl_add_u64 v[2:3], v[18:19], 0, s[54:55]
	s_mov_b32 m0, s1
	v_lshrrev_b32_e32 v7, 1, v139
	global_load_lds_dwordx4 v[2:3], off
	v_add_u32_e32 v2, 0xe000, v6
	v_lshl_add_u64 v[0:1], v[0:1], 0, s[54:55]
	v_readfirstlane_b32 s1, v2
	s_mov_b32 m0, s1
	s_mov_b32 s1, 0x1ffff80
	v_and_or_b32 v7, v7, s1, v152
	v_add_u32_e32 v6, 32, v149
	v_lshlrev_b32_e32 v151, 7, v7
	global_load_lds_dwordx4 v[0:1], off
	v_add_u32_e32 v10, v6, v150
	v_add_u32_e32 v14, v6, v151
	ds_read_b128 v[0:3], v10 offset:32768
	ds_read_b128 v[6:9], v14
	ds_read_b128 v[10:13], v10 offset:36864
	s_waitcnt lgkmcnt(0)
	v_mfma_f32_32x32x16_bf16 v[118:133], v[0:3], v[6:9], 0
	v_bfe_u32 v153, v139, 5, 1
	s_add_i32 s1, 32, 0x18000
	v_mfma_f32_32x32x16_bf16 v[102:117], v[10:13], v[6:9], 0
	ds_read_b128 v[6:9], v14 offset:4096
	s_waitcnt lgkmcnt(0)
	v_mfma_f32_32x32x16_bf16 v[86:101], v[0:3], v[6:9], 0
	v_mfma_f32_32x32x16_bf16 v[70:85], v[10:13], v[6:9], 0
	ds_read_b128 v[6:9], v14 offset:8192
	s_waitcnt lgkmcnt(0)
	v_mfma_f32_32x32x16_bf16 v[54:69], v[0:3], v[6:9], 0
	v_mfma_f32_32x32x16_bf16 v[38:53], v[10:13], v[6:9], 0
	ds_read_b128 v[6:9], v14 offset:12288
	s_waitcnt lgkmcnt(0)
	v_mfma_f32_32x32x16_bf16 v[22:37], v[0:3], v[6:9], 0
	v_bitop3_b32 v0, v153, v148, 2 bitop3:0x36
	v_lshlrev_b32_e32 v154, 4, v0
	v_add_u32_e32 v134, 32, v154
	v_add_u32_e32 v144, v134, v150
	v_add_u32_e32 v155, v134, v151
	ds_read_b128 v[0:3], v144 offset:32768
	ds_read_b128 v[134:137], v155
	ds_read_b128 v[144:147], v144 offset:36864
	s_waitcnt lgkmcnt(0)
	v_mfma_f32_32x32x16_bf16 v[118:133], v[0:3], v[134:137], v[118:133]
	v_mfma_f32_32x32x16_bf16 v[102:117], v[144:147], v[134:137], v[102:117]
	ds_read_b128 v[134:137], v155 offset:4096
	s_waitcnt lgkmcnt(0)
	v_mfma_f32_32x32x16_bf16 v[86:101], v[0:3], v[134:137], v[86:101]
	v_mfma_f32_32x32x16_bf16 v[70:85], v[144:147], v[134:137], v[70:85]
	ds_read_b128 v[134:137], v155 offset:8192
	v_mfma_f32_32x32x16_bf16 v[6:21], v[10:13], v[6:9], 0
	s_waitcnt lgkmcnt(0)
	v_mfma_f32_32x32x16_bf16 v[54:69], v[0:3], v[134:137], v[54:69]
	v_mfma_f32_32x32x16_bf16 v[38:53], v[144:147], v[134:137], v[38:53]
	ds_read_b128 v[134:137], v155 offset:12288
	s_waitcnt lgkmcnt(0)
	v_mfma_f32_32x32x16_bf16 v[22:37], v[0:3], v[134:137], v[22:37]
	v_bitop3_b32 v0, v153, v148, 4 bitop3:0x36
	v_lshlrev_b32_e32 v155, 4, v0
	v_mfma_f32_32x32x16_bf16 v[6:21], v[144:147], v[134:137], v[6:21]
	v_add_u32_e32 v134, 32, v155
	v_add_u32_e32 v144, v134, v150
	v_add_u32_e32 v156, v134, v151
	ds_read_b128 v[0:3], v144 offset:32768
	ds_read_b128 v[134:137], v156
	ds_read_b128 v[144:147], v144 offset:36864
	s_waitcnt lgkmcnt(0)
	v_mfma_f32_32x32x16_bf16 v[118:133], v[0:3], v[134:137], v[118:133]
	v_mfma_f32_32x32x16_bf16 v[102:117], v[144:147], v[134:137], v[102:117]
	ds_read_b128 v[134:137], v156 offset:4096
	s_waitcnt lgkmcnt(0)
	v_mfma_f32_32x32x16_bf16 v[86:101], v[0:3], v[134:137], v[86:101]
	v_mfma_f32_32x32x16_bf16 v[70:85], v[144:147], v[134:137], v[70:85]
	ds_read_b128 v[134:137], v156 offset:8192
	s_waitcnt lgkmcnt(0)
	v_mfma_f32_32x32x16_bf16 v[54:69], v[0:3], v[134:137], v[54:69]
	v_mfma_f32_32x32x16_bf16 v[38:53], v[144:147], v[134:137], v[38:53]
	ds_read_b128 v[134:137], v156 offset:12288
	s_waitcnt lgkmcnt(0)
	v_mfma_f32_32x32x16_bf16 v[22:37], v[0:3], v[134:137], v[22:37]
	v_bitop3_b32 v0, v153, v148, 6 bitop3:0x36
	v_lshlrev_b32_e32 v148, 4, v0
	v_mfma_f32_32x32x16_bf16 v[6:21], v[144:147], v[134:137], v[6:21]
	v_add_u32_e32 v134, 32, v148
	v_add_u32_e32 v144, v134, v150
	v_add_u32_e32 v153, v134, v151
	ds_read_b128 v[0:3], v144 offset:32768
	ds_read_b128 v[134:137], v153
	ds_read_b128 v[144:147], v144 offset:36864
	s_waitcnt lgkmcnt(0)
	v_mfma_f32_32x32x16_bf16 v[118:133], v[0:3], v[134:137], v[118:133]
	v_mfma_f32_32x32x16_bf16 v[102:117], v[144:147], v[134:137], v[102:117]
	ds_read_b128 v[134:137], v153 offset:4096
	s_waitcnt lgkmcnt(0)
	v_mfma_f32_32x32x16_bf16 v[86:101], v[0:3], v[134:137], v[86:101]
	v_mfma_f32_32x32x16_bf16 v[70:85], v[144:147], v[134:137], v[70:85]
	ds_read_b128 v[134:137], v153 offset:8192
	s_waitcnt lgkmcnt(0)
	v_mfma_f32_32x32x16_bf16 v[54:69], v[0:3], v[134:137], v[54:69]
	v_mfma_f32_32x32x16_bf16 v[38:53], v[144:147], v[134:137], v[38:53]
	ds_read_b128 v[134:137], v153 offset:12288
	s_waitcnt vmcnt(0)
	s_waitcnt vmcnt(0) lgkmcnt(0)
	s_barrier
	v_mfma_f32_32x32x16_bf16 v[6:21], v[144:147], v[134:137], v[6:21]
	v_add3_u32 v144, s1, v149, v150
	v_add3_u32 v149, s0, v149, v151
	v_mfma_f32_32x32x16_bf16 v[22:37], v[0:3], v[134:137], v[22:37]
	ds_read_b128 v[0:3], v144
	ds_read_b128 v[134:137], v149
	ds_read_b128 v[144:147], v144 offset:4096
	s_waitcnt lgkmcnt(1)
	v_mfma_f32_32x32x16_bf16 v[118:133], v[0:3], v[134:137], v[118:133]
	s_waitcnt lgkmcnt(0)
	v_mfma_f32_32x32x16_bf16 v[102:117], v[144:147], v[134:137], v[102:117]
	ds_read_b128 v[134:137], v149 offset:4096
	s_waitcnt lgkmcnt(0)
	v_mfma_f32_32x32x16_bf16 v[86:101], v[0:3], v[134:137], v[86:101]
	v_mfma_f32_32x32x16_bf16 v[70:85], v[144:147], v[134:137], v[70:85]
	ds_read_b128 v[134:137], v149 offset:8192
	s_waitcnt lgkmcnt(0)
	v_mfma_f32_32x32x16_bf16 v[54:69], v[0:3], v[134:137], v[54:69]
	v_mfma_f32_32x32x16_bf16 v[38:53], v[144:147], v[134:137], v[38:53]
	ds_read_b128 v[134:137], v149 offset:12288
	v_add3_u32 v149, s0, v154, v151
	s_waitcnt lgkmcnt(0)
	v_mfma_f32_32x32x16_bf16 v[6:21], v[144:147], v[134:137], v[6:21]
	v_add3_u32 v144, s1, v154, v150
	v_mfma_f32_32x32x16_bf16 v[22:37], v[0:3], v[134:137], v[22:37]
	ds_read_b128 v[0:3], v144
	ds_read_b128 v[134:137], v149
	ds_read_b128 v[144:147], v144 offset:4096
	s_waitcnt lgkmcnt(1)
	v_mfma_f32_32x32x16_bf16 v[118:133], v[0:3], v[134:137], v[118:133]
	s_waitcnt lgkmcnt(0)
	v_mfma_f32_32x32x16_bf16 v[102:117], v[144:147], v[134:137], v[102:117]
	ds_read_b128 v[134:137], v149 offset:4096
	s_waitcnt lgkmcnt(0)
	v_mfma_f32_32x32x16_bf16 v[86:101], v[0:3], v[134:137], v[86:101]
	v_mfma_f32_32x32x16_bf16 v[70:85], v[144:147], v[134:137], v[70:85]
	ds_read_b128 v[134:137], v149 offset:8192
	s_waitcnt lgkmcnt(0)
	v_mfma_f32_32x32x16_bf16 v[54:69], v[0:3], v[134:137], v[54:69]
	v_mfma_f32_32x32x16_bf16 v[38:53], v[144:147], v[134:137], v[38:53]
	ds_read_b128 v[134:137], v149 offset:12288
	v_add3_u32 v149, s0, v155, v151
	s_waitcnt lgkmcnt(0)
	v_mfma_f32_32x32x16_bf16 v[6:21], v[144:147], v[134:137], v[6:21]
	v_add3_u32 v144, s1, v155, v150
	v_mfma_f32_32x32x16_bf16 v[22:37], v[0:3], v[134:137], v[22:37]
	ds_read_b128 v[0:3], v144
	ds_read_b128 v[134:137], v149
	ds_read_b128 v[144:147], v144 offset:4096
	s_waitcnt lgkmcnt(1)
	v_mfma_f32_32x32x16_bf16 v[118:133], v[0:3], v[134:137], v[118:133]
	s_waitcnt lgkmcnt(0)
	v_mfma_f32_32x32x16_bf16 v[102:117], v[144:147], v[134:137], v[102:117]
	ds_read_b128 v[134:137], v149 offset:4096
	s_waitcnt lgkmcnt(0)
	v_mfma_f32_32x32x16_bf16 v[86:101], v[0:3], v[134:137], v[86:101]
	v_mfma_f32_32x32x16_bf16 v[70:85], v[144:147], v[134:137], v[70:85]
	ds_read_b128 v[134:137], v149 offset:8192
	s_waitcnt lgkmcnt(0)
	v_mfma_f32_32x32x16_bf16 v[54:69], v[0:3], v[134:137], v[54:69]
	v_mfma_f32_32x32x16_bf16 v[38:53], v[144:147], v[134:137], v[38:53]
	ds_read_b128 v[134:137], v149 offset:12288
	s_waitcnt lgkmcnt(0)
	v_mfma_f32_32x32x16_bf16 v[6:21], v[144:147], v[134:137], v[6:21]
	v_add3_u32 v144, s1, v148, v150
	ds_read_b128 v[154:157], v144 offset:4096
	v_add3_u32 v145, s0, v148, v151
	s_movk_i32 s0, 0x9f
	v_mfma_f32_32x32x16_bf16 v[22:37], v[0:3], v[134:137], v[22:37]
	ds_read_b128 v[0:3], v144
	ds_read_b128 v[134:137], v145
	s_waitcnt lgkmcnt(0)
	v_mfma_f32_32x32x16_bf16 v[118:133], v[0:3], v[134:137], v[118:133]
	v_mfma_f32_32x32x16_bf16 v[102:117], v[154:157], v[134:137], v[102:117]
	ds_read_b128 v[134:137], v145 offset:4096
	ds_read_b128 v[148:151], v145 offset:8192
	ds_read_b128 v[158:161], v145 offset:12288
	s_waitcnt vmcnt(0)
	s_waitcnt lgkmcnt(0)
	s_barrier
	v_mfma_f32_32x32x16_bf16 v[86:101], v[0:3], v[134:137], v[86:101]
	v_mfma_f32_32x32x16_bf16 v[70:85], v[154:157], v[134:137], v[70:85]
	v_ashrrev_i32_e32 v134, 1, v139
	v_and_b32_e32 v134, 0xffffff80, v134
	v_or_b32_e32 v135, v134, v152
	v_lshl_add_u32 v144, s68, 8, v135
	v_bitop3_b32 v146, v134, s0, v152 bitop3:0xc8
	v_subrev_co_u32_e32 v134, vcc, 0x4000, v144
	v_mfma_f32_32x32x16_bf16 v[54:69], v[0:3], v[148:151], v[54:69]
	v_lshrrev_b32_e32 v137, 9, v134
	v_and_b32_e32 v134, 0x19f, v144
	v_ashrrev_i32_e32 v136, 8, v144
	s_mov_b64 s[4:5], vcc
	v_cmp_lt_i32_e64 s[6:7], s89, v144
	v_mov_b32_e32 v152, v146
	v_mov_b32_e32 v145, v136
	v_mfma_f32_32x32x16_bf16 v[38:53], v[154:157], v[148:151], v[38:53]
	v_or_b32_e32 v149, 0x1000, v134
	v_add_u32_e32 v134, 0xffffe000, v144
	v_lshrrev_b32_e32 v150, 12, v134
	v_and_b32_e32 v151, 0xf9f, v144
	v_mov_b64_e32 v[134:135], 0xc952000
	v_cndmask_b32_e64 v147, v149, v151, s[4:5]
	v_cndmask_b32_e64 v148, v137, v150, s[4:5]
	v_mfma_f32_32x32x16_bf16 v[22:37], v[0:3], v[158:161], v[22:37]
	v_mov_b64_e32 v[2:3], 0x100
	v_mov_b64_e32 v[0:1], 0xdb62000
	v_mfma_f32_32x32x16_bf16 v[6:21], v[154:157], v[158:161], v[6:21]
	s_and_saveexec_b64 s[0:1], s[6:7]
	v_cndmask_b32_e64 v152, v149, v151, s[4:5]
	v_cndmask_b32_e64 v145, v137, v150, s[4:5]
	v_mov_b64_e32 v[2:3], 0x1200
	v_mov_b64_e32 v[134:135], 0xd152000
	v_mov_b64_e32 v[0:1], 0xe362000
	s_or_b64 exec, exec, s[0:1]
	v_lshrrev_b32_e32 v3, 3, v139
	v_and_b32_e32 v137, 0x80, v139
	v_lshl_or_b32 v137, s13, 8, v137
	v_and_b32_e32 v151, 4, v3
	v_or_b32_e32 v149, 0xffffffc0, v151
	v_lshrrev_b32_e32 v137, 7, v137
	v_and_b32_e32 v150, 64, v139
	v_lshl_or_b32 v3, v145, 3, v137
	v_cmp_ne_u32_e32 vcc, 0, v150
	v_add_u32_e32 v145, v149, v150
	s_and_saveexec_b64 s[0:1], vcc
	s_xor_b64 s[0:1], exec, s[0:1]
	s_cbranch_execz .LBB0_922
	v_mad_i64_i32 v[134:135], s[14:15], v2, v3, 0
	v_lshl_add_u64 v[0:1], s[26:27], 0, v[0:1]
	v_lshlrev_b64 v[134:135], 7, v[134:135]
	v_lshl_add_u64 v[0:1], v[0:1], 0, v[134:135]
	v_mad_u64_u32 v[134:135], s[14:15], v2, v145, 0
	v_lshl_add_u64 v[0:1], v[134:135], 1, v[0:1]
	v_lshlrev_b32_e32 v134, 1, v152
	v_mov_b32_e32 v135, v4
	v_lshl_add_u64 v[0:1], v[0:1], 0, v[134:135]
	v_cvt_pk_bf16_f32 v3, v118, s0
	global_store_short v[0:1], v3, off nt
	v_cvt_pk_bf16_f32 v3, v119, s0
	v_lshlrev_b32_e32 v118, 1, v2
	v_mov_b32_e32 v119, v4
	v_lshl_add_u64 v[0:1], v[0:1], 0, v[118:119]
	global_store_short v[0:1], v3, off nt
	v_cvt_pk_bf16_f32 v3, v120, s0
	v_lshl_add_u64 v[0:1], v[0:1], 0, v[118:119]
	global_store_short v[0:1], v3, off nt
	v_cvt_pk_bf16_f32 v3, v121, s0
	v_lshl_add_u64 v[0:1], v[0:1], 0, v[118:119]
	global_store_short v[0:1], v3, off nt
	v_cvt_pk_bf16_f32 v3, v122, s0
	v_mad_u64_u32 v[0:1], s[14:15], v2, 10, v[0:1]
	global_store_short v[0:1], v3, off nt
	v_cvt_pk_bf16_f32 v3, v123, s0
	v_lshl_add_u64 v[0:1], v[0:1], 0, v[118:119]
	global_store_short v[0:1], v3, off nt
	v_cvt_pk_bf16_f32 v3, v124, s0
	v_lshl_add_u64 v[0:1], v[0:1], 0, v[118:119]
	global_store_short v[0:1], v3, off nt
	v_cvt_pk_bf16_f32 v3, v125, s0
	v_lshl_add_u64 v[0:1], v[0:1], 0, v[118:119]
	global_store_short v[0:1], v3, off nt
	v_cvt_pk_bf16_f32 v3, v126, s0
	v_mad_u64_u32 v[0:1], s[14:15], v2, 10, v[0:1]
	global_store_short v[0:1], v3, off nt
	v_cvt_pk_bf16_f32 v3, v127, s0
	v_lshl_add_u64 v[0:1], v[0:1], 0, v[118:119]
	global_store_short v[0:1], v3, off nt
	v_cvt_pk_bf16_f32 v3, v128, s0
	v_lshl_add_u64 v[0:1], v[0:1], 0, v[118:119]
	global_store_short v[0:1], v3, off nt
	v_cvt_pk_bf16_f32 v3, v129, s0
	v_lshl_add_u64 v[0:1], v[0:1], 0, v[118:119]
	global_store_short v[0:1], v3, off nt
	v_cvt_pk_bf16_f32 v3, v130, s0
	v_mad_u64_u32 v[0:1], s[14:15], v2, 10, v[0:1]
	global_store_short v[0:1], v3, off nt
	v_cvt_pk_bf16_f32 v2, v131, s0
	v_lshl_add_u64 v[0:1], v[0:1], 0, v[118:119]
	global_store_short v[0:1], v2, off nt
	v_cvt_pk_bf16_f32 v2, v132, s0
	v_lshl_add_u64 v[0:1], v[0:1], 0, v[118:119]
	global_store_short v[0:1], v2, off nt
	v_cvt_pk_bf16_f32 v2, v133, s0
	v_lshl_add_u64 v[0:1], v[0:1], 0, v[118:119]
	global_store_short v[0:1], v2, off nt
.LBB0_922:
	s_or_saveexec_b64 s[0:1], s[0:1]
	v_lshlrev_b32_e32 v0, 1, v151
	s_xor_b64 exec, exec, s[0:1]
	s_cbranch_execz .LBB0_924
	v_lshl_add_u64 v[134:135], s[26:27], 0, v[134:135]
	v_lshlrev_b32_e32 v1, 7, v2
	v_mad_i64_i32 v[2:3], s[14:15], v1, v3, v[134:135]
	v_lshlrev_b32_e32 v134, 7, v152
	v_mov_b32_e32 v135, v4
	v_lshl_add_u64 v[2:3], v[2:3], 0, v[134:135]
	v_mov_b32_e32 v1, v4
	v_lshl_add_u64 v[2:3], v[2:3], 0, v[0:1]
	v_cvt_pk_bf16_f32 v118, v118, v119
	v_cvt_pk_bf16_f32 v119, v120, v121
	global_store_dwordx2 v[2:3], v[118:119], off nt
	v_cvt_pk_bf16_f32 v118, v122, v123
	v_cvt_pk_bf16_f32 v119, v124, v125
	global_store_dwordx2 v[2:3], v[118:119], off offset:16 nt
	v_cvt_pk_bf16_f32 v118, v126, v127
	v_cvt_pk_bf16_f32 v119, v128, v129
	global_store_dwordx2 v[2:3], v[118:119], off offset:32 nt
	v_cvt_pk_bf16_f32 v118, v130, v131
	v_cvt_pk_bf16_f32 v119, v132, v133
	global_store_dwordx2 v[2:3], v[118:119], off offset:48 nt
.LBB0_924:
	s_or_b64 exec, exec, s[0:1]
	v_mov_b64_e32 v[2:3], 0x100
	v_mov_b64_e32 v[118:119], 0xc952000
	v_mov_b64_e32 v[120:121], 0xdb62000
	v_mov_b32_e32 v1, v136
	s_and_saveexec_b64 s[0:1], s[6:7]
	v_mov_b64_e32 v[2:3], 0x1200
	v_mov_b64_e32 v[118:119], 0xd152000
	v_mov_b64_e32 v[120:121], 0xe362000
	v_mov_b32_e32 v146, v147
	v_mov_b32_e32 v1, v148
	s_or_b64 exec, exec, s[0:1]
	v_or_b32_e32 v3, 32, v150
	v_lshl_or_b32 v1, v1, 3, v137
	v_add_u32_e32 v122, v149, v3
	s_and_saveexec_b64 s[0:1], vcc
	s_xor_b64 s[0:1], exec, s[0:1]
	s_cbranch_execz .LBB0_928
	v_lshl_add_u64 v[118:119], s[26:27], 0, v[120:121]
	v_mad_i64_i32 v[120:121], s[6:7], v2, v1, 0
	v_lshlrev_b64 v[120:121], 7, v[120:121]
	v_lshl_add_u64 v[118:119], v[118:119], 0, v[120:121]
	v_mad_u64_u32 v[120:121], s[6:7], v2, v122, 0
	v_lshl_add_u64 v[118:119], v[120:121], 1, v[118:119]
	v_lshlrev_b32_e32 v120, 1, v146
	v_mov_b32_e32 v121, v4
	v_lshl_add_u64 v[118:119], v[118:119], 0, v[120:121]
	v_cvt_pk_bf16_f32 v1, v102, s0
	global_store_short v[118:119], v1, off nt
	v_cvt_pk_bf16_f32 v1, v103, s0
	v_lshlrev_b32_e32 v102, 1, v2
	v_mov_b32_e32 v103, v4
	v_lshl_add_u64 v[118:119], v[118:119], 0, v[102:103]
	global_store_short v[118:119], v1, off nt
	v_cvt_pk_bf16_f32 v1, v104, s0
	v_lshl_add_u64 v[118:119], v[118:119], 0, v[102:103]
	global_store_short v[118:119], v1, off nt
	v_cvt_pk_bf16_f32 v1, v105, s0
	v_lshl_add_u64 v[104:105], v[118:119], 0, v[102:103]
	global_store_short v[104:105], v1, off nt
	v_cvt_pk_bf16_f32 v1, v106, s0
	v_mad_u64_u32 v[104:105], s[6:7], v2, 10, v[104:105]
	global_store_short v[104:105], v1, off nt
	v_cvt_pk_bf16_f32 v1, v107, s0
	v_lshl_add_u64 v[104:105], v[104:105], 0, v[102:103]
	global_store_short v[104:105], v1, off nt
	v_cvt_pk_bf16_f32 v1, v108, s0
	v_lshl_add_u64 v[104:105], v[104:105], 0, v[102:103]
	global_store_short v[104:105], v1, off nt
	v_cvt_pk_bf16_f32 v1, v109, s0
	v_lshl_add_u64 v[104:105], v[104:105], 0, v[102:103]
	global_store_short v[104:105], v1, off nt
	v_cvt_pk_bf16_f32 v1, v110, s0
	v_mad_u64_u32 v[104:105], s[6:7], v2, 10, v[104:105]
	global_store_short v[104:105], v1, off nt
	v_cvt_pk_bf16_f32 v1, v111, s0
	v_lshl_add_u64 v[104:105], v[104:105], 0, v[102:103]
	global_store_short v[104:105], v1, off nt
	v_cvt_pk_bf16_f32 v1, v112, s0
	v_lshl_add_u64 v[104:105], v[104:105], 0, v[102:103]
	global_store_short v[104:105], v1, off nt
	v_cvt_pk_bf16_f32 v1, v113, s0
	v_lshl_add_u64 v[104:105], v[104:105], 0, v[102:103]
	global_store_short v[104:105], v1, off nt
	v_cvt_pk_bf16_f32 v1, v114, s0
	v_mad_u64_u32 v[2:3], s[6:7], v2, 10, v[104:105]
	global_store_short v[2:3], v1, off nt
	v_cvt_pk_bf16_f32 v1, v115, s0
	v_lshl_add_u64 v[2:3], v[2:3], 0, v[102:103]
	global_store_short v[2:3], v1, off nt
	v_cvt_pk_bf16_f32 v1, v116, s0
	v_lshl_add_u64 v[2:3], v[2:3], 0, v[102:103]
	global_store_short v[2:3], v1, off nt
	v_cvt_pk_bf16_f32 v1, v117, s0
	v_lshl_add_u64 v[2:3], v[2:3], 0, v[102:103]
	global_store_short v[2:3], v1, off nt
.LBB0_928:
	s_andn2_saveexec_b64 s[0:1], s[0:1]
	s_cbranch_execz .LBB0_930
	v_lshl_add_u64 v[118:119], s[26:27], 0, v[118:119]
	v_lshlrev_b32_e32 v2, 7, v2
	v_mad_i64_i32 v[2:3], s[6:7], v2, v1, v[118:119]
	v_lshlrev_b32_e32 v118, 7, v146
	v_mov_b32_e32 v119, v4
	v_lshl_add_u64 v[2:3], v[2:3], 0, v[118:119]
	v_mov_b32_e32 v1, v4
	v_lshl_add_u64 v[2:3], v[2:3], 0, v[0:1]
	v_cvt_pk_bf16_f32 v102, v102, v103
	v_cvt_pk_bf16_f32 v103, v104, v105
	global_store_dwordx2 v[2:3], v[102:103], off offset:64 nt
	v_cvt_pk_bf16_f32 v102, v106, v107
	v_cvt_pk_bf16_f32 v103, v108, v109
	global_store_dwordx2 v[2:3], v[102:103], off offset:80 nt
	v_cvt_pk_bf16_f32 v102, v110, v111
	v_cvt_pk_bf16_f32 v103, v112, v113
	global_store_dwordx2 v[2:3], v[102:103], off offset:96 nt
	v_cvt_pk_bf16_f32 v102, v114, v115
	v_cvt_pk_bf16_f32 v103, v116, v117
	global_store_dwordx2 v[2:3], v[102:103], off offset:112 nt
.LBB0_930:
	s_or_b64 exec, exec, s[0:1]
	v_or_b32_e32 v1, 32, v144
	s_movk_i32 s6, 0xbf
	v_cmp_lt_i32_e64 s[0:1], s89, v1
	v_bitop3_b32 v106, v144, s6, 32 bitop3:0xc8
	v_add_u32_e32 v1, 0xffffc020, v144
	s_movk_i32 s6, 0x1bf
	v_lshrrev_b32_e32 v109, 9, v1
	v_bitop3_b32 v1, v144, s6, 32 bitop3:0xc8
	v_or_b32_e32 v111, 0x1000, v1
	v_add_u32_e32 v1, 0xffffe020, v144
	s_movk_i32 s6, 0xfbf
	v_lshrrev_b32_e32 v112, 12, v1
	v_bitop3_b32 v113, v144, s6, 32 bitop3:0xc8
	v_mov_b64_e32 v[2:3], 0x100
	v_mov_b64_e32 v[102:103], 0xc952000
	v_mov_b64_e32 v[104:105], 0xdb62000
	v_cndmask_b32_e64 v107, v111, v113, s[4:5]
	v_cndmask_b32_e64 v108, v109, v112, s[4:5]
	v_mov_b32_e32 v1, v106
	v_mov_b32_e32 v110, v136
	s_and_saveexec_b64 s[6:7], s[0:1]
	v_cndmask_b32_e64 v1, v111, v113, s[4:5]
	v_cndmask_b32_e64 v110, v109, v112, s[4:5]
	v_mov_b64_e32 v[2:3], 0x1200
	v_mov_b64_e32 v[102:103], 0xd152000
	v_mov_b64_e32 v[104:105], 0xe362000
	s_or_b64 exec, exec, s[6:7]
	v_lshl_or_b32 v3, v110, 3, v137
	s_and_saveexec_b64 s[6:7], vcc
	s_xor_b64 s[6:7], exec, s[6:7]
	s_cbranch_execz .LBB0_934
	v_lshl_add_u64 v[102:103], s[26:27], 0, v[104:105]
	v_mad_i64_i32 v[104:105], s[14:15], v2, v3, 0
	v_lshlrev_b64 v[104:105], 7, v[104:105]
	v_lshl_add_u64 v[102:103], v[102:103], 0, v[104:105]
	v_mad_u64_u32 v[104:105], s[14:15], v2, v145, 0
	v_lshl_add_u64 v[102:103], v[104:105], 1, v[102:103]
	v_lshlrev_b32_e32 v104, 1, v1
	v_mov_b32_e32 v105, v4
	v_lshl_add_u64 v[102:103], v[102:103], 0, v[104:105]
	v_cvt_pk_bf16_f32 v1, v86, s0
	global_store_short v[102:103], v1, off nt
	v_cvt_pk_bf16_f32 v1, v87, s0
	v_lshlrev_b32_e32 v86, 1, v2
	v_mov_b32_e32 v87, v4
	v_lshl_add_u64 v[102:103], v[102:103], 0, v[86:87]
	global_store_short v[102:103], v1, off nt
	v_cvt_pk_bf16_f32 v1, v88, s0
	v_lshl_add_u64 v[102:103], v[102:103], 0, v[86:87]
	global_store_short v[102:103], v1, off nt
	v_cvt_pk_bf16_f32 v1, v89, s0
	v_lshl_add_u64 v[88:89], v[102:103], 0, v[86:87]
	global_store_short v[88:89], v1, off nt
	v_cvt_pk_bf16_f32 v1, v90, s0
	v_mad_u64_u32 v[88:89], s[14:15], v2, 10, v[88:89]
	global_store_short v[88:89], v1, off nt
	v_cvt_pk_bf16_f32 v1, v91, s0
	v_lshl_add_u64 v[88:89], v[88:89], 0, v[86:87]
	global_store_short v[88:89], v1, off nt
	v_cvt_pk_bf16_f32 v1, v92, s0
	v_lshl_add_u64 v[88:89], v[88:89], 0, v[86:87]
	global_store_short v[88:89], v1, off nt
	v_cvt_pk_bf16_f32 v1, v93, s0
	v_lshl_add_u64 v[88:89], v[88:89], 0, v[86:87]
	global_store_short v[88:89], v1, off nt
	v_cvt_pk_bf16_f32 v1, v94, s0
	v_mad_u64_u32 v[88:89], s[14:15], v2, 10, v[88:89]
	global_store_short v[88:89], v1, off nt
	v_cvt_pk_bf16_f32 v1, v95, s0
	v_lshl_add_u64 v[88:89], v[88:89], 0, v[86:87]
	global_store_short v[88:89], v1, off nt
	v_cvt_pk_bf16_f32 v1, v96, s0
	v_lshl_add_u64 v[88:89], v[88:89], 0, v[86:87]
	global_store_short v[88:89], v1, off nt
	v_cvt_pk_bf16_f32 v1, v97, s0
	v_lshl_add_u64 v[88:89], v[88:89], 0, v[86:87]
	global_store_short v[88:89], v1, off nt
	v_cvt_pk_bf16_f32 v1, v98, s0
	v_mad_u64_u32 v[2:3], s[14:15], v2, 10, v[88:89]
	global_store_short v[2:3], v1, off nt
	v_cvt_pk_bf16_f32 v1, v99, s0
	v_lshl_add_u64 v[2:3], v[2:3], 0, v[86:87]
	global_store_short v[2:3], v1, off nt
	v_cvt_pk_bf16_f32 v1, v100, s0
	v_lshl_add_u64 v[2:3], v[2:3], 0, v[86:87]
	global_store_short v[2:3], v1, off nt
	v_cvt_pk_bf16_f32 v1, v101, s0
	v_lshl_add_u64 v[2:3], v[2:3], 0, v[86:87]
	global_store_short v[2:3], v1, off nt
.LBB0_934:
	s_andn2_saveexec_b64 s[6:7], s[6:7]
	s_cbranch_execz .LBB0_936
	v_lshl_add_u64 v[102:103], s[26:27], 0, v[102:103]
	v_lshlrev_b32_e32 v2, 7, v2
	v_mad_i64_i32 v[2:3], s[14:15], v2, v3, v[102:103]
	v_lshlrev_b32_e32 v102, 7, v1
	v_mov_b32_e32 v103, v4
	v_lshl_add_u64 v[2:3], v[2:3], 0, v[102:103]
	v_mov_b32_e32 v1, v4
	v_lshl_add_u64 v[2:3], v[2:3], 0, v[0:1]
	v_cvt_pk_bf16_f32 v86, v86, v87
	v_cvt_pk_bf16_f32 v87, v88, v89
	global_store_dwordx2 v[2:3], v[86:87], off nt
	v_cvt_pk_bf16_f32 v86, v90, v91
	v_cvt_pk_bf16_f32 v87, v92, v93
	global_store_dwordx2 v[2:3], v[86:87], off offset:16 nt
	v_cvt_pk_bf16_f32 v86, v94, v95
	v_cvt_pk_bf16_f32 v87, v96, v97
	global_store_dwordx2 v[2:3], v[86:87], off offset:32 nt
	v_cvt_pk_bf16_f32 v86, v98, v99
	v_cvt_pk_bf16_f32 v87, v100, v101
	global_store_dwordx2 v[2:3], v[86:87], off offset:48 nt
.LBB0_936:
	s_or_b64 exec, exec, s[6:7]
	v_mov_b64_e32 v[2:3], 0x100
	v_mov_b64_e32 v[86:87], 0xc952000
	v_mov_b64_e32 v[88:89], 0xdb62000
	v_mov_b32_e32 v1, v136
	s_and_saveexec_b64 s[6:7], s[0:1]
	v_mov_b64_e32 v[2:3], 0x1200
	v_mov_b64_e32 v[86:87], 0xd152000
	v_mov_b64_e32 v[88:89], 0xe362000
	v_mov_b32_e32 v106, v107
	v_mov_b32_e32 v1, v108
	s_or_b64 exec, exec, s[6:7]
	v_lshl_or_b32 v1, v1, 3, v137
	s_and_saveexec_b64 s[0:1], vcc
	s_xor_b64 s[0:1], exec, s[0:1]
	s_cbranch_execz .LBB0_940
	v_lshl_add_u64 v[86:87], s[26:27], 0, v[88:89]
	v_mad_i64_i32 v[88:89], s[6:7], v2, v1, 0
	v_lshlrev_b64 v[88:89], 7, v[88:89]
	v_lshl_add_u64 v[86:87], v[86:87], 0, v[88:89]
	v_mad_u64_u32 v[88:89], s[6:7], v2, v122, 0
	v_lshl_add_u64 v[86:87], v[88:89], 1, v[86:87]
	v_lshlrev_b32_e32 v88, 1, v106
	v_mov_b32_e32 v89, v4
	v_lshl_add_u64 v[86:87], v[86:87], 0, v[88:89]
	v_cvt_pk_bf16_f32 v1, v70, s0
	global_store_short v[86:87], v1, off nt
	v_cvt_pk_bf16_f32 v1, v71, s0
	v_lshlrev_b32_e32 v70, 1, v2
	v_mov_b32_e32 v71, v4
	v_lshl_add_u64 v[86:87], v[86:87], 0, v[70:71]
	global_store_short v[86:87], v1, off nt
	v_cvt_pk_bf16_f32 v1, v72, s0
	v_lshl_add_u64 v[86:87], v[86:87], 0, v[70:71]
	global_store_short v[86:87], v1, off nt
	v_cvt_pk_bf16_f32 v1, v73, s0
	v_lshl_add_u64 v[72:73], v[86:87], 0, v[70:71]
	global_store_short v[72:73], v1, off nt
	v_cvt_pk_bf16_f32 v1, v74, s0
	v_mad_u64_u32 v[72:73], s[6:7], v2, 10, v[72:73]
	global_store_short v[72:73], v1, off nt
	v_cvt_pk_bf16_f32 v1, v75, s0
	v_lshl_add_u64 v[72:73], v[72:73], 0, v[70:71]
	global_store_short v[72:73], v1, off nt
	v_cvt_pk_bf16_f32 v1, v76, s0
	v_lshl_add_u64 v[72:73], v[72:73], 0, v[70:71]
	global_store_short v[72:73], v1, off nt
	v_cvt_pk_bf16_f32 v1, v77, s0
	v_lshl_add_u64 v[72:73], v[72:73], 0, v[70:71]
	global_store_short v[72:73], v1, off nt
	v_cvt_pk_bf16_f32 v1, v78, s0
	v_mad_u64_u32 v[72:73], s[6:7], v2, 10, v[72:73]
	global_store_short v[72:73], v1, off nt
	v_cvt_pk_bf16_f32 v1, v79, s0
	v_lshl_add_u64 v[72:73], v[72:73], 0, v[70:71]
	global_store_short v[72:73], v1, off nt
	v_cvt_pk_bf16_f32 v1, v80, s0
	v_lshl_add_u64 v[72:73], v[72:73], 0, v[70:71]
	global_store_short v[72:73], v1, off nt
	v_cvt_pk_bf16_f32 v1, v81, s0
	v_lshl_add_u64 v[72:73], v[72:73], 0, v[70:71]
	global_store_short v[72:73], v1, off nt
	v_cvt_pk_bf16_f32 v1, v82, s0
	v_mad_u64_u32 v[2:3], s[6:7], v2, 10, v[72:73]
	global_store_short v[2:3], v1, off nt
	v_cvt_pk_bf16_f32 v1, v83, s0
	v_lshl_add_u64 v[2:3], v[2:3], 0, v[70:71]
	global_store_short v[2:3], v1, off nt
	v_cvt_pk_bf16_f32 v1, v84, s0
	v_lshl_add_u64 v[2:3], v[2:3], 0, v[70:71]
	global_store_short v[2:3], v1, off nt
	v_cvt_pk_bf16_f32 v1, v85, s0
	v_lshl_add_u64 v[2:3], v[2:3], 0, v[70:71]
	global_store_short v[2:3], v1, off nt
.LBB0_940:
	s_andn2_saveexec_b64 s[0:1], s[0:1]
	s_cbranch_execz .LBB0_942
	v_lshl_add_u64 v[86:87], s[26:27], 0, v[86:87]
	v_lshlrev_b32_e32 v2, 7, v2
	v_mad_i64_i32 v[2:3], s[6:7], v2, v1, v[86:87]
	v_lshlrev_b32_e32 v86, 7, v106
	v_mov_b32_e32 v87, v4
	v_lshl_add_u64 v[2:3], v[2:3], 0, v[86:87]
	v_mov_b32_e32 v1, v4
	v_lshl_add_u64 v[2:3], v[2:3], 0, v[0:1]
	v_cvt_pk_bf16_f32 v70, v70, v71
	v_cvt_pk_bf16_f32 v71, v72, v73
	global_store_dwordx2 v[2:3], v[70:71], off offset:64 nt
	v_cvt_pk_bf16_f32 v70, v74, v75
	v_cvt_pk_bf16_f32 v71, v76, v77
	global_store_dwordx2 v[2:3], v[70:71], off offset:80 nt
	v_cvt_pk_bf16_f32 v70, v78, v79
	v_cvt_pk_bf16_f32 v71, v80, v81
	global_store_dwordx2 v[2:3], v[70:71], off offset:96 nt
	v_cvt_pk_bf16_f32 v70, v82, v83
	v_cvt_pk_bf16_f32 v71, v84, v85
	global_store_dwordx2 v[2:3], v[70:71], off offset:112 nt
.LBB0_942:
	s_or_b64 exec, exec, s[0:1]
	v_or_b32_e32 v1, 64, v144
	s_movk_i32 s6, 0xdf
	v_cmp_lt_i32_e64 s[0:1], s89, v1
	v_bitop3_b32 v74, v144, s6, 64 bitop3:0xc8
	v_add_u32_e32 v1, 0xffffc040, v144
	s_movk_i32 s6, 0x1df
	v_lshrrev_b32_e32 v77, 9, v1
	v_bitop3_b32 v1, v144, s6, 64 bitop3:0xc8
	v_or_b32_e32 v79, 0x1000, v1
	v_add_u32_e32 v1, 0xffffe040, v144
	s_movk_i32 s6, 0xfdf
	v_lshrrev_b32_e32 v80, 12, v1
	v_bitop3_b32 v81, v144, s6, 64 bitop3:0xc8
	v_mov_b64_e32 v[2:3], 0x100
	v_mov_b64_e32 v[70:71], 0xc952000
	v_mov_b64_e32 v[72:73], 0xdb62000
	v_cndmask_b32_e64 v75, v79, v81, s[4:5]
	v_cndmask_b32_e64 v76, v77, v80, s[4:5]
	v_mov_b32_e32 v1, v74
	v_mov_b32_e32 v78, v136
	s_and_saveexec_b64 s[6:7], s[0:1]
	v_cndmask_b32_e64 v1, v79, v81, s[4:5]
	v_cndmask_b32_e64 v78, v77, v80, s[4:5]
	v_mov_b64_e32 v[2:3], 0x1200
	v_mov_b64_e32 v[70:71], 0xd152000
	v_mov_b64_e32 v[72:73], 0xe362000
	s_or_b64 exec, exec, s[6:7]
	v_lshl_or_b32 v3, v78, 3, v137
	s_and_saveexec_b64 s[6:7], vcc
	s_xor_b64 s[6:7], exec, s[6:7]
	s_cbranch_execz .LBB0_946
	v_lshl_add_u64 v[70:71], s[26:27], 0, v[72:73]
	v_mad_i64_i32 v[72:73], s[14:15], v2, v3, 0
	v_lshlrev_b64 v[72:73], 7, v[72:73]
	v_lshl_add_u64 v[70:71], v[70:71], 0, v[72:73]
	v_mad_u64_u32 v[72:73], s[14:15], v2, v145, 0
	v_lshl_add_u64 v[70:71], v[72:73], 1, v[70:71]
	v_lshlrev_b32_e32 v72, 1, v1
	v_mov_b32_e32 v73, v4
	v_lshl_add_u64 v[70:71], v[70:71], 0, v[72:73]
	v_cvt_pk_bf16_f32 v1, v54, s0
	global_store_short v[70:71], v1, off nt
	v_cvt_pk_bf16_f32 v1, v55, s0
	v_lshlrev_b32_e32 v54, 1, v2
	v_mov_b32_e32 v55, v4
	v_lshl_add_u64 v[70:71], v[70:71], 0, v[54:55]
	global_store_short v[70:71], v1, off nt
	v_cvt_pk_bf16_f32 v1, v56, s0
	v_lshl_add_u64 v[70:71], v[70:71], 0, v[54:55]
	global_store_short v[70:71], v1, off nt
	v_cvt_pk_bf16_f32 v1, v57, s0
	v_lshl_add_u64 v[56:57], v[70:71], 0, v[54:55]
	global_store_short v[56:57], v1, off nt
	v_cvt_pk_bf16_f32 v1, v58, s0
	v_mad_u64_u32 v[56:57], s[14:15], v2, 10, v[56:57]
	global_store_short v[56:57], v1, off nt
	v_cvt_pk_bf16_f32 v1, v59, s0
	v_lshl_add_u64 v[56:57], v[56:57], 0, v[54:55]
	global_store_short v[56:57], v1, off nt
	v_cvt_pk_bf16_f32 v1, v60, s0
	v_lshl_add_u64 v[56:57], v[56:57], 0, v[54:55]
	global_store_short v[56:57], v1, off nt
	v_cvt_pk_bf16_f32 v1, v61, s0
	v_lshl_add_u64 v[56:57], v[56:57], 0, v[54:55]
	global_store_short v[56:57], v1, off nt
	v_cvt_pk_bf16_f32 v1, v62, s0
	v_mad_u64_u32 v[56:57], s[14:15], v2, 10, v[56:57]
	global_store_short v[56:57], v1, off nt
	v_cvt_pk_bf16_f32 v1, v63, s0
	v_lshl_add_u64 v[56:57], v[56:57], 0, v[54:55]
	global_store_short v[56:57], v1, off nt
	v_cvt_pk_bf16_f32 v1, v64, s0
	v_lshl_add_u64 v[56:57], v[56:57], 0, v[54:55]
	global_store_short v[56:57], v1, off nt
	v_cvt_pk_bf16_f32 v1, v65, s0
	v_lshl_add_u64 v[56:57], v[56:57], 0, v[54:55]
	global_store_short v[56:57], v1, off nt
	v_cvt_pk_bf16_f32 v1, v66, s0
	v_mad_u64_u32 v[2:3], s[14:15], v2, 10, v[56:57]
	global_store_short v[2:3], v1, off nt
	v_cvt_pk_bf16_f32 v1, v67, s0
	v_lshl_add_u64 v[2:3], v[2:3], 0, v[54:55]
	global_store_short v[2:3], v1, off nt
	v_cvt_pk_bf16_f32 v1, v68, s0
	v_lshl_add_u64 v[2:3], v[2:3], 0, v[54:55]
	global_store_short v[2:3], v1, off nt
	v_cvt_pk_bf16_f32 v1, v69, s0
	v_lshl_add_u64 v[2:3], v[2:3], 0, v[54:55]
	global_store_short v[2:3], v1, off nt
.LBB0_946:
	s_andn2_saveexec_b64 s[6:7], s[6:7]
	s_cbranch_execz .LBB0_948
	v_lshl_add_u64 v[70:71], s[26:27], 0, v[70:71]
	v_lshlrev_b32_e32 v2, 7, v2
	v_mad_i64_i32 v[2:3], s[14:15], v2, v3, v[70:71]
	v_lshlrev_b32_e32 v70, 7, v1
	v_mov_b32_e32 v71, v4
	v_lshl_add_u64 v[2:3], v[2:3], 0, v[70:71]
	v_mov_b32_e32 v1, v4
	v_lshl_add_u64 v[2:3], v[2:3], 0, v[0:1]
	v_cvt_pk_bf16_f32 v54, v54, v55
	v_cvt_pk_bf16_f32 v55, v56, v57
	global_store_dwordx2 v[2:3], v[54:55], off nt
	v_cvt_pk_bf16_f32 v54, v58, v59
	v_cvt_pk_bf16_f32 v55, v60, v61
	global_store_dwordx2 v[2:3], v[54:55], off offset:16 nt
	v_cvt_pk_bf16_f32 v54, v62, v63
	v_cvt_pk_bf16_f32 v55, v64, v65
	global_store_dwordx2 v[2:3], v[54:55], off offset:32 nt
	v_cvt_pk_bf16_f32 v54, v66, v67
	v_cvt_pk_bf16_f32 v55, v68, v69
	global_store_dwordx2 v[2:3], v[54:55], off offset:48 nt
.LBB0_948:
	s_or_b64 exec, exec, s[6:7]
	v_mov_b64_e32 v[2:3], 0x100
	v_mov_b64_e32 v[54:55], 0xc952000
	v_mov_b64_e32 v[56:57], 0xdb62000
	v_mov_b32_e32 v1, v136
	s_and_saveexec_b64 s[6:7], s[0:1]
	v_mov_b64_e32 v[2:3], 0x1200
	v_mov_b64_e32 v[54:55], 0xd152000
	v_mov_b64_e32 v[56:57], 0xe362000
	v_mov_b32_e32 v74, v75
	v_mov_b32_e32 v1, v76
	s_or_b64 exec, exec, s[6:7]
	v_lshl_or_b32 v1, v1, 3, v137
	s_and_saveexec_b64 s[0:1], vcc
	s_xor_b64 s[0:1], exec, s[0:1]
	s_cbranch_execz .LBB0_952
	v_lshl_add_u64 v[54:55], s[26:27], 0, v[56:57]
	v_mad_i64_i32 v[56:57], s[6:7], v2, v1, 0
	v_lshlrev_b64 v[56:57], 7, v[56:57]
	v_lshl_add_u64 v[54:55], v[54:55], 0, v[56:57]
	v_mad_u64_u32 v[56:57], s[6:7], v2, v122, 0
	v_lshl_add_u64 v[54:55], v[56:57], 1, v[54:55]
	v_lshlrev_b32_e32 v56, 1, v74
	v_mov_b32_e32 v57, v4
	v_lshl_add_u64 v[54:55], v[54:55], 0, v[56:57]
	v_cvt_pk_bf16_f32 v1, v38, s0
	global_store_short v[54:55], v1, off nt
	v_cvt_pk_bf16_f32 v1, v39, s0
	v_lshlrev_b32_e32 v38, 1, v2
	v_mov_b32_e32 v39, v4
	v_lshl_add_u64 v[54:55], v[54:55], 0, v[38:39]
	global_store_short v[54:55], v1, off nt
	v_cvt_pk_bf16_f32 v1, v40, s0
	v_lshl_add_u64 v[54:55], v[54:55], 0, v[38:39]
	global_store_short v[54:55], v1, off nt
	v_cvt_pk_bf16_f32 v1, v41, s0
	v_lshl_add_u64 v[40:41], v[54:55], 0, v[38:39]
	global_store_short v[40:41], v1, off nt
	v_cvt_pk_bf16_f32 v1, v42, s0
	v_mad_u64_u32 v[40:41], s[6:7], v2, 10, v[40:41]
	global_store_short v[40:41], v1, off nt
	v_cvt_pk_bf16_f32 v1, v43, s0
	v_lshl_add_u64 v[40:41], v[40:41], 0, v[38:39]
	global_store_short v[40:41], v1, off nt
	v_cvt_pk_bf16_f32 v1, v44, s0
	v_lshl_add_u64 v[40:41], v[40:41], 0, v[38:39]
	global_store_short v[40:41], v1, off nt
	v_cvt_pk_bf16_f32 v1, v45, s0
	v_lshl_add_u64 v[40:41], v[40:41], 0, v[38:39]
	global_store_short v[40:41], v1, off nt
	v_cvt_pk_bf16_f32 v1, v46, s0
	v_mad_u64_u32 v[40:41], s[6:7], v2, 10, v[40:41]
	global_store_short v[40:41], v1, off nt
	v_cvt_pk_bf16_f32 v1, v47, s0
	v_lshl_add_u64 v[40:41], v[40:41], 0, v[38:39]
	global_store_short v[40:41], v1, off nt
	v_cvt_pk_bf16_f32 v1, v48, s0
	v_lshl_add_u64 v[40:41], v[40:41], 0, v[38:39]
	global_store_short v[40:41], v1, off nt
	v_cvt_pk_bf16_f32 v1, v49, s0
	v_lshl_add_u64 v[40:41], v[40:41], 0, v[38:39]
	global_store_short v[40:41], v1, off nt
	v_cvt_pk_bf16_f32 v1, v50, s0
	v_mad_u64_u32 v[2:3], s[6:7], v2, 10, v[40:41]
	global_store_short v[2:3], v1, off nt
	v_cvt_pk_bf16_f32 v1, v51, s0
	v_lshl_add_u64 v[2:3], v[2:3], 0, v[38:39]
	global_store_short v[2:3], v1, off nt
	v_cvt_pk_bf16_f32 v1, v52, s0
	v_lshl_add_u64 v[2:3], v[2:3], 0, v[38:39]
	global_store_short v[2:3], v1, off nt
	v_cvt_pk_bf16_f32 v1, v53, s0
	v_lshl_add_u64 v[2:3], v[2:3], 0, v[38:39]
	global_store_short v[2:3], v1, off nt
.LBB0_952:
	s_andn2_saveexec_b64 s[0:1], s[0:1]
	s_cbranch_execz .LBB0_954
	v_lshl_add_u64 v[54:55], s[26:27], 0, v[54:55]
	v_lshlrev_b32_e32 v2, 7, v2
	v_mad_i64_i32 v[2:3], s[6:7], v2, v1, v[54:55]
	v_lshlrev_b32_e32 v54, 7, v74
	v_mov_b32_e32 v55, v4
	v_lshl_add_u64 v[2:3], v[2:3], 0, v[54:55]
	v_mov_b32_e32 v1, v4
	v_lshl_add_u64 v[2:3], v[2:3], 0, v[0:1]
	v_cvt_pk_bf16_f32 v38, v38, v39
	v_cvt_pk_bf16_f32 v39, v40, v41
	global_store_dwordx2 v[2:3], v[38:39], off offset:64 nt
	v_cvt_pk_bf16_f32 v38, v42, v43
	v_cvt_pk_bf16_f32 v39, v44, v45
	global_store_dwordx2 v[2:3], v[38:39], off offset:80 nt
	v_cvt_pk_bf16_f32 v38, v46, v47
	v_cvt_pk_bf16_f32 v39, v48, v49
	global_store_dwordx2 v[2:3], v[38:39], off offset:96 nt
	v_cvt_pk_bf16_f32 v38, v50, v51
	v_cvt_pk_bf16_f32 v39, v52, v53
	global_store_dwordx2 v[2:3], v[38:39], off offset:112 nt
.LBB0_954:
	s_or_b64 exec, exec, s[0:1]
	v_or_b32_e32 v1, 0x60, v144
	s_movk_i32 s6, 0xff
	v_cmp_lt_i32_e64 s[0:1], s89, v1
	v_bitop3_b32 v42, v144, s6, v251 bitop3:0xc8
	v_add_u32_e32 v1, 0xffffc060, v144
	s_movk_i32 s6, 0x1ff
	v_lshrrev_b32_e32 v45, 9, v1
	v_bitop3_b32 v1, v144, s6, v251 bitop3:0xc8
	v_or_b32_e32 v47, 0x1000, v1
	v_add_u32_e32 v1, 0xffffe060, v144
	s_movk_i32 s6, 0xfff
	v_lshrrev_b32_e32 v48, 12, v1
	v_bitop3_b32 v49, v144, s6, v251 bitop3:0xc8
	v_mov_b64_e32 v[2:3], 0x100
	v_mov_b64_e32 v[38:39], 0xc952000
	v_mov_b64_e32 v[40:41], 0xdb62000
	v_cndmask_b32_e64 v43, v47, v49, s[4:5]
	v_cndmask_b32_e64 v44, v45, v48, s[4:5]
	v_mov_b32_e32 v1, v42
	v_mov_b32_e32 v46, v136
	s_and_saveexec_b64 s[6:7], s[0:1]
	v_cndmask_b32_e64 v1, v47, v49, s[4:5]
	v_cndmask_b32_e64 v46, v45, v48, s[4:5]
	v_mov_b64_e32 v[2:3], 0x1200
	v_mov_b64_e32 v[38:39], 0xd152000
	v_mov_b64_e32 v[40:41], 0xe362000
	s_or_b64 exec, exec, s[6:7]
	v_lshl_or_b32 v3, v46, 3, v137
	s_and_saveexec_b64 s[4:5], vcc
	s_xor_b64 s[4:5], exec, s[4:5]
	s_cbranch_execz .LBB0_958
	v_lshl_add_u64 v[38:39], s[26:27], 0, v[40:41]
	v_mad_i64_i32 v[40:41], s[6:7], v2, v3, 0
	v_lshlrev_b64 v[40:41], 7, v[40:41]
	v_lshl_add_u64 v[38:39], v[38:39], 0, v[40:41]
	v_mad_u64_u32 v[40:41], s[6:7], v2, v145, 0
	v_lshl_add_u64 v[38:39], v[40:41], 1, v[38:39]
	v_lshlrev_b32_e32 v40, 1, v1
	v_mov_b32_e32 v41, v4
	v_lshl_add_u64 v[38:39], v[38:39], 0, v[40:41]
	v_cvt_pk_bf16_f32 v1, v22, s0
	global_store_short v[38:39], v1, off nt
	v_cvt_pk_bf16_f32 v1, v23, s0
	v_lshlrev_b32_e32 v22, 1, v2
	v_mov_b32_e32 v23, v4
	v_lshl_add_u64 v[38:39], v[38:39], 0, v[22:23]
	global_store_short v[38:39], v1, off nt
	v_cvt_pk_bf16_f32 v1, v24, s0
	v_lshl_add_u64 v[38:39], v[38:39], 0, v[22:23]
	global_store_short v[38:39], v1, off nt
	v_cvt_pk_bf16_f32 v1, v25, s0
	v_lshl_add_u64 v[24:25], v[38:39], 0, v[22:23]
	global_store_short v[24:25], v1, off nt
	v_cvt_pk_bf16_f32 v1, v26, s0
	v_mad_u64_u32 v[24:25], s[6:7], v2, 10, v[24:25]
	global_store_short v[24:25], v1, off nt
	v_cvt_pk_bf16_f32 v1, v27, s0
	v_lshl_add_u64 v[24:25], v[24:25], 0, v[22:23]
	global_store_short v[24:25], v1, off nt
	v_cvt_pk_bf16_f32 v1, v28, s0
	v_lshl_add_u64 v[24:25], v[24:25], 0, v[22:23]
	global_store_short v[24:25], v1, off nt
	v_cvt_pk_bf16_f32 v1, v29, s0
	v_lshl_add_u64 v[24:25], v[24:25], 0, v[22:23]
	global_store_short v[24:25], v1, off nt
	v_cvt_pk_bf16_f32 v1, v30, s0
	v_mad_u64_u32 v[24:25], s[6:7], v2, 10, v[24:25]
	global_store_short v[24:25], v1, off nt
	v_cvt_pk_bf16_f32 v1, v31, s0
	v_lshl_add_u64 v[24:25], v[24:25], 0, v[22:23]
	global_store_short v[24:25], v1, off nt
	v_cvt_pk_bf16_f32 v1, v32, s0
	v_lshl_add_u64 v[24:25], v[24:25], 0, v[22:23]
	global_store_short v[24:25], v1, off nt
	v_cvt_pk_bf16_f32 v1, v33, s0
	v_lshl_add_u64 v[24:25], v[24:25], 0, v[22:23]
	global_store_short v[24:25], v1, off nt
	v_cvt_pk_bf16_f32 v1, v34, s0
	v_mad_u64_u32 v[2:3], s[6:7], v2, 10, v[24:25]
	global_store_short v[2:3], v1, off nt
	v_cvt_pk_bf16_f32 v1, v35, s0
	v_lshl_add_u64 v[2:3], v[2:3], 0, v[22:23]
	global_store_short v[2:3], v1, off nt
	v_cvt_pk_bf16_f32 v1, v36, s0
	v_lshl_add_u64 v[2:3], v[2:3], 0, v[22:23]
	global_store_short v[2:3], v1, off nt
	v_cvt_pk_bf16_f32 v1, v37, s0
	v_lshl_add_u64 v[2:3], v[2:3], 0, v[22:23]
	global_store_short v[2:3], v1, off nt
.LBB0_958:
	s_andn2_saveexec_b64 s[4:5], s[4:5]
	s_cbranch_execz .LBB0_960
	v_lshl_add_u64 v[38:39], s[26:27], 0, v[38:39]
	v_lshlrev_b32_e32 v2, 7, v2
	v_mad_i64_i32 v[2:3], s[6:7], v2, v3, v[38:39]
	v_lshlrev_b32_e32 v38, 7, v1
	v_mov_b32_e32 v39, v4
	v_lshl_add_u64 v[2:3], v[2:3], 0, v[38:39]
	v_mov_b32_e32 v1, v4
	v_lshl_add_u64 v[2:3], v[2:3], 0, v[0:1]
	v_cvt_pk_bf16_f32 v22, v22, v23
	v_cvt_pk_bf16_f32 v23, v24, v25
	global_store_dwordx2 v[2:3], v[22:23], off nt
	v_cvt_pk_bf16_f32 v22, v26, v27
	v_cvt_pk_bf16_f32 v23, v28, v29
	global_store_dwordx2 v[2:3], v[22:23], off offset:16 nt
	v_cvt_pk_bf16_f32 v22, v30, v31
	v_cvt_pk_bf16_f32 v23, v32, v33
	global_store_dwordx2 v[2:3], v[22:23], off offset:32 nt
	v_cvt_pk_bf16_f32 v22, v34, v35
	v_cvt_pk_bf16_f32 v23, v36, v37
	global_store_dwordx2 v[2:3], v[22:23], off offset:48 nt
.LBB0_960:
	s_or_b64 exec, exec, s[4:5]
	v_mov_b64_e32 v[2:3], 0x100
	v_mov_b64_e32 v[22:23], 0xc952000
	v_mov_b64_e32 v[24:25], 0xdb62000
	s_and_saveexec_b64 s[4:5], s[0:1]
	v_mov_b64_e32 v[2:3], 0x1200
	v_mov_b64_e32 v[22:23], 0xd152000
	v_mov_b64_e32 v[24:25], 0xe362000
	v_mov_b32_e32 v42, v43
	v_mov_b32_e32 v136, v44
	s_or_b64 exec, exec, s[4:5]
	v_lshl_or_b32 v1, v136, 3, v137
	s_and_saveexec_b64 s[0:1], vcc
	s_xor_b64 s[0:1], exec, s[0:1]
	s_cbranch_execz .LBB0_964
	v_mad_i64_i32 v[0:1], s[4:5], v2, v1, 0
	v_lshl_add_u64 v[22:23], s[26:27], 0, v[24:25]
	v_lshlrev_b64 v[0:1], 7, v[0:1]
	v_lshl_add_u64 v[0:1], v[22:23], 0, v[0:1]
	v_mad_u64_u32 v[22:23], s[4:5], v2, v122, 0
	v_lshl_add_u64 v[0:1], v[22:23], 1, v[0:1]
	v_lshlrev_b32_e32 v22, 1, v42
	v_mov_b32_e32 v23, v4
	v_lshl_add_u64 v[0:1], v[0:1], 0, v[22:23]
	v_cvt_pk_bf16_f32 v3, v6, s0
	global_store_short v[0:1], v3, off nt
	v_cvt_pk_bf16_f32 v3, v7, s0
	v_lshlrev_b32_e32 v6, 1, v2
	v_mov_b32_e32 v7, v4
	v_lshl_add_u64 v[0:1], v[0:1], 0, v[6:7]
	global_store_short v[0:1], v3, off nt
	v_cvt_pk_bf16_f32 v3, v8, s0
	v_lshl_add_u64 v[0:1], v[0:1], 0, v[6:7]
	global_store_short v[0:1], v3, off nt
	v_cvt_pk_bf16_f32 v3, v9, s0
	v_lshl_add_u64 v[0:1], v[0:1], 0, v[6:7]
	global_store_short v[0:1], v3, off nt
	v_cvt_pk_bf16_f32 v3, v10, s0
	v_mad_u64_u32 v[0:1], s[4:5], v2, 10, v[0:1]
	global_store_short v[0:1], v3, off nt
	v_cvt_pk_bf16_f32 v3, v11, s0
	v_lshl_add_u64 v[0:1], v[0:1], 0, v[6:7]
	global_store_short v[0:1], v3, off nt
	v_cvt_pk_bf16_f32 v3, v12, s0
	v_lshl_add_u64 v[0:1], v[0:1], 0, v[6:7]
	global_store_short v[0:1], v3, off nt
	v_cvt_pk_bf16_f32 v3, v13, s0
	v_lshl_add_u64 v[0:1], v[0:1], 0, v[6:7]
	global_store_short v[0:1], v3, off nt
	v_cvt_pk_bf16_f32 v3, v14, s0
	v_mad_u64_u32 v[0:1], s[4:5], v2, 10, v[0:1]
	global_store_short v[0:1], v3, off nt
	v_cvt_pk_bf16_f32 v3, v15, s0
	v_lshl_add_u64 v[0:1], v[0:1], 0, v[6:7]
	global_store_short v[0:1], v3, off nt
	v_cvt_pk_bf16_f32 v3, v16, s0
	v_lshl_add_u64 v[0:1], v[0:1], 0, v[6:7]
	global_store_short v[0:1], v3, off nt
	v_cvt_pk_bf16_f32 v3, v17, s0
	v_lshl_add_u64 v[0:1], v[0:1], 0, v[6:7]
	global_store_short v[0:1], v3, off nt
	v_cvt_pk_bf16_f32 v3, v18, s0
	v_mad_u64_u32 v[0:1], s[4:5], v2, 10, v[0:1]
	global_store_short v[0:1], v3, off nt
	v_cvt_pk_bf16_f32 v2, v19, s0
	v_lshl_add_u64 v[0:1], v[0:1], 0, v[6:7]
	global_store_short v[0:1], v2, off nt
	v_cvt_pk_bf16_f32 v2, v20, s0
	v_lshl_add_u64 v[0:1], v[0:1], 0, v[6:7]
	global_store_short v[0:1], v2, off nt
	v_cvt_pk_bf16_f32 v2, v21, s0
	v_lshl_add_u64 v[0:1], v[0:1], 0, v[6:7]
	global_store_short v[0:1], v2, off nt
.LBB0_964:
	s_andn2_saveexec_b64 s[0:1], s[0:1]
	s_cbranch_execz .LBB0_966
	v_lshl_add_u64 v[22:23], s[26:27], 0, v[22:23]
	v_lshlrev_b32_e32 v2, 7, v2
	v_mad_i64_i32 v[2:3], s[4:5], v2, v1, v[22:23]
	v_lshlrev_b32_e32 v22, 7, v42
	v_mov_b32_e32 v23, v4
	v_lshl_add_u64 v[2:3], v[2:3], 0, v[22:23]
	v_mov_b32_e32 v1, v4
	v_lshl_add_u64 v[0:1], v[2:3], 0, v[0:1]
	v_cvt_pk_bf16_f32 v2, v6, v7
	v_cvt_pk_bf16_f32 v3, v8, v9
	global_store_dwordx2 v[0:1], v[2:3], off offset:64 nt
	v_cvt_pk_bf16_f32 v2, v10, v11
	v_cvt_pk_bf16_f32 v3, v12, v13
	global_store_dwordx2 v[0:1], v[2:3], off offset:80 nt
	v_cvt_pk_bf16_f32 v2, v14, v15
	v_cvt_pk_bf16_f32 v3, v16, v17
	global_store_dwordx2 v[0:1], v[2:3], off offset:96 nt
	v_cvt_pk_bf16_f32 v2, v18, v19
	v_cvt_pk_bf16_f32 v3, v20, v21
	global_store_dwordx2 v[0:1], v[2:3], off offset:112 nt

.LBB0_972:
	s_or_b64 exec, exec, s[0:1]
	v_add_u32_e32 v154, v3, v139
	v_ashrrev_i32_e32 v155, 31, v154
	v_lshlrev_b64 v[2:3], v2, v[154:155]
	v_mov_b32_e32 v145, v4
	v_lshl_add_u64 v[146:147], s[26:27], 0, v[146:147]
	v_lshl_add_u64 v[2:3], v[2:3], 0, v[144:145]
	v_mad_u64_u32 v[144:145], s[0:1], v2, s50, v[146:147]
	v_mad_i32_i24 v145, v3, s50, v145
	v_ashrrev_i32_e32 v135, 31, v134
	v_lshl_add_u64 v[144:145], v[134:135], 1, v[144:145]
	v_lshlrev_b32_e32 v2, 1, v152
	v_mov_b32_e32 v3, v4
	v_pk_mul_f32 v[118:119], v[118:119], s[64:65] op_sel_hi:[1,0]
	v_pk_mul_f32 v[120:121], v[120:121], s[64:65] op_sel_hi:[1,0]
	v_lshl_add_u64 v[144:145], v[144:145], 0, v[2:3]
	v_cvt_pk_bf16_f32 v118, v118, v119
	v_cvt_pk_bf16_f32 v119, v120, v121
	global_store_dwordx2 v[144:145], v[118:119], off nt
	v_pk_mul_f32 v[118:119], v[122:123], s[64:65] op_sel_hi:[1,0]
	v_pk_mul_f32 v[120:121], v[124:125], s[64:65] op_sel_hi:[1,0]
	v_cvt_pk_bf16_f32 v118, v118, v119
	v_cvt_pk_bf16_f32 v119, v120, v121
	global_store_dwordx2 v[144:145], v[118:119], off offset:16 nt
	v_pk_mul_f32 v[118:119], v[126:127], s[64:65] op_sel_hi:[1,0]
	v_pk_mul_f32 v[120:121], v[128:129], s[64:65] op_sel_hi:[1,0]
	v_cvt_pk_bf16_f32 v118, v118, v119
	v_cvt_pk_bf16_f32 v119, v120, v121
	global_store_dwordx2 v[144:145], v[118:119], off offset:32 nt
	v_pk_mul_f32 v[118:119], v[130:131], s[64:65] op_sel_hi:[1,0]
	v_pk_mul_f32 v[120:121], v[132:133], s[64:65] op_sel_hi:[1,0]
	v_cvt_pk_bf16_f32 v118, v118, v119
	v_cvt_pk_bf16_f32 v119, v120, v121
	v_mov_b64_e32 v[122:123], 0xb152000
	v_mov_b64_e32 v[120:121], 8
	v_mov_b32_e32 v3, v148
	global_store_dwordx2 v[144:145], v[118:119], off offset:48 nt
	s_and_saveexec_b64 s[0:1], s[6:7]
	v_mov_b64_e32 v[122:123], 0xbd52000
	v_mov_b64_e32 v[120:121], 12
	v_mov_b32_e32 v3, v150
	v_mov_b32_e32 v136, v137
	s_or_b64 exec, exec, s[0:1]
	v_or_b32_e32 v1, 32, v151
	s_mov_b32 s0, 0x2aaaaaab
	v_mul_hi_i32 v118, v1, s0
	v_lshrrev_b32_e32 v119, 31, v118
	v_ashrrev_i32_e32 v118, 4, v118
	v_add_u32_e32 v121, v118, v119
	s_movk_i32 s0, 0x60
	v_mul_lo_u32 v118, v121, s0
	v_sub_u32_e32 v118, v1, v118
	v_cmp_eq_u32_e64 s[4:5], 64, v118
	s_and_b64 s[6:7], s[6:7], s[4:5]
	s_and_saveexec_b64 s[0:1], s[6:7]
	s_cbranch_execz .LBB0_976
	v_readlane_b32 s6, v253, 31
	v_lshlrev_b32_e32 v124, 7, v136
	v_mov_b32_e32 v125, v4
	v_readlane_b32 s7, v253, 32
	v_mov_b32_e32 v1, v4
	s_nop 0
	v_lshl_add_u64 v[126:127], s[6:7], 0, v[124:125]
	v_readlane_b32 s6, v254, 47
	v_readlane_b32 s7, v254, 48
	v_lshl_add_u64 v[132:133], v[126:127], 0, v[0:1]
	s_nop 0
	v_lshl_add_u64 v[124:125], s[6:7], 0, v[124:125]
	v_lshl_add_u64 v[144:145], v[124:125], 0, v[0:1]
	global_load_dwordx4 v[124:127], v[132:133], off
	global_load_dwordx4 v[128:131], v[144:145], off
	s_waitcnt vmcnt(0)
	v_pk_mul_f32 v[146:147], v[106:107], v[128:129]
	s_nop 0
	v_pk_fma_f32 v[146:147], v[102:103], v[124:125], v[146:147] neg_lo:[0,0,1] neg_hi:[0,0,1]
	v_pk_mul_f32 v[102:103], v[102:103], v[128:129]
	s_nop 0
	v_pk_fma_f32 v[106:107], v[106:107], v[124:125], v[102:103]
	v_pk_mul_f32 v[102:103], v[108:109], v[130:131]
	s_nop 0
	v_pk_fma_f32 v[128:129], v[104:105], v[126:127], v[102:103] neg_lo:[0,0,1] neg_hi:[0,0,1]
	v_pk_mul_f32 v[102:103], v[104:105], v[130:131]
	s_nop 0
	v_pk_fma_f32 v[108:109], v[108:109], v[126:127], v[102:103]
	global_load_dwordx4 v[102:105], v[132:133], off offset:64
	global_load_dwordx4 v[124:127], v[144:145], off offset:64
	s_waitcnt vmcnt(0)
	v_pk_mul_f32 v[130:131], v[114:115], v[124:125]
	s_nop 0
	v_pk_fma_f32 v[130:131], v[110:111], v[102:103], v[130:131] neg_lo:[0,0,1] neg_hi:[0,0,1]
	v_pk_mul_f32 v[110:111], v[110:111], v[124:125]
	s_nop 0
	v_pk_fma_f32 v[114:115], v[114:115], v[102:103], v[110:111]
	v_pk_mul_f32 v[102:103], v[116:117], v[126:127]
	v_mov_b32_e32 v110, v130
	v_pk_fma_f32 v[124:125], v[112:113], v[104:105], v[102:103] neg_lo:[0,0,1] neg_hi:[0,0,1]
	v_pk_mul_f32 v[102:103], v[112:113], v[126:127]
	v_mov_b32_e32 v111, v131
	v_pk_fma_f32 v[116:117], v[116:117], v[104:105], v[102:103]
	v_mov_b32_e32 v102, v146
	v_mov_b32_e32 v103, v147
	v_mov_b32_e32 v104, v128
	v_mov_b32_e32 v105, v129
	v_mov_b32_e32 v112, v124
	v_mov_b32_e32 v113, v125
.LBB0_976:
	s_or_b64 exec, exec, s[0:1]
	v_add_u32_e32 v124, v3, v121
	v_ashrrev_i32_e32 v125, 31, v124
	v_lshlrev_b64 v[124:125], v120, v[124:125]
	v_mov_b32_e32 v137, v4
	v_lshl_add_u64 v[122:123], s[26:27], 0, v[122:123]
	v_lshl_add_u64 v[124:125], v[124:125], 0, v[136:137]
	v_mad_u64_u32 v[122:123], s[0:1], v124, s50, v[122:123]
	v_mad_i32_i24 v123, v125, s50, v123
	v_ashrrev_i32_e32 v119, 31, v118
	v_lshl_add_u64 v[122:123], v[118:119], 1, v[122:123]
	v_mov_b32_e32 v3, v4
	v_pk_mul_f32 v[102:103], v[102:103], s[64:65] op_sel_hi:[1,0]
	v_pk_mul_f32 v[104:105], v[104:105], s[64:65] op_sel_hi:[1,0]
	v_lshl_add_u64 v[122:123], v[122:123], 0, v[2:3]
	v_cvt_pk_bf16_f32 v102, v102, v103
	v_cvt_pk_bf16_f32 v103, v104, v105
	global_store_dwordx2 v[122:123], v[102:103], off nt
	v_pk_mul_f32 v[102:103], v[106:107], s[64:65] op_sel_hi:[1,0]
	v_pk_mul_f32 v[104:105], v[108:109], s[64:65] op_sel_hi:[1,0]
	v_cvt_pk_bf16_f32 v102, v102, v103
	v_cvt_pk_bf16_f32 v103, v104, v105
	global_store_dwordx2 v[122:123], v[102:103], off offset:16 nt
	v_pk_mul_f32 v[102:103], v[110:111], s[64:65] op_sel_hi:[1,0]
	v_pk_mul_f32 v[104:105], v[112:113], s[64:65] op_sel_hi:[1,0]
	v_cvt_pk_bf16_f32 v102, v102, v103
	v_cvt_pk_bf16_f32 v103, v104, v105
	global_store_dwordx2 v[122:123], v[102:103], off offset:32 nt
	v_pk_mul_f32 v[102:103], v[114:115], s[64:65] op_sel_hi:[1,0]
	v_pk_mul_f32 v[104:105], v[116:117], s[64:65] op_sel_hi:[1,0]
	v_or_b32_e32 v1, 32, v149
	v_cvt_pk_bf16_f32 v102, v102, v103
	v_cvt_pk_bf16_f32 v103, v104, v105
	v_cmp_lt_i32_e64 s[6:7], s89, v1
	s_movk_i32 s0, 0xbf
	v_add_u32_e32 v1, 0xffffe020, v149
	global_store_dwordx2 v[122:123], v[102:103], off offset:48 nt
	v_bitop3_b32 v102, v149, s0, 32 bitop3:0xc8
	s_movk_i32 s0, 0xfbf
	v_lshrrev_b32_e32 v1, 9, v1
	v_bitop3_b32 v103, v149, s0, 32 bitop3:0xc8
	v_and_b32_e32 v110, 0x7ffff8, v1
	v_mov_b64_e32 v[108:109], 0xb152000
	v_mov_b64_e32 v[104:105], 8
	v_mov_b32_e32 v3, v148
	v_mov_b32_e32 v106, v102
	s_and_saveexec_b64 s[0:1], s[6:7]
	v_mov_b64_e32 v[108:109], 0xbd52000
	v_mov_b64_e32 v[104:105], 12
	v_mov_b32_e32 v3, v110
	v_mov_b32_e32 v106, v103
	s_or_b64 exec, exec, s[0:1]
	s_and_b64 s[14:15], s[6:7], vcc
	s_and_saveexec_b64 s[0:1], s[14:15]
	s_cbranch_execz .LBB0_980
	v_readlane_b32 s14, v253, 31
	v_lshlrev_b32_e32 v112, 7, v106
	v_mov_b32_e32 v113, v4
	v_readlane_b32 s15, v253, 32
	v_mov_b32_e32 v1, v4
	s_nop 0
	v_lshl_add_u64 v[114:115], s[14:15], 0, v[112:113]
	v_readlane_b32 s14, v254, 47
	v_readlane_b32 s15, v254, 48
	v_lshl_add_u64 v[116:117], v[114:115], 0, v[0:1]
	s_nop 0
	v_lshl_add_u64 v[112:113], s[14:15], 0, v[112:113]
	v_lshl_add_u64 v[126:127], v[112:113], 0, v[0:1]
	global_load_dwordx4 v[112:115], v[116:117], off
	global_load_dwordx4 v[122:125], v[126:127], off
	s_waitcnt vmcnt(0)
	v_pk_mul_f32 v[128:129], v[90:91], v[122:123]
	s_nop 0
	v_pk_fma_f32 v[128:129], v[86:87], v[112:113], v[128:129] neg_lo:[0,0,1] neg_hi:[0,0,1]
	v_pk_mul_f32 v[86:87], v[86:87], v[122:123]
	s_nop 0
	v_pk_fma_f32 v[90:91], v[90:91], v[112:113], v[86:87]
	v_pk_mul_f32 v[86:87], v[92:93], v[124:125]
	s_nop 0
	v_pk_fma_f32 v[122:123], v[88:89], v[114:115], v[86:87] neg_lo:[0,0,1] neg_hi:[0,0,1]
	v_pk_mul_f32 v[86:87], v[88:89], v[124:125]
	s_nop 0
	v_pk_fma_f32 v[92:93], v[92:93], v[114:115], v[86:87]
	global_load_dwordx4 v[86:89], v[116:117], off offset:64
	global_load_dwordx4 v[112:115], v[126:127], off offset:64
	s_waitcnt vmcnt(0)
	v_pk_mul_f32 v[116:117], v[98:99], v[112:113]
	s_nop 0
	v_pk_fma_f32 v[116:117], v[94:95], v[86:87], v[116:117] neg_lo:[0,0,1] neg_hi:[0,0,1]
	v_pk_mul_f32 v[94:95], v[94:95], v[112:113]
	s_nop 0
	v_pk_fma_f32 v[98:99], v[98:99], v[86:87], v[94:95]
	v_pk_mul_f32 v[86:87], v[100:101], v[114:115]
	v_mov_b32_e32 v94, v116
	v_pk_fma_f32 v[112:113], v[96:97], v[88:89], v[86:87] neg_lo:[0,0,1] neg_hi:[0,0,1]
	v_pk_mul_f32 v[86:87], v[96:97], v[114:115]
	v_mov_b32_e32 v95, v117
	v_pk_fma_f32 v[100:101], v[100:101], v[88:89], v[86:87]
	v_mov_b32_e32 v86, v128
	v_mov_b32_e32 v87, v129
	v_mov_b32_e32 v88, v122
	v_mov_b32_e32 v89, v123
	v_mov_b32_e32 v96, v112
	v_mov_b32_e32 v97, v113
.LBB0_980:
	s_or_b64 exec, exec, s[0:1]
	v_add_u32_e32 v112, v3, v139
	v_ashrrev_i32_e32 v113, 31, v112
	v_lshlrev_b64 v[104:105], v104, v[112:113]
	v_mov_b32_e32 v107, v4
	v_lshl_add_u64 v[108:109], s[26:27], 0, v[108:109]
	v_lshl_add_u64 v[104:105], v[104:105], 0, v[106:107]
	v_mad_u64_u32 v[106:107], s[0:1], v104, s50, v[108:109]
	v_mad_i32_i24 v107, v105, s50, v107
	v_lshl_add_u64 v[104:105], v[134:135], 1, v[106:107]
	v_mov_b32_e32 v3, v4
	v_pk_mul_f32 v[86:87], v[86:87], s[64:65] op_sel_hi:[1,0]
	v_pk_mul_f32 v[88:89], v[88:89], s[64:65] op_sel_hi:[1,0]
	v_lshl_add_u64 v[104:105], v[104:105], 0, v[2:3]
	v_cvt_pk_bf16_f32 v86, v86, v87
	v_cvt_pk_bf16_f32 v87, v88, v89
	global_store_dwordx2 v[104:105], v[86:87], off nt
	v_pk_mul_f32 v[86:87], v[90:91], s[64:65] op_sel_hi:[1,0]
	v_pk_mul_f32 v[88:89], v[92:93], s[64:65] op_sel_hi:[1,0]
	v_cvt_pk_bf16_f32 v86, v86, v87
	v_cvt_pk_bf16_f32 v87, v88, v89
	global_store_dwordx2 v[104:105], v[86:87], off offset:16 nt
	v_pk_mul_f32 v[86:87], v[94:95], s[64:65] op_sel_hi:[1,0]
	v_pk_mul_f32 v[88:89], v[96:97], s[64:65] op_sel_hi:[1,0]
	v_cvt_pk_bf16_f32 v86, v86, v87
	v_cvt_pk_bf16_f32 v87, v88, v89
	global_store_dwordx2 v[104:105], v[86:87], off offset:32 nt
	v_pk_mul_f32 v[86:87], v[98:99], s[64:65] op_sel_hi:[1,0]
	v_pk_mul_f32 v[88:89], v[100:101], s[64:65] op_sel_hi:[1,0]
	v_cvt_pk_bf16_f32 v86, v86, v87
	v_cvt_pk_bf16_f32 v87, v88, v89
	global_store_dwordx2 v[104:105], v[86:87], off offset:48 nt
	v_mov_b64_e32 v[88:89], 0xb152000
	v_mov_b64_e32 v[86:87], 8
	v_mov_b32_e32 v3, v148
	s_and_saveexec_b64 s[0:1], s[6:7]
	v_mov_b64_e32 v[88:89], 0xbd52000
	v_mov_b64_e32 v[86:87], 12
	v_mov_b32_e32 v3, v110
	v_mov_b32_e32 v102, v103
	s_or_b64 exec, exec, s[0:1]
	s_and_b64 s[6:7], s[6:7], s[4:5]
	s_and_saveexec_b64 s[0:1], s[6:7]
	s_cbranch_execz .LBB0_984
	v_readlane_b32 s6, v253, 31
	v_lshlrev_b32_e32 v90, 7, v102
	v_mov_b32_e32 v91, v4
	v_readlane_b32 s7, v253, 32
	v_mov_b32_e32 v1, v4
	s_nop 0
	v_lshl_add_u64 v[92:93], s[6:7], 0, v[90:91]
	v_readlane_b32 s6, v254, 47
	v_readlane_b32 s7, v254, 48
	v_lshl_add_u64 v[98:99], v[92:93], 0, v[0:1]
	s_nop 0
	v_lshl_add_u64 v[90:91], s[6:7], 0, v[90:91]
	v_lshl_add_u64 v[100:101], v[90:91], 0, v[0:1]
	global_load_dwordx4 v[90:93], v[98:99], off
	global_load_dwordx4 v[94:97], v[100:101], off
	s_waitcnt vmcnt(0)
	v_pk_mul_f32 v[104:105], v[74:75], v[94:95]
	s_nop 0
	v_pk_fma_f32 v[104:105], v[70:71], v[90:91], v[104:105] neg_lo:[0,0,1] neg_hi:[0,0,1]
	v_pk_mul_f32 v[70:71], v[70:71], v[94:95]
	s_nop 0
	v_pk_fma_f32 v[74:75], v[74:75], v[90:91], v[70:71]
	v_pk_mul_f32 v[70:71], v[76:77], v[96:97]
	s_nop 0
	v_pk_fma_f32 v[94:95], v[72:73], v[92:93], v[70:71] neg_lo:[0,0,1] neg_hi:[0,0,1]
	v_pk_mul_f32 v[70:71], v[72:73], v[96:97]
	s_nop 0
	v_pk_fma_f32 v[76:77], v[76:77], v[92:93], v[70:71]
	global_load_dwordx4 v[70:73], v[98:99], off offset:64
	global_load_dwordx4 v[90:93], v[100:101], off offset:64
	s_waitcnt vmcnt(0)
	v_pk_mul_f32 v[96:97], v[82:83], v[90:91]
	s_nop 0
	v_pk_fma_f32 v[96:97], v[78:79], v[70:71], v[96:97] neg_lo:[0,0,1] neg_hi:[0,0,1]
	v_pk_mul_f32 v[78:79], v[78:79], v[90:91]
	s_nop 0
	v_pk_fma_f32 v[82:83], v[82:83], v[70:71], v[78:79]
	v_pk_mul_f32 v[70:71], v[84:85], v[92:93]
	v_mov_b32_e32 v78, v96
	v_pk_fma_f32 v[90:91], v[80:81], v[72:73], v[70:71] neg_lo:[0,0,1] neg_hi:[0,0,1]
	v_pk_mul_f32 v[70:71], v[80:81], v[92:93]
	v_mov_b32_e32 v79, v97
	v_pk_fma_f32 v[84:85], v[84:85], v[72:73], v[70:71]
	v_mov_b32_e32 v70, v104
	v_mov_b32_e32 v71, v105
	v_mov_b32_e32 v72, v94
	v_mov_b32_e32 v73, v95
	v_mov_b32_e32 v80, v90
	v_mov_b32_e32 v81, v91
.LBB0_984:
	s_or_b64 exec, exec, s[0:1]
	v_add_u32_e32 v90, v3, v121
	v_ashrrev_i32_e32 v91, 31, v90
	v_lshlrev_b64 v[86:87], v86, v[90:91]
	v_mov_b32_e32 v103, v4
	v_lshl_add_u64 v[88:89], s[26:27], 0, v[88:89]
	v_lshl_add_u64 v[86:87], v[86:87], 0, v[102:103]
	v_mad_u64_u32 v[88:89], s[0:1], v86, s50, v[88:89]
	v_mad_i32_i24 v89, v87, s50, v89
	v_lshl_add_u64 v[86:87], v[118:119], 1, v[88:89]
	v_mov_b32_e32 v3, v4
	v_pk_mul_f32 v[70:71], v[70:71], s[64:65] op_sel_hi:[1,0]
	v_pk_mul_f32 v[72:73], v[72:73], s[64:65] op_sel_hi:[1,0]
	v_lshl_add_u64 v[86:87], v[86:87], 0, v[2:3]
	v_cvt_pk_bf16_f32 v70, v70, v71
	v_cvt_pk_bf16_f32 v71, v72, v73
	global_store_dwordx2 v[86:87], v[70:71], off nt
	v_pk_mul_f32 v[70:71], v[74:75], s[64:65] op_sel_hi:[1,0]
	v_pk_mul_f32 v[72:73], v[76:77], s[64:65] op_sel_hi:[1,0]
	v_cvt_pk_bf16_f32 v70, v70, v71
	v_cvt_pk_bf16_f32 v71, v72, v73
	global_store_dwordx2 v[86:87], v[70:71], off offset:16 nt
	v_pk_mul_f32 v[70:71], v[78:79], s[64:65] op_sel_hi:[1,0]
	v_pk_mul_f32 v[72:73], v[80:81], s[64:65] op_sel_hi:[1,0]
	v_cvt_pk_bf16_f32 v70, v70, v71
	v_cvt_pk_bf16_f32 v71, v72, v73
	global_store_dwordx2 v[86:87], v[70:71], off offset:32 nt
	v_pk_mul_f32 v[70:71], v[82:83], s[64:65] op_sel_hi:[1,0]
	v_pk_mul_f32 v[72:73], v[84:85], s[64:65] op_sel_hi:[1,0]
	v_or_b32_e32 v1, 64, v149
	v_cvt_pk_bf16_f32 v70, v70, v71
	v_cvt_pk_bf16_f32 v71, v72, v73
	v_cmp_lt_i32_e64 s[6:7], s89, v1
	s_movk_i32 s0, 0xdf
	v_add_u32_e32 v1, 0xffffe040, v149
	global_store_dwordx2 v[86:87], v[70:71], off offset:48 nt
	v_bitop3_b32 v70, v149, s0, 64 bitop3:0xc8
	s_movk_i32 s0, 0xfdf
	v_lshrrev_b32_e32 v1, 9, v1
	v_bitop3_b32 v71, v149, s0, 64 bitop3:0xc8
	v_and_b32_e32 v78, 0x7ffff8, v1
	v_mov_b64_e32 v[76:77], 0xb152000
	v_mov_b64_e32 v[72:73], 8
	v_mov_b32_e32 v3, v148
	v_mov_b32_e32 v74, v70
	s_and_saveexec_b64 s[0:1], s[6:7]
	v_mov_b64_e32 v[76:77], 0xbd52000
	v_mov_b64_e32 v[72:73], 12
	v_mov_b32_e32 v3, v78
	v_mov_b32_e32 v74, v71
	s_or_b64 exec, exec, s[0:1]
	s_and_b64 s[14:15], s[6:7], vcc
	s_and_saveexec_b64 s[0:1], s[14:15]
	s_cbranch_execz .LBB0_988
	v_readlane_b32 s14, v253, 31
	v_lshlrev_b32_e32 v80, 7, v74
	v_mov_b32_e32 v81, v4
	v_readlane_b32 s15, v253, 32
	v_mov_b32_e32 v1, v4
	s_nop 0
	v_lshl_add_u64 v[82:83], s[14:15], 0, v[80:81]
	v_readlane_b32 s14, v254, 47
	v_readlane_b32 s15, v254, 48
	v_lshl_add_u64 v[88:89], v[82:83], 0, v[0:1]
	s_nop 0
	v_lshl_add_u64 v[80:81], s[14:15], 0, v[80:81]
	v_lshl_add_u64 v[90:91], v[80:81], 0, v[0:1]
	global_load_dwordx4 v[80:83], v[88:89], off
	global_load_dwordx4 v[84:87], v[90:91], off
	s_waitcnt vmcnt(0)
	v_pk_mul_f32 v[92:93], v[58:59], v[84:85]
	s_nop 0
	v_pk_fma_f32 v[92:93], v[54:55], v[80:81], v[92:93] neg_lo:[0,0,1] neg_hi:[0,0,1]
	v_pk_mul_f32 v[54:55], v[54:55], v[84:85]
	s_nop 0
	v_pk_fma_f32 v[58:59], v[58:59], v[80:81], v[54:55]
	v_pk_mul_f32 v[54:55], v[60:61], v[86:87]
	s_nop 0
	v_pk_fma_f32 v[84:85], v[56:57], v[82:83], v[54:55] neg_lo:[0,0,1] neg_hi:[0,0,1]
	v_pk_mul_f32 v[54:55], v[56:57], v[86:87]
	s_nop 0
	v_pk_fma_f32 v[60:61], v[60:61], v[82:83], v[54:55]
	global_load_dwordx4 v[54:57], v[88:89], off offset:64
	global_load_dwordx4 v[80:83], v[90:91], off offset:64
	s_waitcnt vmcnt(0)
	v_pk_mul_f32 v[86:87], v[66:67], v[80:81]
	s_nop 0
	v_pk_fma_f32 v[86:87], v[62:63], v[54:55], v[86:87] neg_lo:[0,0,1] neg_hi:[0,0,1]
	v_pk_mul_f32 v[62:63], v[62:63], v[80:81]
	s_nop 0
	v_pk_fma_f32 v[66:67], v[66:67], v[54:55], v[62:63]
	v_pk_mul_f32 v[54:55], v[68:69], v[82:83]
	v_mov_b32_e32 v62, v86
	v_pk_fma_f32 v[80:81], v[64:65], v[56:57], v[54:55] neg_lo:[0,0,1] neg_hi:[0,0,1]
	v_pk_mul_f32 v[54:55], v[64:65], v[82:83]
	v_mov_b32_e32 v63, v87
	v_pk_fma_f32 v[68:69], v[68:69], v[56:57], v[54:55]
	v_mov_b32_e32 v54, v92
	v_mov_b32_e32 v55, v93
	v_mov_b32_e32 v56, v84
	v_mov_b32_e32 v57, v85
	v_mov_b32_e32 v64, v80
	v_mov_b32_e32 v65, v81
.LBB0_988:
	s_or_b64 exec, exec, s[0:1]
	v_add_u32_e32 v80, v3, v139
	v_ashrrev_i32_e32 v81, 31, v80
	v_lshlrev_b64 v[72:73], v72, v[80:81]
	v_mov_b32_e32 v75, v4
	v_lshl_add_u64 v[76:77], s[26:27], 0, v[76:77]
	v_lshl_add_u64 v[72:73], v[72:73], 0, v[74:75]
	v_mad_u64_u32 v[74:75], s[0:1], v72, s50, v[76:77]
	v_mad_i32_i24 v75, v73, s50, v75
	v_lshl_add_u64 v[72:73], v[134:135], 1, v[74:75]
	v_mov_b32_e32 v3, v4
	v_pk_mul_f32 v[54:55], v[54:55], s[64:65] op_sel_hi:[1,0]
	v_pk_mul_f32 v[56:57], v[56:57], s[64:65] op_sel_hi:[1,0]
	v_lshl_add_u64 v[72:73], v[72:73], 0, v[2:3]
	v_cvt_pk_bf16_f32 v54, v54, v55
	v_cvt_pk_bf16_f32 v55, v56, v57
	global_store_dwordx2 v[72:73], v[54:55], off nt
	v_pk_mul_f32 v[54:55], v[58:59], s[64:65] op_sel_hi:[1,0]
	v_pk_mul_f32 v[56:57], v[60:61], s[64:65] op_sel_hi:[1,0]
	v_cvt_pk_bf16_f32 v54, v54, v55
	v_cvt_pk_bf16_f32 v55, v56, v57
	global_store_dwordx2 v[72:73], v[54:55], off offset:16 nt
	v_pk_mul_f32 v[54:55], v[62:63], s[64:65] op_sel_hi:[1,0]
	v_pk_mul_f32 v[56:57], v[64:65], s[64:65] op_sel_hi:[1,0]
	v_cvt_pk_bf16_f32 v54, v54, v55
	v_cvt_pk_bf16_f32 v55, v56, v57
	global_store_dwordx2 v[72:73], v[54:55], off offset:32 nt
	v_pk_mul_f32 v[54:55], v[66:67], s[64:65] op_sel_hi:[1,0]
	v_pk_mul_f32 v[56:57], v[68:69], s[64:65] op_sel_hi:[1,0]
	v_cvt_pk_bf16_f32 v54, v54, v55
	v_cvt_pk_bf16_f32 v55, v56, v57
	global_store_dwordx2 v[72:73], v[54:55], off offset:48 nt
	v_mov_b64_e32 v[56:57], 0xb152000
	v_mov_b64_e32 v[54:55], 8
	v_mov_b32_e32 v3, v148
	s_and_saveexec_b64 s[0:1], s[6:7]
	v_mov_b64_e32 v[56:57], 0xbd52000
	v_mov_b64_e32 v[54:55], 12
	v_mov_b32_e32 v3, v78
	v_mov_b32_e32 v70, v71
	s_or_b64 exec, exec, s[0:1]
	s_and_b64 s[6:7], s[6:7], s[4:5]
	s_and_saveexec_b64 s[0:1], s[6:7]
	s_cbranch_execz .LBB0_992
	v_readlane_b32 s6, v253, 31
	v_lshlrev_b32_e32 v58, 7, v70
	v_mov_b32_e32 v59, v4
	v_readlane_b32 s7, v253, 32
	v_mov_b32_e32 v1, v4
	s_nop 0
	v_lshl_add_u64 v[60:61], s[6:7], 0, v[58:59]
	v_readlane_b32 s6, v254, 47
	v_readlane_b32 s7, v254, 48
	v_lshl_add_u64 v[66:67], v[60:61], 0, v[0:1]
	s_nop 0
	v_lshl_add_u64 v[58:59], s[6:7], 0, v[58:59]
	v_lshl_add_u64 v[68:69], v[58:59], 0, v[0:1]
	global_load_dwordx4 v[58:61], v[66:67], off
	global_load_dwordx4 v[62:65], v[68:69], off
	s_waitcnt vmcnt(0)
	v_pk_mul_f32 v[72:73], v[42:43], v[62:63]
	s_nop 0
	v_pk_fma_f32 v[72:73], v[38:39], v[58:59], v[72:73] neg_lo:[0,0,1] neg_hi:[0,0,1]
	v_pk_mul_f32 v[38:39], v[38:39], v[62:63]
	s_nop 0
	v_pk_fma_f32 v[42:43], v[42:43], v[58:59], v[38:39]
	v_pk_mul_f32 v[38:39], v[44:45], v[64:65]
	s_nop 0
	v_pk_fma_f32 v[62:63], v[40:41], v[60:61], v[38:39] neg_lo:[0,0,1] neg_hi:[0,0,1]
	v_pk_mul_f32 v[38:39], v[40:41], v[64:65]
	s_nop 0
	v_pk_fma_f32 v[44:45], v[44:45], v[60:61], v[38:39]
	global_load_dwordx4 v[38:41], v[66:67], off offset:64
	global_load_dwordx4 v[58:61], v[68:69], off offset:64
	s_waitcnt vmcnt(0)
	v_pk_mul_f32 v[64:65], v[50:51], v[58:59]
	s_nop 0
	v_pk_fma_f32 v[64:65], v[46:47], v[38:39], v[64:65] neg_lo:[0,0,1] neg_hi:[0,0,1]
	v_pk_mul_f32 v[46:47], v[46:47], v[58:59]
	s_nop 0
	v_pk_fma_f32 v[50:51], v[50:51], v[38:39], v[46:47]
	v_pk_mul_f32 v[38:39], v[52:53], v[60:61]
	v_mov_b32_e32 v46, v64
	v_pk_fma_f32 v[58:59], v[48:49], v[40:41], v[38:39] neg_lo:[0,0,1] neg_hi:[0,0,1]
	v_pk_mul_f32 v[38:39], v[48:49], v[60:61]
	v_mov_b32_e32 v47, v65
	v_pk_fma_f32 v[52:53], v[52:53], v[40:41], v[38:39]
	v_mov_b32_e32 v38, v72
	v_mov_b32_e32 v39, v73
	v_mov_b32_e32 v40, v62
	v_mov_b32_e32 v41, v63
	v_mov_b32_e32 v48, v58
	v_mov_b32_e32 v49, v59
.LBB0_992:
	s_or_b64 exec, exec, s[0:1]
	v_add_u32_e32 v58, v3, v121
	v_ashrrev_i32_e32 v59, 31, v58
	v_lshlrev_b64 v[54:55], v54, v[58:59]
	v_mov_b32_e32 v71, v4
	v_lshl_add_u64 v[56:57], s[26:27], 0, v[56:57]
	v_lshl_add_u64 v[54:55], v[54:55], 0, v[70:71]
	v_mad_u64_u32 v[56:57], s[0:1], v54, s50, v[56:57]
	v_mad_i32_i24 v57, v55, s50, v57
	v_lshl_add_u64 v[54:55], v[118:119], 1, v[56:57]
	v_mov_b32_e32 v3, v4
	v_pk_mul_f32 v[38:39], v[38:39], s[64:65] op_sel_hi:[1,0]
	v_pk_mul_f32 v[40:41], v[40:41], s[64:65] op_sel_hi:[1,0]
	v_lshl_add_u64 v[54:55], v[54:55], 0, v[2:3]
	v_cvt_pk_bf16_f32 v38, v38, v39
	v_cvt_pk_bf16_f32 v39, v40, v41
	global_store_dwordx2 v[54:55], v[38:39], off nt
	v_pk_mul_f32 v[38:39], v[42:43], s[64:65] op_sel_hi:[1,0]
	v_pk_mul_f32 v[40:41], v[44:45], s[64:65] op_sel_hi:[1,0]
	v_cvt_pk_bf16_f32 v38, v38, v39
	v_cvt_pk_bf16_f32 v39, v40, v41
	global_store_dwordx2 v[54:55], v[38:39], off offset:16 nt
	v_pk_mul_f32 v[38:39], v[46:47], s[64:65] op_sel_hi:[1,0]
	v_pk_mul_f32 v[40:41], v[48:49], s[64:65] op_sel_hi:[1,0]
	v_cvt_pk_bf16_f32 v38, v38, v39
	v_cvt_pk_bf16_f32 v39, v40, v41
	global_store_dwordx2 v[54:55], v[38:39], off offset:32 nt
	v_pk_mul_f32 v[38:39], v[50:51], s[64:65] op_sel_hi:[1,0]
	v_pk_mul_f32 v[40:41], v[52:53], s[64:65] op_sel_hi:[1,0]
	v_or_b32_e32 v1, 0x60, v149
	v_cvt_pk_bf16_f32 v38, v38, v39
	v_cvt_pk_bf16_f32 v39, v40, v41
	v_cmp_lt_i32_e64 s[6:7], s89, v1
	s_movk_i32 s0, 0xff
	v_add_u32_e32 v1, 0xffffe060, v149
	global_store_dwordx2 v[54:55], v[38:39], off offset:48 nt
	v_bitop3_b32 v38, v149, s0, v251 bitop3:0xc8
	s_movk_i32 s0, 0xfff
	v_lshrrev_b32_e32 v1, 9, v1
	v_bitop3_b32 v39, v149, s0, v251 bitop3:0xc8
	v_and_b32_e32 v46, 0x7ffff8, v1
	v_mov_b64_e32 v[44:45], 0xb152000
	v_mov_b64_e32 v[40:41], 8
	v_mov_b32_e32 v3, v148
	v_mov_b32_e32 v42, v38
	s_and_saveexec_b64 s[0:1], s[6:7]
	v_mov_b64_e32 v[44:45], 0xbd52000
	v_mov_b64_e32 v[40:41], 12
	v_mov_b32_e32 v3, v46
	v_mov_b32_e32 v42, v39
	s_or_b64 exec, exec, s[0:1]
	s_and_b64 s[14:15], s[6:7], vcc
	s_and_saveexec_b64 s[0:1], s[14:15]
	s_cbranch_execz .LBB0_996
	v_readlane_b32 s14, v253, 31
	v_lshlrev_b32_e32 v48, 7, v42
	v_mov_b32_e32 v49, v4
	v_readlane_b32 s15, v253, 32
	v_mov_b32_e32 v1, v4
	s_nop 0
	v_lshl_add_u64 v[50:51], s[14:15], 0, v[48:49]
	v_readlane_b32 s14, v254, 47
	v_readlane_b32 s15, v254, 48
	v_lshl_add_u64 v[56:57], v[50:51], 0, v[0:1]
	s_nop 0
	v_lshl_add_u64 v[48:49], s[14:15], 0, v[48:49]
	v_lshl_add_u64 v[58:59], v[48:49], 0, v[0:1]
	global_load_dwordx4 v[48:51], v[56:57], off
	global_load_dwordx4 v[52:55], v[58:59], off
	s_waitcnt vmcnt(0)
	v_pk_mul_f32 v[60:61], v[26:27], v[52:53]
	s_nop 0
	v_pk_fma_f32 v[60:61], v[22:23], v[48:49], v[60:61] neg_lo:[0,0,1] neg_hi:[0,0,1]
	v_pk_mul_f32 v[22:23], v[22:23], v[52:53]
	s_nop 0
	v_pk_fma_f32 v[26:27], v[26:27], v[48:49], v[22:23]
	v_pk_mul_f32 v[22:23], v[28:29], v[54:55]
	s_nop 0
	v_pk_fma_f32 v[52:53], v[24:25], v[50:51], v[22:23] neg_lo:[0,0,1] neg_hi:[0,0,1]
	v_pk_mul_f32 v[22:23], v[24:25], v[54:55]
	s_nop 0
	v_pk_fma_f32 v[28:29], v[28:29], v[50:51], v[22:23]
	global_load_dwordx4 v[22:25], v[56:57], off offset:64
	global_load_dwordx4 v[48:51], v[58:59], off offset:64
	s_waitcnt vmcnt(0)
	v_pk_mul_f32 v[54:55], v[34:35], v[48:49]
	s_nop 0
	v_pk_fma_f32 v[54:55], v[30:31], v[22:23], v[54:55] neg_lo:[0,0,1] neg_hi:[0,0,1]
	v_pk_mul_f32 v[30:31], v[30:31], v[48:49]
	s_nop 0
	v_pk_fma_f32 v[34:35], v[34:35], v[22:23], v[30:31]
	v_pk_mul_f32 v[22:23], v[36:37], v[50:51]
	v_mov_b32_e32 v30, v54
	v_pk_fma_f32 v[48:49], v[32:33], v[24:25], v[22:23] neg_lo:[0,0,1] neg_hi:[0,0,1]
	v_pk_mul_f32 v[22:23], v[32:33], v[50:51]
	v_mov_b32_e32 v31, v55
	v_pk_fma_f32 v[36:37], v[36:37], v[24:25], v[22:23]
	v_mov_b32_e32 v22, v60
	v_mov_b32_e32 v23, v61
	v_mov_b32_e32 v24, v52
	v_mov_b32_e32 v25, v53
	v_mov_b32_e32 v32, v48
	v_mov_b32_e32 v33, v49
.LBB0_996:
	s_or_b64 exec, exec, s[0:1]
	v_add_u32_e32 v48, v3, v139
	v_ashrrev_i32_e32 v49, 31, v48
	v_lshlrev_b64 v[40:41], v40, v[48:49]
	v_mov_b32_e32 v43, v4
	v_lshl_add_u64 v[44:45], s[26:27], 0, v[44:45]
	v_lshl_add_u64 v[40:41], v[40:41], 0, v[42:43]
	v_mad_u64_u32 v[42:43], s[0:1], v40, s50, v[44:45]
	v_mad_i32_i24 v43, v41, s50, v43
	v_lshl_add_u64 v[40:41], v[134:135], 1, v[42:43]
	v_mov_b32_e32 v3, v4
	v_pk_mul_f32 v[22:23], v[22:23], s[64:65] op_sel_hi:[1,0]
	v_pk_mul_f32 v[24:25], v[24:25], s[64:65] op_sel_hi:[1,0]
	v_lshl_add_u64 v[40:41], v[40:41], 0, v[2:3]
	v_cvt_pk_bf16_f32 v22, v22, v23
	v_cvt_pk_bf16_f32 v23, v24, v25
	global_store_dwordx2 v[40:41], v[22:23], off nt
	v_pk_mul_f32 v[22:23], v[26:27], s[64:65] op_sel_hi:[1,0]
	v_pk_mul_f32 v[24:25], v[28:29], s[64:65] op_sel_hi:[1,0]
	v_cvt_pk_bf16_f32 v22, v22, v23
	v_cvt_pk_bf16_f32 v23, v24, v25
	global_store_dwordx2 v[40:41], v[22:23], off offset:16 nt
	v_pk_mul_f32 v[22:23], v[30:31], s[64:65] op_sel_hi:[1,0]
	v_pk_mul_f32 v[24:25], v[32:33], s[64:65] op_sel_hi:[1,0]
	v_cvt_pk_bf16_f32 v22, v22, v23
	v_cvt_pk_bf16_f32 v23, v24, v25
	global_store_dwordx2 v[40:41], v[22:23], off offset:32 nt
	v_pk_mul_f32 v[22:23], v[34:35], s[64:65] op_sel_hi:[1,0]
	v_pk_mul_f32 v[24:25], v[36:37], s[64:65] op_sel_hi:[1,0]
	v_cvt_pk_bf16_f32 v22, v22, v23
	v_cvt_pk_bf16_f32 v23, v24, v25
	global_store_dwordx2 v[40:41], v[22:23], off offset:48 nt
	v_mov_b64_e32 v[24:25], 0xb152000
	v_mov_b64_e32 v[22:23], 8
	s_and_saveexec_b64 s[0:1], s[6:7]
	v_mov_b64_e32 v[24:25], 0xbd52000
	v_mov_b64_e32 v[22:23], 12
	v_mov_b32_e32 v148, v46
	v_mov_b32_e32 v38, v39
	s_or_b64 exec, exec, s[0:1]
	s_and_b64 s[4:5], s[6:7], s[4:5]
	s_and_saveexec_b64 s[0:1], s[4:5]
	s_cbranch_execz .LBB0_915
	v_readlane_b32 s4, v253, 31
	v_lshlrev_b32_e32 v26, 7, v38
	v_mov_b32_e32 v27, v4
	v_readlane_b32 s5, v253, 32
	v_mov_b32_e32 v1, v4
	s_nop 0
	v_lshl_add_u64 v[28:29], s[4:5], 0, v[26:27]
	v_readlane_b32 s4, v254, 47
	v_readlane_b32 s5, v254, 48
	v_lshl_add_u64 v[34:35], v[28:29], 0, v[0:1]
	s_nop 0
	v_lshl_add_u64 v[26:27], s[4:5], 0, v[26:27]
	v_lshl_add_u64 v[0:1], v[26:27], 0, v[0:1]
	global_load_dwordx4 v[26:29], v[34:35], off
	global_load_dwordx4 v[30:33], v[0:1], off
	s_waitcnt vmcnt(0)
	v_pk_mul_f32 v[36:37], v[10:11], v[30:31]
	s_nop 0
	v_pk_fma_f32 v[36:37], v[6:7], v[26:27], v[36:37] neg_lo:[0,0,1] neg_hi:[0,0,1]
	v_pk_mul_f32 v[6:7], v[6:7], v[30:31]
	s_nop 0
	v_pk_fma_f32 v[10:11], v[10:11], v[26:27], v[6:7]
	v_pk_mul_f32 v[6:7], v[12:13], v[32:33]
	s_nop 0
	v_pk_fma_f32 v[30:31], v[8:9], v[28:29], v[6:7] neg_lo:[0,0,1] neg_hi:[0,0,1]
	v_pk_mul_f32 v[6:7], v[8:9], v[32:33]
	s_nop 0
	v_pk_fma_f32 v[12:13], v[12:13], v[28:29], v[6:7]
	global_load_dwordx4 v[6:9], v[34:35], off offset:64
	global_load_dwordx4 v[26:29], v[0:1], off offset:64
	s_waitcnt vmcnt(0)
	v_pk_mul_f32 v[0:1], v[18:19], v[26:27]
	s_nop 0
	v_pk_fma_f32 v[0:1], v[14:15], v[6:7], v[0:1] neg_lo:[0,0,1] neg_hi:[0,0,1]
	v_pk_mul_f32 v[14:15], v[14:15], v[26:27]
	s_nop 0
	v_pk_fma_f32 v[18:19], v[18:19], v[6:7], v[14:15]
	v_pk_mul_f32 v[6:7], v[20:21], v[28:29]
	v_mov_b32_e32 v14, v0
	v_pk_fma_f32 v[26:27], v[16:17], v[8:9], v[6:7] neg_lo:[0,0,1] neg_hi:[0,0,1]
	v_pk_mul_f32 v[6:7], v[16:17], v[28:29]
	v_mov_b32_e32 v15, v1
	v_pk_fma_f32 v[20:21], v[20:21], v[8:9], v[6:7]
	v_mov_b32_e32 v6, v36
	v_mov_b32_e32 v7, v37
	v_mov_b32_e32 v8, v30
	v_mov_b32_e32 v9, v31
	v_mov_b32_e32 v16, v26
	v_mov_b32_e32 v17, v27
	s_branch .LBB0_915

.LBB0_1053:
	ds_bpermute_b32 v0, v146, v148
	s_lshl_b32 s68, s17, 7
	v_lshlrev_b32_e32 v10, 3, v132
	v_mov_b32_e32 v11, v4
	s_waitcnt lgkmcnt(0)
	v_add_f32_e32 v0, v148, v0
	v_div_scale_f32 v1, s[0:1], v0, v0, 1.0
	v_rcp_f32_e32 v2, v1
	s_add_i32 s0, s19, s18
	v_fma_f32 v3, -v1, v2, 1.0
	v_fmac_f32_e32 v2, v3, v2
	v_div_scale_f32 v3, vcc, 1.0, v0, 1.0
	v_mul_f32_e32 v5, v3, v2
	v_fma_f32 v6, -v1, v5, v3
	v_fmac_f32_e32 v5, v6, v2
	v_fma_f32 v1, -v1, v5, v3
	v_div_fmas_f32 v1, v1, v2, v5
	v_add_u32_e32 v2, s0, v133
	v_ashrrev_i32_e32 v3, 31, v2
	v_mov_b64_e32 v[6:7], s[26:27]
	v_mad_i64_i32 v[8:9], s[0:1], v2, s92, v[6:7]
	v_lshlrev_b64 v[2:3], 9, v[2:3]
	v_sub_co_u32_e32 v2, vcc, 0, v2
	v_lshl_add_u64 v[6:7], v[8:9], 0, s[68:69]
	s_nop 0
	v_subb_co_u32_e32 v3, vcc, 0, v3, vcc
	v_lshl_add_u64 v[2:3], v[8:9], 0, v[2:3]
	v_lshl_add_u64 v[12:13], v[6:7], 0, v[10:11]
	s_mov_b64 s[0:1], 0x4512600
	v_lshl_add_u64 v[2:3], v[2:3], 0, s[68:69]
	v_lshl_add_u64 v[6:7], v[12:13], 0, s[0:1]
	v_lshl_add_u64 v[8:9], v[2:3], 0, v[10:11]
	s_mov_b64 s[0:1], 0x6d12400
	v_lshl_add_u64 v[2:3], v[8:9], 0, s[0:1]
	v_div_fixup_f32 v0, v1, v0, 1.0
	global_load_dwordx2 v[150:151], v[6:7], off
	global_load_dwordx2 v[152:153], v[6:7], off offset:16
	global_load_dwordx2 v[154:155], v[6:7], off offset:32
	global_load_dwordx2 v[156:157], v[6:7], off offset:48
	global_load_dwordx2 v[158:159], v[6:7], off offset:64
	global_load_dwordx2 v[160:161], v[6:7], off offset:80
	global_load_dwordx2 v[162:163], v[6:7], off offset:96
	global_load_dwordx2 v[164:165], v[6:7], off offset:112
	s_waitcnt vmcnt(7)
	v_pk_mul_f32 v[12:13], v[32:33], v[0:1] op_sel_hi:[1,0]
	v_lshlrev_b32_e32 v14, 16, v150
	v_and_b32_e32 v15, 0xffff0000, v150
	v_pk_mul_f32 v[12:13], v[12:13], v[14:15]
	v_pk_mul_f32 v[8:9], v[34:35], v[0:1] op_sel_hi:[1,0]
	v_cvt_pk_bf16_f32 v10, v12, v13
	v_lshlrev_b32_e32 v14, 16, v151
	v_and_b32_e32 v15, 0xffff0000, v151
	v_pk_mul_f32 v[8:9], v[8:9], v[14:15]
	s_nop 0
	v_cvt_pk_bf16_f32 v11, v8, v9
	global_store_dwordx2 v[2:3], v[10:11], off nt
	s_waitcnt vmcnt(7)
	v_pk_mul_f32 v[12:13], v[36:37], v[0:1] op_sel_hi:[1,0]
	v_lshlrev_b32_e32 v14, 16, v152
	v_and_b32_e32 v15, 0xffff0000, v152
	v_pk_mul_f32 v[12:13], v[12:13], v[14:15]
	v_pk_mul_f32 v[8:9], v[38:39], v[0:1] op_sel_hi:[1,0]
	v_cvt_pk_bf16_f32 v10, v12, v13
	v_lshlrev_b32_e32 v14, 16, v153
	v_and_b32_e32 v15, 0xffff0000, v153
	v_pk_mul_f32 v[8:9], v[8:9], v[14:15]
	s_nop 0
	v_cvt_pk_bf16_f32 v11, v8, v9
	global_store_dwordx2 v[2:3], v[10:11], off offset:16 nt
	s_waitcnt vmcnt(7)
	v_pk_mul_f32 v[12:13], v[40:41], v[0:1] op_sel_hi:[1,0]
	v_lshlrev_b32_e32 v14, 16, v154
	v_and_b32_e32 v15, 0xffff0000, v154
	v_pk_mul_f32 v[12:13], v[12:13], v[14:15]
	v_pk_mul_f32 v[8:9], v[42:43], v[0:1] op_sel_hi:[1,0]
	v_cvt_pk_bf16_f32 v10, v12, v13
	v_lshlrev_b32_e32 v14, 16, v155
	v_and_b32_e32 v15, 0xffff0000, v155
	v_pk_mul_f32 v[8:9], v[8:9], v[14:15]
	s_nop 0
	v_cvt_pk_bf16_f32 v11, v8, v9
	global_store_dwordx2 v[2:3], v[10:11], off offset:32 nt
	s_waitcnt vmcnt(7)
	v_pk_mul_f32 v[12:13], v[44:45], v[0:1] op_sel_hi:[1,0]
	v_lshlrev_b32_e32 v14, 16, v156
	v_and_b32_e32 v15, 0xffff0000, v156
	v_pk_mul_f32 v[12:13], v[12:13], v[14:15]
	v_pk_mul_f32 v[8:9], v[46:47], v[0:1] op_sel_hi:[1,0]
	v_cvt_pk_bf16_f32 v10, v12, v13
	v_lshlrev_b32_e32 v14, 16, v157
	v_and_b32_e32 v15, 0xffff0000, v157
	v_pk_mul_f32 v[8:9], v[8:9], v[14:15]
	s_nop 0
	v_cvt_pk_bf16_f32 v11, v8, v9
	global_store_dwordx2 v[2:3], v[10:11], off offset:48 nt
	s_waitcnt vmcnt(7)
	v_pk_mul_f32 v[12:13], v[16:17], v[0:1] op_sel_hi:[1,0]
	v_lshlrev_b32_e32 v14, 16, v158
	v_and_b32_e32 v15, 0xffff0000, v158
	v_pk_mul_f32 v[12:13], v[12:13], v[14:15]
	v_pk_mul_f32 v[8:9], v[18:19], v[0:1] op_sel_hi:[1,0]
	v_cvt_pk_bf16_f32 v10, v12, v13
	v_lshlrev_b32_e32 v14, 16, v159
	v_and_b32_e32 v15, 0xffff0000, v159
	v_pk_mul_f32 v[8:9], v[8:9], v[14:15]
	s_nop 0
	v_cvt_pk_bf16_f32 v11, v8, v9
	global_store_dwordx2 v[2:3], v[10:11], off offset:64 nt
	s_waitcnt vmcnt(7)
	v_pk_mul_f32 v[12:13], v[20:21], v[0:1] op_sel_hi:[1,0]
	v_lshlrev_b32_e32 v14, 16, v160
	v_and_b32_e32 v15, 0xffff0000, v160
	v_pk_mul_f32 v[12:13], v[12:13], v[14:15]
	v_pk_mul_f32 v[8:9], v[22:23], v[0:1] op_sel_hi:[1,0]
	v_cvt_pk_bf16_f32 v10, v12, v13
	v_lshlrev_b32_e32 v14, 16, v161
	v_and_b32_e32 v15, 0xffff0000, v161
	v_pk_mul_f32 v[8:9], v[8:9], v[14:15]
	s_nop 0
	v_cvt_pk_bf16_f32 v11, v8, v9
	global_store_dwordx2 v[2:3], v[10:11], off offset:80 nt
	s_waitcnt vmcnt(7)
	v_pk_mul_f32 v[12:13], v[24:25], v[0:1] op_sel_hi:[1,0]
	v_lshlrev_b32_e32 v14, 16, v162
	v_and_b32_e32 v15, 0xffff0000, v162
	v_pk_mul_f32 v[12:13], v[12:13], v[14:15]
	v_pk_mul_f32 v[8:9], v[26:27], v[0:1] op_sel_hi:[1,0]
	v_cvt_pk_bf16_f32 v10, v12, v13
	v_lshlrev_b32_e32 v14, 16, v163
	v_and_b32_e32 v15, 0xffff0000, v163
	v_pk_mul_f32 v[8:9], v[8:9], v[14:15]
	s_nop 0
	v_cvt_pk_bf16_f32 v11, v8, v9
	global_store_dwordx2 v[2:3], v[10:11], off offset:96 nt
	s_waitcnt vmcnt(7)
	v_pk_mul_f32 v[12:13], v[28:29], v[0:1] op_sel_hi:[1,0]
	v_lshlrev_b32_e32 v14, 16, v164
	v_and_b32_e32 v15, 0xffff0000, v164
	v_pk_mul_f32 v[12:13], v[12:13], v[14:15]
	v_pk_mul_f32 v[8:9], v[30:31], v[0:1] op_sel_hi:[1,0]
	v_cvt_pk_bf16_f32 v10, v12, v13
	v_lshlrev_b32_e32 v14, 16, v165
	v_and_b32_e32 v15, 0xffff0000, v165
	v_pk_mul_f32 v[8:9], v[8:9], v[14:15]
	s_nop 0
	v_cvt_pk_bf16_f32 v11, v8, v9
	global_store_dwordx2 v[2:3], v[10:11], off offset:112 nt

.LBB0_1086:
	s_waitcnt vmcnt(0)
	s_mov_b64 s[4:5], -1
	s_and_b64 vcc, exec, s[20:21]
	s_barrier
	s_cbranch_vccz .LBB0_1152
	v_ashrrev_i32_e32 v3, 1, v144
	s_movk_i32 s4, 0xff80
	v_and_or_b32 v3, v3, s4, v161
	v_and_b32_e32 v5, 0xc0, v144
	v_and_b32_e32 v2, 4, v145
	v_add_u32_e32 v5, v5, v2
	v_lshlrev_b32_e32 v2, 2, v5
	v_lshlrev_b32_e32 v5, 1, v5
	v_mad_u32_u24 v0, v3, s92, v5
	v_lshl_add_u32 v1, v3, 11, v5
	v_readlane_b32 s70, v254, 8
	v_readlane_b32 s71, v254, 9
	s_mul_i32 s4, s68, 0xa00
	s_lshl_b32 s5, s14, 1
	s_add_u32 s4, s4, s5
	s_add_u32 s70, s70, s4
	s_addc_u32 s71, s71, 0
	s_lshl_b32 s4, s68, 11
	s_lshl_b32 s5, s12, 1
	s_add_u32 s4, s4, s5
	s_add_u32 s72, s46, s4
	s_addc_u32 s73, s47, 0
	s_cmp_lg_u64 s[0:1], 0
	s_cbranch_scc1 .Lgepi_scale
	s_add_u32 s74, s70, 0x0
	s_addc_u32 s75, s71, 0
	global_load_dwordx2 v[146:147], v0, s[74:75]
	global_load_dwordx2 v[148:149], v0, s[74:75] offset:16
	global_load_dwordx2 v[150:151], v0, s[74:75] offset:32
	global_load_dwordx2 v[152:153], v0, s[74:75] offset:48
	global_load_dwordx2 v[154:155], v0, s[74:75] offset:64
	global_load_dwordx2 v[156:157], v0, s[74:75] offset:80
	global_load_dwordx2 v[158:159], v0, s[74:75] offset:96
	global_load_dwordx2 v[160:161], v0, s[74:75] offset:112
	s_add_u32 s74, s70, 0x14000
	s_addc_u32 s75, s71, 0
	global_load_dwordx2 v[162:163], v0, s[74:75]
	global_load_dwordx2 v[164:165], v0, s[74:75] offset:16
	global_load_dwordx2 v[166:167], v0, s[74:75] offset:32
	global_load_dwordx2 v[168:169], v0, s[74:75] offset:48
	global_load_dwordx2 v[170:171], v0, s[74:75] offset:64
	global_load_dwordx2 v[172:173], v0, s[74:75] offset:80
	global_load_dwordx2 v[174:175], v0, s[74:75] offset:96
	global_load_dwordx2 v[176:177], v0, s[74:75] offset:112
	s_add_u32 s74, s70, 0x28000
	s_addc_u32 s75, s71, 0
	global_load_dwordx2 v[178:179], v0, s[74:75]
	global_load_dwordx2 v[180:181], v0, s[74:75] offset:16
	global_load_dwordx2 v[182:183], v0, s[74:75] offset:32
	global_load_dwordx2 v[184:185], v0, s[74:75] offset:48
	global_load_dwordx2 v[186:187], v0, s[74:75] offset:64
	global_load_dwordx2 v[188:189], v0, s[74:75] offset:80
	global_load_dwordx2 v[190:191], v0, s[74:75] offset:96
	global_load_dwordx2 v[192:193], v0, s[74:75] offset:112
	s_add_u32 s74, s70, 0x3c000
	s_addc_u32 s75, s71, 0
	global_load_dwordx2 v[194:195], v0, s[74:75]
	global_load_dwordx2 v[196:197], v0, s[74:75] offset:16
	global_load_dwordx2 v[198:199], v0, s[74:75] offset:32
	global_load_dwordx2 v[200:201], v0, s[74:75] offset:48
	global_load_dwordx2 v[202:203], v0, s[74:75] offset:64
	global_load_dwordx2 v[204:205], v0, s[74:75] offset:80
	global_load_dwordx2 v[206:207], v0, s[74:75] offset:96
	global_load_dwordx2 v[208:209], v0, s[74:75] offset:112
	s_add_u32 s74, s72, 0x0
	s_addc_u32 s75, s73, 0
	s_waitcnt vmcnt(31)
	v_and_b32_e32 v3, 0xffff0000, v146
	v_lshlrev_b32_e32 v2, 16, v146
	v_pk_mul_f32 v[118:119], v[118:119], v[2:3]
	v_and_b32_e32 v3, 0xffff0000, v147
	v_lshlrev_b32_e32 v2, 16, v147
	v_pk_mul_f32 v[120:121], v[120:121], v[2:3]
	v_cvt_pk_bf16_f32 v146, v118, v119
	v_cvt_pk_bf16_f32 v147, v120, v121
	global_store_dwordx2 v1, v[146:147], s[74:75] nt
	s_waitcnt vmcnt(31)
	v_and_b32_e32 v3, 0xffff0000, v148
	v_lshlrev_b32_e32 v2, 16, v148
	v_pk_mul_f32 v[122:123], v[122:123], v[2:3]
	v_and_b32_e32 v3, 0xffff0000, v149
	v_lshlrev_b32_e32 v2, 16, v149
	v_pk_mul_f32 v[124:125], v[124:125], v[2:3]
	v_cvt_pk_bf16_f32 v148, v122, v123
	v_cvt_pk_bf16_f32 v149, v124, v125
	global_store_dwordx2 v1, v[148:149], s[74:75] offset:16 nt
	s_waitcnt vmcnt(31)
	v_and_b32_e32 v3, 0xffff0000, v150
	v_lshlrev_b32_e32 v2, 16, v150
	v_pk_mul_f32 v[126:127], v[126:127], v[2:3]
	v_and_b32_e32 v3, 0xffff0000, v151
	v_lshlrev_b32_e32 v2, 16, v151
	v_pk_mul_f32 v[128:129], v[128:129], v[2:3]
	v_cvt_pk_bf16_f32 v150, v126, v127
	v_cvt_pk_bf16_f32 v151, v128, v129
	global_store_dwordx2 v1, v[150:151], s[74:75] offset:32 nt
	s_waitcnt vmcnt(31)
	v_and_b32_e32 v3, 0xffff0000, v152
	v_lshlrev_b32_e32 v2, 16, v152
	v_pk_mul_f32 v[130:131], v[130:131], v[2:3]
	v_and_b32_e32 v3, 0xffff0000, v153
	v_lshlrev_b32_e32 v2, 16, v153
	v_pk_mul_f32 v[132:133], v[132:133], v[2:3]
	v_cvt_pk_bf16_f32 v152, v130, v131
	v_cvt_pk_bf16_f32 v153, v132, v133
	global_store_dwordx2 v1, v[152:153], s[74:75] offset:48 nt
	s_waitcnt vmcnt(31)
	v_and_b32_e32 v3, 0xffff0000, v154
	v_lshlrev_b32_e32 v2, 16, v154
	v_pk_mul_f32 v[102:103], v[102:103], v[2:3]
	v_and_b32_e32 v3, 0xffff0000, v155
	v_lshlrev_b32_e32 v2, 16, v155
	v_pk_mul_f32 v[104:105], v[104:105], v[2:3]
	v_cvt_pk_bf16_f32 v154, v102, v103
	v_cvt_pk_bf16_f32 v155, v104, v105
	global_store_dwordx2 v1, v[154:155], s[74:75] offset:64 nt
	s_waitcnt vmcnt(31)
	v_and_b32_e32 v3, 0xffff0000, v156
	v_lshlrev_b32_e32 v2, 16, v156
	v_pk_mul_f32 v[106:107], v[106:107], v[2:3]
	v_and_b32_e32 v3, 0xffff0000, v157
	v_lshlrev_b32_e32 v2, 16, v157
	v_pk_mul_f32 v[108:109], v[108:109], v[2:3]
	v_cvt_pk_bf16_f32 v156, v106, v107
	v_cvt_pk_bf16_f32 v157, v108, v109
	global_store_dwordx2 v1, v[156:157], s[74:75] offset:80 nt
	s_waitcnt vmcnt(31)
	v_and_b32_e32 v3, 0xffff0000, v158
	v_lshlrev_b32_e32 v2, 16, v158
	v_pk_mul_f32 v[110:111], v[110:111], v[2:3]
	v_and_b32_e32 v3, 0xffff0000, v159
	v_lshlrev_b32_e32 v2, 16, v159
	v_pk_mul_f32 v[112:113], v[112:113], v[2:3]
	v_cvt_pk_bf16_f32 v158, v110, v111
	v_cvt_pk_bf16_f32 v159, v112, v113
	global_store_dwordx2 v1, v[158:159], s[74:75] offset:96 nt
	s_waitcnt vmcnt(31)
	v_and_b32_e32 v3, 0xffff0000, v160
	v_lshlrev_b32_e32 v2, 16, v160
	v_pk_mul_f32 v[114:115], v[114:115], v[2:3]
	v_and_b32_e32 v3, 0xffff0000, v161
	v_lshlrev_b32_e32 v2, 16, v161
	v_pk_mul_f32 v[116:117], v[116:117], v[2:3]
	v_cvt_pk_bf16_f32 v160, v114, v115
	v_cvt_pk_bf16_f32 v161, v116, v117
	global_store_dwordx2 v1, v[160:161], s[74:75] offset:112 nt
	s_add_u32 s74, s72, 0x10000
	s_addc_u32 s75, s73, 0
	s_waitcnt vmcnt(31)
	v_and_b32_e32 v3, 0xffff0000, v162
	v_lshlrev_b32_e32 v2, 16, v162
	v_pk_mul_f32 v[86:87], v[86:87], v[2:3]
	v_and_b32_e32 v3, 0xffff0000, v163
	v_lshlrev_b32_e32 v2, 16, v163
	v_pk_mul_f32 v[88:89], v[88:89], v[2:3]
	v_cvt_pk_bf16_f32 v162, v86, v87
	v_cvt_pk_bf16_f32 v163, v88, v89
	global_store_dwordx2 v1, v[162:163], s[74:75] nt
	s_waitcnt vmcnt(31)
	v_and_b32_e32 v3, 0xffff0000, v164
	v_lshlrev_b32_e32 v2, 16, v164
	v_pk_mul_f32 v[90:91], v[90:91], v[2:3]
	v_and_b32_e32 v3, 0xffff0000, v165
	v_lshlrev_b32_e32 v2, 16, v165
	v_pk_mul_f32 v[92:93], v[92:93], v[2:3]
	v_cvt_pk_bf16_f32 v164, v90, v91
	v_cvt_pk_bf16_f32 v165, v92, v93
	global_store_dwordx2 v1, v[164:165], s[74:75] offset:16 nt
	s_waitcnt vmcnt(31)
	v_and_b32_e32 v3, 0xffff0000, v166
	v_lshlrev_b32_e32 v2, 16, v166
	v_pk_mul_f32 v[94:95], v[94:95], v[2:3]
	v_and_b32_e32 v3, 0xffff0000, v167
	v_lshlrev_b32_e32 v2, 16, v167
	v_pk_mul_f32 v[96:97], v[96:97], v[2:3]
	v_cvt_pk_bf16_f32 v166, v94, v95
	v_cvt_pk_bf16_f32 v167, v96, v97
	global_store_dwordx2 v1, v[166:167], s[74:75] offset:32 nt
	s_waitcnt vmcnt(31)
	v_and_b32_e32 v3, 0xffff0000, v168
	v_lshlrev_b32_e32 v2, 16, v168
	v_pk_mul_f32 v[98:99], v[98:99], v[2:3]
	v_and_b32_e32 v3, 0xffff0000, v169
	v_lshlrev_b32_e32 v2, 16, v169
	v_pk_mul_f32 v[100:101], v[100:101], v[2:3]
	v_cvt_pk_bf16_f32 v168, v98, v99
	v_cvt_pk_bf16_f32 v169, v100, v101
	global_store_dwordx2 v1, v[168:169], s[74:75] offset:48 nt
	s_waitcnt vmcnt(31)
	v_and_b32_e32 v3, 0xffff0000, v170
	v_lshlrev_b32_e32 v2, 16, v170
	v_pk_mul_f32 v[70:71], v[70:71], v[2:3]
	v_and_b32_e32 v3, 0xffff0000, v171
	v_lshlrev_b32_e32 v2, 16, v171
	v_pk_mul_f32 v[72:73], v[72:73], v[2:3]
	v_cvt_pk_bf16_f32 v170, v70, v71
	v_cvt_pk_bf16_f32 v171, v72, v73
	global_store_dwordx2 v1, v[170:171], s[74:75] offset:64 nt
	s_waitcnt vmcnt(31)
	v_and_b32_e32 v3, 0xffff0000, v172
	v_lshlrev_b32_e32 v2, 16, v172
	v_pk_mul_f32 v[74:75], v[74:75], v[2:3]
	v_and_b32_e32 v3, 0xffff0000, v173
	v_lshlrev_b32_e32 v2, 16, v173
	v_pk_mul_f32 v[76:77], v[76:77], v[2:3]
	v_cvt_pk_bf16_f32 v172, v74, v75
	v_cvt_pk_bf16_f32 v173, v76, v77
	global_store_dwordx2 v1, v[172:173], s[74:75] offset:80 nt
	s_waitcnt vmcnt(31)
	v_and_b32_e32 v3, 0xffff0000, v174
	v_lshlrev_b32_e32 v2, 16, v174
	v_pk_mul_f32 v[78:79], v[78:79], v[2:3]
	v_and_b32_e32 v3, 0xffff0000, v175
	v_lshlrev_b32_e32 v2, 16, v175
	v_pk_mul_f32 v[80:81], v[80:81], v[2:3]
	v_cvt_pk_bf16_f32 v174, v78, v79
	v_cvt_pk_bf16_f32 v175, v80, v81
	global_store_dwordx2 v1, v[174:175], s[74:75] offset:96 nt
	s_waitcnt vmcnt(31)
	v_and_b32_e32 v3, 0xffff0000, v176
	v_lshlrev_b32_e32 v2, 16, v176
	v_pk_mul_f32 v[82:83], v[82:83], v[2:3]
	v_and_b32_e32 v3, 0xffff0000, v177
	v_lshlrev_b32_e32 v2, 16, v177
	v_pk_mul_f32 v[84:85], v[84:85], v[2:3]
	v_cvt_pk_bf16_f32 v176, v82, v83
	v_cvt_pk_bf16_f32 v177, v84, v85
	global_store_dwordx2 v1, v[176:177], s[74:75] offset:112 nt
	s_add_u32 s74, s72, 0x20000
	s_addc_u32 s75, s73, 0
	s_waitcnt vmcnt(31)
	v_and_b32_e32 v3, 0xffff0000, v178
	v_lshlrev_b32_e32 v2, 16, v178
	v_pk_mul_f32 v[54:55], v[54:55], v[2:3]
	v_and_b32_e32 v3, 0xffff0000, v179
	v_lshlrev_b32_e32 v2, 16, v179
	v_pk_mul_f32 v[56:57], v[56:57], v[2:3]
	v_cvt_pk_bf16_f32 v178, v54, v55
	v_cvt_pk_bf16_f32 v179, v56, v57
	global_store_dwordx2 v1, v[178:179], s[74:75] nt
	s_waitcnt vmcnt(31)
	v_and_b32_e32 v3, 0xffff0000, v180
	v_lshlrev_b32_e32 v2, 16, v180
	v_pk_mul_f32 v[58:59], v[58:59], v[2:3]
	v_and_b32_e32 v3, 0xffff0000, v181
	v_lshlrev_b32_e32 v2, 16, v181
	v_pk_mul_f32 v[60:61], v[60:61], v[2:3]
	v_cvt_pk_bf16_f32 v180, v58, v59
	v_cvt_pk_bf16_f32 v181, v60, v61
	global_store_dwordx2 v1, v[180:181], s[74:75] offset:16 nt
	s_waitcnt vmcnt(31)
	v_and_b32_e32 v3, 0xffff0000, v182
	v_lshlrev_b32_e32 v2, 16, v182
	v_pk_mul_f32 v[62:63], v[62:63], v[2:3]
	v_and_b32_e32 v3, 0xffff0000, v183
	v_lshlrev_b32_e32 v2, 16, v183
	v_pk_mul_f32 v[64:65], v[64:65], v[2:3]
	v_cvt_pk_bf16_f32 v182, v62, v63
	v_cvt_pk_bf16_f32 v183, v64, v65
	global_store_dwordx2 v1, v[182:183], s[74:75] offset:32 nt
	s_waitcnt vmcnt(31)
	v_and_b32_e32 v3, 0xffff0000, v184
	v_lshlrev_b32_e32 v2, 16, v184
	v_pk_mul_f32 v[66:67], v[66:67], v[2:3]
	v_and_b32_e32 v3, 0xffff0000, v185
	v_lshlrev_b32_e32 v2, 16, v185
	v_pk_mul_f32 v[68:69], v[68:69], v[2:3]
	v_cvt_pk_bf16_f32 v184, v66, v67
	v_cvt_pk_bf16_f32 v185, v68, v69
	global_store_dwordx2 v1, v[184:185], s[74:75] offset:48 nt
	s_waitcnt vmcnt(31)
	v_and_b32_e32 v3, 0xffff0000, v186
	v_lshlrev_b32_e32 v2, 16, v186
	v_pk_mul_f32 v[38:39], v[38:39], v[2:3]
	v_and_b32_e32 v3, 0xffff0000, v187
	v_lshlrev_b32_e32 v2, 16, v187
	v_pk_mul_f32 v[40:41], v[40:41], v[2:3]
	v_cvt_pk_bf16_f32 v186, v38, v39
	v_cvt_pk_bf16_f32 v187, v40, v41
	global_store_dwordx2 v1, v[186:187], s[74:75] offset:64 nt
	s_waitcnt vmcnt(31)
	v_and_b32_e32 v3, 0xffff0000, v188
	v_lshlrev_b32_e32 v2, 16, v188
	v_pk_mul_f32 v[42:43], v[42:43], v[2:3]
	v_and_b32_e32 v3, 0xffff0000, v189
	v_lshlrev_b32_e32 v2, 16, v189
	v_pk_mul_f32 v[44:45], v[44:45], v[2:3]
	v_cvt_pk_bf16_f32 v188, v42, v43
	v_cvt_pk_bf16_f32 v189, v44, v45
	global_store_dwordx2 v1, v[188:189], s[74:75] offset:80 nt
	s_waitcnt vmcnt(31)
	v_and_b32_e32 v3, 0xffff0000, v190
	v_lshlrev_b32_e32 v2, 16, v190
	v_pk_mul_f32 v[46:47], v[46:47], v[2:3]
	v_and_b32_e32 v3, 0xffff0000, v191
	v_lshlrev_b32_e32 v2, 16, v191
	v_pk_mul_f32 v[48:49], v[48:49], v[2:3]
	v_cvt_pk_bf16_f32 v190, v46, v47
	v_cvt_pk_bf16_f32 v191, v48, v49
	global_store_dwordx2 v1, v[190:191], s[74:75] offset:96 nt
	s_waitcnt vmcnt(31)
	v_and_b32_e32 v3, 0xffff0000, v192
	v_lshlrev_b32_e32 v2, 16, v192
	v_pk_mul_f32 v[50:51], v[50:51], v[2:3]
	v_and_b32_e32 v3, 0xffff0000, v193
	v_lshlrev_b32_e32 v2, 16, v193
	v_pk_mul_f32 v[52:53], v[52:53], v[2:3]
	v_cvt_pk_bf16_f32 v192, v50, v51
	v_cvt_pk_bf16_f32 v193, v52, v53
	global_store_dwordx2 v1, v[192:193], s[74:75] offset:112 nt
	s_add_u32 s74, s72, 0x30000
	s_addc_u32 s75, s73, 0
	s_waitcnt vmcnt(31)
	v_and_b32_e32 v3, 0xffff0000, v194
	v_lshlrev_b32_e32 v2, 16, v194
	v_pk_mul_f32 v[22:23], v[22:23], v[2:3]
	v_and_b32_e32 v3, 0xffff0000, v195
	v_lshlrev_b32_e32 v2, 16, v195
	v_pk_mul_f32 v[24:25], v[24:25], v[2:3]
	v_cvt_pk_bf16_f32 v194, v22, v23
	v_cvt_pk_bf16_f32 v195, v24, v25
	global_store_dwordx2 v1, v[194:195], s[74:75] nt
	s_waitcnt vmcnt(31)
	v_and_b32_e32 v3, 0xffff0000, v196
	v_lshlrev_b32_e32 v2, 16, v196
	v_pk_mul_f32 v[26:27], v[26:27], v[2:3]
	v_and_b32_e32 v3, 0xffff0000, v197
	v_lshlrev_b32_e32 v2, 16, v197
	v_pk_mul_f32 v[28:29], v[28:29], v[2:3]
	v_cvt_pk_bf16_f32 v196, v26, v27
	v_cvt_pk_bf16_f32 v197, v28, v29
	global_store_dwordx2 v1, v[196:197], s[74:75] offset:16 nt
	s_waitcnt vmcnt(31)
	v_and_b32_e32 v3, 0xffff0000, v198
	v_lshlrev_b32_e32 v2, 16, v198
	v_pk_mul_f32 v[30:31], v[30:31], v[2:3]
	v_and_b32_e32 v3, 0xffff0000, v199
	v_lshlrev_b32_e32 v2, 16, v199
	v_pk_mul_f32 v[32:33], v[32:33], v[2:3]
	v_cvt_pk_bf16_f32 v198, v30, v31
	v_cvt_pk_bf16_f32 v199, v32, v33
	global_store_dwordx2 v1, v[198:199], s[74:75] offset:32 nt
	s_waitcnt vmcnt(31)
	v_and_b32_e32 v3, 0xffff0000, v200
	v_lshlrev_b32_e32 v2, 16, v200
	v_pk_mul_f32 v[34:35], v[34:35], v[2:3]
	v_and_b32_e32 v3, 0xffff0000, v201
	v_lshlrev_b32_e32 v2, 16, v201
	v_pk_mul_f32 v[36:37], v[36:37], v[2:3]
	v_cvt_pk_bf16_f32 v200, v34, v35
	v_cvt_pk_bf16_f32 v201, v36, v37
	global_store_dwordx2 v1, v[200:201], s[74:75] offset:48 nt
	s_waitcnt vmcnt(31)
	v_and_b32_e32 v3, 0xffff0000, v202
	v_lshlrev_b32_e32 v2, 16, v202
	v_pk_mul_f32 v[6:7], v[6:7], v[2:3]
	v_and_b32_e32 v3, 0xffff0000, v203
	v_lshlrev_b32_e32 v2, 16, v203
	v_pk_mul_f32 v[8:9], v[8:9], v[2:3]
	v_cvt_pk_bf16_f32 v202, v6, v7
	v_cvt_pk_bf16_f32 v203, v8, v9
	global_store_dwordx2 v1, v[202:203], s[74:75] offset:64 nt
	s_waitcnt vmcnt(31)
	v_and_b32_e32 v3, 0xffff0000, v204
	v_lshlrev_b32_e32 v2, 16, v204
	v_pk_mul_f32 v[10:11], v[10:11], v[2:3]
	v_and_b32_e32 v3, 0xffff0000, v205
	v_lshlrev_b32_e32 v2, 16, v205
	v_pk_mul_f32 v[12:13], v[12:13], v[2:3]
	v_cvt_pk_bf16_f32 v204, v10, v11
	v_cvt_pk_bf16_f32 v205, v12, v13
	global_store_dwordx2 v1, v[204:205], s[74:75] offset:80 nt
	s_waitcnt vmcnt(31)
	v_and_b32_e32 v3, 0xffff0000, v206
	v_lshlrev_b32_e32 v2, 16, v206
	v_pk_mul_f32 v[14:15], v[14:15], v[2:3]
	v_and_b32_e32 v3, 0xffff0000, v207
	v_lshlrev_b32_e32 v2, 16, v207
	v_pk_mul_f32 v[16:17], v[16:17], v[2:3]
	v_cvt_pk_bf16_f32 v206, v14, v15
	v_cvt_pk_bf16_f32 v207, v16, v17
	global_store_dwordx2 v1, v[206:207], s[74:75] offset:96 nt
	s_waitcnt vmcnt(31)
	v_and_b32_e32 v3, 0xffff0000, v208
	v_lshlrev_b32_e32 v2, 16, v208
	v_pk_mul_f32 v[18:19], v[18:19], v[2:3]
	v_and_b32_e32 v3, 0xffff0000, v209
	v_lshlrev_b32_e32 v2, 16, v209
	v_pk_mul_f32 v[20:21], v[20:21], v[2:3]
	v_cvt_pk_bf16_f32 v208, v18, v19
	v_cvt_pk_bf16_f32 v209, v20, v21
	global_store_dwordx2 v1, v[208:209], s[74:75] offset:112 nt
	s_branch .Lgepi_done
.Lgepi_scale:
	global_load_dwordx4 v[210:213], v2, s[0:1]
	global_load_dwordx4 v[214:217], v2, s[0:1] offset:32
	global_load_dwordx4 v[218:221], v2, s[0:1] offset:64
	global_load_dwordx4 v[222:225], v2, s[0:1] offset:96
	global_load_dwordx4 v[226:229], v2, s[0:1] offset:128
	global_load_dwordx4 v[230:233], v2, s[0:1] offset:160
	global_load_dwordx4 v[234:237], v2, s[0:1] offset:192
	global_load_dwordx4 v[134:137], v2, s[0:1] offset:224
	s_add_u32 s74, s70, 0x0
	s_addc_u32 s75, s71, 0
	global_load_dwordx2 v[146:147], v0, s[74:75]
	global_load_dwordx2 v[148:149], v0, s[74:75] offset:16
	global_load_dwordx2 v[150:151], v0, s[74:75] offset:32
	global_load_dwordx2 v[152:153], v0, s[74:75] offset:48
	global_load_dwordx2 v[154:155], v0, s[74:75] offset:64
	global_load_dwordx2 v[156:157], v0, s[74:75] offset:80
	global_load_dwordx2 v[158:159], v0, s[74:75] offset:96
	global_load_dwordx2 v[160:161], v0, s[74:75] offset:112
	s_add_u32 s74, s70, 0x14000
	s_addc_u32 s75, s71, 0
	global_load_dwordx2 v[162:163], v0, s[74:75]
	global_load_dwordx2 v[164:165], v0, s[74:75] offset:16
	global_load_dwordx2 v[166:167], v0, s[74:75] offset:32
	global_load_dwordx2 v[168:169], v0, s[74:75] offset:48
	global_load_dwordx2 v[170:171], v0, s[74:75] offset:64
	global_load_dwordx2 v[172:173], v0, s[74:75] offset:80
	global_load_dwordx2 v[174:175], v0, s[74:75] offset:96
	global_load_dwordx2 v[176:177], v0, s[74:75] offset:112
	s_add_u32 s74, s70, 0x28000
	s_addc_u32 s75, s71, 0
	global_load_dwordx2 v[178:179], v0, s[74:75]
	global_load_dwordx2 v[180:181], v0, s[74:75] offset:16
	global_load_dwordx2 v[182:183], v0, s[74:75] offset:32
	global_load_dwordx2 v[184:185], v0, s[74:75] offset:48
	global_load_dwordx2 v[186:187], v0, s[74:75] offset:64
	global_load_dwordx2 v[188:189], v0, s[74:75] offset:80
	global_load_dwordx2 v[190:191], v0, s[74:75] offset:96
	global_load_dwordx2 v[192:193], v0, s[74:75] offset:112
	s_add_u32 s74, s70, 0x3c000
	s_addc_u32 s75, s71, 0
	global_load_dwordx2 v[194:195], v0, s[74:75]
	global_load_dwordx2 v[196:197], v0, s[74:75] offset:16
	global_load_dwordx2 v[198:199], v0, s[74:75] offset:32
	global_load_dwordx2 v[200:201], v0, s[74:75] offset:48
	global_load_dwordx2 v[202:203], v0, s[74:75] offset:64
	global_load_dwordx2 v[204:205], v0, s[74:75] offset:80
	global_load_dwordx2 v[206:207], v0, s[74:75] offset:96
	global_load_dwordx2 v[208:209], v0, s[74:75] offset:112
	s_add_u32 s74, s72, 0x0
	s_addc_u32 s75, s73, 0
	s_waitcnt vmcnt(31)
	v_pk_mul_f32 v[118:119], v[118:119], v[210:211]
	v_pk_mul_f32 v[120:121], v[120:121], v[212:213]
	v_and_b32_e32 v3, 0xffff0000, v146
	v_lshlrev_b32_e32 v2, 16, v146
	v_pk_mul_f32 v[118:119], v[118:119], v[2:3]
	v_and_b32_e32 v3, 0xffff0000, v147
	v_lshlrev_b32_e32 v2, 16, v147
	v_pk_mul_f32 v[120:121], v[120:121], v[2:3]
	v_cvt_pk_bf16_f32 v146, v118, v119
	v_cvt_pk_bf16_f32 v147, v120, v121
	global_store_dwordx2 v1, v[146:147], s[74:75] nt
	s_waitcnt vmcnt(31)
	v_pk_mul_f32 v[122:123], v[122:123], v[214:215]
	v_pk_mul_f32 v[124:125], v[124:125], v[216:217]
	v_and_b32_e32 v3, 0xffff0000, v148
	v_lshlrev_b32_e32 v2, 16, v148
	v_pk_mul_f32 v[122:123], v[122:123], v[2:3]
	v_and_b32_e32 v3, 0xffff0000, v149
	v_lshlrev_b32_e32 v2, 16, v149
	v_pk_mul_f32 v[124:125], v[124:125], v[2:3]
	v_cvt_pk_bf16_f32 v148, v122, v123
	v_cvt_pk_bf16_f32 v149, v124, v125
	global_store_dwordx2 v1, v[148:149], s[74:75] offset:16 nt
	s_waitcnt vmcnt(31)
	v_pk_mul_f32 v[126:127], v[126:127], v[218:219]
	v_pk_mul_f32 v[128:129], v[128:129], v[220:221]
	v_and_b32_e32 v3, 0xffff0000, v150
	v_lshlrev_b32_e32 v2, 16, v150
	v_pk_mul_f32 v[126:127], v[126:127], v[2:3]
	v_and_b32_e32 v3, 0xffff0000, v151
	v_lshlrev_b32_e32 v2, 16, v151
	v_pk_mul_f32 v[128:129], v[128:129], v[2:3]
	v_cvt_pk_bf16_f32 v150, v126, v127
	v_cvt_pk_bf16_f32 v151, v128, v129
	global_store_dwordx2 v1, v[150:151], s[74:75] offset:32 nt
	s_waitcnt vmcnt(31)
	v_pk_mul_f32 v[130:131], v[130:131], v[222:223]
	v_pk_mul_f32 v[132:133], v[132:133], v[224:225]
	v_and_b32_e32 v3, 0xffff0000, v152
	v_lshlrev_b32_e32 v2, 16, v152
	v_pk_mul_f32 v[130:131], v[130:131], v[2:3]
	v_and_b32_e32 v3, 0xffff0000, v153
	v_lshlrev_b32_e32 v2, 16, v153
	v_pk_mul_f32 v[132:133], v[132:133], v[2:3]
	v_cvt_pk_bf16_f32 v152, v130, v131
	v_cvt_pk_bf16_f32 v153, v132, v133
	global_store_dwordx2 v1, v[152:153], s[74:75] offset:48 nt
	s_waitcnt vmcnt(31)
	v_pk_mul_f32 v[102:103], v[102:103], v[226:227]
	v_pk_mul_f32 v[104:105], v[104:105], v[228:229]
	v_and_b32_e32 v3, 0xffff0000, v154
	v_lshlrev_b32_e32 v2, 16, v154
	v_pk_mul_f32 v[102:103], v[102:103], v[2:3]
	v_and_b32_e32 v3, 0xffff0000, v155
	v_lshlrev_b32_e32 v2, 16, v155
	v_pk_mul_f32 v[104:105], v[104:105], v[2:3]
	v_cvt_pk_bf16_f32 v154, v102, v103
	v_cvt_pk_bf16_f32 v155, v104, v105
	global_store_dwordx2 v1, v[154:155], s[74:75] offset:64 nt
	s_waitcnt vmcnt(31)
	v_pk_mul_f32 v[106:107], v[106:107], v[230:231]
	v_pk_mul_f32 v[108:109], v[108:109], v[232:233]
	v_and_b32_e32 v3, 0xffff0000, v156
	v_lshlrev_b32_e32 v2, 16, v156
	v_pk_mul_f32 v[106:107], v[106:107], v[2:3]
	v_and_b32_e32 v3, 0xffff0000, v157
	v_lshlrev_b32_e32 v2, 16, v157
	v_pk_mul_f32 v[108:109], v[108:109], v[2:3]
	v_cvt_pk_bf16_f32 v156, v106, v107
	v_cvt_pk_bf16_f32 v157, v108, v109
	global_store_dwordx2 v1, v[156:157], s[74:75] offset:80 nt
	s_waitcnt vmcnt(31)
	v_pk_mul_f32 v[110:111], v[110:111], v[234:235]
	v_pk_mul_f32 v[112:113], v[112:113], v[236:237]
	v_and_b32_e32 v3, 0xffff0000, v158
	v_lshlrev_b32_e32 v2, 16, v158
	v_pk_mul_f32 v[110:111], v[110:111], v[2:3]
	v_and_b32_e32 v3, 0xffff0000, v159
	v_lshlrev_b32_e32 v2, 16, v159
	v_pk_mul_f32 v[112:113], v[112:113], v[2:3]
	v_cvt_pk_bf16_f32 v158, v110, v111
	v_cvt_pk_bf16_f32 v159, v112, v113
	global_store_dwordx2 v1, v[158:159], s[74:75] offset:96 nt
	s_waitcnt vmcnt(31)
	v_pk_mul_f32 v[114:115], v[114:115], v[134:135]
	v_pk_mul_f32 v[116:117], v[116:117], v[136:137]
	v_and_b32_e32 v3, 0xffff0000, v160
	v_lshlrev_b32_e32 v2, 16, v160
	v_pk_mul_f32 v[114:115], v[114:115], v[2:3]
	v_and_b32_e32 v3, 0xffff0000, v161
	v_lshlrev_b32_e32 v2, 16, v161
	v_pk_mul_f32 v[116:117], v[116:117], v[2:3]
	v_cvt_pk_bf16_f32 v160, v114, v115
	v_cvt_pk_bf16_f32 v161, v116, v117
	global_store_dwordx2 v1, v[160:161], s[74:75] offset:112 nt
	s_add_u32 s74, s72, 0x10000
	s_addc_u32 s75, s73, 0
	s_waitcnt vmcnt(31)
	v_pk_mul_f32 v[86:87], v[86:87], v[210:211]
	v_pk_mul_f32 v[88:89], v[88:89], v[212:213]
	v_and_b32_e32 v3, 0xffff0000, v162
	v_lshlrev_b32_e32 v2, 16, v162
	v_pk_mul_f32 v[86:87], v[86:87], v[2:3]
	v_and_b32_e32 v3, 0xffff0000, v163
	v_lshlrev_b32_e32 v2, 16, v163
	v_pk_mul_f32 v[88:89], v[88:89], v[2:3]
	v_cvt_pk_bf16_f32 v162, v86, v87
	v_cvt_pk_bf16_f32 v163, v88, v89
	global_store_dwordx2 v1, v[162:163], s[74:75] nt
	s_waitcnt vmcnt(31)
	v_pk_mul_f32 v[90:91], v[90:91], v[214:215]
	v_pk_mul_f32 v[92:93], v[92:93], v[216:217]
	v_and_b32_e32 v3, 0xffff0000, v164
	v_lshlrev_b32_e32 v2, 16, v164
	v_pk_mul_f32 v[90:91], v[90:91], v[2:3]
	v_and_b32_e32 v3, 0xffff0000, v165
	v_lshlrev_b32_e32 v2, 16, v165
	v_pk_mul_f32 v[92:93], v[92:93], v[2:3]
	v_cvt_pk_bf16_f32 v164, v90, v91
	v_cvt_pk_bf16_f32 v165, v92, v93
	global_store_dwordx2 v1, v[164:165], s[74:75] offset:16 nt
	s_waitcnt vmcnt(31)
	v_pk_mul_f32 v[94:95], v[94:95], v[218:219]
	v_pk_mul_f32 v[96:97], v[96:97], v[220:221]
	v_and_b32_e32 v3, 0xffff0000, v166
	v_lshlrev_b32_e32 v2, 16, v166
	v_pk_mul_f32 v[94:95], v[94:95], v[2:3]
	v_and_b32_e32 v3, 0xffff0000, v167
	v_lshlrev_b32_e32 v2, 16, v167
	v_pk_mul_f32 v[96:97], v[96:97], v[2:3]
	v_cvt_pk_bf16_f32 v166, v94, v95
	v_cvt_pk_bf16_f32 v167, v96, v97
	global_store_dwordx2 v1, v[166:167], s[74:75] offset:32 nt
	s_waitcnt vmcnt(31)
	v_pk_mul_f32 v[98:99], v[98:99], v[222:223]
	v_pk_mul_f32 v[100:101], v[100:101], v[224:225]
	v_and_b32_e32 v3, 0xffff0000, v168
	v_lshlrev_b32_e32 v2, 16, v168
	v_pk_mul_f32 v[98:99], v[98:99], v[2:3]
	v_and_b32_e32 v3, 0xffff0000, v169
	v_lshlrev_b32_e32 v2, 16, v169
	v_pk_mul_f32 v[100:101], v[100:101], v[2:3]
	v_cvt_pk_bf16_f32 v168, v98, v99
	v_cvt_pk_bf16_f32 v169, v100, v101
	global_store_dwordx2 v1, v[168:169], s[74:75] offset:48 nt
	s_waitcnt vmcnt(31)
	v_pk_mul_f32 v[70:71], v[70:71], v[226:227]
	v_pk_mul_f32 v[72:73], v[72:73], v[228:229]
	v_and_b32_e32 v3, 0xffff0000, v170
	v_lshlrev_b32_e32 v2, 16, v170
	v_pk_mul_f32 v[70:71], v[70:71], v[2:3]
	v_and_b32_e32 v3, 0xffff0000, v171
	v_lshlrev_b32_e32 v2, 16, v171
	v_pk_mul_f32 v[72:73], v[72:73], v[2:3]
	v_cvt_pk_bf16_f32 v170, v70, v71
	v_cvt_pk_bf16_f32 v171, v72, v73
	global_store_dwordx2 v1, v[170:171], s[74:75] offset:64 nt
	s_waitcnt vmcnt(31)
	v_pk_mul_f32 v[74:75], v[74:75], v[230:231]
	v_pk_mul_f32 v[76:77], v[76:77], v[232:233]
	v_and_b32_e32 v3, 0xffff0000, v172
	v_lshlrev_b32_e32 v2, 16, v172
	v_pk_mul_f32 v[74:75], v[74:75], v[2:3]
	v_and_b32_e32 v3, 0xffff0000, v173
	v_lshlrev_b32_e32 v2, 16, v173
	v_pk_mul_f32 v[76:77], v[76:77], v[2:3]
	v_cvt_pk_bf16_f32 v172, v74, v75
	v_cvt_pk_bf16_f32 v173, v76, v77
	global_store_dwordx2 v1, v[172:173], s[74:75] offset:80 nt
	s_waitcnt vmcnt(31)
	v_pk_mul_f32 v[78:79], v[78:79], v[234:235]
	v_pk_mul_f32 v[80:81], v[80:81], v[236:237]
	v_and_b32_e32 v3, 0xffff0000, v174
	v_lshlrev_b32_e32 v2, 16, v174
	v_pk_mul_f32 v[78:79], v[78:79], v[2:3]
	v_and_b32_e32 v3, 0xffff0000, v175
	v_lshlrev_b32_e32 v2, 16, v175
	v_pk_mul_f32 v[80:81], v[80:81], v[2:3]
	v_cvt_pk_bf16_f32 v174, v78, v79
	v_cvt_pk_bf16_f32 v175, v80, v81
	global_store_dwordx2 v1, v[174:175], s[74:75] offset:96 nt
	s_waitcnt vmcnt(31)
	v_pk_mul_f32 v[82:83], v[82:83], v[134:135]
	v_pk_mul_f32 v[84:85], v[84:85], v[136:137]
	v_and_b32_e32 v3, 0xffff0000, v176
	v_lshlrev_b32_e32 v2, 16, v176
	v_pk_mul_f32 v[82:83], v[82:83], v[2:3]
	v_and_b32_e32 v3, 0xffff0000, v177
	v_lshlrev_b32_e32 v2, 16, v177
	v_pk_mul_f32 v[84:85], v[84:85], v[2:3]
	v_cvt_pk_bf16_f32 v176, v82, v83
	v_cvt_pk_bf16_f32 v177, v84, v85
	global_store_dwordx2 v1, v[176:177], s[74:75] offset:112 nt
	s_add_u32 s74, s72, 0x20000
	s_addc_u32 s75, s73, 0
	s_waitcnt vmcnt(31)
	v_pk_mul_f32 v[54:55], v[54:55], v[210:211]
	v_pk_mul_f32 v[56:57], v[56:57], v[212:213]
	v_and_b32_e32 v3, 0xffff0000, v178
	v_lshlrev_b32_e32 v2, 16, v178
	v_pk_mul_f32 v[54:55], v[54:55], v[2:3]
	v_and_b32_e32 v3, 0xffff0000, v179
	v_lshlrev_b32_e32 v2, 16, v179
	v_pk_mul_f32 v[56:57], v[56:57], v[2:3]
	v_cvt_pk_bf16_f32 v178, v54, v55
	v_cvt_pk_bf16_f32 v179, v56, v57
	global_store_dwordx2 v1, v[178:179], s[74:75] nt
	s_waitcnt vmcnt(31)
	v_pk_mul_f32 v[58:59], v[58:59], v[214:215]
	v_pk_mul_f32 v[60:61], v[60:61], v[216:217]
	v_and_b32_e32 v3, 0xffff0000, v180
	v_lshlrev_b32_e32 v2, 16, v180
	v_pk_mul_f32 v[58:59], v[58:59], v[2:3]
	v_and_b32_e32 v3, 0xffff0000, v181
	v_lshlrev_b32_e32 v2, 16, v181
	v_pk_mul_f32 v[60:61], v[60:61], v[2:3]
	v_cvt_pk_bf16_f32 v180, v58, v59
	v_cvt_pk_bf16_f32 v181, v60, v61
	global_store_dwordx2 v1, v[180:181], s[74:75] offset:16 nt
	s_waitcnt vmcnt(31)
	v_pk_mul_f32 v[62:63], v[62:63], v[218:219]
	v_pk_mul_f32 v[64:65], v[64:65], v[220:221]
	v_and_b32_e32 v3, 0xffff0000, v182
	v_lshlrev_b32_e32 v2, 16, v182
	v_pk_mul_f32 v[62:63], v[62:63], v[2:3]
	v_and_b32_e32 v3, 0xffff0000, v183
	v_lshlrev_b32_e32 v2, 16, v183
	v_pk_mul_f32 v[64:65], v[64:65], v[2:3]
	v_cvt_pk_bf16_f32 v182, v62, v63
	v_cvt_pk_bf16_f32 v183, v64, v65
	global_store_dwordx2 v1, v[182:183], s[74:75] offset:32 nt
	s_waitcnt vmcnt(31)
	v_pk_mul_f32 v[66:67], v[66:67], v[222:223]
	v_pk_mul_f32 v[68:69], v[68:69], v[224:225]
	v_and_b32_e32 v3, 0xffff0000, v184
	v_lshlrev_b32_e32 v2, 16, v184
	v_pk_mul_f32 v[66:67], v[66:67], v[2:3]
	v_and_b32_e32 v3, 0xffff0000, v185
	v_lshlrev_b32_e32 v2, 16, v185
	v_pk_mul_f32 v[68:69], v[68:69], v[2:3]
	v_cvt_pk_bf16_f32 v184, v66, v67
	v_cvt_pk_bf16_f32 v185, v68, v69
	global_store_dwordx2 v1, v[184:185], s[74:75] offset:48 nt
	s_waitcnt vmcnt(31)
	v_pk_mul_f32 v[38:39], v[38:39], v[226:227]
	v_pk_mul_f32 v[40:41], v[40:41], v[228:229]
	v_and_b32_e32 v3, 0xffff0000, v186
	v_lshlrev_b32_e32 v2, 16, v186
	v_pk_mul_f32 v[38:39], v[38:39], v[2:3]
	v_and_b32_e32 v3, 0xffff0000, v187
	v_lshlrev_b32_e32 v2, 16, v187
	v_pk_mul_f32 v[40:41], v[40:41], v[2:3]
	v_cvt_pk_bf16_f32 v186, v38, v39
	v_cvt_pk_bf16_f32 v187, v40, v41
	global_store_dwordx2 v1, v[186:187], s[74:75] offset:64 nt
	s_waitcnt vmcnt(31)
	v_pk_mul_f32 v[42:43], v[42:43], v[230:231]
	v_pk_mul_f32 v[44:45], v[44:45], v[232:233]
	v_and_b32_e32 v3, 0xffff0000, v188
	v_lshlrev_b32_e32 v2, 16, v188
	v_pk_mul_f32 v[42:43], v[42:43], v[2:3]
	v_and_b32_e32 v3, 0xffff0000, v189
	v_lshlrev_b32_e32 v2, 16, v189
	v_pk_mul_f32 v[44:45], v[44:45], v[2:3]
	v_cvt_pk_bf16_f32 v188, v42, v43
	v_cvt_pk_bf16_f32 v189, v44, v45
	global_store_dwordx2 v1, v[188:189], s[74:75] offset:80 nt
	s_waitcnt vmcnt(31)
	v_pk_mul_f32 v[46:47], v[46:47], v[234:235]
	v_pk_mul_f32 v[48:49], v[48:49], v[236:237]
	v_and_b32_e32 v3, 0xffff0000, v190
	v_lshlrev_b32_e32 v2, 16, v190
	v_pk_mul_f32 v[46:47], v[46:47], v[2:3]
	v_and_b32_e32 v3, 0xffff0000, v191
	v_lshlrev_b32_e32 v2, 16, v191
	v_pk_mul_f32 v[48:49], v[48:49], v[2:3]
	v_cvt_pk_bf16_f32 v190, v46, v47
	v_cvt_pk_bf16_f32 v191, v48, v49
	global_store_dwordx2 v1, v[190:191], s[74:75] offset:96 nt
	s_waitcnt vmcnt(31)
	v_pk_mul_f32 v[50:51], v[50:51], v[134:135]
	v_pk_mul_f32 v[52:53], v[52:53], v[136:137]
	v_and_b32_e32 v3, 0xffff0000, v192
	v_lshlrev_b32_e32 v2, 16, v192
	v_pk_mul_f32 v[50:51], v[50:51], v[2:3]
	v_and_b32_e32 v3, 0xffff0000, v193
	v_lshlrev_b32_e32 v2, 16, v193
	v_pk_mul_f32 v[52:53], v[52:53], v[2:3]
	v_cvt_pk_bf16_f32 v192, v50, v51
	v_cvt_pk_bf16_f32 v193, v52, v53
	global_store_dwordx2 v1, v[192:193], s[74:75] offset:112 nt
	s_add_u32 s74, s72, 0x30000
	s_addc_u32 s75, s73, 0
	s_waitcnt vmcnt(31)
	v_pk_mul_f32 v[22:23], v[22:23], v[210:211]
	v_pk_mul_f32 v[24:25], v[24:25], v[212:213]
	v_and_b32_e32 v3, 0xffff0000, v194
	v_lshlrev_b32_e32 v2, 16, v194
	v_pk_mul_f32 v[22:23], v[22:23], v[2:3]
	v_and_b32_e32 v3, 0xffff0000, v195
	v_lshlrev_b32_e32 v2, 16, v195
	v_pk_mul_f32 v[24:25], v[24:25], v[2:3]
	v_cvt_pk_bf16_f32 v194, v22, v23
	v_cvt_pk_bf16_f32 v195, v24, v25
	global_store_dwordx2 v1, v[194:195], s[74:75] nt
	s_waitcnt vmcnt(31)
	v_pk_mul_f32 v[26:27], v[26:27], v[214:215]
	v_pk_mul_f32 v[28:29], v[28:29], v[216:217]
	v_and_b32_e32 v3, 0xffff0000, v196
	v_lshlrev_b32_e32 v2, 16, v196
	v_pk_mul_f32 v[26:27], v[26:27], v[2:3]
	v_and_b32_e32 v3, 0xffff0000, v197
	v_lshlrev_b32_e32 v2, 16, v197
	v_pk_mul_f32 v[28:29], v[28:29], v[2:3]
	v_cvt_pk_bf16_f32 v196, v26, v27
	v_cvt_pk_bf16_f32 v197, v28, v29
	global_store_dwordx2 v1, v[196:197], s[74:75] offset:16 nt
	s_waitcnt vmcnt(31)
	v_pk_mul_f32 v[30:31], v[30:31], v[218:219]
	v_pk_mul_f32 v[32:33], v[32:33], v[220:221]
	v_and_b32_e32 v3, 0xffff0000, v198
	v_lshlrev_b32_e32 v2, 16, v198
	v_pk_mul_f32 v[30:31], v[30:31], v[2:3]
	v_and_b32_e32 v3, 0xffff0000, v199
	v_lshlrev_b32_e32 v2, 16, v199
	v_pk_mul_f32 v[32:33], v[32:33], v[2:3]
	v_cvt_pk_bf16_f32 v198, v30, v31
	v_cvt_pk_bf16_f32 v199, v32, v33
	global_store_dwordx2 v1, v[198:199], s[74:75] offset:32 nt
	s_waitcnt vmcnt(31)
	v_pk_mul_f32 v[34:35], v[34:35], v[222:223]
	v_pk_mul_f32 v[36:37], v[36:37], v[224:225]
	v_and_b32_e32 v3, 0xffff0000, v200
	v_lshlrev_b32_e32 v2, 16, v200
	v_pk_mul_f32 v[34:35], v[34:35], v[2:3]
	v_and_b32_e32 v3, 0xffff0000, v201
	v_lshlrev_b32_e32 v2, 16, v201
	v_pk_mul_f32 v[36:37], v[36:37], v[2:3]
	v_cvt_pk_bf16_f32 v200, v34, v35
	v_cvt_pk_bf16_f32 v201, v36, v37
	global_store_dwordx2 v1, v[200:201], s[74:75] offset:48 nt
	s_waitcnt vmcnt(31)
	v_pk_mul_f32 v[6:7], v[6:7], v[226:227]
	v_pk_mul_f32 v[8:9], v[8:9], v[228:229]
	v_and_b32_e32 v3, 0xffff0000, v202
	v_lshlrev_b32_e32 v2, 16, v202
	v_pk_mul_f32 v[6:7], v[6:7], v[2:3]
	v_and_b32_e32 v3, 0xffff0000, v203
	v_lshlrev_b32_e32 v2, 16, v203
	v_pk_mul_f32 v[8:9], v[8:9], v[2:3]
	v_cvt_pk_bf16_f32 v202, v6, v7
	v_cvt_pk_bf16_f32 v203, v8, v9
	global_store_dwordx2 v1, v[202:203], s[74:75] offset:64 nt
	s_waitcnt vmcnt(31)
	v_pk_mul_f32 v[10:11], v[10:11], v[230:231]
	v_pk_mul_f32 v[12:13], v[12:13], v[232:233]
	v_and_b32_e32 v3, 0xffff0000, v204
	v_lshlrev_b32_e32 v2, 16, v204
	v_pk_mul_f32 v[10:11], v[10:11], v[2:3]
	v_and_b32_e32 v3, 0xffff0000, v205
	v_lshlrev_b32_e32 v2, 16, v205
	v_pk_mul_f32 v[12:13], v[12:13], v[2:3]
	v_cvt_pk_bf16_f32 v204, v10, v11
	v_cvt_pk_bf16_f32 v205, v12, v13
	global_store_dwordx2 v1, v[204:205], s[74:75] offset:80 nt
	s_waitcnt vmcnt(31)
	v_pk_mul_f32 v[14:15], v[14:15], v[234:235]
	v_pk_mul_f32 v[16:17], v[16:17], v[236:237]
	v_and_b32_e32 v3, 0xffff0000, v206
	v_lshlrev_b32_e32 v2, 16, v206
	v_pk_mul_f32 v[14:15], v[14:15], v[2:3]
	v_and_b32_e32 v3, 0xffff0000, v207
	v_lshlrev_b32_e32 v2, 16, v207
	v_pk_mul_f32 v[16:17], v[16:17], v[2:3]
	v_cvt_pk_bf16_f32 v206, v14, v15
	v_cvt_pk_bf16_f32 v207, v16, v17
	global_store_dwordx2 v1, v[206:207], s[74:75] offset:96 nt
	s_waitcnt vmcnt(31)
	v_pk_mul_f32 v[18:19], v[18:19], v[134:135]
	v_pk_mul_f32 v[20:21], v[20:21], v[136:137]
	v_and_b32_e32 v3, 0xffff0000, v208
	v_lshlrev_b32_e32 v2, 16, v208
	v_pk_mul_f32 v[18:19], v[18:19], v[2:3]
	v_and_b32_e32 v3, 0xffff0000, v209
	v_lshlrev_b32_e32 v2, 16, v209
	v_pk_mul_f32 v[20:21], v[20:21], v[2:3]
	v_cvt_pk_bf16_f32 v208, v18, v19
	v_cvt_pk_bf16_f32 v209, v20, v21
	global_store_dwordx2 v1, v[208:209], s[74:75] offset:112 nt

.LBB0_1152:
	s_and_b64 vcc, exec, s[4:5]
	s_cbranch_vccz .LBB0_1154
	v_readlane_b32 s70, v254, 8
	v_readlane_b32 s71, v254, 9
	v_ashrrev_i32_e32 v0, 1, v144
	s_movk_i32 s0, 0xff80
	v_and_or_b32 v0, v0, s0, v161
	v_lshlrev_b32_e32 v2, 6, v145
	v_and_or_b32 v2, v2, s33, v160
	v_add_u32_e32 v2, s68, v2
	v_lshlrev_b32_e32 v0, 1, v0
	v_mad_u32_u24 v1, v2, s92, v0
	v_lshl_add_u32 v3, v2, 11, v0
	s_mov_b64 s[72:73], s[46:47]
	v_mov_b32_e32 v146, 0
	v_mov_b32_e32 v147, 0
	v_mov_b32_e32 v148, 0
	v_mov_b32_e32 v149, 0
	v_mov_b32_e32 v150, 0
	v_mov_b32_e32 v151, 0
	v_mov_b32_e32 v152, 0
	v_mov_b32_e32 v153, 0
	v_mov_b32_e32 v154, 0
	v_mov_b32_e32 v155, 0
	v_mov_b32_e32 v156, 0
	v_mov_b32_e32 v157, 0
	v_mov_b32_e32 v158, 0
	v_mov_b32_e32 v159, 0
	v_mov_b32_e32 v160, 0
	v_mov_b32_e32 v161, 0
	v_mov_b32_e32 v162, 0
	v_mov_b32_e32 v163, 0
	v_mov_b32_e32 v164, 0
	v_mov_b32_e32 v165, 0
	v_mov_b32_e32 v166, 0
	v_mov_b32_e32 v167, 0
	v_mov_b32_e32 v168, 0
	v_mov_b32_e32 v169, 0
	v_mov_b32_e32 v170, 0
	v_mov_b32_e32 v171, 0
	v_mov_b32_e32 v172, 0
	v_mov_b32_e32 v173, 0
	v_mov_b32_e32 v174, 0
	v_mov_b32_e32 v175, 0
	v_mov_b32_e32 v176, 0
	v_mov_b32_e32 v177, 0
	global_load_short_d16_hi v146, v1, s[70:71]
	global_load_short_d16_hi v147, v1, s[70:71] offset:64
	global_load_short_d16_hi v148, v1, s[70:71] offset:128
	global_load_short_d16_hi v149, v1, s[70:71] offset:192
	s_add_u32 s70, s70, 0x28000
	s_addc_u32 s71, s71, 0
	global_load_short_d16_hi v150, v1, s[70:71]
	global_load_short_d16_hi v151, v1, s[70:71] offset:64
	global_load_short_d16_hi v152, v1, s[70:71] offset:128
	global_load_short_d16_hi v153, v1, s[70:71] offset:192
	s_add_u32 s70, s70, 0x28000
	s_addc_u32 s71, s71, 0
	global_load_short_d16_hi v154, v1, s[70:71]
	global_load_short_d16_hi v155, v1, s[70:71] offset:64
	global_load_short_d16_hi v156, v1, s[70:71] offset:128
	global_load_short_d16_hi v157, v1, s[70:71] offset:192
	s_add_u32 s70, s70, 0x28000
	s_addc_u32 s71, s71, 0
	global_load_short_d16_hi v158, v1, s[70:71]
	global_load_short_d16_hi v159, v1, s[70:71] offset:64
	global_load_short_d16_hi v160, v1, s[70:71] offset:128
	global_load_short_d16_hi v161, v1, s[70:71] offset:192
	s_add_u32 s70, s70, 0xc8000
	s_addc_u32 s71, s71, 0
	global_load_short_d16_hi v162, v1, s[70:71]
	global_load_short_d16_hi v163, v1, s[70:71] offset:64
	global_load_short_d16_hi v164, v1, s[70:71] offset:128
	global_load_short_d16_hi v165, v1, s[70:71] offset:192
	s_add_u32 s70, s70, 0x28000
	s_addc_u32 s71, s71, 0
	global_load_short_d16_hi v166, v1, s[70:71]
	global_load_short_d16_hi v167, v1, s[70:71] offset:64
	global_load_short_d16_hi v168, v1, s[70:71] offset:128
	global_load_short_d16_hi v169, v1, s[70:71] offset:192
	s_add_u32 s70, s70, 0x28000
	s_addc_u32 s71, s71, 0
	global_load_short_d16_hi v170, v1, s[70:71]
	global_load_short_d16_hi v171, v1, s[70:71] offset:64
	global_load_short_d16_hi v172, v1, s[70:71] offset:128
	global_load_short_d16_hi v173, v1, s[70:71] offset:192
	s_add_u32 s70, s70, 0x28000
	s_addc_u32 s71, s71, 0
	global_load_short_d16_hi v174, v1, s[70:71]
	global_load_short_d16_hi v175, v1, s[70:71] offset:64
	global_load_short_d16_hi v176, v1, s[70:71] offset:128
	global_load_short_d16_hi v177, v1, s[70:71] offset:192
	s_add_u32 s70, s70, 0xc8000
	s_addc_u32 s71, s71, 0
	s_waitcnt vmcnt(16)
	v_mul_f32_e32 v178, v118, v146
	v_cvt_pk_bf16_f32 v178, v178, v178
	global_store_short v3, v178, s[72:73] nt
	v_mul_f32_e32 v179, v86, v147
	v_cvt_pk_bf16_f32 v179, v179, v179
	global_store_short v3, v179, s[72:73] offset:64 nt
	v_mul_f32_e32 v180, v54, v148
	v_cvt_pk_bf16_f32 v180, v180, v180
	global_store_short v3, v180, s[72:73] offset:128 nt
	v_mul_f32_e32 v181, v22, v149
	v_cvt_pk_bf16_f32 v181, v181, v181
	global_store_short v3, v181, s[72:73] offset:192 nt
	s_add_u32 s72, s72, 0x20000
	s_addc_u32 s73, s73, 0
	v_mul_f32_e32 v178, v119, v150
	v_cvt_pk_bf16_f32 v178, v178, v178
	global_store_short v3, v178, s[72:73] nt
	v_mul_f32_e32 v179, v87, v151
	v_cvt_pk_bf16_f32 v179, v179, v179
	global_store_short v3, v179, s[72:73] offset:64 nt
	v_mul_f32_e32 v180, v55, v152
	v_cvt_pk_bf16_f32 v180, v180, v180
	global_store_short v3, v180, s[72:73] offset:128 nt
	v_mul_f32_e32 v181, v23, v153
	v_cvt_pk_bf16_f32 v181, v181, v181
	global_store_short v3, v181, s[72:73] offset:192 nt
	s_add_u32 s72, s72, 0x20000
	s_addc_u32 s73, s73, 0
	v_mul_f32_e32 v178, v120, v154
	v_cvt_pk_bf16_f32 v178, v178, v178
	global_store_short v3, v178, s[72:73] nt
	v_mul_f32_e32 v179, v88, v155
	v_cvt_pk_bf16_f32 v179, v179, v179
	global_store_short v3, v179, s[72:73] offset:64 nt
	v_mul_f32_e32 v180, v56, v156
	v_cvt_pk_bf16_f32 v180, v180, v180
	global_store_short v3, v180, s[72:73] offset:128 nt
	v_mul_f32_e32 v181, v24, v157
	v_cvt_pk_bf16_f32 v181, v181, v181
	global_store_short v3, v181, s[72:73] offset:192 nt
	s_add_u32 s72, s72, 0x20000
	s_addc_u32 s73, s73, 0
	v_mul_f32_e32 v178, v121, v158
	v_cvt_pk_bf16_f32 v178, v178, v178
	global_store_short v3, v178, s[72:73] nt
	v_mul_f32_e32 v179, v89, v159
	v_cvt_pk_bf16_f32 v179, v179, v179
	global_store_short v3, v179, s[72:73] offset:64 nt
	v_mul_f32_e32 v180, v57, v160
	v_cvt_pk_bf16_f32 v180, v180, v180
	global_store_short v3, v180, s[72:73] offset:128 nt
	v_mul_f32_e32 v181, v25, v161
	v_cvt_pk_bf16_f32 v181, v181, v181
	global_store_short v3, v181, s[72:73] offset:192 nt
	s_add_u32 s72, s72, 0xa0000
	s_addc_u32 s73, s73, 0
	global_load_short_d16_hi v146, v1, s[70:71]
	global_load_short_d16_hi v147, v1, s[70:71] offset:64
	global_load_short_d16_hi v148, v1, s[70:71] offset:128
	global_load_short_d16_hi v149, v1, s[70:71] offset:192
	s_add_u32 s70, s70, 0x28000
	s_addc_u32 s71, s71, 0
	global_load_short_d16_hi v150, v1, s[70:71]
	global_load_short_d16_hi v151, v1, s[70:71] offset:64
	global_load_short_d16_hi v152, v1, s[70:71] offset:128
	global_load_short_d16_hi v153, v1, s[70:71] offset:192
	s_add_u32 s70, s70, 0x28000
	s_addc_u32 s71, s71, 0
	global_load_short_d16_hi v154, v1, s[70:71]
	global_load_short_d16_hi v155, v1, s[70:71] offset:64
	global_load_short_d16_hi v156, v1, s[70:71] offset:128
	global_load_short_d16_hi v157, v1, s[70:71] offset:192
	s_add_u32 s70, s70, 0x28000
	s_addc_u32 s71, s71, 0
	global_load_short_d16_hi v158, v1, s[70:71]
	global_load_short_d16_hi v159, v1, s[70:71] offset:64
	global_load_short_d16_hi v160, v1, s[70:71] offset:128
	global_load_short_d16_hi v161, v1, s[70:71] offset:192
	s_add_u32 s70, s70, 0xc8000
	s_addc_u32 s71, s71, 0
	s_waitcnt vmcnt(32)
	v_mul_f32_e32 v178, v122, v162
	v_cvt_pk_bf16_f32 v178, v178, v178
	global_store_short v3, v178, s[72:73] nt
	v_mul_f32_e32 v179, v90, v163
	v_cvt_pk_bf16_f32 v179, v179, v179
	global_store_short v3, v179, s[72:73] offset:64 nt
	v_mul_f32_e32 v180, v58, v164
	v_cvt_pk_bf16_f32 v180, v180, v180
	global_store_short v3, v180, s[72:73] offset:128 nt
	v_mul_f32_e32 v181, v26, v165
	v_cvt_pk_bf16_f32 v181, v181, v181
	global_store_short v3, v181, s[72:73] offset:192 nt
	s_add_u32 s72, s72, 0x20000
	s_addc_u32 s73, s73, 0
	v_mul_f32_e32 v178, v123, v166
	v_cvt_pk_bf16_f32 v178, v178, v178
	global_store_short v3, v178, s[72:73] nt
	v_mul_f32_e32 v179, v91, v167
	v_cvt_pk_bf16_f32 v179, v179, v179
	global_store_short v3, v179, s[72:73] offset:64 nt
	v_mul_f32_e32 v180, v59, v168
	v_cvt_pk_bf16_f32 v180, v180, v180
	global_store_short v3, v180, s[72:73] offset:128 nt
	v_mul_f32_e32 v181, v27, v169
	v_cvt_pk_bf16_f32 v181, v181, v181
	global_store_short v3, v181, s[72:73] offset:192 nt
	s_add_u32 s72, s72, 0x20000
	s_addc_u32 s73, s73, 0
	v_mul_f32_e32 v178, v124, v170
	v_cvt_pk_bf16_f32 v178, v178, v178
	global_store_short v3, v178, s[72:73] nt
	v_mul_f32_e32 v179, v92, v171
	v_cvt_pk_bf16_f32 v179, v179, v179
	global_store_short v3, v179, s[72:73] offset:64 nt
	v_mul_f32_e32 v180, v60, v172
	v_cvt_pk_bf16_f32 v180, v180, v180
	global_store_short v3, v180, s[72:73] offset:128 nt
	v_mul_f32_e32 v181, v28, v173
	v_cvt_pk_bf16_f32 v181, v181, v181
	global_store_short v3, v181, s[72:73] offset:192 nt
	s_add_u32 s72, s72, 0x20000
	s_addc_u32 s73, s73, 0
	v_mul_f32_e32 v178, v125, v174
	v_cvt_pk_bf16_f32 v178, v178, v178
	global_store_short v3, v178, s[72:73] nt
	v_mul_f32_e32 v179, v93, v175
	v_cvt_pk_bf16_f32 v179, v179, v179
	global_store_short v3, v179, s[72:73] offset:64 nt
	v_mul_f32_e32 v180, v61, v176
	v_cvt_pk_bf16_f32 v180, v180, v180
	global_store_short v3, v180, s[72:73] offset:128 nt
	v_mul_f32_e32 v181, v29, v177
	v_cvt_pk_bf16_f32 v181, v181, v181
	global_store_short v3, v181, s[72:73] offset:192 nt
	s_add_u32 s72, s72, 0xa0000
	s_addc_u32 s73, s73, 0
	global_load_short_d16_hi v162, v1, s[70:71]
	global_load_short_d16_hi v163, v1, s[70:71] offset:64
	global_load_short_d16_hi v164, v1, s[70:71] offset:128
	global_load_short_d16_hi v165, v1, s[70:71] offset:192
	s_add_u32 s70, s70, 0x28000
	s_addc_u32 s71, s71, 0
	global_load_short_d16_hi v166, v1, s[70:71]
	global_load_short_d16_hi v167, v1, s[70:71] offset:64
	global_load_short_d16_hi v168, v1, s[70:71] offset:128
	global_load_short_d16_hi v169, v1, s[70:71] offset:192
	s_add_u32 s70, s70, 0x28000
	s_addc_u32 s71, s71, 0
	global_load_short_d16_hi v170, v1, s[70:71]
	global_load_short_d16_hi v171, v1, s[70:71] offset:64
	global_load_short_d16_hi v172, v1, s[70:71] offset:128
	global_load_short_d16_hi v173, v1, s[70:71] offset:192
	s_add_u32 s70, s70, 0x28000
	s_addc_u32 s71, s71, 0
	global_load_short_d16_hi v174, v1, s[70:71]
	global_load_short_d16_hi v175, v1, s[70:71] offset:64
	global_load_short_d16_hi v176, v1, s[70:71] offset:128
	global_load_short_d16_hi v177, v1, s[70:71] offset:192
	s_add_u32 s70, s70, 0xc8000
	s_addc_u32 s71, s71, 0
	s_waitcnt vmcnt(32)
	v_mul_f32_e32 v178, v126, v146
	v_cvt_pk_bf16_f32 v178, v178, v178
	global_store_short v3, v178, s[72:73] nt
	v_mul_f32_e32 v179, v94, v147
	v_cvt_pk_bf16_f32 v179, v179, v179
	global_store_short v3, v179, s[72:73] offset:64 nt
	v_mul_f32_e32 v180, v62, v148
	v_cvt_pk_bf16_f32 v180, v180, v180
	global_store_short v3, v180, s[72:73] offset:128 nt
	v_mul_f32_e32 v181, v30, v149
	v_cvt_pk_bf16_f32 v181, v181, v181
	global_store_short v3, v181, s[72:73] offset:192 nt
	s_add_u32 s72, s72, 0x20000
	s_addc_u32 s73, s73, 0
	v_mul_f32_e32 v178, v127, v150
	v_cvt_pk_bf16_f32 v178, v178, v178
	global_store_short v3, v178, s[72:73] nt
	v_mul_f32_e32 v179, v95, v151
	v_cvt_pk_bf16_f32 v179, v179, v179
	global_store_short v3, v179, s[72:73] offset:64 nt
	v_mul_f32_e32 v180, v63, v152
	v_cvt_pk_bf16_f32 v180, v180, v180
	global_store_short v3, v180, s[72:73] offset:128 nt
	v_mul_f32_e32 v181, v31, v153
	v_cvt_pk_bf16_f32 v181, v181, v181
	global_store_short v3, v181, s[72:73] offset:192 nt
	s_add_u32 s72, s72, 0x20000
	s_addc_u32 s73, s73, 0
	v_mul_f32_e32 v178, v128, v154
	v_cvt_pk_bf16_f32 v178, v178, v178
	global_store_short v3, v178, s[72:73] nt
	v_mul_f32_e32 v179, v96, v155
	v_cvt_pk_bf16_f32 v179, v179, v179
	global_store_short v3, v179, s[72:73] offset:64 nt
	v_mul_f32_e32 v180, v64, v156
	v_cvt_pk_bf16_f32 v180, v180, v180
	global_store_short v3, v180, s[72:73] offset:128 nt
	v_mul_f32_e32 v181, v32, v157
	v_cvt_pk_bf16_f32 v181, v181, v181
	global_store_short v3, v181, s[72:73] offset:192 nt
	s_add_u32 s72, s72, 0x20000
	s_addc_u32 s73, s73, 0
	v_mul_f32_e32 v178, v129, v158
	v_cvt_pk_bf16_f32 v178, v178, v178
	global_store_short v3, v178, s[72:73] nt
	v_mul_f32_e32 v179, v97, v159
	v_cvt_pk_bf16_f32 v179, v179, v179
	global_store_short v3, v179, s[72:73] offset:64 nt
	v_mul_f32_e32 v180, v65, v160
	v_cvt_pk_bf16_f32 v180, v180, v180
	global_store_short v3, v180, s[72:73] offset:128 nt
	v_mul_f32_e32 v181, v33, v161
	v_cvt_pk_bf16_f32 v181, v181, v181
	global_store_short v3, v181, s[72:73] offset:192 nt
	s_add_u32 s72, s72, 0xa0000
	s_addc_u32 s73, s73, 0
	global_load_short_d16_hi v146, v1, s[70:71]
	global_load_short_d16_hi v147, v1, s[70:71] offset:64
	global_load_short_d16_hi v148, v1, s[70:71] offset:128
	global_load_short_d16_hi v149, v1, s[70:71] offset:192
	s_add_u32 s70, s70, 0x28000
	s_addc_u32 s71, s71, 0
	global_load_short_d16_hi v150, v1, s[70:71]
	global_load_short_d16_hi v151, v1, s[70:71] offset:64
	global_load_short_d16_hi v152, v1, s[70:71] offset:128
	global_load_short_d16_hi v153, v1, s[70:71] offset:192
	s_add_u32 s70, s70, 0x28000
	s_addc_u32 s71, s71, 0
	global_load_short_d16_hi v154, v1, s[70:71]
	global_load_short_d16_hi v155, v1, s[70:71] offset:64
	global_load_short_d16_hi v156, v1, s[70:71] offset:128
	global_load_short_d16_hi v157, v1, s[70:71] offset:192
	s_add_u32 s70, s70, 0x28000
	s_addc_u32 s71, s71, 0
	global_load_short_d16_hi v158, v1, s[70:71]
	global_load_short_d16_hi v159, v1, s[70:71] offset:64
	global_load_short_d16_hi v160, v1, s[70:71] offset:128
	global_load_short_d16_hi v161, v1, s[70:71] offset:192
	s_add_u32 s70, s70, 0xc8000
	s_addc_u32 s71, s71, 0
	s_waitcnt vmcnt(32)
	v_mul_f32_e32 v178, v130, v162
	v_cvt_pk_bf16_f32 v178, v178, v178
	global_store_short v3, v178, s[72:73] nt
	v_mul_f32_e32 v179, v98, v163
	v_cvt_pk_bf16_f32 v179, v179, v179
	global_store_short v3, v179, s[72:73] offset:64 nt
	v_mul_f32_e32 v180, v66, v164
	v_cvt_pk_bf16_f32 v180, v180, v180
	global_store_short v3, v180, s[72:73] offset:128 nt
	v_mul_f32_e32 v181, v34, v165
	v_cvt_pk_bf16_f32 v181, v181, v181
	global_store_short v3, v181, s[72:73] offset:192 nt
	s_add_u32 s72, s72, 0x20000
	s_addc_u32 s73, s73, 0
	v_mul_f32_e32 v178, v131, v166
	v_cvt_pk_bf16_f32 v178, v178, v178
	global_store_short v3, v178, s[72:73] nt
	v_mul_f32_e32 v179, v99, v167
	v_cvt_pk_bf16_f32 v179, v179, v179
	global_store_short v3, v179, s[72:73] offset:64 nt
	v_mul_f32_e32 v180, v67, v168
	v_cvt_pk_bf16_f32 v180, v180, v180
	global_store_short v3, v180, s[72:73] offset:128 nt
	v_mul_f32_e32 v181, v35, v169
	v_cvt_pk_bf16_f32 v181, v181, v181
	global_store_short v3, v181, s[72:73] offset:192 nt
	s_add_u32 s72, s72, 0x20000
	s_addc_u32 s73, s73, 0
	v_mul_f32_e32 v178, v132, v170
	v_cvt_pk_bf16_f32 v178, v178, v178
	global_store_short v3, v178, s[72:73] nt
	v_mul_f32_e32 v179, v100, v171
	v_cvt_pk_bf16_f32 v179, v179, v179
	global_store_short v3, v179, s[72:73] offset:64 nt
	v_mul_f32_e32 v180, v68, v172
	v_cvt_pk_bf16_f32 v180, v180, v180
	global_store_short v3, v180, s[72:73] offset:128 nt
	v_mul_f32_e32 v181, v36, v173
	v_cvt_pk_bf16_f32 v181, v181, v181
	global_store_short v3, v181, s[72:73] offset:192 nt
	s_add_u32 s72, s72, 0x20000
	s_addc_u32 s73, s73, 0
	v_mul_f32_e32 v178, v133, v174
	v_cvt_pk_bf16_f32 v178, v178, v178
	global_store_short v3, v178, s[72:73] nt
	v_mul_f32_e32 v179, v101, v175
	v_cvt_pk_bf16_f32 v179, v179, v179
	global_store_short v3, v179, s[72:73] offset:64 nt
	v_mul_f32_e32 v180, v69, v176
	v_cvt_pk_bf16_f32 v180, v180, v180
	global_store_short v3, v180, s[72:73] offset:128 nt
	v_mul_f32_e32 v181, v37, v177
	v_cvt_pk_bf16_f32 v181, v181, v181
	global_store_short v3, v181, s[72:73] offset:192 nt
	s_add_u32 s72, s72, 0xa0000
	s_addc_u32 s73, s73, 0
	global_load_short_d16_hi v162, v1, s[70:71]
	global_load_short_d16_hi v163, v1, s[70:71] offset:64
	global_load_short_d16_hi v164, v1, s[70:71] offset:128
	global_load_short_d16_hi v165, v1, s[70:71] offset:192
	s_add_u32 s70, s70, 0x28000
	s_addc_u32 s71, s71, 0
	global_load_short_d16_hi v166, v1, s[70:71]
	global_load_short_d16_hi v167, v1, s[70:71] offset:64
	global_load_short_d16_hi v168, v1, s[70:71] offset:128
	global_load_short_d16_hi v169, v1, s[70:71] offset:192
	s_add_u32 s70, s70, 0x28000
	s_addc_u32 s71, s71, 0
	global_load_short_d16_hi v170, v1, s[70:71]
	global_load_short_d16_hi v171, v1, s[70:71] offset:64
	global_load_short_d16_hi v172, v1, s[70:71] offset:128
	global_load_short_d16_hi v173, v1, s[70:71] offset:192
	s_add_u32 s70, s70, 0x28000
	s_addc_u32 s71, s71, 0
	global_load_short_d16_hi v174, v1, s[70:71]
	global_load_short_d16_hi v175, v1, s[70:71] offset:64
	global_load_short_d16_hi v176, v1, s[70:71] offset:128
	global_load_short_d16_hi v177, v1, s[70:71] offset:192
	s_add_u32 s70, s70, 0xc8000
	s_addc_u32 s71, s71, 0
	s_waitcnt vmcnt(32)
	v_mul_f32_e32 v178, v102, v146
	v_cvt_pk_bf16_f32 v178, v178, v178
	global_store_short v3, v178, s[72:73] nt
	v_mul_f32_e32 v179, v70, v147
	v_cvt_pk_bf16_f32 v179, v179, v179
	global_store_short v3, v179, s[72:73] offset:64 nt
	v_mul_f32_e32 v180, v38, v148
	v_cvt_pk_bf16_f32 v180, v180, v180
	global_store_short v3, v180, s[72:73] offset:128 nt
	v_mul_f32_e32 v181, v6, v149
	v_cvt_pk_bf16_f32 v181, v181, v181
	global_store_short v3, v181, s[72:73] offset:192 nt
	s_add_u32 s72, s72, 0x20000
	s_addc_u32 s73, s73, 0
	v_mul_f32_e32 v178, v103, v150
	v_cvt_pk_bf16_f32 v178, v178, v178
	global_store_short v3, v178, s[72:73] nt
	v_mul_f32_e32 v179, v71, v151
	v_cvt_pk_bf16_f32 v179, v179, v179
	global_store_short v3, v179, s[72:73] offset:64 nt
	v_mul_f32_e32 v180, v39, v152
	v_cvt_pk_bf16_f32 v180, v180, v180
	global_store_short v3, v180, s[72:73] offset:128 nt
	v_mul_f32_e32 v181, v7, v153
	v_cvt_pk_bf16_f32 v181, v181, v181
	global_store_short v3, v181, s[72:73] offset:192 nt
	s_add_u32 s72, s72, 0x20000
	s_addc_u32 s73, s73, 0
	v_mul_f32_e32 v178, v104, v154
	v_cvt_pk_bf16_f32 v178, v178, v178
	global_store_short v3, v178, s[72:73] nt
	v_mul_f32_e32 v179, v72, v155
	v_cvt_pk_bf16_f32 v179, v179, v179
	global_store_short v3, v179, s[72:73] offset:64 nt
	v_mul_f32_e32 v180, v40, v156
	v_cvt_pk_bf16_f32 v180, v180, v180
	global_store_short v3, v180, s[72:73] offset:128 nt
	v_mul_f32_e32 v181, v8, v157
	v_cvt_pk_bf16_f32 v181, v181, v181
	global_store_short v3, v181, s[72:73] offset:192 nt
	s_add_u32 s72, s72, 0x20000
	s_addc_u32 s73, s73, 0
	v_mul_f32_e32 v178, v105, v158
	v_cvt_pk_bf16_f32 v178, v178, v178
	global_store_short v3, v178, s[72:73] nt
	v_mul_f32_e32 v179, v73, v159
	v_cvt_pk_bf16_f32 v179, v179, v179
	global_store_short v3, v179, s[72:73] offset:64 nt
	v_mul_f32_e32 v180, v41, v160
	v_cvt_pk_bf16_f32 v180, v180, v180
	global_store_short v3, v180, s[72:73] offset:128 nt
	v_mul_f32_e32 v181, v9, v161
	v_cvt_pk_bf16_f32 v181, v181, v181
	global_store_short v3, v181, s[72:73] offset:192 nt
	s_add_u32 s72, s72, 0xa0000
	s_addc_u32 s73, s73, 0
	global_load_short_d16_hi v146, v1, s[70:71]
	global_load_short_d16_hi v147, v1, s[70:71] offset:64
	global_load_short_d16_hi v148, v1, s[70:71] offset:128
	global_load_short_d16_hi v149, v1, s[70:71] offset:192
	s_add_u32 s70, s70, 0x28000
	s_addc_u32 s71, s71, 0
	global_load_short_d16_hi v150, v1, s[70:71]
	global_load_short_d16_hi v151, v1, s[70:71] offset:64
	global_load_short_d16_hi v152, v1, s[70:71] offset:128
	global_load_short_d16_hi v153, v1, s[70:71] offset:192
	s_add_u32 s70, s70, 0x28000
	s_addc_u32 s71, s71, 0
	global_load_short_d16_hi v154, v1, s[70:71]
	global_load_short_d16_hi v155, v1, s[70:71] offset:64
	global_load_short_d16_hi v156, v1, s[70:71] offset:128
	global_load_short_d16_hi v157, v1, s[70:71] offset:192
	s_add_u32 s70, s70, 0x28000
	s_addc_u32 s71, s71, 0
	global_load_short_d16_hi v158, v1, s[70:71]
	global_load_short_d16_hi v159, v1, s[70:71] offset:64
	global_load_short_d16_hi v160, v1, s[70:71] offset:128
	global_load_short_d16_hi v161, v1, s[70:71] offset:192
	s_add_u32 s70, s70, 0xc8000
	s_addc_u32 s71, s71, 0
	s_waitcnt vmcnt(32)
	v_mul_f32_e32 v178, v106, v162
	v_cvt_pk_bf16_f32 v178, v178, v178
	global_store_short v3, v178, s[72:73] nt
	v_mul_f32_e32 v179, v74, v163
	v_cvt_pk_bf16_f32 v179, v179, v179
	global_store_short v3, v179, s[72:73] offset:64 nt
	v_mul_f32_e32 v180, v42, v164
	v_cvt_pk_bf16_f32 v180, v180, v180
	global_store_short v3, v180, s[72:73] offset:128 nt
	v_mul_f32_e32 v181, v10, v165
	v_cvt_pk_bf16_f32 v181, v181, v181
	global_store_short v3, v181, s[72:73] offset:192 nt
	s_add_u32 s72, s72, 0x20000
	s_addc_u32 s73, s73, 0
	v_mul_f32_e32 v178, v107, v166
	v_cvt_pk_bf16_f32 v178, v178, v178
	global_store_short v3, v178, s[72:73] nt
	v_mul_f32_e32 v179, v75, v167
	v_cvt_pk_bf16_f32 v179, v179, v179
	global_store_short v3, v179, s[72:73] offset:64 nt
	v_mul_f32_e32 v180, v43, v168
	v_cvt_pk_bf16_f32 v180, v180, v180
	global_store_short v3, v180, s[72:73] offset:128 nt
	v_mul_f32_e32 v181, v11, v169
	v_cvt_pk_bf16_f32 v181, v181, v181
	global_store_short v3, v181, s[72:73] offset:192 nt
	s_add_u32 s72, s72, 0x20000
	s_addc_u32 s73, s73, 0
	v_mul_f32_e32 v178, v108, v170
	v_cvt_pk_bf16_f32 v178, v178, v178
	global_store_short v3, v178, s[72:73] nt
	v_mul_f32_e32 v179, v76, v171
	v_cvt_pk_bf16_f32 v179, v179, v179
	global_store_short v3, v179, s[72:73] offset:64 nt
	v_mul_f32_e32 v180, v44, v172
	v_cvt_pk_bf16_f32 v180, v180, v180
	global_store_short v3, v180, s[72:73] offset:128 nt
	v_mul_f32_e32 v181, v12, v173
	v_cvt_pk_bf16_f32 v181, v181, v181
	global_store_short v3, v181, s[72:73] offset:192 nt
	s_add_u32 s72, s72, 0x20000
	s_addc_u32 s73, s73, 0
	v_mul_f32_e32 v178, v109, v174
	v_cvt_pk_bf16_f32 v178, v178, v178
	global_store_short v3, v178, s[72:73] nt
	v_mul_f32_e32 v179, v77, v175
	v_cvt_pk_bf16_f32 v179, v179, v179
	global_store_short v3, v179, s[72:73] offset:64 nt
	v_mul_f32_e32 v180, v45, v176
	v_cvt_pk_bf16_f32 v180, v180, v180
	global_store_short v3, v180, s[72:73] offset:128 nt
	v_mul_f32_e32 v181, v13, v177
	v_cvt_pk_bf16_f32 v181, v181, v181
	global_store_short v3, v181, s[72:73] offset:192 nt
	s_add_u32 s72, s72, 0xa0000
	s_addc_u32 s73, s73, 0
	global_load_short_d16_hi v162, v1, s[70:71]
	global_load_short_d16_hi v163, v1, s[70:71] offset:64
	global_load_short_d16_hi v164, v1, s[70:71] offset:128
	global_load_short_d16_hi v165, v1, s[70:71] offset:192
	s_add_u32 s70, s70, 0x28000
	s_addc_u32 s71, s71, 0
	global_load_short_d16_hi v166, v1, s[70:71]
	global_load_short_d16_hi v167, v1, s[70:71] offset:64
	global_load_short_d16_hi v168, v1, s[70:71] offset:128
	global_load_short_d16_hi v169, v1, s[70:71] offset:192
	s_add_u32 s70, s70, 0x28000
	s_addc_u32 s71, s71, 0
	global_load_short_d16_hi v170, v1, s[70:71]
	global_load_short_d16_hi v171, v1, s[70:71] offset:64
	global_load_short_d16_hi v172, v1, s[70:71] offset:128
	global_load_short_d16_hi v173, v1, s[70:71] offset:192
	s_add_u32 s70, s70, 0x28000
	s_addc_u32 s71, s71, 0
	global_load_short_d16_hi v174, v1, s[70:71]
	global_load_short_d16_hi v175, v1, s[70:71] offset:64
	global_load_short_d16_hi v176, v1, s[70:71] offset:128
	global_load_short_d16_hi v177, v1, s[70:71] offset:192
	s_waitcnt vmcnt(32)
	v_mul_f32_e32 v178, v110, v146
	v_cvt_pk_bf16_f32 v178, v178, v178
	global_store_short v3, v178, s[72:73] nt
	v_mul_f32_e32 v179, v78, v147
	v_cvt_pk_bf16_f32 v179, v179, v179
	global_store_short v3, v179, s[72:73] offset:64 nt
	v_mul_f32_e32 v180, v46, v148
	v_cvt_pk_bf16_f32 v180, v180, v180
	global_store_short v3, v180, s[72:73] offset:128 nt
	v_mul_f32_e32 v181, v14, v149
	v_cvt_pk_bf16_f32 v181, v181, v181
	global_store_short v3, v181, s[72:73] offset:192 nt
	s_add_u32 s72, s72, 0x20000
	s_addc_u32 s73, s73, 0
	v_mul_f32_e32 v178, v111, v150
	v_cvt_pk_bf16_f32 v178, v178, v178
	global_store_short v3, v178, s[72:73] nt
	v_mul_f32_e32 v179, v79, v151
	v_cvt_pk_bf16_f32 v179, v179, v179
	global_store_short v3, v179, s[72:73] offset:64 nt
	v_mul_f32_e32 v180, v47, v152
	v_cvt_pk_bf16_f32 v180, v180, v180
	global_store_short v3, v180, s[72:73] offset:128 nt
	v_mul_f32_e32 v181, v15, v153
	v_cvt_pk_bf16_f32 v181, v181, v181
	global_store_short v3, v181, s[72:73] offset:192 nt
	s_add_u32 s72, s72, 0x20000
	s_addc_u32 s73, s73, 0
	v_mul_f32_e32 v178, v112, v154
	v_cvt_pk_bf16_f32 v178, v178, v178
	global_store_short v3, v178, s[72:73] nt
	v_mul_f32_e32 v179, v80, v155
	v_cvt_pk_bf16_f32 v179, v179, v179
	global_store_short v3, v179, s[72:73] offset:64 nt
	v_mul_f32_e32 v180, v48, v156
	v_cvt_pk_bf16_f32 v180, v180, v180
	global_store_short v3, v180, s[72:73] offset:128 nt
	v_mul_f32_e32 v181, v16, v157
	v_cvt_pk_bf16_f32 v181, v181, v181
	global_store_short v3, v181, s[72:73] offset:192 nt
	s_add_u32 s72, s72, 0x20000
	s_addc_u32 s73, s73, 0
	v_mul_f32_e32 v178, v113, v158
	v_cvt_pk_bf16_f32 v178, v178, v178
	global_store_short v3, v178, s[72:73] nt
	v_mul_f32_e32 v179, v81, v159
	v_cvt_pk_bf16_f32 v179, v179, v179
	global_store_short v3, v179, s[72:73] offset:64 nt
	v_mul_f32_e32 v180, v49, v160
	v_cvt_pk_bf16_f32 v180, v180, v180
	global_store_short v3, v180, s[72:73] offset:128 nt
	v_mul_f32_e32 v181, v17, v161
	v_cvt_pk_bf16_f32 v181, v181, v181
	global_store_short v3, v181, s[72:73] offset:192 nt
	s_add_u32 s72, s72, 0xa0000
	s_addc_u32 s73, s73, 0
	s_waitcnt vmcnt(16)
	v_mul_f32_e32 v178, v114, v162
	v_cvt_pk_bf16_f32 v178, v178, v178
	global_store_short v3, v178, s[72:73] nt
	v_mul_f32_e32 v179, v82, v163
	v_cvt_pk_bf16_f32 v179, v179, v179
	global_store_short v3, v179, s[72:73] offset:64 nt
	v_mul_f32_e32 v180, v50, v164
	v_cvt_pk_bf16_f32 v180, v180, v180
	global_store_short v3, v180, s[72:73] offset:128 nt
	v_mul_f32_e32 v181, v18, v165
	v_cvt_pk_bf16_f32 v181, v181, v181
	global_store_short v3, v181, s[72:73] offset:192 nt
	s_add_u32 s72, s72, 0x20000
	s_addc_u32 s73, s73, 0
	v_mul_f32_e32 v178, v115, v166
	v_cvt_pk_bf16_f32 v178, v178, v178
	global_store_short v3, v178, s[72:73] nt
	v_mul_f32_e32 v179, v83, v167
	v_cvt_pk_bf16_f32 v179, v179, v179
	global_store_short v3, v179, s[72:73] offset:64 nt
	v_mul_f32_e32 v180, v51, v168
	v_cvt_pk_bf16_f32 v180, v180, v180
	global_store_short v3, v180, s[72:73] offset:128 nt
	v_mul_f32_e32 v181, v19, v169
	v_cvt_pk_bf16_f32 v181, v181, v181
	global_store_short v3, v181, s[72:73] offset:192 nt
	s_add_u32 s72, s72, 0x20000
	s_addc_u32 s73, s73, 0
	v_mul_f32_e32 v178, v116, v170
	v_cvt_pk_bf16_f32 v178, v178, v178
	global_store_short v3, v178, s[72:73] nt
	v_mul_f32_e32 v179, v84, v171
	v_cvt_pk_bf16_f32 v179, v179, v179
	global_store_short v3, v179, s[72:73] offset:64 nt
	v_mul_f32_e32 v180, v52, v172
	v_cvt_pk_bf16_f32 v180, v180, v180
	global_store_short v3, v180, s[72:73] offset:128 nt
	v_mul_f32_e32 v181, v20, v173
	v_cvt_pk_bf16_f32 v181, v181, v181
	global_store_short v3, v181, s[72:73] offset:192 nt
	s_add_u32 s72, s72, 0x20000
	s_addc_u32 s73, s73, 0
	v_mul_f32_e32 v178, v117, v174
	v_cvt_pk_bf16_f32 v178, v178, v178
	global_store_short v3, v178, s[72:73] nt
	v_mul_f32_e32 v179, v85, v175
	v_cvt_pk_bf16_f32 v179, v179, v179
	global_store_short v3, v179, s[72:73] offset:64 nt
	v_mul_f32_e32 v180, v53, v176
	v_cvt_pk_bf16_f32 v180, v180, v180
	global_store_short v3, v180, s[72:73] offset:128 nt
	v_mul_f32_e32 v181, v21, v177
	v_cvt_pk_bf16_f32 v181, v181, v181
	global_store_short v3, v181, s[72:73] offset:192 nt

.Lmrg_seg0:
	s_mov_b64 s[70:71], s[72:73]
	v_mov_b32_e32 v230, 0
	v_mov_b32_e32 v231, 0
	s_add_u32 s4, s70, 0x0
	s_addc_u32 s5, s71, 0
	global_load_dwordx4 v[130:133], v232, s[4:5]
	s_add_u32 s4, s70, 0x2000
	s_addc_u32 s5, s71, 0
	global_load_dwordx4 v[134:137], v232, s[4:5]
	s_add_u32 s4, s70, 0x4000
	s_addc_u32 s5, s71, 0
	global_load_dwordx4 v[156:159], v232, s[4:5]
	s_add_u32 s4, s70, 0x6000
	s_addc_u32 s5, s71, 0
	global_load_dwordx4 v[162:165], v232, s[4:5]
	s_add_u32 s4, s70, 0x8000
	s_addc_u32 s5, s71, 0
	global_load_dwordx4 v[166:169], v232, s[4:5]
	s_add_u32 s4, s70, 0xa000
	s_addc_u32 s5, s71, 0
	global_load_dwordx4 v[170:173], v232, s[4:5]
	s_add_u32 s4, s70, 0xc000
	s_addc_u32 s5, s71, 0
	global_load_dwordx4 v[174:177], v232, s[4:5]
	s_add_u32 s4, s70, 0xe000
	s_addc_u32 s5, s71, 0
	global_load_dwordx4 v[178:181], v232, s[4:5]
	s_waitcnt vmcnt(7)
	v_lshlrev_b32_e32 v224, 16, v130
	v_and_b32_e32 v225, 0xffff0000, v130
	v_pk_fma_f32 v[126:127], v[126:127], v[224:225], v[230:231]
	v_lshlrev_b32_e32 v226, 16, v131
	v_and_b32_e32 v227, 0xffff0000, v131
	v_pk_fma_f32 v[128:129], v[128:129], v[226:227], v[230:231]
	v_lshlrev_b32_e32 v224, 16, v132
	v_and_b32_e32 v225, 0xffff0000, v132
	v_pk_fma_f32 v[122:123], v[122:123], v[224:225], v[230:231]
	v_lshlrev_b32_e32 v226, 16, v133
	v_and_b32_e32 v227, 0xffff0000, v133
	v_pk_fma_f32 v[124:125], v[124:125], v[226:227], v[230:231]
	v_cvt_pk_bf16_f32 v126, v126, v127
	v_cvt_pk_bf16_f32 v127, v128, v129
	v_cvt_pk_bf16_f32 v128, v122, v123
	v_cvt_pk_bf16_f32 v129, v124, v125
	s_add_u32 s76, s72, 0x0
	s_addc_u32 s77, s73, 0
	global_store_dwordx4 v232, v[126:129], s[76:77] nt
	s_add_u32 s4, s70, 0x10000
	s_addc_u32 s5, s71, 0
	global_load_dwordx4 v[130:133], v232, s[4:5]
	s_waitcnt vmcnt(8)
	v_lshlrev_b32_e32 v224, 16, v134
	v_and_b32_e32 v225, 0xffff0000, v134
	v_pk_fma_f32 v[118:119], v[118:119], v[224:225], v[230:231]
	v_lshlrev_b32_e32 v226, 16, v135
	v_and_b32_e32 v227, 0xffff0000, v135
	v_pk_fma_f32 v[120:121], v[120:121], v[226:227], v[230:231]
	v_lshlrev_b32_e32 v224, 16, v136
	v_and_b32_e32 v225, 0xffff0000, v136
	v_pk_fma_f32 v[114:115], v[114:115], v[224:225], v[230:231]
	v_lshlrev_b32_e32 v226, 16, v137
	v_and_b32_e32 v227, 0xffff0000, v137
	v_pk_fma_f32 v[116:117], v[116:117], v[226:227], v[230:231]
	v_cvt_pk_bf16_f32 v118, v118, v119
	v_cvt_pk_bf16_f32 v119, v120, v121
	v_cvt_pk_bf16_f32 v120, v114, v115
	v_cvt_pk_bf16_f32 v121, v116, v117
	s_add_u32 s76, s72, 0x2000
	s_addc_u32 s77, s73, 0
	global_store_dwordx4 v232, v[118:121], s[76:77] nt
	s_add_u32 s4, s70, 0x12000
	s_addc_u32 s5, s71, 0
	global_load_dwordx4 v[134:137], v232, s[4:5]
	s_waitcnt vmcnt(9)
	v_lshlrev_b32_e32 v224, 16, v156
	v_and_b32_e32 v225, 0xffff0000, v156
	v_pk_fma_f32 v[110:111], v[110:111], v[224:225], v[230:231]
	v_lshlrev_b32_e32 v226, 16, v157
	v_and_b32_e32 v227, 0xffff0000, v157
	v_pk_fma_f32 v[112:113], v[112:113], v[226:227], v[230:231]
	v_lshlrev_b32_e32 v224, 16, v158
	v_and_b32_e32 v225, 0xffff0000, v158
	v_pk_fma_f32 v[106:107], v[106:107], v[224:225], v[230:231]
	v_lshlrev_b32_e32 v226, 16, v159
	v_and_b32_e32 v227, 0xffff0000, v159
	v_pk_fma_f32 v[108:109], v[108:109], v[226:227], v[230:231]
	v_cvt_pk_bf16_f32 v110, v110, v111
	v_cvt_pk_bf16_f32 v111, v112, v113
	v_cvt_pk_bf16_f32 v112, v106, v107
	v_cvt_pk_bf16_f32 v113, v108, v109
	s_add_u32 s76, s72, 0x4000
	s_addc_u32 s77, s73, 0
	global_store_dwordx4 v232, v[110:113], s[76:77] nt
	s_add_u32 s4, s70, 0x14000
	s_addc_u32 s5, s71, 0
	global_load_dwordx4 v[156:159], v232, s[4:5]
	s_waitcnt vmcnt(10)
	v_lshlrev_b32_e32 v224, 16, v162
	v_and_b32_e32 v225, 0xffff0000, v162
	v_pk_fma_f32 v[102:103], v[102:103], v[224:225], v[230:231]
	v_lshlrev_b32_e32 v226, 16, v163
	v_and_b32_e32 v227, 0xffff0000, v163
	v_pk_fma_f32 v[104:105], v[104:105], v[226:227], v[230:231]
	v_lshlrev_b32_e32 v224, 16, v164
	v_and_b32_e32 v225, 0xffff0000, v164
	v_pk_fma_f32 v[98:99], v[98:99], v[224:225], v[230:231]
	v_lshlrev_b32_e32 v226, 16, v165
	v_and_b32_e32 v227, 0xffff0000, v165
	v_pk_fma_f32 v[100:101], v[100:101], v[226:227], v[230:231]
	v_cvt_pk_bf16_f32 v102, v102, v103
	v_cvt_pk_bf16_f32 v103, v104, v105
	v_cvt_pk_bf16_f32 v104, v98, v99
	v_cvt_pk_bf16_f32 v105, v100, v101
	s_add_u32 s76, s72, 0x6000
	s_addc_u32 s77, s73, 0
	global_store_dwordx4 v232, v[102:105], s[76:77] nt
	s_add_u32 s4, s70, 0x16000
	s_addc_u32 s5, s71, 0
	global_load_dwordx4 v[162:165], v232, s[4:5]
	s_waitcnt vmcnt(11)
	v_lshlrev_b32_e32 v224, 16, v166
	v_and_b32_e32 v225, 0xffff0000, v166
	v_pk_fma_f32 v[94:95], v[94:95], v[224:225], v[230:231]
	v_lshlrev_b32_e32 v226, 16, v167
	v_and_b32_e32 v227, 0xffff0000, v167
	v_pk_fma_f32 v[96:97], v[96:97], v[226:227], v[230:231]
	v_lshlrev_b32_e32 v224, 16, v168
	v_and_b32_e32 v225, 0xffff0000, v168
	v_pk_fma_f32 v[90:91], v[90:91], v[224:225], v[230:231]
	v_lshlrev_b32_e32 v226, 16, v169
	v_and_b32_e32 v227, 0xffff0000, v169
	v_pk_fma_f32 v[92:93], v[92:93], v[226:227], v[230:231]
	v_cvt_pk_bf16_f32 v94, v94, v95
	v_cvt_pk_bf16_f32 v95, v96, v97
	v_cvt_pk_bf16_f32 v96, v90, v91
	v_cvt_pk_bf16_f32 v97, v92, v93
	s_add_u32 s76, s72, 0x8000
	s_addc_u32 s77, s73, 0
	global_store_dwordx4 v232, v[94:97], s[76:77] nt
	s_add_u32 s4, s70, 0x18000
	s_addc_u32 s5, s71, 0
	global_load_dwordx4 v[166:169], v232, s[4:5]
	s_waitcnt vmcnt(12)
	v_lshlrev_b32_e32 v224, 16, v170
	v_and_b32_e32 v225, 0xffff0000, v170
	v_pk_fma_f32 v[86:87], v[86:87], v[224:225], v[230:231]
	v_lshlrev_b32_e32 v226, 16, v171
	v_and_b32_e32 v227, 0xffff0000, v171
	v_pk_fma_f32 v[88:89], v[88:89], v[226:227], v[230:231]
	v_lshlrev_b32_e32 v224, 16, v172
	v_and_b32_e32 v225, 0xffff0000, v172
	v_pk_fma_f32 v[82:83], v[82:83], v[224:225], v[230:231]
	v_lshlrev_b32_e32 v226, 16, v173
	v_and_b32_e32 v227, 0xffff0000, v173
	v_pk_fma_f32 v[84:85], v[84:85], v[226:227], v[230:231]
	v_cvt_pk_bf16_f32 v86, v86, v87
	v_cvt_pk_bf16_f32 v87, v88, v89
	v_cvt_pk_bf16_f32 v88, v82, v83
	v_cvt_pk_bf16_f32 v89, v84, v85
	s_add_u32 s76, s72, 0xa000
	s_addc_u32 s77, s73, 0
	global_store_dwordx4 v232, v[86:89], s[76:77] nt
	s_add_u32 s4, s70, 0x1a000
	s_addc_u32 s5, s71, 0
	global_load_dwordx4 v[170:173], v232, s[4:5]
	s_waitcnt vmcnt(13)
	v_lshlrev_b32_e32 v224, 16, v174
	v_and_b32_e32 v225, 0xffff0000, v174
	v_pk_fma_f32 v[78:79], v[78:79], v[224:225], v[230:231]
	v_lshlrev_b32_e32 v226, 16, v175
	v_and_b32_e32 v227, 0xffff0000, v175
	v_pk_fma_f32 v[80:81], v[80:81], v[226:227], v[230:231]
	v_lshlrev_b32_e32 v224, 16, v176
	v_and_b32_e32 v225, 0xffff0000, v176
	v_pk_fma_f32 v[74:75], v[74:75], v[224:225], v[230:231]
	v_lshlrev_b32_e32 v226, 16, v177
	v_and_b32_e32 v227, 0xffff0000, v177
	v_pk_fma_f32 v[76:77], v[76:77], v[226:227], v[230:231]
	v_cvt_pk_bf16_f32 v78, v78, v79
	v_cvt_pk_bf16_f32 v79, v80, v81
	v_cvt_pk_bf16_f32 v80, v74, v75
	v_cvt_pk_bf16_f32 v81, v76, v77
	s_add_u32 s76, s72, 0xc000
	s_addc_u32 s77, s73, 0
	global_store_dwordx4 v232, v[78:81], s[76:77] nt
	s_add_u32 s4, s70, 0x1c000
	s_addc_u32 s5, s71, 0
	global_load_dwordx4 v[174:177], v232, s[4:5]
	s_waitcnt vmcnt(14)
	v_lshlrev_b32_e32 v224, 16, v178
	v_and_b32_e32 v225, 0xffff0000, v178
	v_pk_fma_f32 v[70:71], v[70:71], v[224:225], v[230:231]
	v_lshlrev_b32_e32 v226, 16, v179
	v_and_b32_e32 v227, 0xffff0000, v179
	v_pk_fma_f32 v[72:73], v[72:73], v[226:227], v[230:231]
	v_lshlrev_b32_e32 v224, 16, v180
	v_and_b32_e32 v225, 0xffff0000, v180
	v_pk_fma_f32 v[66:67], v[66:67], v[224:225], v[230:231]
	v_lshlrev_b32_e32 v226, 16, v181
	v_and_b32_e32 v227, 0xffff0000, v181
	v_pk_fma_f32 v[68:69], v[68:69], v[226:227], v[230:231]
	v_cvt_pk_bf16_f32 v70, v70, v71
	v_cvt_pk_bf16_f32 v71, v72, v73
	v_cvt_pk_bf16_f32 v72, v66, v67
	v_cvt_pk_bf16_f32 v73, v68, v69
	s_add_u32 s76, s72, 0xe000
	s_addc_u32 s77, s73, 0
	global_store_dwordx4 v232, v[70:73], s[76:77] nt
	s_add_u32 s4, s70, 0x1e000
	s_addc_u32 s5, s71, 0
	global_load_dwordx4 v[178:181], v232, s[4:5]
	s_waitcnt vmcnt(14)
	v_lshlrev_b32_e32 v224, 16, v130
	v_and_b32_e32 v225, 0xffff0000, v130
	v_pk_fma_f32 v[62:63], v[62:63], v[224:225], v[230:231]
	v_lshlrev_b32_e32 v226, 16, v131
	v_and_b32_e32 v227, 0xffff0000, v131
	v_pk_fma_f32 v[64:65], v[64:65], v[226:227], v[230:231]
	v_lshlrev_b32_e32 v224, 16, v132
	v_and_b32_e32 v225, 0xffff0000, v132
	v_pk_fma_f32 v[58:59], v[58:59], v[224:225], v[230:231]
	v_lshlrev_b32_e32 v226, 16, v133
	v_and_b32_e32 v227, 0xffff0000, v133
	v_pk_fma_f32 v[60:61], v[60:61], v[226:227], v[230:231]
	v_cvt_pk_bf16_f32 v62, v62, v63
	v_cvt_pk_bf16_f32 v63, v64, v65
	v_cvt_pk_bf16_f32 v64, v58, v59
	v_cvt_pk_bf16_f32 v65, v60, v61
	s_add_u32 s76, s72, 0x10000
	s_addc_u32 s77, s73, 0
	global_store_dwordx4 v232, v[62:65], s[76:77] nt
	s_waitcnt vmcnt(13)
	v_lshlrev_b32_e32 v224, 16, v134
	v_and_b32_e32 v225, 0xffff0000, v134
	v_pk_fma_f32 v[54:55], v[54:55], v[224:225], v[230:231]
	v_lshlrev_b32_e32 v226, 16, v135
	v_and_b32_e32 v227, 0xffff0000, v135
	v_pk_fma_f32 v[56:57], v[56:57], v[226:227], v[230:231]
	v_lshlrev_b32_e32 v224, 16, v136
	v_and_b32_e32 v225, 0xffff0000, v136
	v_pk_fma_f32 v[50:51], v[50:51], v[224:225], v[230:231]
	v_lshlrev_b32_e32 v226, 16, v137
	v_and_b32_e32 v227, 0xffff0000, v137
	v_pk_fma_f32 v[52:53], v[52:53], v[226:227], v[230:231]
	v_cvt_pk_bf16_f32 v54, v54, v55
	v_cvt_pk_bf16_f32 v55, v56, v57
	v_cvt_pk_bf16_f32 v56, v50, v51
	v_cvt_pk_bf16_f32 v57, v52, v53
	s_add_u32 s76, s72, 0x12000
	s_addc_u32 s77, s73, 0
	global_store_dwordx4 v232, v[54:57], s[76:77] nt
	s_waitcnt vmcnt(12)
	v_lshlrev_b32_e32 v224, 16, v156
	v_and_b32_e32 v225, 0xffff0000, v156
	v_pk_fma_f32 v[46:47], v[46:47], v[224:225], v[230:231]
	v_lshlrev_b32_e32 v226, 16, v157
	v_and_b32_e32 v227, 0xffff0000, v157
	v_pk_fma_f32 v[48:49], v[48:49], v[226:227], v[230:231]
	v_lshlrev_b32_e32 v224, 16, v158
	v_and_b32_e32 v225, 0xffff0000, v158
	v_pk_fma_f32 v[42:43], v[42:43], v[224:225], v[230:231]
	v_lshlrev_b32_e32 v226, 16, v159
	v_and_b32_e32 v227, 0xffff0000, v159
	v_pk_fma_f32 v[44:45], v[44:45], v[226:227], v[230:231]
	v_cvt_pk_bf16_f32 v46, v46, v47
	v_cvt_pk_bf16_f32 v47, v48, v49
	v_cvt_pk_bf16_f32 v48, v42, v43
	v_cvt_pk_bf16_f32 v49, v44, v45
	s_add_u32 s76, s72, 0x14000
	s_addc_u32 s77, s73, 0
	global_store_dwordx4 v232, v[46:49], s[76:77] nt
	s_waitcnt vmcnt(11)
	v_lshlrev_b32_e32 v224, 16, v162
	v_and_b32_e32 v225, 0xffff0000, v162
	v_pk_fma_f32 v[38:39], v[38:39], v[224:225], v[230:231]
	v_lshlrev_b32_e32 v226, 16, v163
	v_and_b32_e32 v227, 0xffff0000, v163
	v_pk_fma_f32 v[40:41], v[40:41], v[226:227], v[230:231]
	v_lshlrev_b32_e32 v224, 16, v164
	v_and_b32_e32 v225, 0xffff0000, v164
	v_pk_fma_f32 v[34:35], v[34:35], v[224:225], v[230:231]
	v_lshlrev_b32_e32 v226, 16, v165
	v_and_b32_e32 v227, 0xffff0000, v165
	v_pk_fma_f32 v[36:37], v[36:37], v[226:227], v[230:231]
	v_cvt_pk_bf16_f32 v38, v38, v39
	v_cvt_pk_bf16_f32 v39, v40, v41
	v_cvt_pk_bf16_f32 v40, v34, v35
	v_cvt_pk_bf16_f32 v41, v36, v37
	s_add_u32 s76, s72, 0x16000
	s_addc_u32 s77, s73, 0
	global_store_dwordx4 v232, v[38:41], s[76:77] nt
	s_waitcnt vmcnt(10)
	v_lshlrev_b32_e32 v224, 16, v166
	v_and_b32_e32 v225, 0xffff0000, v166
	v_pk_fma_f32 v[30:31], v[30:31], v[224:225], v[230:231]
	v_lshlrev_b32_e32 v226, 16, v167
	v_and_b32_e32 v227, 0xffff0000, v167
	v_pk_fma_f32 v[32:33], v[32:33], v[226:227], v[230:231]
	v_lshlrev_b32_e32 v224, 16, v168
	v_and_b32_e32 v225, 0xffff0000, v168
	v_pk_fma_f32 v[26:27], v[26:27], v[224:225], v[230:231]
	v_lshlrev_b32_e32 v226, 16, v169
	v_and_b32_e32 v227, 0xffff0000, v169
	v_pk_fma_f32 v[28:29], v[28:29], v[226:227], v[230:231]
	v_cvt_pk_bf16_f32 v30, v30, v31
	v_cvt_pk_bf16_f32 v31, v32, v33
	v_cvt_pk_bf16_f32 v32, v26, v27
	v_cvt_pk_bf16_f32 v33, v28, v29
	s_add_u32 s76, s72, 0x18000
	s_addc_u32 s77, s73, 0
	global_store_dwordx4 v232, v[30:33], s[76:77] nt
	s_waitcnt vmcnt(9)
	v_lshlrev_b32_e32 v224, 16, v170
	v_and_b32_e32 v225, 0xffff0000, v170
	v_pk_fma_f32 v[22:23], v[22:23], v[224:225], v[230:231]
	v_lshlrev_b32_e32 v226, 16, v171
	v_and_b32_e32 v227, 0xffff0000, v171
	v_pk_fma_f32 v[24:25], v[24:25], v[226:227], v[230:231]
	v_lshlrev_b32_e32 v224, 16, v172
	v_and_b32_e32 v225, 0xffff0000, v172
	v_pk_fma_f32 v[18:19], v[18:19], v[224:225], v[230:231]
	v_lshlrev_b32_e32 v226, 16, v173
	v_and_b32_e32 v227, 0xffff0000, v173
	v_pk_fma_f32 v[20:21], v[20:21], v[226:227], v[230:231]
	v_cvt_pk_bf16_f32 v22, v22, v23
	v_cvt_pk_bf16_f32 v23, v24, v25
	v_cvt_pk_bf16_f32 v24, v18, v19
	v_cvt_pk_bf16_f32 v25, v20, v21
	s_add_u32 s76, s72, 0x1a000
	s_addc_u32 s77, s73, 0
	global_store_dwordx4 v232, v[22:25], s[76:77] nt
	s_waitcnt vmcnt(8)
	v_lshlrev_b32_e32 v224, 16, v174
	v_and_b32_e32 v225, 0xffff0000, v174
	v_pk_fma_f32 v[14:15], v[14:15], v[224:225], v[230:231]
	v_lshlrev_b32_e32 v226, 16, v175
	v_and_b32_e32 v227, 0xffff0000, v175
	v_pk_fma_f32 v[16:17], v[16:17], v[226:227], v[230:231]
	v_lshlrev_b32_e32 v224, 16, v176
	v_and_b32_e32 v225, 0xffff0000, v176
	v_pk_fma_f32 v[10:11], v[10:11], v[224:225], v[230:231]
	v_lshlrev_b32_e32 v226, 16, v177
	v_and_b32_e32 v227, 0xffff0000, v177
	v_pk_fma_f32 v[12:13], v[12:13], v[226:227], v[230:231]
	v_cvt_pk_bf16_f32 v14, v14, v15
	v_cvt_pk_bf16_f32 v15, v16, v17
	v_cvt_pk_bf16_f32 v16, v10, v11
	v_cvt_pk_bf16_f32 v17, v12, v13
	s_add_u32 s76, s72, 0x1c000
	s_addc_u32 s77, s73, 0
	global_store_dwordx4 v232, v[14:17], s[76:77] nt
	s_waitcnt vmcnt(7)
	v_lshlrev_b32_e32 v224, 16, v178
	v_and_b32_e32 v225, 0xffff0000, v178
	v_pk_fma_f32 v[6:7], v[6:7], v[224:225], v[230:231]
	v_lshlrev_b32_e32 v226, 16, v179
	v_and_b32_e32 v227, 0xffff0000, v179
	v_pk_fma_f32 v[8:9], v[8:9], v[226:227], v[230:231]
	v_lshlrev_b32_e32 v224, 16, v180
	v_and_b32_e32 v225, 0xffff0000, v180
	v_pk_fma_f32 v[0:1], v[0:1], v[224:225], v[230:231]
	v_lshlrev_b32_e32 v226, 16, v181
	v_and_b32_e32 v227, 0xffff0000, v181
	v_pk_fma_f32 v[2:3], v[2:3], v[226:227], v[230:231]
	v_cvt_pk_bf16_f32 v6, v6, v7
	v_cvt_pk_bf16_f32 v7, v8, v9
	v_cvt_pk_bf16_f32 v8, v0, v1
	v_cvt_pk_bf16_f32 v9, v2, v3
	s_add_u32 s76, s72, 0x1e000
	s_addc_u32 s77, s73, 0
	global_store_dwordx4 v232, v[6:9], s[76:77] nt
	s_branch .Lmrg_done
.Lmrg_seg1:
	s_add_u32 s70, s26, 0x4512000
	s_addc_u32 s71, s27, 0
	s_add_u32 s70, s70, s4
	s_addc_u32 s71, s71, 0
	s_add_u32 s4, s70, 0x0
	s_addc_u32 s5, s71, 0
	global_load_dwordx4 v[130:133], v232, s[4:5]
	s_add_u32 s4, s72, 0x0
	s_addc_u32 s5, s73, 0
	global_load_dwordx4 v[182:185], v232, s[4:5]
	s_add_u32 s4, s70, 0x2000
	s_addc_u32 s5, s71, 0
	global_load_dwordx4 v[134:137], v232, s[4:5]
	s_add_u32 s4, s72, 0x2000
	s_addc_u32 s5, s73, 0
	global_load_dwordx4 v[186:189], v232, s[4:5]
	s_add_u32 s4, s70, 0x4000
	s_addc_u32 s5, s71, 0
	global_load_dwordx4 v[156:159], v232, s[4:5]
	s_add_u32 s4, s72, 0x4000
	s_addc_u32 s5, s73, 0
	global_load_dwordx4 v[190:193], v232, s[4:5]
	s_add_u32 s4, s70, 0x6000
	s_addc_u32 s5, s71, 0
	global_load_dwordx4 v[162:165], v232, s[4:5]
	s_add_u32 s4, s72, 0x6000
	s_addc_u32 s5, s73, 0
	global_load_dwordx4 v[194:197], v232, s[4:5]
	s_add_u32 s4, s70, 0x8000
	s_addc_u32 s5, s71, 0
	global_load_dwordx4 v[166:169], v232, s[4:5]
	s_add_u32 s4, s72, 0x8000
	s_addc_u32 s5, s73, 0
	global_load_dwordx4 v[198:201], v232, s[4:5]
	s_add_u32 s4, s70, 0xa000
	s_addc_u32 s5, s71, 0
	global_load_dwordx4 v[170:173], v232, s[4:5]
	s_add_u32 s4, s72, 0xa000
	s_addc_u32 s5, s73, 0
	global_load_dwordx4 v[202:205], v232, s[4:5]
	s_add_u32 s4, s70, 0xc000
	s_addc_u32 s5, s71, 0
	global_load_dwordx4 v[174:177], v232, s[4:5]
	s_add_u32 s4, s72, 0xc000
	s_addc_u32 s5, s73, 0
	global_load_dwordx4 v[206:209], v232, s[4:5]
	s_add_u32 s4, s70, 0xe000
	s_addc_u32 s5, s71, 0
	global_load_dwordx4 v[178:181], v232, s[4:5]
	s_add_u32 s4, s72, 0xe000
	s_addc_u32 s5, s73, 0
	global_load_dwordx4 v[210:213], v232, s[4:5]
	s_waitcnt vmcnt(14)
	v_lshlrev_b32_e32 v224, 16, v130
	v_and_b32_e32 v225, 0xffff0000, v130
	v_lshlrev_b32_e32 v228, 16, v182
	v_and_b32_e32 v229, 0xffff0000, v182
	v_pk_fma_f32 v[126:127], v[126:127], v[224:225], v[228:229]
	v_lshlrev_b32_e32 v226, 16, v131
	v_and_b32_e32 v227, 0xffff0000, v131
	v_lshlrev_b32_e32 v230, 16, v183
	v_and_b32_e32 v231, 0xffff0000, v183
	v_pk_fma_f32 v[128:129], v[128:129], v[226:227], v[230:231]
	v_lshlrev_b32_e32 v224, 16, v132
	v_and_b32_e32 v225, 0xffff0000, v132
	v_lshlrev_b32_e32 v228, 16, v184
	v_and_b32_e32 v229, 0xffff0000, v184
	v_pk_fma_f32 v[122:123], v[122:123], v[224:225], v[228:229]
	v_lshlrev_b32_e32 v226, 16, v133
	v_and_b32_e32 v227, 0xffff0000, v133
	v_lshlrev_b32_e32 v230, 16, v185
	v_and_b32_e32 v231, 0xffff0000, v185
	v_pk_fma_f32 v[124:125], v[124:125], v[226:227], v[230:231]
	v_cvt_pk_bf16_f32 v126, v126, v127
	v_cvt_pk_bf16_f32 v127, v128, v129
	v_cvt_pk_bf16_f32 v128, v122, v123
	v_cvt_pk_bf16_f32 v129, v124, v125
	s_add_u32 s76, s72, 0x0
	s_addc_u32 s77, s73, 0
	global_store_dwordx4 v232, v[126:129], s[76:77] nt
	s_add_u32 s4, s70, 0x10000
	s_addc_u32 s5, s71, 0
	global_load_dwordx4 v[130:133], v232, s[4:5]
	s_add_u32 s4, s72, 0x10000
	s_addc_u32 s5, s73, 0
	global_load_dwordx4 v[182:185], v232, s[4:5]
	s_waitcnt vmcnt(15)
	v_lshlrev_b32_e32 v224, 16, v134
	v_and_b32_e32 v225, 0xffff0000, v134
	v_lshlrev_b32_e32 v228, 16, v186
	v_and_b32_e32 v229, 0xffff0000, v186
	v_pk_fma_f32 v[118:119], v[118:119], v[224:225], v[228:229]
	v_lshlrev_b32_e32 v226, 16, v135
	v_and_b32_e32 v227, 0xffff0000, v135
	v_lshlrev_b32_e32 v230, 16, v187
	v_and_b32_e32 v231, 0xffff0000, v187
	v_pk_fma_f32 v[120:121], v[120:121], v[226:227], v[230:231]
	v_lshlrev_b32_e32 v224, 16, v136
	v_and_b32_e32 v225, 0xffff0000, v136
	v_lshlrev_b32_e32 v228, 16, v188
	v_and_b32_e32 v229, 0xffff0000, v188
	v_pk_fma_f32 v[114:115], v[114:115], v[224:225], v[228:229]
	v_lshlrev_b32_e32 v226, 16, v137
	v_and_b32_e32 v227, 0xffff0000, v137
	v_lshlrev_b32_e32 v230, 16, v189
	v_and_b32_e32 v231, 0xffff0000, v189
	v_pk_fma_f32 v[116:117], v[116:117], v[226:227], v[230:231]
	v_cvt_pk_bf16_f32 v118, v118, v119
	v_cvt_pk_bf16_f32 v119, v120, v121
	v_cvt_pk_bf16_f32 v120, v114, v115
	v_cvt_pk_bf16_f32 v121, v116, v117
	s_add_u32 s76, s72, 0x2000
	s_addc_u32 s77, s73, 0
	global_store_dwordx4 v232, v[118:121], s[76:77] nt
	s_add_u32 s4, s70, 0x12000
	s_addc_u32 s5, s71, 0
	global_load_dwordx4 v[134:137], v232, s[4:5]
	s_add_u32 s4, s72, 0x12000
	s_addc_u32 s5, s73, 0
	global_load_dwordx4 v[186:189], v232, s[4:5]
	s_waitcnt vmcnt(16)
	v_lshlrev_b32_e32 v224, 16, v156
	v_and_b32_e32 v225, 0xffff0000, v156
	v_lshlrev_b32_e32 v228, 16, v190
	v_and_b32_e32 v229, 0xffff0000, v190
	v_pk_fma_f32 v[110:111], v[110:111], v[224:225], v[228:229]
	v_lshlrev_b32_e32 v226, 16, v157
	v_and_b32_e32 v227, 0xffff0000, v157
	v_lshlrev_b32_e32 v230, 16, v191
	v_and_b32_e32 v231, 0xffff0000, v191
	v_pk_fma_f32 v[112:113], v[112:113], v[226:227], v[230:231]
	v_lshlrev_b32_e32 v224, 16, v158
	v_and_b32_e32 v225, 0xffff0000, v158
	v_lshlrev_b32_e32 v228, 16, v192
	v_and_b32_e32 v229, 0xffff0000, v192
	v_pk_fma_f32 v[106:107], v[106:107], v[224:225], v[228:229]
	v_lshlrev_b32_e32 v226, 16, v159
	v_and_b32_e32 v227, 0xffff0000, v159
	v_lshlrev_b32_e32 v230, 16, v193
	v_and_b32_e32 v231, 0xffff0000, v193
	v_pk_fma_f32 v[108:109], v[108:109], v[226:227], v[230:231]
	v_cvt_pk_bf16_f32 v110, v110, v111
	v_cvt_pk_bf16_f32 v111, v112, v113
	v_cvt_pk_bf16_f32 v112, v106, v107
	v_cvt_pk_bf16_f32 v113, v108, v109
	s_add_u32 s76, s72, 0x4000
	s_addc_u32 s77, s73, 0
	global_store_dwordx4 v232, v[110:113], s[76:77] nt
	s_add_u32 s4, s70, 0x14000
	s_addc_u32 s5, s71, 0
	global_load_dwordx4 v[156:159], v232, s[4:5]
	s_add_u32 s4, s72, 0x14000
	s_addc_u32 s5, s73, 0
	global_load_dwordx4 v[190:193], v232, s[4:5]
	s_waitcnt vmcnt(17)
	v_lshlrev_b32_e32 v224, 16, v162
	v_and_b32_e32 v225, 0xffff0000, v162
	v_lshlrev_b32_e32 v228, 16, v194
	v_and_b32_e32 v229, 0xffff0000, v194
	v_pk_fma_f32 v[102:103], v[102:103], v[224:225], v[228:229]
	v_lshlrev_b32_e32 v226, 16, v163
	v_and_b32_e32 v227, 0xffff0000, v163
	v_lshlrev_b32_e32 v230, 16, v195
	v_and_b32_e32 v231, 0xffff0000, v195
	v_pk_fma_f32 v[104:105], v[104:105], v[226:227], v[230:231]
	v_lshlrev_b32_e32 v224, 16, v164
	v_and_b32_e32 v225, 0xffff0000, v164
	v_lshlrev_b32_e32 v228, 16, v196
	v_and_b32_e32 v229, 0xffff0000, v196
	v_pk_fma_f32 v[98:99], v[98:99], v[224:225], v[228:229]
	v_lshlrev_b32_e32 v226, 16, v165
	v_and_b32_e32 v227, 0xffff0000, v165
	v_lshlrev_b32_e32 v230, 16, v197
	v_and_b32_e32 v231, 0xffff0000, v197
	v_pk_fma_f32 v[100:101], v[100:101], v[226:227], v[230:231]
	v_cvt_pk_bf16_f32 v102, v102, v103
	v_cvt_pk_bf16_f32 v103, v104, v105
	v_cvt_pk_bf16_f32 v104, v98, v99
	v_cvt_pk_bf16_f32 v105, v100, v101
	s_add_u32 s76, s72, 0x6000
	s_addc_u32 s77, s73, 0
	global_store_dwordx4 v232, v[102:105], s[76:77] nt
	s_add_u32 s4, s70, 0x16000
	s_addc_u32 s5, s71, 0
	global_load_dwordx4 v[162:165], v232, s[4:5]
	s_add_u32 s4, s72, 0x16000
	s_addc_u32 s5, s73, 0
	global_load_dwordx4 v[194:197], v232, s[4:5]
	s_waitcnt vmcnt(18)
	v_lshlrev_b32_e32 v224, 16, v166
	v_and_b32_e32 v225, 0xffff0000, v166
	v_lshlrev_b32_e32 v228, 16, v198
	v_and_b32_e32 v229, 0xffff0000, v198
	v_pk_fma_f32 v[94:95], v[94:95], v[224:225], v[228:229]
	v_lshlrev_b32_e32 v226, 16, v167
	v_and_b32_e32 v227, 0xffff0000, v167
	v_lshlrev_b32_e32 v230, 16, v199
	v_and_b32_e32 v231, 0xffff0000, v199
	v_pk_fma_f32 v[96:97], v[96:97], v[226:227], v[230:231]
	v_lshlrev_b32_e32 v224, 16, v168
	v_and_b32_e32 v225, 0xffff0000, v168
	v_lshlrev_b32_e32 v228, 16, v200
	v_and_b32_e32 v229, 0xffff0000, v200
	v_pk_fma_f32 v[90:91], v[90:91], v[224:225], v[228:229]
	v_lshlrev_b32_e32 v226, 16, v169
	v_and_b32_e32 v227, 0xffff0000, v169
	v_lshlrev_b32_e32 v230, 16, v201
	v_and_b32_e32 v231, 0xffff0000, v201
	v_pk_fma_f32 v[92:93], v[92:93], v[226:227], v[230:231]
	v_cvt_pk_bf16_f32 v94, v94, v95
	v_cvt_pk_bf16_f32 v95, v96, v97
	v_cvt_pk_bf16_f32 v96, v90, v91
	v_cvt_pk_bf16_f32 v97, v92, v93
	s_add_u32 s76, s72, 0x8000
	s_addc_u32 s77, s73, 0
	global_store_dwordx4 v232, v[94:97], s[76:77] nt
	s_add_u32 s4, s70, 0x18000
	s_addc_u32 s5, s71, 0
	global_load_dwordx4 v[166:169], v232, s[4:5]
	s_add_u32 s4, s72, 0x18000
	s_addc_u32 s5, s73, 0
	global_load_dwordx4 v[198:201], v232, s[4:5]
	s_waitcnt vmcnt(19)
	v_lshlrev_b32_e32 v224, 16, v170
	v_and_b32_e32 v225, 0xffff0000, v170
	v_lshlrev_b32_e32 v228, 16, v202
	v_and_b32_e32 v229, 0xffff0000, v202
	v_pk_fma_f32 v[86:87], v[86:87], v[224:225], v[228:229]
	v_lshlrev_b32_e32 v226, 16, v171
	v_and_b32_e32 v227, 0xffff0000, v171
	v_lshlrev_b32_e32 v230, 16, v203
	v_and_b32_e32 v231, 0xffff0000, v203
	v_pk_fma_f32 v[88:89], v[88:89], v[226:227], v[230:231]
	v_lshlrev_b32_e32 v224, 16, v172
	v_and_b32_e32 v225, 0xffff0000, v172
	v_lshlrev_b32_e32 v228, 16, v204
	v_and_b32_e32 v229, 0xffff0000, v204
	v_pk_fma_f32 v[82:83], v[82:83], v[224:225], v[228:229]
	v_lshlrev_b32_e32 v226, 16, v173
	v_and_b32_e32 v227, 0xffff0000, v173
	v_lshlrev_b32_e32 v230, 16, v205
	v_and_b32_e32 v231, 0xffff0000, v205
	v_pk_fma_f32 v[84:85], v[84:85], v[226:227], v[230:231]
	v_cvt_pk_bf16_f32 v86, v86, v87
	v_cvt_pk_bf16_f32 v87, v88, v89
	v_cvt_pk_bf16_f32 v88, v82, v83
	v_cvt_pk_bf16_f32 v89, v84, v85
	s_add_u32 s76, s72, 0xa000
	s_addc_u32 s77, s73, 0
	global_store_dwordx4 v232, v[86:89], s[76:77] nt
	s_add_u32 s4, s70, 0x1a000
	s_addc_u32 s5, s71, 0
	global_load_dwordx4 v[170:173], v232, s[4:5]
	s_add_u32 s4, s72, 0x1a000
	s_addc_u32 s5, s73, 0
	global_load_dwordx4 v[202:205], v232, s[4:5]
	s_waitcnt vmcnt(20)
	v_lshlrev_b32_e32 v224, 16, v174
	v_and_b32_e32 v225, 0xffff0000, v174
	v_lshlrev_b32_e32 v228, 16, v206
	v_and_b32_e32 v229, 0xffff0000, v206
	v_pk_fma_f32 v[78:79], v[78:79], v[224:225], v[228:229]
	v_lshlrev_b32_e32 v226, 16, v175
	v_and_b32_e32 v227, 0xffff0000, v175
	v_lshlrev_b32_e32 v230, 16, v207
	v_and_b32_e32 v231, 0xffff0000, v207
	v_pk_fma_f32 v[80:81], v[80:81], v[226:227], v[230:231]
	v_lshlrev_b32_e32 v224, 16, v176
	v_and_b32_e32 v225, 0xffff0000, v176
	v_lshlrev_b32_e32 v228, 16, v208
	v_and_b32_e32 v229, 0xffff0000, v208
	v_pk_fma_f32 v[74:75], v[74:75], v[224:225], v[228:229]
	v_lshlrev_b32_e32 v226, 16, v177
	v_and_b32_e32 v227, 0xffff0000, v177
	v_lshlrev_b32_e32 v230, 16, v209
	v_and_b32_e32 v231, 0xffff0000, v209
	v_pk_fma_f32 v[76:77], v[76:77], v[226:227], v[230:231]
	v_cvt_pk_bf16_f32 v78, v78, v79
	v_cvt_pk_bf16_f32 v79, v80, v81
	v_cvt_pk_bf16_f32 v80, v74, v75
	v_cvt_pk_bf16_f32 v81, v76, v77
	s_add_u32 s76, s72, 0xc000
	s_addc_u32 s77, s73, 0
	global_store_dwordx4 v232, v[78:81], s[76:77] nt
	s_add_u32 s4, s70, 0x1c000
	s_addc_u32 s5, s71, 0
	global_load_dwordx4 v[174:177], v232, s[4:5]
	s_add_u32 s4, s72, 0x1c000
	s_addc_u32 s5, s73, 0
	global_load_dwordx4 v[206:209], v232, s[4:5]
	s_waitcnt vmcnt(21)
	v_lshlrev_b32_e32 v224, 16, v178
	v_and_b32_e32 v225, 0xffff0000, v178
	v_lshlrev_b32_e32 v228, 16, v210
	v_and_b32_e32 v229, 0xffff0000, v210
	v_pk_fma_f32 v[70:71], v[70:71], v[224:225], v[228:229]
	v_lshlrev_b32_e32 v226, 16, v179
	v_and_b32_e32 v227, 0xffff0000, v179
	v_lshlrev_b32_e32 v230, 16, v211
	v_and_b32_e32 v231, 0xffff0000, v211
	v_pk_fma_f32 v[72:73], v[72:73], v[226:227], v[230:231]
	v_lshlrev_b32_e32 v224, 16, v180
	v_and_b32_e32 v225, 0xffff0000, v180
	v_lshlrev_b32_e32 v228, 16, v212
	v_and_b32_e32 v229, 0xffff0000, v212
	v_pk_fma_f32 v[66:67], v[66:67], v[224:225], v[228:229]
	v_lshlrev_b32_e32 v226, 16, v181
	v_and_b32_e32 v227, 0xffff0000, v181
	v_lshlrev_b32_e32 v230, 16, v213
	v_and_b32_e32 v231, 0xffff0000, v213
	v_pk_fma_f32 v[68:69], v[68:69], v[226:227], v[230:231]
	v_cvt_pk_bf16_f32 v70, v70, v71
	v_cvt_pk_bf16_f32 v71, v72, v73
	v_cvt_pk_bf16_f32 v72, v66, v67
	v_cvt_pk_bf16_f32 v73, v68, v69
	s_add_u32 s76, s72, 0xe000
	s_addc_u32 s77, s73, 0
	global_store_dwordx4 v232, v[70:73], s[76:77] nt
	s_add_u32 s4, s70, 0x1e000
	s_addc_u32 s5, s71, 0
	global_load_dwordx4 v[178:181], v232, s[4:5]
	s_add_u32 s4, s72, 0x1e000
	s_addc_u32 s5, s73, 0
	global_load_dwordx4 v[210:213], v232, s[4:5]
	s_waitcnt vmcnt(21)
	v_lshlrev_b32_e32 v224, 16, v130
	v_and_b32_e32 v225, 0xffff0000, v130
	v_lshlrev_b32_e32 v228, 16, v182
	v_and_b32_e32 v229, 0xffff0000, v182
	v_pk_fma_f32 v[62:63], v[62:63], v[224:225], v[228:229]
	v_lshlrev_b32_e32 v226, 16, v131
	v_and_b32_e32 v227, 0xffff0000, v131
	v_lshlrev_b32_e32 v230, 16, v183
	v_and_b32_e32 v231, 0xffff0000, v183
	v_pk_fma_f32 v[64:65], v[64:65], v[226:227], v[230:231]
	v_lshlrev_b32_e32 v224, 16, v132
	v_and_b32_e32 v225, 0xffff0000, v132
	v_lshlrev_b32_e32 v228, 16, v184
	v_and_b32_e32 v229, 0xffff0000, v184
	v_pk_fma_f32 v[58:59], v[58:59], v[224:225], v[228:229]
	v_lshlrev_b32_e32 v226, 16, v133
	v_and_b32_e32 v227, 0xffff0000, v133
	v_lshlrev_b32_e32 v230, 16, v185
	v_and_b32_e32 v231, 0xffff0000, v185
	v_pk_fma_f32 v[60:61], v[60:61], v[226:227], v[230:231]
	v_cvt_pk_bf16_f32 v62, v62, v63
	v_cvt_pk_bf16_f32 v63, v64, v65
	v_cvt_pk_bf16_f32 v64, v58, v59
	v_cvt_pk_bf16_f32 v65, v60, v61
	s_add_u32 s76, s72, 0x10000
	s_addc_u32 s77, s73, 0
	global_store_dwordx4 v232, v[62:65], s[76:77] nt
	s_waitcnt vmcnt(19)
	v_lshlrev_b32_e32 v224, 16, v134
	v_and_b32_e32 v225, 0xffff0000, v134
	v_lshlrev_b32_e32 v228, 16, v186
	v_and_b32_e32 v229, 0xffff0000, v186
	v_pk_fma_f32 v[54:55], v[54:55], v[224:225], v[228:229]
	v_lshlrev_b32_e32 v226, 16, v135
	v_and_b32_e32 v227, 0xffff0000, v135
	v_lshlrev_b32_e32 v230, 16, v187
	v_and_b32_e32 v231, 0xffff0000, v187
	v_pk_fma_f32 v[56:57], v[56:57], v[226:227], v[230:231]
	v_lshlrev_b32_e32 v224, 16, v136
	v_and_b32_e32 v225, 0xffff0000, v136
	v_lshlrev_b32_e32 v228, 16, v188
	v_and_b32_e32 v229, 0xffff0000, v188
	v_pk_fma_f32 v[50:51], v[50:51], v[224:225], v[228:229]
	v_lshlrev_b32_e32 v226, 16, v137
	v_and_b32_e32 v227, 0xffff0000, v137
	v_lshlrev_b32_e32 v230, 16, v189
	v_and_b32_e32 v231, 0xffff0000, v189
	v_pk_fma_f32 v[52:53], v[52:53], v[226:227], v[230:231]
	v_cvt_pk_bf16_f32 v54, v54, v55
	v_cvt_pk_bf16_f32 v55, v56, v57
	v_cvt_pk_bf16_f32 v56, v50, v51
	v_cvt_pk_bf16_f32 v57, v52, v53
	s_add_u32 s76, s72, 0x12000
	s_addc_u32 s77, s73, 0
	global_store_dwordx4 v232, v[54:57], s[76:77] nt
	s_waitcnt vmcnt(17)
	v_lshlrev_b32_e32 v224, 16, v156
	v_and_b32_e32 v225, 0xffff0000, v156
	v_lshlrev_b32_e32 v228, 16, v190
	v_and_b32_e32 v229, 0xffff0000, v190
	v_pk_fma_f32 v[46:47], v[46:47], v[224:225], v[228:229]
	v_lshlrev_b32_e32 v226, 16, v157
	v_and_b32_e32 v227, 0xffff0000, v157
	v_lshlrev_b32_e32 v230, 16, v191
	v_and_b32_e32 v231, 0xffff0000, v191
	v_pk_fma_f32 v[48:49], v[48:49], v[226:227], v[230:231]
	v_lshlrev_b32_e32 v224, 16, v158
	v_and_b32_e32 v225, 0xffff0000, v158
	v_lshlrev_b32_e32 v228, 16, v192
	v_and_b32_e32 v229, 0xffff0000, v192
	v_pk_fma_f32 v[42:43], v[42:43], v[224:225], v[228:229]
	v_lshlrev_b32_e32 v226, 16, v159
	v_and_b32_e32 v227, 0xffff0000, v159
	v_lshlrev_b32_e32 v230, 16, v193
	v_and_b32_e32 v231, 0xffff0000, v193
	v_pk_fma_f32 v[44:45], v[44:45], v[226:227], v[230:231]
	v_cvt_pk_bf16_f32 v46, v46, v47
	v_cvt_pk_bf16_f32 v47, v48, v49
	v_cvt_pk_bf16_f32 v48, v42, v43
	v_cvt_pk_bf16_f32 v49, v44, v45
	s_add_u32 s76, s72, 0x14000
	s_addc_u32 s77, s73, 0
	global_store_dwordx4 v232, v[46:49], s[76:77] nt
	s_waitcnt vmcnt(15)
	v_lshlrev_b32_e32 v224, 16, v162
	v_and_b32_e32 v225, 0xffff0000, v162
	v_lshlrev_b32_e32 v228, 16, v194
	v_and_b32_e32 v229, 0xffff0000, v194
	v_pk_fma_f32 v[38:39], v[38:39], v[224:225], v[228:229]
	v_lshlrev_b32_e32 v226, 16, v163
	v_and_b32_e32 v227, 0xffff0000, v163
	v_lshlrev_b32_e32 v230, 16, v195
	v_and_b32_e32 v231, 0xffff0000, v195
	v_pk_fma_f32 v[40:41], v[40:41], v[226:227], v[230:231]
	v_lshlrev_b32_e32 v224, 16, v164
	v_and_b32_e32 v225, 0xffff0000, v164
	v_lshlrev_b32_e32 v228, 16, v196
	v_and_b32_e32 v229, 0xffff0000, v196
	v_pk_fma_f32 v[34:35], v[34:35], v[224:225], v[228:229]
	v_lshlrev_b32_e32 v226, 16, v165
	v_and_b32_e32 v227, 0xffff0000, v165
	v_lshlrev_b32_e32 v230, 16, v197
	v_and_b32_e32 v231, 0xffff0000, v197
	v_pk_fma_f32 v[36:37], v[36:37], v[226:227], v[230:231]
	v_cvt_pk_bf16_f32 v38, v38, v39
	v_cvt_pk_bf16_f32 v39, v40, v41
	v_cvt_pk_bf16_f32 v40, v34, v35
	v_cvt_pk_bf16_f32 v41, v36, v37
	s_add_u32 s76, s72, 0x16000
	s_addc_u32 s77, s73, 0
	global_store_dwordx4 v232, v[38:41], s[76:77] nt
	s_waitcnt vmcnt(13)
	v_lshlrev_b32_e32 v224, 16, v166
	v_and_b32_e32 v225, 0xffff0000, v166
	v_lshlrev_b32_e32 v228, 16, v198
	v_and_b32_e32 v229, 0xffff0000, v198
	v_pk_fma_f32 v[30:31], v[30:31], v[224:225], v[228:229]
	v_lshlrev_b32_e32 v226, 16, v167
	v_and_b32_e32 v227, 0xffff0000, v167
	v_lshlrev_b32_e32 v230, 16, v199
	v_and_b32_e32 v231, 0xffff0000, v199
	v_pk_fma_f32 v[32:33], v[32:33], v[226:227], v[230:231]
	v_lshlrev_b32_e32 v224, 16, v168
	v_and_b32_e32 v225, 0xffff0000, v168
	v_lshlrev_b32_e32 v228, 16, v200
	v_and_b32_e32 v229, 0xffff0000, v200
	v_pk_fma_f32 v[26:27], v[26:27], v[224:225], v[228:229]
	v_lshlrev_b32_e32 v226, 16, v169
	v_and_b32_e32 v227, 0xffff0000, v169
	v_lshlrev_b32_e32 v230, 16, v201
	v_and_b32_e32 v231, 0xffff0000, v201
	v_pk_fma_f32 v[28:29], v[28:29], v[226:227], v[230:231]
	v_cvt_pk_bf16_f32 v30, v30, v31
	v_cvt_pk_bf16_f32 v31, v32, v33
	v_cvt_pk_bf16_f32 v32, v26, v27
	v_cvt_pk_bf16_f32 v33, v28, v29
	s_add_u32 s76, s72, 0x18000
	s_addc_u32 s77, s73, 0
	global_store_dwordx4 v232, v[30:33], s[76:77] nt
	s_waitcnt vmcnt(11)
	v_lshlrev_b32_e32 v224, 16, v170
	v_and_b32_e32 v225, 0xffff0000, v170
	v_lshlrev_b32_e32 v228, 16, v202
	v_and_b32_e32 v229, 0xffff0000, v202
	v_pk_fma_f32 v[22:23], v[22:23], v[224:225], v[228:229]
	v_lshlrev_b32_e32 v226, 16, v171
	v_and_b32_e32 v227, 0xffff0000, v171
	v_lshlrev_b32_e32 v230, 16, v203
	v_and_b32_e32 v231, 0xffff0000, v203
	v_pk_fma_f32 v[24:25], v[24:25], v[226:227], v[230:231]
	v_lshlrev_b32_e32 v224, 16, v172
	v_and_b32_e32 v225, 0xffff0000, v172
	v_lshlrev_b32_e32 v228, 16, v204
	v_and_b32_e32 v229, 0xffff0000, v204
	v_pk_fma_f32 v[18:19], v[18:19], v[224:225], v[228:229]
	v_lshlrev_b32_e32 v226, 16, v173
	v_and_b32_e32 v227, 0xffff0000, v173
	v_lshlrev_b32_e32 v230, 16, v205
	v_and_b32_e32 v231, 0xffff0000, v205
	v_pk_fma_f32 v[20:21], v[20:21], v[226:227], v[230:231]
	v_cvt_pk_bf16_f32 v22, v22, v23
	v_cvt_pk_bf16_f32 v23, v24, v25
	v_cvt_pk_bf16_f32 v24, v18, v19
	v_cvt_pk_bf16_f32 v25, v20, v21
	s_add_u32 s76, s72, 0x1a000
	s_addc_u32 s77, s73, 0
	global_store_dwordx4 v232, v[22:25], s[76:77] nt
	s_waitcnt vmcnt(9)
	v_lshlrev_b32_e32 v224, 16, v174
	v_and_b32_e32 v225, 0xffff0000, v174
	v_lshlrev_b32_e32 v228, 16, v206
	v_and_b32_e32 v229, 0xffff0000, v206
	v_pk_fma_f32 v[14:15], v[14:15], v[224:225], v[228:229]
	v_lshlrev_b32_e32 v226, 16, v175
	v_and_b32_e32 v227, 0xffff0000, v175
	v_lshlrev_b32_e32 v230, 16, v207
	v_and_b32_e32 v231, 0xffff0000, v207
	v_pk_fma_f32 v[16:17], v[16:17], v[226:227], v[230:231]
	v_lshlrev_b32_e32 v224, 16, v176
	v_and_b32_e32 v225, 0xffff0000, v176
	v_lshlrev_b32_e32 v228, 16, v208
	v_and_b32_e32 v229, 0xffff0000, v208
	v_pk_fma_f32 v[10:11], v[10:11], v[224:225], v[228:229]
	v_lshlrev_b32_e32 v226, 16, v177
	v_and_b32_e32 v227, 0xffff0000, v177
	v_lshlrev_b32_e32 v230, 16, v209
	v_and_b32_e32 v231, 0xffff0000, v209
	v_pk_fma_f32 v[12:13], v[12:13], v[226:227], v[230:231]
	v_cvt_pk_bf16_f32 v14, v14, v15
	v_cvt_pk_bf16_f32 v15, v16, v17
	v_cvt_pk_bf16_f32 v16, v10, v11
	v_cvt_pk_bf16_f32 v17, v12, v13
	s_add_u32 s76, s72, 0x1c000
	s_addc_u32 s77, s73, 0
	global_store_dwordx4 v232, v[14:17], s[76:77] nt
	s_waitcnt vmcnt(7)
	v_lshlrev_b32_e32 v224, 16, v178
	v_and_b32_e32 v225, 0xffff0000, v178
	v_lshlrev_b32_e32 v228, 16, v210
	v_and_b32_e32 v229, 0xffff0000, v210
	v_pk_fma_f32 v[6:7], v[6:7], v[224:225], v[228:229]
	v_lshlrev_b32_e32 v226, 16, v179
	v_and_b32_e32 v227, 0xffff0000, v179
	v_lshlrev_b32_e32 v230, 16, v211
	v_and_b32_e32 v231, 0xffff0000, v211
	v_pk_fma_f32 v[8:9], v[8:9], v[226:227], v[230:231]
	v_lshlrev_b32_e32 v224, 16, v180
	v_and_b32_e32 v225, 0xffff0000, v180
	v_lshlrev_b32_e32 v228, 16, v212
	v_and_b32_e32 v229, 0xffff0000, v212
	v_pk_fma_f32 v[0:1], v[0:1], v[224:225], v[228:229]
	v_lshlrev_b32_e32 v226, 16, v181
	v_and_b32_e32 v227, 0xffff0000, v181
	v_lshlrev_b32_e32 v230, 16, v213
	v_and_b32_e32 v231, 0xffff0000, v213
	v_pk_fma_f32 v[2:3], v[2:3], v[226:227], v[230:231]
	v_cvt_pk_bf16_f32 v6, v6, v7
	v_cvt_pk_bf16_f32 v7, v8, v9
	v_cvt_pk_bf16_f32 v8, v0, v1
	v_cvt_pk_bf16_f32 v9, v2, v3
	s_add_u32 s76, s72, 0x1e000
	s_addc_u32 s77, s73, 0
	global_store_dwordx4 v232, v[6:9], s[76:77] nt
	s_branch .Lmrg_done
.Lmrg_seg2:
	s_add_u32 s70, s26, s93
	s_addc_u32 s71, s27, 0
	s_add_u32 s70, s70, s4
	s_addc_u32 s71, s71, 0
	s_lshl_b32 s5, s8, 19
	s_lshl_b32 s76, s6, 9
	s_add_u32 s5, s5, s76
	s_add_u32 s74, s24, s5
	s_addc_u32 s75, s25, 0
	v_add_u32_e32 v233, s45, v5
	v_lshlrev_b32_e32 v233, 11, v233
	v_lshl_add_u32 v234, v139, 3, s51
	v_lshl_add_u32 v233, v234, 1, v233
	s_add_u32 s4, s70, 0x0
	s_addc_u32 s5, s71, 0
	global_load_dwordx4 v[130:133], v232, s[4:5]
	s_add_u32 s4, s72, 0x0
	s_addc_u32 s5, s73, 0
	global_load_dwordx4 v[182:185], v232, s[4:5]
	s_add_u32 s4, s70, 0x2000
	s_addc_u32 s5, s71, 0
	global_load_dwordx4 v[134:137], v232, s[4:5]
	s_add_u32 s4, s72, 0x2000
	s_addc_u32 s5, s73, 0
	global_load_dwordx4 v[186:189], v232, s[4:5]
	s_add_u32 s4, s70, 0x4000
	s_addc_u32 s5, s71, 0
	global_load_dwordx4 v[156:159], v232, s[4:5]
	s_add_u32 s4, s72, 0x4000
	s_addc_u32 s5, s73, 0
	global_load_dwordx4 v[190:193], v232, s[4:5]
	s_add_u32 s4, s70, 0x6000
	s_addc_u32 s5, s71, 0
	global_load_dwordx4 v[162:165], v232, s[4:5]
	s_add_u32 s4, s72, 0x6000
	s_addc_u32 s5, s73, 0
	global_load_dwordx4 v[194:197], v232, s[4:5]
	s_add_u32 s4, s70, 0x8000
	s_addc_u32 s5, s71, 0
	global_load_dwordx4 v[166:169], v232, s[4:5]
	s_add_u32 s4, s72, 0x8000
	s_addc_u32 s5, s73, 0
	global_load_dwordx4 v[198:201], v232, s[4:5]
	s_add_u32 s4, s70, 0xa000
	s_addc_u32 s5, s71, 0
	global_load_dwordx4 v[170:173], v232, s[4:5]
	s_add_u32 s4, s72, 0xa000
	s_addc_u32 s5, s73, 0
	global_load_dwordx4 v[202:205], v232, s[4:5]
	s_add_u32 s4, s70, 0xc000
	s_addc_u32 s5, s71, 0
	global_load_dwordx4 v[174:177], v232, s[4:5]
	s_add_u32 s4, s72, 0xc000
	s_addc_u32 s5, s73, 0
	global_load_dwordx4 v[206:209], v232, s[4:5]
	s_add_u32 s4, s70, 0xe000
	s_addc_u32 s5, s71, 0
	global_load_dwordx4 v[178:181], v232, s[4:5]
	s_add_u32 s4, s72, 0xe000
	s_addc_u32 s5, s73, 0
	global_load_dwordx4 v[210:213], v232, s[4:5]
	s_waitcnt vmcnt(14)
	v_lshlrev_b32_e32 v224, 16, v130
	v_and_b32_e32 v225, 0xffff0000, v130
	v_lshlrev_b32_e32 v228, 16, v182
	v_and_b32_e32 v229, 0xffff0000, v182
	v_pk_fma_f32 v[126:127], v[126:127], v[224:225], v[228:229]
	v_lshlrev_b32_e32 v226, 16, v131
	v_and_b32_e32 v227, 0xffff0000, v131
	v_lshlrev_b32_e32 v230, 16, v183
	v_and_b32_e32 v231, 0xffff0000, v183
	v_pk_fma_f32 v[128:129], v[128:129], v[226:227], v[230:231]
	v_lshlrev_b32_e32 v224, 16, v132
	v_and_b32_e32 v225, 0xffff0000, v132
	v_lshlrev_b32_e32 v228, 16, v184
	v_and_b32_e32 v229, 0xffff0000, v184
	v_pk_fma_f32 v[122:123], v[122:123], v[224:225], v[228:229]
	v_lshlrev_b32_e32 v226, 16, v133
	v_and_b32_e32 v227, 0xffff0000, v133
	v_lshlrev_b32_e32 v230, 16, v185
	v_and_b32_e32 v231, 0xffff0000, v185
	v_pk_fma_f32 v[124:125], v[124:125], v[226:227], v[230:231]
	v_cvt_pk_bf16_f32 v126, v126, v127
	v_cvt_pk_bf16_f32 v127, v128, v129
	v_cvt_pk_bf16_f32 v128, v122, v123
	v_cvt_pk_bf16_f32 v129, v124, v125
	s_add_u32 s76, s74, 0x0
	s_addc_u32 s77, s75, 0
	global_store_dwordx4 v233, v[126:129], s[76:77] nt
	s_add_u32 s4, s70, 0x10000
	s_addc_u32 s5, s71, 0
	global_load_dwordx4 v[130:133], v232, s[4:5]
	s_add_u32 s4, s72, 0x10000
	s_addc_u32 s5, s73, 0
	global_load_dwordx4 v[182:185], v232, s[4:5]
	s_waitcnt vmcnt(15)
	v_lshlrev_b32_e32 v224, 16, v134
	v_and_b32_e32 v225, 0xffff0000, v134
	v_lshlrev_b32_e32 v228, 16, v186
	v_and_b32_e32 v229, 0xffff0000, v186
	v_pk_fma_f32 v[118:119], v[118:119], v[224:225], v[228:229]
	v_lshlrev_b32_e32 v226, 16, v135
	v_and_b32_e32 v227, 0xffff0000, v135
	v_lshlrev_b32_e32 v230, 16, v187
	v_and_b32_e32 v231, 0xffff0000, v187
	v_pk_fma_f32 v[120:121], v[120:121], v[226:227], v[230:231]
	v_lshlrev_b32_e32 v224, 16, v136
	v_and_b32_e32 v225, 0xffff0000, v136
	v_lshlrev_b32_e32 v228, 16, v188
	v_and_b32_e32 v229, 0xffff0000, v188
	v_pk_fma_f32 v[114:115], v[114:115], v[224:225], v[228:229]
	v_lshlrev_b32_e32 v226, 16, v137
	v_and_b32_e32 v227, 0xffff0000, v137
	v_lshlrev_b32_e32 v230, 16, v189
	v_and_b32_e32 v231, 0xffff0000, v189
	v_pk_fma_f32 v[116:117], v[116:117], v[226:227], v[230:231]
	v_cvt_pk_bf16_f32 v118, v118, v119
	v_cvt_pk_bf16_f32 v119, v120, v121
	v_cvt_pk_bf16_f32 v120, v114, v115
	v_cvt_pk_bf16_f32 v121, v116, v117
	s_add_u32 s76, s74, 0x8000
	s_addc_u32 s77, s75, 0
	global_store_dwordx4 v233, v[118:121], s[76:77] nt
	s_add_u32 s4, s70, 0x12000
	s_addc_u32 s5, s71, 0
	global_load_dwordx4 v[134:137], v232, s[4:5]
	s_add_u32 s4, s72, 0x12000
	s_addc_u32 s5, s73, 0
	global_load_dwordx4 v[186:189], v232, s[4:5]
	s_waitcnt vmcnt(16)
	v_lshlrev_b32_e32 v224, 16, v156
	v_and_b32_e32 v225, 0xffff0000, v156
	v_lshlrev_b32_e32 v228, 16, v190
	v_and_b32_e32 v229, 0xffff0000, v190
	v_pk_fma_f32 v[110:111], v[110:111], v[224:225], v[228:229]
	v_lshlrev_b32_e32 v226, 16, v157
	v_and_b32_e32 v227, 0xffff0000, v157
	v_lshlrev_b32_e32 v230, 16, v191
	v_and_b32_e32 v231, 0xffff0000, v191
	v_pk_fma_f32 v[112:113], v[112:113], v[226:227], v[230:231]
	v_lshlrev_b32_e32 v224, 16, v158
	v_and_b32_e32 v225, 0xffff0000, v158
	v_lshlrev_b32_e32 v228, 16, v192
	v_and_b32_e32 v229, 0xffff0000, v192
	v_pk_fma_f32 v[106:107], v[106:107], v[224:225], v[228:229]
	v_lshlrev_b32_e32 v226, 16, v159
	v_and_b32_e32 v227, 0xffff0000, v159
	v_lshlrev_b32_e32 v230, 16, v193
	v_and_b32_e32 v231, 0xffff0000, v193
	v_pk_fma_f32 v[108:109], v[108:109], v[226:227], v[230:231]
	v_cvt_pk_bf16_f32 v110, v110, v111
	v_cvt_pk_bf16_f32 v111, v112, v113
	v_cvt_pk_bf16_f32 v112, v106, v107
	v_cvt_pk_bf16_f32 v113, v108, v109
	s_add_u32 s76, s74, 0x10000
	s_addc_u32 s77, s75, 0
	global_store_dwordx4 v233, v[110:113], s[76:77] nt
	s_add_u32 s4, s70, 0x14000
	s_addc_u32 s5, s71, 0
	global_load_dwordx4 v[156:159], v232, s[4:5]
	s_add_u32 s4, s72, 0x14000
	s_addc_u32 s5, s73, 0
	global_load_dwordx4 v[190:193], v232, s[4:5]
	s_waitcnt vmcnt(17)
	v_lshlrev_b32_e32 v224, 16, v162
	v_and_b32_e32 v225, 0xffff0000, v162
	v_lshlrev_b32_e32 v228, 16, v194
	v_and_b32_e32 v229, 0xffff0000, v194
	v_pk_fma_f32 v[102:103], v[102:103], v[224:225], v[228:229]
	v_lshlrev_b32_e32 v226, 16, v163
	v_and_b32_e32 v227, 0xffff0000, v163
	v_lshlrev_b32_e32 v230, 16, v195
	v_and_b32_e32 v231, 0xffff0000, v195
	v_pk_fma_f32 v[104:105], v[104:105], v[226:227], v[230:231]
	v_lshlrev_b32_e32 v224, 16, v164
	v_and_b32_e32 v225, 0xffff0000, v164
	v_lshlrev_b32_e32 v228, 16, v196
	v_and_b32_e32 v229, 0xffff0000, v196
	v_pk_fma_f32 v[98:99], v[98:99], v[224:225], v[228:229]
	v_lshlrev_b32_e32 v226, 16, v165
	v_and_b32_e32 v227, 0xffff0000, v165
	v_lshlrev_b32_e32 v230, 16, v197
	v_and_b32_e32 v231, 0xffff0000, v197
	v_pk_fma_f32 v[100:101], v[100:101], v[226:227], v[230:231]
	v_cvt_pk_bf16_f32 v102, v102, v103
	v_cvt_pk_bf16_f32 v103, v104, v105
	v_cvt_pk_bf16_f32 v104, v98, v99
	v_cvt_pk_bf16_f32 v105, v100, v101
	s_add_u32 s76, s74, 0x18000
	s_addc_u32 s77, s75, 0
	global_store_dwordx4 v233, v[102:105], s[76:77] nt
	s_add_u32 s4, s70, 0x16000
	s_addc_u32 s5, s71, 0
	global_load_dwordx4 v[162:165], v232, s[4:5]
	s_add_u32 s4, s72, 0x16000
	s_addc_u32 s5, s73, 0
	global_load_dwordx4 v[194:197], v232, s[4:5]
	s_waitcnt vmcnt(18)
	v_lshlrev_b32_e32 v224, 16, v166
	v_and_b32_e32 v225, 0xffff0000, v166
	v_lshlrev_b32_e32 v228, 16, v198
	v_and_b32_e32 v229, 0xffff0000, v198
	v_pk_fma_f32 v[94:95], v[94:95], v[224:225], v[228:229]
	v_lshlrev_b32_e32 v226, 16, v167
	v_and_b32_e32 v227, 0xffff0000, v167
	v_lshlrev_b32_e32 v230, 16, v199
	v_and_b32_e32 v231, 0xffff0000, v199
	v_pk_fma_f32 v[96:97], v[96:97], v[226:227], v[230:231]
	v_lshlrev_b32_e32 v224, 16, v168
	v_and_b32_e32 v225, 0xffff0000, v168
	v_lshlrev_b32_e32 v228, 16, v200
	v_and_b32_e32 v229, 0xffff0000, v200
	v_pk_fma_f32 v[90:91], v[90:91], v[224:225], v[228:229]
	v_lshlrev_b32_e32 v226, 16, v169
	v_and_b32_e32 v227, 0xffff0000, v169
	v_lshlrev_b32_e32 v230, 16, v201
	v_and_b32_e32 v231, 0xffff0000, v201
	v_pk_fma_f32 v[92:93], v[92:93], v[226:227], v[230:231]
	v_cvt_pk_bf16_f32 v94, v94, v95
	v_cvt_pk_bf16_f32 v95, v96, v97
	v_cvt_pk_bf16_f32 v96, v90, v91
	v_cvt_pk_bf16_f32 v97, v92, v93
	s_add_u32 s76, s74, 0x40000
	s_addc_u32 s77, s75, 0
	global_store_dwordx4 v233, v[94:97], s[76:77] nt
	s_add_u32 s4, s70, 0x18000
	s_addc_u32 s5, s71, 0
	global_load_dwordx4 v[166:169], v232, s[4:5]
	s_add_u32 s4, s72, 0x18000
	s_addc_u32 s5, s73, 0
	global_load_dwordx4 v[198:201], v232, s[4:5]
	s_waitcnt vmcnt(19)
	v_lshlrev_b32_e32 v224, 16, v170
	v_and_b32_e32 v225, 0xffff0000, v170
	v_lshlrev_b32_e32 v228, 16, v202
	v_and_b32_e32 v229, 0xffff0000, v202
	v_pk_fma_f32 v[86:87], v[86:87], v[224:225], v[228:229]
	v_lshlrev_b32_e32 v226, 16, v171
	v_and_b32_e32 v227, 0xffff0000, v171
	v_lshlrev_b32_e32 v230, 16, v203
	v_and_b32_e32 v231, 0xffff0000, v203
	v_pk_fma_f32 v[88:89], v[88:89], v[226:227], v[230:231]
	v_lshlrev_b32_e32 v224, 16, v172
	v_and_b32_e32 v225, 0xffff0000, v172
	v_lshlrev_b32_e32 v228, 16, v204
	v_and_b32_e32 v229, 0xffff0000, v204
	v_pk_fma_f32 v[82:83], v[82:83], v[224:225], v[228:229]
	v_lshlrev_b32_e32 v226, 16, v173
	v_and_b32_e32 v227, 0xffff0000, v173
	v_lshlrev_b32_e32 v230, 16, v205
	v_and_b32_e32 v231, 0xffff0000, v205
	v_pk_fma_f32 v[84:85], v[84:85], v[226:227], v[230:231]
	v_cvt_pk_bf16_f32 v86, v86, v87
	v_cvt_pk_bf16_f32 v87, v88, v89
	v_cvt_pk_bf16_f32 v88, v82, v83
	v_cvt_pk_bf16_f32 v89, v84, v85
	s_add_u32 s76, s74, 0x48000
	s_addc_u32 s77, s75, 0
	global_store_dwordx4 v233, v[86:89], s[76:77] nt
	s_add_u32 s4, s70, 0x1a000
	s_addc_u32 s5, s71, 0
	global_load_dwordx4 v[170:173], v232, s[4:5]
	s_add_u32 s4, s72, 0x1a000
	s_addc_u32 s5, s73, 0
	global_load_dwordx4 v[202:205], v232, s[4:5]
	s_waitcnt vmcnt(20)
	v_lshlrev_b32_e32 v224, 16, v174
	v_and_b32_e32 v225, 0xffff0000, v174
	v_lshlrev_b32_e32 v228, 16, v206
	v_and_b32_e32 v229, 0xffff0000, v206
	v_pk_fma_f32 v[78:79], v[78:79], v[224:225], v[228:229]
	v_lshlrev_b32_e32 v226, 16, v175
	v_and_b32_e32 v227, 0xffff0000, v175
	v_lshlrev_b32_e32 v230, 16, v207
	v_and_b32_e32 v231, 0xffff0000, v207
	v_pk_fma_f32 v[80:81], v[80:81], v[226:227], v[230:231]
	v_lshlrev_b32_e32 v224, 16, v176
	v_and_b32_e32 v225, 0xffff0000, v176
	v_lshlrev_b32_e32 v228, 16, v208
	v_and_b32_e32 v229, 0xffff0000, v208
	v_pk_fma_f32 v[74:75], v[74:75], v[224:225], v[228:229]
	v_lshlrev_b32_e32 v226, 16, v177
	v_and_b32_e32 v227, 0xffff0000, v177
	v_lshlrev_b32_e32 v230, 16, v209
	v_and_b32_e32 v231, 0xffff0000, v209
	v_pk_fma_f32 v[76:77], v[76:77], v[226:227], v[230:231]
	v_cvt_pk_bf16_f32 v78, v78, v79
	v_cvt_pk_bf16_f32 v79, v80, v81
	v_cvt_pk_bf16_f32 v80, v74, v75
	v_cvt_pk_bf16_f32 v81, v76, v77
	s_add_u32 s76, s74, 0x50000
	s_addc_u32 s77, s75, 0
	global_store_dwordx4 v233, v[78:81], s[76:77] nt
	s_add_u32 s4, s70, 0x1c000
	s_addc_u32 s5, s71, 0
	global_load_dwordx4 v[174:177], v232, s[4:5]
	s_add_u32 s4, s72, 0x1c000
	s_addc_u32 s5, s73, 0
	global_load_dwordx4 v[206:209], v232, s[4:5]
	s_waitcnt vmcnt(21)
	v_lshlrev_b32_e32 v224, 16, v178
	v_and_b32_e32 v225, 0xffff0000, v178
	v_lshlrev_b32_e32 v228, 16, v210
	v_and_b32_e32 v229, 0xffff0000, v210
	v_pk_fma_f32 v[70:71], v[70:71], v[224:225], v[228:229]
	v_lshlrev_b32_e32 v226, 16, v179
	v_and_b32_e32 v227, 0xffff0000, v179
	v_lshlrev_b32_e32 v230, 16, v211
	v_and_b32_e32 v231, 0xffff0000, v211
	v_pk_fma_f32 v[72:73], v[72:73], v[226:227], v[230:231]
	v_lshlrev_b32_e32 v224, 16, v180
	v_and_b32_e32 v225, 0xffff0000, v180
	v_lshlrev_b32_e32 v228, 16, v212
	v_and_b32_e32 v229, 0xffff0000, v212
	v_pk_fma_f32 v[66:67], v[66:67], v[224:225], v[228:229]
	v_lshlrev_b32_e32 v226, 16, v181
	v_and_b32_e32 v227, 0xffff0000, v181
	v_lshlrev_b32_e32 v230, 16, v213
	v_and_b32_e32 v231, 0xffff0000, v213
	v_pk_fma_f32 v[68:69], v[68:69], v[226:227], v[230:231]
	v_cvt_pk_bf16_f32 v70, v70, v71
	v_cvt_pk_bf16_f32 v71, v72, v73
	v_cvt_pk_bf16_f32 v72, v66, v67
	v_cvt_pk_bf16_f32 v73, v68, v69
	s_add_u32 s76, s74, 0x58000
	s_addc_u32 s77, s75, 0
	global_store_dwordx4 v233, v[70:73], s[76:77] nt
	s_add_u32 s4, s70, 0x1e000
	s_addc_u32 s5, s71, 0
	global_load_dwordx4 v[178:181], v232, s[4:5]
	s_add_u32 s4, s72, 0x1e000
	s_addc_u32 s5, s73, 0
	global_load_dwordx4 v[210:213], v232, s[4:5]
	s_waitcnt vmcnt(21)
	v_lshlrev_b32_e32 v224, 16, v130
	v_and_b32_e32 v225, 0xffff0000, v130
	v_lshlrev_b32_e32 v228, 16, v182
	v_and_b32_e32 v229, 0xffff0000, v182
	v_pk_fma_f32 v[62:63], v[62:63], v[224:225], v[228:229]
	v_lshlrev_b32_e32 v226, 16, v131
	v_and_b32_e32 v227, 0xffff0000, v131
	v_lshlrev_b32_e32 v230, 16, v183
	v_and_b32_e32 v231, 0xffff0000, v183
	v_pk_fma_f32 v[64:65], v[64:65], v[226:227], v[230:231]
	v_lshlrev_b32_e32 v224, 16, v132
	v_and_b32_e32 v225, 0xffff0000, v132
	v_lshlrev_b32_e32 v228, 16, v184
	v_and_b32_e32 v229, 0xffff0000, v184
	v_pk_fma_f32 v[58:59], v[58:59], v[224:225], v[228:229]
	v_lshlrev_b32_e32 v226, 16, v133
	v_and_b32_e32 v227, 0xffff0000, v133
	v_lshlrev_b32_e32 v230, 16, v185
	v_and_b32_e32 v231, 0xffff0000, v185
	v_pk_fma_f32 v[60:61], v[60:61], v[226:227], v[230:231]
	v_cvt_pk_bf16_f32 v62, v62, v63
	v_cvt_pk_bf16_f32 v63, v64, v65
	v_cvt_pk_bf16_f32 v64, v58, v59
	v_cvt_pk_bf16_f32 v65, v60, v61
	s_add_u32 s76, s74, 0x100
	s_addc_u32 s77, s75, 0
	global_store_dwordx4 v233, v[62:65], s[76:77] nt
	s_waitcnt vmcnt(19)
	v_lshlrev_b32_e32 v224, 16, v134
	v_and_b32_e32 v225, 0xffff0000, v134
	v_lshlrev_b32_e32 v228, 16, v186
	v_and_b32_e32 v229, 0xffff0000, v186
	v_pk_fma_f32 v[54:55], v[54:55], v[224:225], v[228:229]
	v_lshlrev_b32_e32 v226, 16, v135
	v_and_b32_e32 v227, 0xffff0000, v135
	v_lshlrev_b32_e32 v230, 16, v187
	v_and_b32_e32 v231, 0xffff0000, v187
	v_pk_fma_f32 v[56:57], v[56:57], v[226:227], v[230:231]
	v_lshlrev_b32_e32 v224, 16, v136
	v_and_b32_e32 v225, 0xffff0000, v136
	v_lshlrev_b32_e32 v228, 16, v188
	v_and_b32_e32 v229, 0xffff0000, v188
	v_pk_fma_f32 v[50:51], v[50:51], v[224:225], v[228:229]
	v_lshlrev_b32_e32 v226, 16, v137
	v_and_b32_e32 v227, 0xffff0000, v137
	v_lshlrev_b32_e32 v230, 16, v189
	v_and_b32_e32 v231, 0xffff0000, v189
	v_pk_fma_f32 v[52:53], v[52:53], v[226:227], v[230:231]
	v_cvt_pk_bf16_f32 v54, v54, v55
	v_cvt_pk_bf16_f32 v55, v56, v57
	v_cvt_pk_bf16_f32 v56, v50, v51
	v_cvt_pk_bf16_f32 v57, v52, v53
	s_add_u32 s76, s74, 0x8100
	s_addc_u32 s77, s75, 0
	global_store_dwordx4 v233, v[54:57], s[76:77] nt
	s_waitcnt vmcnt(17)
	v_lshlrev_b32_e32 v224, 16, v156
	v_and_b32_e32 v225, 0xffff0000, v156
	v_lshlrev_b32_e32 v228, 16, v190
	v_and_b32_e32 v229, 0xffff0000, v190
	v_pk_fma_f32 v[46:47], v[46:47], v[224:225], v[228:229]
	v_lshlrev_b32_e32 v226, 16, v157
	v_and_b32_e32 v227, 0xffff0000, v157
	v_lshlrev_b32_e32 v230, 16, v191
	v_and_b32_e32 v231, 0xffff0000, v191
	v_pk_fma_f32 v[48:49], v[48:49], v[226:227], v[230:231]
	v_lshlrev_b32_e32 v224, 16, v158
	v_and_b32_e32 v225, 0xffff0000, v158
	v_lshlrev_b32_e32 v228, 16, v192
	v_and_b32_e32 v229, 0xffff0000, v192
	v_pk_fma_f32 v[42:43], v[42:43], v[224:225], v[228:229]
	v_lshlrev_b32_e32 v226, 16, v159
	v_and_b32_e32 v227, 0xffff0000, v159
	v_lshlrev_b32_e32 v230, 16, v193
	v_and_b32_e32 v231, 0xffff0000, v193
	v_pk_fma_f32 v[44:45], v[44:45], v[226:227], v[230:231]
	v_cvt_pk_bf16_f32 v46, v46, v47
	v_cvt_pk_bf16_f32 v47, v48, v49
	v_cvt_pk_bf16_f32 v48, v42, v43
	v_cvt_pk_bf16_f32 v49, v44, v45
	s_add_u32 s76, s74, 0x10100
	s_addc_u32 s77, s75, 0
	global_store_dwordx4 v233, v[46:49], s[76:77] nt
	s_waitcnt vmcnt(15)
	v_lshlrev_b32_e32 v224, 16, v162
	v_and_b32_e32 v225, 0xffff0000, v162
	v_lshlrev_b32_e32 v228, 16, v194
	v_and_b32_e32 v229, 0xffff0000, v194
	v_pk_fma_f32 v[38:39], v[38:39], v[224:225], v[228:229]
	v_lshlrev_b32_e32 v226, 16, v163
	v_and_b32_e32 v227, 0xffff0000, v163
	v_lshlrev_b32_e32 v230, 16, v195
	v_and_b32_e32 v231, 0xffff0000, v195
	v_pk_fma_f32 v[40:41], v[40:41], v[226:227], v[230:231]
	v_lshlrev_b32_e32 v224, 16, v164
	v_and_b32_e32 v225, 0xffff0000, v164
	v_lshlrev_b32_e32 v228, 16, v196
	v_and_b32_e32 v229, 0xffff0000, v196
	v_pk_fma_f32 v[34:35], v[34:35], v[224:225], v[228:229]
	v_lshlrev_b32_e32 v226, 16, v165
	v_and_b32_e32 v227, 0xffff0000, v165
	v_lshlrev_b32_e32 v230, 16, v197
	v_and_b32_e32 v231, 0xffff0000, v197
	v_pk_fma_f32 v[36:37], v[36:37], v[226:227], v[230:231]
	v_cvt_pk_bf16_f32 v38, v38, v39
	v_cvt_pk_bf16_f32 v39, v40, v41
	v_cvt_pk_bf16_f32 v40, v34, v35
	v_cvt_pk_bf16_f32 v41, v36, v37
	s_add_u32 s76, s74, 0x18100
	s_addc_u32 s77, s75, 0
	global_store_dwordx4 v233, v[38:41], s[76:77] nt
	s_waitcnt vmcnt(13)
	v_lshlrev_b32_e32 v224, 16, v166
	v_and_b32_e32 v225, 0xffff0000, v166
	v_lshlrev_b32_e32 v228, 16, v198
	v_and_b32_e32 v229, 0xffff0000, v198
	v_pk_fma_f32 v[30:31], v[30:31], v[224:225], v[228:229]
	v_lshlrev_b32_e32 v226, 16, v167
	v_and_b32_e32 v227, 0xffff0000, v167
	v_lshlrev_b32_e32 v230, 16, v199
	v_and_b32_e32 v231, 0xffff0000, v199
	v_pk_fma_f32 v[32:33], v[32:33], v[226:227], v[230:231]
	v_lshlrev_b32_e32 v224, 16, v168
	v_and_b32_e32 v225, 0xffff0000, v168
	v_lshlrev_b32_e32 v228, 16, v200
	v_and_b32_e32 v229, 0xffff0000, v200
	v_pk_fma_f32 v[26:27], v[26:27], v[224:225], v[228:229]
	v_lshlrev_b32_e32 v226, 16, v169
	v_and_b32_e32 v227, 0xffff0000, v169
	v_lshlrev_b32_e32 v230, 16, v201
	v_and_b32_e32 v231, 0xffff0000, v201
	v_pk_fma_f32 v[28:29], v[28:29], v[226:227], v[230:231]
	v_cvt_pk_bf16_f32 v30, v30, v31
	v_cvt_pk_bf16_f32 v31, v32, v33
	v_cvt_pk_bf16_f32 v32, v26, v27
	v_cvt_pk_bf16_f32 v33, v28, v29
	s_add_u32 s76, s74, 0x40100
	s_addc_u32 s77, s75, 0
	global_store_dwordx4 v233, v[30:33], s[76:77] nt
	s_waitcnt vmcnt(11)
	v_lshlrev_b32_e32 v224, 16, v170
	v_and_b32_e32 v225, 0xffff0000, v170
	v_lshlrev_b32_e32 v228, 16, v202
	v_and_b32_e32 v229, 0xffff0000, v202
	v_pk_fma_f32 v[22:23], v[22:23], v[224:225], v[228:229]
	v_lshlrev_b32_e32 v226, 16, v171
	v_and_b32_e32 v227, 0xffff0000, v171
	v_lshlrev_b32_e32 v230, 16, v203
	v_and_b32_e32 v231, 0xffff0000, v203
	v_pk_fma_f32 v[24:25], v[24:25], v[226:227], v[230:231]
	v_lshlrev_b32_e32 v224, 16, v172
	v_and_b32_e32 v225, 0xffff0000, v172
	v_lshlrev_b32_e32 v228, 16, v204
	v_and_b32_e32 v229, 0xffff0000, v204
	v_pk_fma_f32 v[18:19], v[18:19], v[224:225], v[228:229]
	v_lshlrev_b32_e32 v226, 16, v173
	v_and_b32_e32 v227, 0xffff0000, v173
	v_lshlrev_b32_e32 v230, 16, v205
	v_and_b32_e32 v231, 0xffff0000, v205
	v_pk_fma_f32 v[20:21], v[20:21], v[226:227], v[230:231]
	v_cvt_pk_bf16_f32 v22, v22, v23
	v_cvt_pk_bf16_f32 v23, v24, v25
	v_cvt_pk_bf16_f32 v24, v18, v19
	v_cvt_pk_bf16_f32 v25, v20, v21
	s_add_u32 s76, s74, 0x48100
	s_addc_u32 s77, s75, 0
	global_store_dwordx4 v233, v[22:25], s[76:77] nt
	s_waitcnt vmcnt(9)
	v_lshlrev_b32_e32 v224, 16, v174
	v_and_b32_e32 v225, 0xffff0000, v174
	v_lshlrev_b32_e32 v228, 16, v206
	v_and_b32_e32 v229, 0xffff0000, v206
	v_pk_fma_f32 v[14:15], v[14:15], v[224:225], v[228:229]
	v_lshlrev_b32_e32 v226, 16, v175
	v_and_b32_e32 v227, 0xffff0000, v175
	v_lshlrev_b32_e32 v230, 16, v207
	v_and_b32_e32 v231, 0xffff0000, v207
	v_pk_fma_f32 v[16:17], v[16:17], v[226:227], v[230:231]
	v_lshlrev_b32_e32 v224, 16, v176
	v_and_b32_e32 v225, 0xffff0000, v176
	v_lshlrev_b32_e32 v228, 16, v208
	v_and_b32_e32 v229, 0xffff0000, v208
	v_pk_fma_f32 v[10:11], v[10:11], v[224:225], v[228:229]
	v_lshlrev_b32_e32 v226, 16, v177
	v_and_b32_e32 v227, 0xffff0000, v177
	v_lshlrev_b32_e32 v230, 16, v209
	v_and_b32_e32 v231, 0xffff0000, v209
	v_pk_fma_f32 v[12:13], v[12:13], v[226:227], v[230:231]
	v_cvt_pk_bf16_f32 v14, v14, v15
	v_cvt_pk_bf16_f32 v15, v16, v17
	v_cvt_pk_bf16_f32 v16, v10, v11
	v_cvt_pk_bf16_f32 v17, v12, v13
	s_add_u32 s76, s74, 0x50100
	s_addc_u32 s77, s75, 0
	global_store_dwordx4 v233, v[14:17], s[76:77] nt
	s_waitcnt vmcnt(7)
	v_lshlrev_b32_e32 v224, 16, v178
	v_and_b32_e32 v225, 0xffff0000, v178
	v_lshlrev_b32_e32 v228, 16, v210
	v_and_b32_e32 v229, 0xffff0000, v210
	v_pk_fma_f32 v[6:7], v[6:7], v[224:225], v[228:229]
	v_lshlrev_b32_e32 v226, 16, v179
	v_and_b32_e32 v227, 0xffff0000, v179
	v_lshlrev_b32_e32 v230, 16, v211
	v_and_b32_e32 v231, 0xffff0000, v211
	v_pk_fma_f32 v[8:9], v[8:9], v[226:227], v[230:231]
	v_lshlrev_b32_e32 v224, 16, v180
	v_and_b32_e32 v225, 0xffff0000, v180
	v_lshlrev_b32_e32 v228, 16, v212
	v_and_b32_e32 v229, 0xffff0000, v212
	v_pk_fma_f32 v[0:1], v[0:1], v[224:225], v[228:229]
	v_lshlrev_b32_e32 v226, 16, v181
	v_and_b32_e32 v227, 0xffff0000, v181
	v_lshlrev_b32_e32 v230, 16, v213
	v_and_b32_e32 v231, 0xffff0000, v213
	v_pk_fma_f32 v[2:3], v[2:3], v[226:227], v[230:231]
	v_cvt_pk_bf16_f32 v6, v6, v7
	v_cvt_pk_bf16_f32 v7, v8, v9
	v_cvt_pk_bf16_f32 v8, v0, v1
	v_cvt_pk_bf16_f32 v9, v2, v3
	s_add_u32 s76, s74, 0x58100
	s_addc_u32 s77, s75, 0
	global_store_dwordx4 v233, v[6:9], s[76:77] nt

.Lwout_l0:
	s_cmp_lt_u32 s11, 32
	s_cselect_b32 s12, s36, s38
	s_cselect_b32 s13, s37, s39
	s_and_b32 s0, s11, 31
	s_lshl_b32 s0, s0, 20
	s_add_u32 s12, s12, s0
	s_addc_u32 s13, s13, 0
	s_lshl_b32 s0, s16, 2
	s_add_u32 s12, s12, s0
	s_addc_u32 s13, s13, 0
	s_add_u32 s0, s12, 0x0
	s_addc_u32 s1, s13, 0
	global_load_dwordx4 v[130:133], v232, s[0:1]
	global_load_dwordx4 v[134:137], v232, s[0:1] offset:16
	s_add_u32 s0, s12, 0x10000
	s_addc_u32 s1, s13, 0
	global_load_dwordx4 v[156:159], v232, s[0:1]
	global_load_dwordx4 v[160:163], v232, s[0:1] offset:16
	s_add_u32 s0, s12, 0x20000
	s_addc_u32 s1, s13, 0
	global_load_dwordx4 v[164:167], v232, s[0:1]
	global_load_dwordx4 v[168:171], v232, s[0:1] offset:16
	s_add_u32 s0, s12, 0x30000
	s_addc_u32 s1, s13, 0
	global_load_dwordx4 v[172:175], v232, s[0:1]
	global_load_dwordx4 v[176:179], v232, s[0:1] offset:16
	s_add_u32 s0, s12, 0x80000
	s_addc_u32 s1, s13, 0
	global_load_dwordx4 v[198:201], v232, s[0:1]
	global_load_dwordx4 v[202:205], v232, s[0:1] offset:16
	s_add_u32 s0, s12, 0x90000
	s_addc_u32 s1, s13, 0
	global_load_dwordx4 v[206:209], v232, s[0:1]
	global_load_dwordx4 v[210:213], v232, s[0:1] offset:16
	s_waitcnt vmcnt(10)
	v_pk_fma_f32 v[126:127], v[126:127], v[182:183], v[130:131]
	v_pk_fma_f32 v[128:129], v[128:129], v[184:185], v[132:133]
	v_pk_fma_f32 v[122:123], v[122:123], v[186:187], v[134:135]
	v_pk_fma_f32 v[124:125], v[124:125], v[188:189], v[136:137]
	v_cvt_pk_bf16_f32 v126, v126, v127
	v_cvt_pk_bf16_f32 v127, v128, v129
	v_cvt_pk_bf16_f32 v128, v122, v123
	v_cvt_pk_bf16_f32 v129, v124, v125
	s_add_u32 s8, s14, 0x0
	s_addc_u32 s9, s15, 0
	global_store_dwordx4 v233, v[126:129], s[8:9] nt
	s_add_u32 s0, s12, 0xa0000
	s_addc_u32 s1, s13, 0
	global_load_dwordx4 v[130:133], v232, s[0:1]
	global_load_dwordx4 v[134:137], v232, s[0:1] offset:16
	s_waitcnt vmcnt(11)
	v_pk_fma_f32 v[118:119], v[118:119], v[182:183], v[156:157]
	v_pk_fma_f32 v[120:121], v[120:121], v[184:185], v[158:159]
	v_pk_fma_f32 v[114:115], v[114:115], v[186:187], v[160:161]
	v_pk_fma_f32 v[116:117], v[116:117], v[188:189], v[162:163]
	v_cvt_pk_bf16_f32 v118, v118, v119
	v_cvt_pk_bf16_f32 v119, v120, v121
	v_cvt_pk_bf16_f32 v120, v114, v115
	v_cvt_pk_bf16_f32 v121, v116, v117
	s_add_u32 s8, s14, 0x8000
	s_addc_u32 s9, s15, 0
	global_store_dwordx4 v233, v[118:121], s[8:9] nt
	s_add_u32 s0, s12, 0xb0000
	s_addc_u32 s1, s13, 0
	global_load_dwordx4 v[156:159], v232, s[0:1]
	global_load_dwordx4 v[160:163], v232, s[0:1] offset:16
	s_waitcnt vmcnt(12)
	v_pk_fma_f32 v[110:111], v[110:111], v[182:183], v[164:165]
	v_pk_fma_f32 v[112:113], v[112:113], v[184:185], v[166:167]
	v_pk_fma_f32 v[106:107], v[106:107], v[186:187], v[168:169]
	v_pk_fma_f32 v[108:109], v[108:109], v[188:189], v[170:171]
	v_cvt_pk_bf16_f32 v110, v110, v111
	v_cvt_pk_bf16_f32 v111, v112, v113
	v_cvt_pk_bf16_f32 v112, v106, v107
	v_cvt_pk_bf16_f32 v113, v108, v109
	s_add_u32 s8, s14, 0x10000
	s_addc_u32 s9, s15, 0
	global_store_dwordx4 v233, v[110:113], s[8:9] nt
	s_add_u32 s0, s12, 0x200
	s_addc_u32 s1, s13, 0
	global_load_dwordx4 v[164:167], v232, s[0:1]
	global_load_dwordx4 v[168:171], v232, s[0:1] offset:16
	s_waitcnt vmcnt(13)
	v_pk_fma_f32 v[102:103], v[102:103], v[182:183], v[172:173]
	v_pk_fma_f32 v[104:105], v[104:105], v[184:185], v[174:175]
	v_pk_fma_f32 v[98:99], v[98:99], v[186:187], v[176:177]
	v_pk_fma_f32 v[100:101], v[100:101], v[188:189], v[178:179]
	v_cvt_pk_bf16_f32 v102, v102, v103
	v_cvt_pk_bf16_f32 v103, v104, v105
	v_cvt_pk_bf16_f32 v104, v98, v99
	v_cvt_pk_bf16_f32 v105, v100, v101
	s_add_u32 s8, s14, 0x18000
	s_addc_u32 s9, s15, 0
	global_store_dwordx4 v233, v[102:105], s[8:9] nt
	s_add_u32 s0, s12, 0x10200
	s_addc_u32 s1, s13, 0
	global_load_dwordx4 v[172:175], v232, s[0:1]
	global_load_dwordx4 v[176:179], v232, s[0:1] offset:16
	s_waitcnt vmcnt(14)
	v_pk_fma_f32 v[94:95], v[94:95], v[182:183], v[198:199]
	v_pk_fma_f32 v[96:97], v[96:97], v[184:185], v[200:201]
	v_pk_fma_f32 v[90:91], v[90:91], v[186:187], v[202:203]
	v_pk_fma_f32 v[92:93], v[92:93], v[188:189], v[204:205]
	v_cvt_pk_bf16_f32 v94, v94, v95
	v_cvt_pk_bf16_f32 v95, v96, v97
	v_cvt_pk_bf16_f32 v96, v90, v91
	v_cvt_pk_bf16_f32 v97, v92, v93
	s_add_u32 s8, s14, 0x40000
	s_addc_u32 s9, s15, 0
	global_store_dwordx4 v233, v[94:97], s[8:9] nt
	s_add_u32 s0, s12, 0x20200
	s_addc_u32 s1, s13, 0
	global_load_dwordx4 v[198:201], v232, s[0:1]
	global_load_dwordx4 v[202:205], v232, s[0:1] offset:16
	s_waitcnt vmcnt(15)
	v_pk_fma_f32 v[86:87], v[86:87], v[182:183], v[206:207]
	v_pk_fma_f32 v[88:89], v[88:89], v[184:185], v[208:209]
	v_pk_fma_f32 v[82:83], v[82:83], v[186:187], v[210:211]
	v_pk_fma_f32 v[84:85], v[84:85], v[188:189], v[212:213]
	v_cvt_pk_bf16_f32 v86, v86, v87
	v_cvt_pk_bf16_f32 v87, v88, v89
	v_cvt_pk_bf16_f32 v88, v82, v83
	v_cvt_pk_bf16_f32 v89, v84, v85
	s_add_u32 s8, s14, 0x48000
	s_addc_u32 s9, s15, 0
	global_store_dwordx4 v233, v[86:89], s[8:9] nt
	s_add_u32 s0, s12, 0x30200
	s_addc_u32 s1, s13, 0
	global_load_dwordx4 v[206:209], v232, s[0:1]
	global_load_dwordx4 v[210:213], v232, s[0:1] offset:16
	s_waitcnt vmcnt(15)
	v_pk_fma_f32 v[78:79], v[78:79], v[182:183], v[130:131]
	v_pk_fma_f32 v[80:81], v[80:81], v[184:185], v[132:133]
	v_pk_fma_f32 v[74:75], v[74:75], v[186:187], v[134:135]
	v_pk_fma_f32 v[76:77], v[76:77], v[188:189], v[136:137]
	v_cvt_pk_bf16_f32 v78, v78, v79
	v_cvt_pk_bf16_f32 v79, v80, v81
	v_cvt_pk_bf16_f32 v80, v74, v75
	v_cvt_pk_bf16_f32 v81, v76, v77
	s_add_u32 s8, s14, 0x50000
	s_addc_u32 s9, s15, 0
	global_store_dwordx4 v233, v[78:81], s[8:9] nt
	s_add_u32 s0, s12, 0x80200
	s_addc_u32 s1, s13, 0
	global_load_dwordx4 v[130:133], v232, s[0:1]
	global_load_dwordx4 v[134:137], v232, s[0:1] offset:16
	s_waitcnt vmcnt(15)
	v_pk_fma_f32 v[70:71], v[70:71], v[182:183], v[156:157]
	v_pk_fma_f32 v[72:73], v[72:73], v[184:185], v[158:159]
	v_pk_fma_f32 v[66:67], v[66:67], v[186:187], v[160:161]
	v_pk_fma_f32 v[68:69], v[68:69], v[188:189], v[162:163]
	v_cvt_pk_bf16_f32 v70, v70, v71
	v_cvt_pk_bf16_f32 v71, v72, v73
	v_cvt_pk_bf16_f32 v72, v66, v67
	v_cvt_pk_bf16_f32 v73, v68, v69
	s_add_u32 s8, s14, 0x58000
	s_addc_u32 s9, s15, 0
	global_store_dwordx4 v233, v[70:73], s[8:9] nt
	s_add_u32 s0, s12, 0x90200
	s_addc_u32 s1, s13, 0
	global_load_dwordx4 v[156:159], v232, s[0:1]
	global_load_dwordx4 v[160:163], v232, s[0:1] offset:16
	s_waitcnt vmcnt(15)
	v_pk_fma_f32 v[62:63], v[62:63], v[190:191], v[164:165]
	v_pk_fma_f32 v[64:65], v[64:65], v[192:193], v[166:167]
	v_pk_fma_f32 v[58:59], v[58:59], v[194:195], v[168:169]
	v_pk_fma_f32 v[60:61], v[60:61], v[196:197], v[170:171]
	v_cvt_pk_bf16_f32 v62, v62, v63
	v_cvt_pk_bf16_f32 v63, v64, v65
	v_cvt_pk_bf16_f32 v64, v58, v59
	v_cvt_pk_bf16_f32 v65, v60, v61
	s_add_u32 s8, s14, 0x100
	s_addc_u32 s9, s15, 0
	global_store_dwordx4 v233, v[62:65], s[8:9] nt
	s_add_u32 s0, s12, 0xa0200
	s_addc_u32 s1, s13, 0
	global_load_dwordx4 v[164:167], v232, s[0:1]
	global_load_dwordx4 v[168:171], v232, s[0:1] offset:16
	s_waitcnt vmcnt(15)
	v_pk_fma_f32 v[54:55], v[54:55], v[190:191], v[172:173]
	v_pk_fma_f32 v[56:57], v[56:57], v[192:193], v[174:175]
	v_pk_fma_f32 v[50:51], v[50:51], v[194:195], v[176:177]
	v_pk_fma_f32 v[52:53], v[52:53], v[196:197], v[178:179]
	v_cvt_pk_bf16_f32 v54, v54, v55
	v_cvt_pk_bf16_f32 v55, v56, v57
	v_cvt_pk_bf16_f32 v56, v50, v51
	v_cvt_pk_bf16_f32 v57, v52, v53
	s_add_u32 s8, s14, 0x8100
	s_addc_u32 s9, s15, 0
	global_store_dwordx4 v233, v[54:57], s[8:9] nt
	s_add_u32 s0, s12, 0xb0200
	s_addc_u32 s1, s13, 0
	global_load_dwordx4 v[172:175], v232, s[0:1]
	global_load_dwordx4 v[176:179], v232, s[0:1] offset:16
	s_waitcnt vmcnt(15)
	v_pk_fma_f32 v[46:47], v[46:47], v[190:191], v[198:199]
	v_pk_fma_f32 v[48:49], v[48:49], v[192:193], v[200:201]
	v_pk_fma_f32 v[42:43], v[42:43], v[194:195], v[202:203]
	v_pk_fma_f32 v[44:45], v[44:45], v[196:197], v[204:205]
	v_cvt_pk_bf16_f32 v46, v46, v47
	v_cvt_pk_bf16_f32 v47, v48, v49
	v_cvt_pk_bf16_f32 v48, v42, v43
	v_cvt_pk_bf16_f32 v49, v44, v45
	s_add_u32 s8, s14, 0x10100
	s_addc_u32 s9, s15, 0
	global_store_dwordx4 v233, v[46:49], s[8:9] nt
	s_waitcnt vmcnt(13)
	v_pk_fma_f32 v[38:39], v[38:39], v[190:191], v[206:207]
	v_pk_fma_f32 v[40:41], v[40:41], v[192:193], v[208:209]
	v_pk_fma_f32 v[34:35], v[34:35], v[194:195], v[210:211]
	v_pk_fma_f32 v[36:37], v[36:37], v[196:197], v[212:213]
	v_cvt_pk_bf16_f32 v38, v38, v39
	v_cvt_pk_bf16_f32 v39, v40, v41
	v_cvt_pk_bf16_f32 v40, v34, v35
	v_cvt_pk_bf16_f32 v41, v36, v37
	s_add_u32 s8, s14, 0x18100
	s_addc_u32 s9, s15, 0
	global_store_dwordx4 v233, v[38:41], s[8:9] nt
	s_waitcnt vmcnt(11)
	v_pk_fma_f32 v[30:31], v[30:31], v[190:191], v[130:131]
	v_pk_fma_f32 v[32:33], v[32:33], v[192:193], v[132:133]
	v_pk_fma_f32 v[26:27], v[26:27], v[194:195], v[134:135]
	v_pk_fma_f32 v[28:29], v[28:29], v[196:197], v[136:137]
	v_cvt_pk_bf16_f32 v30, v30, v31
	v_cvt_pk_bf16_f32 v31, v32, v33
	v_cvt_pk_bf16_f32 v32, v26, v27
	v_cvt_pk_bf16_f32 v33, v28, v29
	s_add_u32 s8, s14, 0x40100
	s_addc_u32 s9, s15, 0
	global_store_dwordx4 v233, v[30:33], s[8:9] nt
	s_waitcnt vmcnt(9)
	v_pk_fma_f32 v[22:23], v[22:23], v[190:191], v[156:157]
	v_pk_fma_f32 v[24:25], v[24:25], v[192:193], v[158:159]
	v_pk_fma_f32 v[18:19], v[18:19], v[194:195], v[160:161]
	v_pk_fma_f32 v[20:21], v[20:21], v[196:197], v[162:163]
	v_cvt_pk_bf16_f32 v22, v22, v23
	v_cvt_pk_bf16_f32 v23, v24, v25
	v_cvt_pk_bf16_f32 v24, v18, v19
	v_cvt_pk_bf16_f32 v25, v20, v21
	s_add_u32 s8, s14, 0x48100
	s_addc_u32 s9, s15, 0
	global_store_dwordx4 v233, v[22:25], s[8:9] nt
	s_waitcnt vmcnt(7)
	v_pk_fma_f32 v[14:15], v[14:15], v[190:191], v[164:165]
	v_pk_fma_f32 v[16:17], v[16:17], v[192:193], v[166:167]
	v_pk_fma_f32 v[10:11], v[10:11], v[194:195], v[168:169]
	v_pk_fma_f32 v[12:13], v[12:13], v[196:197], v[170:171]
	v_cvt_pk_bf16_f32 v14, v14, v15
	v_cvt_pk_bf16_f32 v15, v16, v17
	v_cvt_pk_bf16_f32 v16, v10, v11
	v_cvt_pk_bf16_f32 v17, v12, v13
	s_add_u32 s8, s14, 0x50100
	s_addc_u32 s9, s15, 0
	global_store_dwordx4 v233, v[14:17], s[8:9] nt
	s_waitcnt vmcnt(5)
	v_pk_fma_f32 v[6:7], v[6:7], v[190:191], v[172:173]
	v_pk_fma_f32 v[8:9], v[8:9], v[192:193], v[174:175]
	v_pk_fma_f32 v[0:1], v[0:1], v[194:195], v[176:177]
	v_pk_fma_f32 v[2:3], v[2:3], v[196:197], v[178:179]
	v_cvt_pk_bf16_f32 v6, v6, v7
	v_cvt_pk_bf16_f32 v7, v8, v9
	v_cvt_pk_bf16_f32 v8, v0, v1
	v_cvt_pk_bf16_f32 v9, v2, v3
	s_add_u32 s8, s14, 0x58100
	s_addc_u32 s9, s15, 0
	global_store_dwordx4 v233, v[6:9], s[8:9] nt
	s_branch .Lwout_done
.Lwout_l1:
	s_lshl_b32 s0, s11, 19
	s_lshl_b32 s1, s16, 1
	s_add_u32 s0, s0, s1
	s_add_u32 s12, s30, s0
	s_addc_u32 s13, s31, 0
	s_add_u32 s0, s12, 0x0
	s_addc_u32 s1, s13, 0
	global_load_dwordx4 v[130:133], v233, s[0:1]
	s_add_u32 s0, s12, 0x8000
	s_addc_u32 s1, s13, 0
	global_load_dwordx4 v[134:137], v233, s[0:1]
	s_add_u32 s0, s12, 0x10000
	s_addc_u32 s1, s13, 0
	global_load_dwordx4 v[156:159], v233, s[0:1]
	s_add_u32 s0, s12, 0x18000
	s_addc_u32 s1, s13, 0
	global_load_dwordx4 v[160:163], v233, s[0:1]
	s_add_u32 s0, s12, 0x40000
	s_addc_u32 s1, s13, 0
	global_load_dwordx4 v[164:167], v233, s[0:1]
	s_add_u32 s0, s12, 0x48000
	s_addc_u32 s1, s13, 0
	global_load_dwordx4 v[168:171], v233, s[0:1]
	s_add_u32 s0, s12, 0x50000
	s_addc_u32 s1, s13, 0
	global_load_dwordx4 v[172:175], v233, s[0:1]
	s_add_u32 s0, s12, 0x58000
	s_addc_u32 s1, s13, 0
	global_load_dwordx4 v[176:179], v233, s[0:1]
	s_waitcnt vmcnt(7)
	v_lshlrev_b32_e32 v224, 16, v130
	v_and_b32_e32 v225, 0xffff0000, v130
	v_pk_fma_f32 v[126:127], v[126:127], v[182:183], v[224:225]
	v_lshlrev_b32_e32 v226, 16, v131
	v_and_b32_e32 v227, 0xffff0000, v131
	v_pk_fma_f32 v[128:129], v[128:129], v[184:185], v[226:227]
	v_lshlrev_b32_e32 v228, 16, v132
	v_and_b32_e32 v229, 0xffff0000, v132
	v_pk_fma_f32 v[122:123], v[122:123], v[186:187], v[228:229]
	v_lshlrev_b32_e32 v230, 16, v133
	v_and_b32_e32 v231, 0xffff0000, v133
	v_pk_fma_f32 v[124:125], v[124:125], v[188:189], v[230:231]
	v_cvt_pk_bf16_f32 v126, v126, v127
	v_cvt_pk_bf16_f32 v127, v128, v129
	v_cvt_pk_bf16_f32 v128, v122, v123
	v_cvt_pk_bf16_f32 v129, v124, v125
	s_add_u32 s8, s14, 0x0
	s_addc_u32 s9, s15, 0
	global_store_dwordx4 v233, v[126:129], s[8:9] nt
	s_add_u32 s0, s12, 0x100
	s_addc_u32 s1, s13, 0
	global_load_dwordx4 v[130:133], v233, s[0:1]
	s_waitcnt vmcnt(8)
	v_lshlrev_b32_e32 v224, 16, v134
	v_and_b32_e32 v225, 0xffff0000, v134
	v_pk_fma_f32 v[118:119], v[118:119], v[182:183], v[224:225]
	v_lshlrev_b32_e32 v226, 16, v135
	v_and_b32_e32 v227, 0xffff0000, v135
	v_pk_fma_f32 v[120:121], v[120:121], v[184:185], v[226:227]
	v_lshlrev_b32_e32 v228, 16, v136
	v_and_b32_e32 v229, 0xffff0000, v136
	v_pk_fma_f32 v[114:115], v[114:115], v[186:187], v[228:229]
	v_lshlrev_b32_e32 v230, 16, v137
	v_and_b32_e32 v231, 0xffff0000, v137
	v_pk_fma_f32 v[116:117], v[116:117], v[188:189], v[230:231]
	v_cvt_pk_bf16_f32 v118, v118, v119
	v_cvt_pk_bf16_f32 v119, v120, v121
	v_cvt_pk_bf16_f32 v120, v114, v115
	v_cvt_pk_bf16_f32 v121, v116, v117
	s_add_u32 s8, s14, 0x8000
	s_addc_u32 s9, s15, 0
	global_store_dwordx4 v233, v[118:121], s[8:9] nt
	s_add_u32 s0, s12, 0x8100
	s_addc_u32 s1, s13, 0
	global_load_dwordx4 v[134:137], v233, s[0:1]
	s_waitcnt vmcnt(9)
	v_lshlrev_b32_e32 v224, 16, v156
	v_and_b32_e32 v225, 0xffff0000, v156
	v_pk_fma_f32 v[110:111], v[110:111], v[182:183], v[224:225]
	v_lshlrev_b32_e32 v226, 16, v157
	v_and_b32_e32 v227, 0xffff0000, v157
	v_pk_fma_f32 v[112:113], v[112:113], v[184:185], v[226:227]
	v_lshlrev_b32_e32 v228, 16, v158
	v_and_b32_e32 v229, 0xffff0000, v158
	v_pk_fma_f32 v[106:107], v[106:107], v[186:187], v[228:229]
	v_lshlrev_b32_e32 v230, 16, v159
	v_and_b32_e32 v231, 0xffff0000, v159
	v_pk_fma_f32 v[108:109], v[108:109], v[188:189], v[230:231]
	v_cvt_pk_bf16_f32 v110, v110, v111
	v_cvt_pk_bf16_f32 v111, v112, v113
	v_cvt_pk_bf16_f32 v112, v106, v107
	v_cvt_pk_bf16_f32 v113, v108, v109
	s_add_u32 s8, s14, 0x10000
	s_addc_u32 s9, s15, 0
	global_store_dwordx4 v233, v[110:113], s[8:9] nt
	s_add_u32 s0, s12, 0x10100
	s_addc_u32 s1, s13, 0
	global_load_dwordx4 v[156:159], v233, s[0:1]
	s_waitcnt vmcnt(10)
	v_lshlrev_b32_e32 v224, 16, v160
	v_and_b32_e32 v225, 0xffff0000, v160
	v_pk_fma_f32 v[102:103], v[102:103], v[182:183], v[224:225]
	v_lshlrev_b32_e32 v226, 16, v161
	v_and_b32_e32 v227, 0xffff0000, v161
	v_pk_fma_f32 v[104:105], v[104:105], v[184:185], v[226:227]
	v_lshlrev_b32_e32 v228, 16, v162
	v_and_b32_e32 v229, 0xffff0000, v162
	v_pk_fma_f32 v[98:99], v[98:99], v[186:187], v[228:229]
	v_lshlrev_b32_e32 v230, 16, v163
	v_and_b32_e32 v231, 0xffff0000, v163
	v_pk_fma_f32 v[100:101], v[100:101], v[188:189], v[230:231]
	v_cvt_pk_bf16_f32 v102, v102, v103
	v_cvt_pk_bf16_f32 v103, v104, v105
	v_cvt_pk_bf16_f32 v104, v98, v99
	v_cvt_pk_bf16_f32 v105, v100, v101
	s_add_u32 s8, s14, 0x18000
	s_addc_u32 s9, s15, 0
	global_store_dwordx4 v233, v[102:105], s[8:9] nt
	s_add_u32 s0, s12, 0x18100
	s_addc_u32 s1, s13, 0
	global_load_dwordx4 v[160:163], v233, s[0:1]
	s_waitcnt vmcnt(11)
	v_lshlrev_b32_e32 v224, 16, v164
	v_and_b32_e32 v225, 0xffff0000, v164
	v_pk_fma_f32 v[94:95], v[94:95], v[182:183], v[224:225]
	v_lshlrev_b32_e32 v226, 16, v165
	v_and_b32_e32 v227, 0xffff0000, v165
	v_pk_fma_f32 v[96:97], v[96:97], v[184:185], v[226:227]
	v_lshlrev_b32_e32 v228, 16, v166
	v_and_b32_e32 v229, 0xffff0000, v166
	v_pk_fma_f32 v[90:91], v[90:91], v[186:187], v[228:229]
	v_lshlrev_b32_e32 v230, 16, v167
	v_and_b32_e32 v231, 0xffff0000, v167
	v_pk_fma_f32 v[92:93], v[92:93], v[188:189], v[230:231]
	v_cvt_pk_bf16_f32 v94, v94, v95
	v_cvt_pk_bf16_f32 v95, v96, v97
	v_cvt_pk_bf16_f32 v96, v90, v91
	v_cvt_pk_bf16_f32 v97, v92, v93
	s_add_u32 s8, s14, 0x40000
	s_addc_u32 s9, s15, 0
	global_store_dwordx4 v233, v[94:97], s[8:9] nt
	s_add_u32 s0, s12, 0x40100
	s_addc_u32 s1, s13, 0
	global_load_dwordx4 v[164:167], v233, s[0:1]
	s_waitcnt vmcnt(12)
	v_lshlrev_b32_e32 v224, 16, v168
	v_and_b32_e32 v225, 0xffff0000, v168
	v_pk_fma_f32 v[86:87], v[86:87], v[182:183], v[224:225]
	v_lshlrev_b32_e32 v226, 16, v169
	v_and_b32_e32 v227, 0xffff0000, v169
	v_pk_fma_f32 v[88:89], v[88:89], v[184:185], v[226:227]
	v_lshlrev_b32_e32 v228, 16, v170
	v_and_b32_e32 v229, 0xffff0000, v170
	v_pk_fma_f32 v[82:83], v[82:83], v[186:187], v[228:229]
	v_lshlrev_b32_e32 v230, 16, v171
	v_and_b32_e32 v231, 0xffff0000, v171
	v_pk_fma_f32 v[84:85], v[84:85], v[188:189], v[230:231]
	v_cvt_pk_bf16_f32 v86, v86, v87
	v_cvt_pk_bf16_f32 v87, v88, v89
	v_cvt_pk_bf16_f32 v88, v82, v83
	v_cvt_pk_bf16_f32 v89, v84, v85
	s_add_u32 s8, s14, 0x48000
	s_addc_u32 s9, s15, 0
	global_store_dwordx4 v233, v[86:89], s[8:9] nt
	s_add_u32 s0, s12, 0x48100
	s_addc_u32 s1, s13, 0
	global_load_dwordx4 v[168:171], v233, s[0:1]
	s_waitcnt vmcnt(13)
	v_lshlrev_b32_e32 v224, 16, v172
	v_and_b32_e32 v225, 0xffff0000, v172
	v_pk_fma_f32 v[78:79], v[78:79], v[182:183], v[224:225]
	v_lshlrev_b32_e32 v226, 16, v173
	v_and_b32_e32 v227, 0xffff0000, v173
	v_pk_fma_f32 v[80:81], v[80:81], v[184:185], v[226:227]
	v_lshlrev_b32_e32 v228, 16, v174
	v_and_b32_e32 v229, 0xffff0000, v174
	v_pk_fma_f32 v[74:75], v[74:75], v[186:187], v[228:229]
	v_lshlrev_b32_e32 v230, 16, v175
	v_and_b32_e32 v231, 0xffff0000, v175
	v_pk_fma_f32 v[76:77], v[76:77], v[188:189], v[230:231]
	v_cvt_pk_bf16_f32 v78, v78, v79
	v_cvt_pk_bf16_f32 v79, v80, v81
	v_cvt_pk_bf16_f32 v80, v74, v75
	v_cvt_pk_bf16_f32 v81, v76, v77
	s_add_u32 s8, s14, 0x50000
	s_addc_u32 s9, s15, 0
	global_store_dwordx4 v233, v[78:81], s[8:9] nt
	s_add_u32 s0, s12, 0x50100
	s_addc_u32 s1, s13, 0
	global_load_dwordx4 v[172:175], v233, s[0:1]
	s_waitcnt vmcnt(14)
	v_lshlrev_b32_e32 v224, 16, v176
	v_and_b32_e32 v225, 0xffff0000, v176
	v_pk_fma_f32 v[70:71], v[70:71], v[182:183], v[224:225]
	v_lshlrev_b32_e32 v226, 16, v177
	v_and_b32_e32 v227, 0xffff0000, v177
	v_pk_fma_f32 v[72:73], v[72:73], v[184:185], v[226:227]
	v_lshlrev_b32_e32 v228, 16, v178
	v_and_b32_e32 v229, 0xffff0000, v178
	v_pk_fma_f32 v[66:67], v[66:67], v[186:187], v[228:229]
	v_lshlrev_b32_e32 v230, 16, v179
	v_and_b32_e32 v231, 0xffff0000, v179
	v_pk_fma_f32 v[68:69], v[68:69], v[188:189], v[230:231]
	v_cvt_pk_bf16_f32 v70, v70, v71
	v_cvt_pk_bf16_f32 v71, v72, v73
	v_cvt_pk_bf16_f32 v72, v66, v67
	v_cvt_pk_bf16_f32 v73, v68, v69
	s_add_u32 s8, s14, 0x58000
	s_addc_u32 s9, s15, 0
	global_store_dwordx4 v233, v[70:73], s[8:9] nt
	s_add_u32 s0, s12, 0x58100
	s_addc_u32 s1, s13, 0
	global_load_dwordx4 v[176:179], v233, s[0:1]
	s_waitcnt vmcnt(14)
	v_lshlrev_b32_e32 v224, 16, v130
	v_and_b32_e32 v225, 0xffff0000, v130
	v_pk_fma_f32 v[62:63], v[62:63], v[190:191], v[224:225]
	v_lshlrev_b32_e32 v226, 16, v131
	v_and_b32_e32 v227, 0xffff0000, v131
	v_pk_fma_f32 v[64:65], v[64:65], v[192:193], v[226:227]
	v_lshlrev_b32_e32 v228, 16, v132
	v_and_b32_e32 v229, 0xffff0000, v132
	v_pk_fma_f32 v[58:59], v[58:59], v[194:195], v[228:229]
	v_lshlrev_b32_e32 v230, 16, v133
	v_and_b32_e32 v231, 0xffff0000, v133
	v_pk_fma_f32 v[60:61], v[60:61], v[196:197], v[230:231]
	v_cvt_pk_bf16_f32 v62, v62, v63
	v_cvt_pk_bf16_f32 v63, v64, v65
	v_cvt_pk_bf16_f32 v64, v58, v59
	v_cvt_pk_bf16_f32 v65, v60, v61
	s_add_u32 s8, s14, 0x100
	s_addc_u32 s9, s15, 0
	global_store_dwordx4 v233, v[62:65], s[8:9] nt
	s_waitcnt vmcnt(13)
	v_lshlrev_b32_e32 v224, 16, v134
	v_and_b32_e32 v225, 0xffff0000, v134
	v_pk_fma_f32 v[54:55], v[54:55], v[190:191], v[224:225]
	v_lshlrev_b32_e32 v226, 16, v135
	v_and_b32_e32 v227, 0xffff0000, v135
	v_pk_fma_f32 v[56:57], v[56:57], v[192:193], v[226:227]
	v_lshlrev_b32_e32 v228, 16, v136
	v_and_b32_e32 v229, 0xffff0000, v136
	v_pk_fma_f32 v[50:51], v[50:51], v[194:195], v[228:229]
	v_lshlrev_b32_e32 v230, 16, v137
	v_and_b32_e32 v231, 0xffff0000, v137
	v_pk_fma_f32 v[52:53], v[52:53], v[196:197], v[230:231]
	v_cvt_pk_bf16_f32 v54, v54, v55
	v_cvt_pk_bf16_f32 v55, v56, v57
	v_cvt_pk_bf16_f32 v56, v50, v51
	v_cvt_pk_bf16_f32 v57, v52, v53
	s_add_u32 s8, s14, 0x8100
	s_addc_u32 s9, s15, 0
	global_store_dwordx4 v233, v[54:57], s[8:9] nt
	s_waitcnt vmcnt(12)
	v_lshlrev_b32_e32 v224, 16, v156
	v_and_b32_e32 v225, 0xffff0000, v156
	v_pk_fma_f32 v[46:47], v[46:47], v[190:191], v[224:225]
	v_lshlrev_b32_e32 v226, 16, v157
	v_and_b32_e32 v227, 0xffff0000, v157
	v_pk_fma_f32 v[48:49], v[48:49], v[192:193], v[226:227]
	v_lshlrev_b32_e32 v228, 16, v158
	v_and_b32_e32 v229, 0xffff0000, v158
	v_pk_fma_f32 v[42:43], v[42:43], v[194:195], v[228:229]
	v_lshlrev_b32_e32 v230, 16, v159
	v_and_b32_e32 v231, 0xffff0000, v159
	v_pk_fma_f32 v[44:45], v[44:45], v[196:197], v[230:231]
	v_cvt_pk_bf16_f32 v46, v46, v47
	v_cvt_pk_bf16_f32 v47, v48, v49
	v_cvt_pk_bf16_f32 v48, v42, v43
	v_cvt_pk_bf16_f32 v49, v44, v45
	s_add_u32 s8, s14, 0x10100
	s_addc_u32 s9, s15, 0
	global_store_dwordx4 v233, v[46:49], s[8:9] nt
	s_waitcnt vmcnt(11)
	v_lshlrev_b32_e32 v224, 16, v160
	v_and_b32_e32 v225, 0xffff0000, v160
	v_pk_fma_f32 v[38:39], v[38:39], v[190:191], v[224:225]
	v_lshlrev_b32_e32 v226, 16, v161
	v_and_b32_e32 v227, 0xffff0000, v161
	v_pk_fma_f32 v[40:41], v[40:41], v[192:193], v[226:227]
	v_lshlrev_b32_e32 v228, 16, v162
	v_and_b32_e32 v229, 0xffff0000, v162
	v_pk_fma_f32 v[34:35], v[34:35], v[194:195], v[228:229]
	v_lshlrev_b32_e32 v230, 16, v163
	v_and_b32_e32 v231, 0xffff0000, v163
	v_pk_fma_f32 v[36:37], v[36:37], v[196:197], v[230:231]
	v_cvt_pk_bf16_f32 v38, v38, v39
	v_cvt_pk_bf16_f32 v39, v40, v41
	v_cvt_pk_bf16_f32 v40, v34, v35
	v_cvt_pk_bf16_f32 v41, v36, v37
	s_add_u32 s8, s14, 0x18100
	s_addc_u32 s9, s15, 0
	global_store_dwordx4 v233, v[38:41], s[8:9] nt
	s_waitcnt vmcnt(10)
	v_lshlrev_b32_e32 v224, 16, v164
	v_and_b32_e32 v225, 0xffff0000, v164
	v_pk_fma_f32 v[30:31], v[30:31], v[190:191], v[224:225]
	v_lshlrev_b32_e32 v226, 16, v165
	v_and_b32_e32 v227, 0xffff0000, v165
	v_pk_fma_f32 v[32:33], v[32:33], v[192:193], v[226:227]
	v_lshlrev_b32_e32 v228, 16, v166
	v_and_b32_e32 v229, 0xffff0000, v166
	v_pk_fma_f32 v[26:27], v[26:27], v[194:195], v[228:229]
	v_lshlrev_b32_e32 v230, 16, v167
	v_and_b32_e32 v231, 0xffff0000, v167
	v_pk_fma_f32 v[28:29], v[28:29], v[196:197], v[230:231]
	v_cvt_pk_bf16_f32 v30, v30, v31
	v_cvt_pk_bf16_f32 v31, v32, v33
	v_cvt_pk_bf16_f32 v32, v26, v27
	v_cvt_pk_bf16_f32 v33, v28, v29
	s_add_u32 s8, s14, 0x40100
	s_addc_u32 s9, s15, 0
	global_store_dwordx4 v233, v[30:33], s[8:9] nt
	s_waitcnt vmcnt(9)
	v_lshlrev_b32_e32 v224, 16, v168
	v_and_b32_e32 v225, 0xffff0000, v168
	v_pk_fma_f32 v[22:23], v[22:23], v[190:191], v[224:225]
	v_lshlrev_b32_e32 v226, 16, v169
	v_and_b32_e32 v227, 0xffff0000, v169
	v_pk_fma_f32 v[24:25], v[24:25], v[192:193], v[226:227]
	v_lshlrev_b32_e32 v228, 16, v170
	v_and_b32_e32 v229, 0xffff0000, v170
	v_pk_fma_f32 v[18:19], v[18:19], v[194:195], v[228:229]
	v_lshlrev_b32_e32 v230, 16, v171
	v_and_b32_e32 v231, 0xffff0000, v171
	v_pk_fma_f32 v[20:21], v[20:21], v[196:197], v[230:231]
	v_cvt_pk_bf16_f32 v22, v22, v23
	v_cvt_pk_bf16_f32 v23, v24, v25
	v_cvt_pk_bf16_f32 v24, v18, v19
	v_cvt_pk_bf16_f32 v25, v20, v21
	s_add_u32 s8, s14, 0x48100
	s_addc_u32 s9, s15, 0
	global_store_dwordx4 v233, v[22:25], s[8:9] nt
	s_waitcnt vmcnt(8)
	v_lshlrev_b32_e32 v224, 16, v172
	v_and_b32_e32 v225, 0xffff0000, v172
	v_pk_fma_f32 v[14:15], v[14:15], v[190:191], v[224:225]
	v_lshlrev_b32_e32 v226, 16, v173
	v_and_b32_e32 v227, 0xffff0000, v173
	v_pk_fma_f32 v[16:17], v[16:17], v[192:193], v[226:227]
	v_lshlrev_b32_e32 v228, 16, v174
	v_and_b32_e32 v229, 0xffff0000, v174
	v_pk_fma_f32 v[10:11], v[10:11], v[194:195], v[228:229]
	v_lshlrev_b32_e32 v230, 16, v175
	v_and_b32_e32 v231, 0xffff0000, v175
	v_pk_fma_f32 v[12:13], v[12:13], v[196:197], v[230:231]
	v_cvt_pk_bf16_f32 v14, v14, v15
	v_cvt_pk_bf16_f32 v15, v16, v17
	v_cvt_pk_bf16_f32 v16, v10, v11
	v_cvt_pk_bf16_f32 v17, v12, v13
	s_add_u32 s8, s14, 0x50100
	s_addc_u32 s9, s15, 0
	global_store_dwordx4 v233, v[14:17], s[8:9] nt
	s_waitcnt vmcnt(7)
	v_lshlrev_b32_e32 v224, 16, v176
	v_and_b32_e32 v225, 0xffff0000, v176
	v_pk_fma_f32 v[6:7], v[6:7], v[190:191], v[224:225]
	v_lshlrev_b32_e32 v226, 16, v177
	v_and_b32_e32 v227, 0xffff0000, v177
	v_pk_fma_f32 v[8:9], v[8:9], v[192:193], v[226:227]
	v_lshlrev_b32_e32 v228, 16, v178
	v_and_b32_e32 v229, 0xffff0000, v178
	v_pk_fma_f32 v[0:1], v[0:1], v[194:195], v[228:229]
	v_lshlrev_b32_e32 v230, 16, v179
	v_and_b32_e32 v231, 0xffff0000, v179
	v_pk_fma_f32 v[2:3], v[2:3], v[196:197], v[230:231]
	v_cvt_pk_bf16_f32 v6, v6, v7
	v_cvt_pk_bf16_f32 v7, v8, v9
	v_cvt_pk_bf16_f32 v8, v0, v1
	v_cvt_pk_bf16_f32 v9, v2, v3
	s_add_u32 s8, s14, 0x58100
	s_addc_u32 s9, s15, 0
	global_store_dwordx4 v233, v[6:9], s[8:9] nt
